# v12 + removed 102 back-to-back duplicate s_waitcnt lgkmcnt(0) (the first of each pair already drains the counter)
# speedup vs baseline: 1.0238x; 1.0033x over previous
; #define PG8_STAGE(bufoff, gbase, voff) do { _Pragma("unroll") for (int _i = 0; _i < 2; ++_i) \
;         __builtin_amdgcn_global_load_lds((const unsigned*)((const char*)(gbase) + (voff)[_i]), (LAS unsigned*)(lds + (bufoff) + ldsw + _i * 8192), 16, 0, 0); } while (0)
; #define PG8_LDA(dst, b, h) do { _Pragma("unroll") for (int m = 0; m < 4; ++m) _Pragma("unroll") for (int k = 0; k < 2; ++k) dst[m][k] = *(const LAS bf16x8*)(lds + PG8_SA(b, h) + aoff + m * 2048 + k * 1024); } while (0)
; #define PG8_LDB(dst, b, h) do { _Pragma("unroll") for (int n = 0; n < 2; ++n) _Pragma("unroll") for (int k = 0; k < 2; ++k) dst[n][k] = *(const LAS bf16x8*)(lds + PG8_SB(b, h) + boff + n * 2048 + k * 1024); } while (0)
; #define PG8_MMA(ai, bj, At, Bt) do { __builtin_amdgcn_s_setprio(1); _Pragma("unroll") for (int m = 0; m < 4; ++m) _Pragma("unroll") for (int n = 0; n < 2; ++n) _Pragma("unroll") for (int k = 0; k < 2; ++k) \
;         acc[ai][bj][m][n] = __builtin_amdgcn_mfma_f32_16x16x32_bf16(Bt[n][k], At[m][k], acc[ai][bj][m][n], 0, 0, 0); __builtin_amdgcn_s_setprio(0); } while (0)
; #define PG8_WAIT_V(n) asm volatile("s_waitcnt vmcnt(" #n ")" ::: "memory")
; #define PG8_WAIT_L(n) asm volatile("s_waitcnt lgkmcnt(" #n ")" ::: "memory")
; #define PG8_BAR __builtin_amdgcn_s_barrier()
; template <class Epi>
; __device__ __forceinline__ void gemm_phase(LAS unsigned char* lds, const Gemm g, const StaticOrder& S, const Epi& E, int wv) {
;     ...
;             const bool last = (t == nt - 2);
;             const char* a1 = cA + (ptrdiff_t)(t + 1) * kstep;
;             const char* a2 = last ? nA : cA + (ptrdiff_t)(t + 2) * kstep; const char* b2 = last ? nB : cB + (ptrdiff_t)(t + 2) * kstep;
;             const char* a3 = a2 + kstep; const char* b3 = b2 + kstep;
;             PG8_LDB(B0, 0, 0); PG8_SCHED; PG8_LDA(At, 0, 0); PG8_STAGE(PG8_SA(1, 1), a1 + hstepA, voffA);
;             PG8_WAIT_L(8); PG8_BAR; PG8_WAIT_L(0); PG8_MMA(0, 0, At, B0); PG8_BAR; PG8_SCHED;
;             PG8_LDB(B1, 0, 1); PG8_STAGE(PG8_SB(0, 0), b2, voffB);
;             PG8_BAR; PG8_WAIT_L(0); PG8_MMA(0, 1, At, B1); PG8_BAR;
;             PG8_LDA(At, 0, 1); PG8_STAGE(PG8_SA(0, 0), a2, voffA);
;             PG8_BAR; PG8_WAIT_L(0); PG8_MMA(1, 0, At, B0); PG8_BAR; PG8_SCHED;
;             PG8_STAGE(PG8_SB(0, 1), b2 + hstepB, voffB);
;             PG8_WAIT_V(6); PG8_BAR; PG8_MMA(1, 1, At, B1); PG8_BAR;
.Lrot_in_208:
	s_add_u32 s39, s70, 0xfff80080
	s_addc_u32 s40, s71, -1
	s_cmp_eq_u32 s38, 28
	s_cselect_b32 s75, s21, s40
	s_cselect_b32 s74, s30, s39
	s_cselect_b32 s73, s31, s35
	s_cselect_b32 s72, s33, s34
	s_add_i32 m0, s10, 0xc000
	ds_read_b128 v[160:163], v191
	ds_read_b128 v[164:167], v191 offset:1024
	ds_read_b128 v[168:171], v191 offset:2048
	ds_read_b128 v[172:175], v191 offset:3072
	ds_read_b128 v[176:179], v191 offset:4096
	ds_read_b128 v[198:201], v191 offset:5120
	ds_read_b128 v[202:205], v191 offset:6144
	ds_read_b128 v[206:209], v191 offset:7168
	global_load_lds_dwordx4 v144, s[70:71]
	s_add_i32 m0, s10, 0xe000
	s_nop 0
	global_load_lds_dwordx4 v146, s[70:71]
	s_waitcnt lgkmcnt(8)
	s_barrier
	s_waitcnt lgkmcnt(0)
	v_mfma_f32_16x16x32_bf16 v[124:127], v[128:131], v[160:163], v[124:127]
	v_mfma_f32_16x16x32_bf16 v[120:123], v[152:155], v[160:163], v[120:123]
	v_mfma_f32_16x16x32_bf16 v[108:111], v[128:131], v[168:171], v[108:111]
	v_mfma_f32_16x16x32_bf16 v[104:107], v[152:155], v[168:171], v[104:107]
	v_mfma_f32_16x16x32_bf16 v[92:95], v[128:131], v[176:179], v[92:95]
	v_mfma_f32_16x16x32_bf16 v[88:91], v[152:155], v[176:179], v[88:91]
	v_mfma_f32_16x16x32_bf16 v[76:79], v[128:131], v[202:205], v[76:79]
	v_mfma_f32_16x16x32_bf16 v[72:75], v[152:155], v[202:205], v[72:75]
	v_mfma_f32_16x16x32_bf16 v[124:127], v[132:135], v[164:167], v[124:127]
	v_mfma_f32_16x16x32_bf16 v[120:123], v[156:159], v[164:167], v[120:123]
	v_mfma_f32_16x16x32_bf16 v[108:111], v[132:135], v[172:175], v[108:111]
	v_mfma_f32_16x16x32_bf16 v[104:107], v[156:159], v[172:175], v[104:107]
	v_mfma_f32_16x16x32_bf16 v[92:95], v[132:135], v[198:201], v[92:95]
	v_mfma_f32_16x16x32_bf16 v[88:91], v[156:159], v[198:201], v[88:91]
	v_mfma_f32_16x16x32_bf16 v[76:79], v[132:135], v[206:209], v[76:79]
	v_mfma_f32_16x16x32_bf16 v[72:75], v[156:159], v[206:209], v[72:75]
	s_barrier
	s_add_i32 s39, s23, s9
	s_add_u32 s98, s72, s58
	s_addc_u32 s99, s73, s59
	s_mov_b32 m0, s39
	ds_read_b128 v[210:213], v192
	ds_read_b128 v[214:217], v192 offset:1024
	ds_read_b128 v[218:221], v192 offset:2048
	ds_read_b128 v[222:225], v192 offset:3072
	global_load_lds_dwordx4 v138, s[72:73]
	s_add_i32 m0, s39, 0x2000
	s_nop 0
	global_load_lds_dwordx4 v142, s[72:73]
	s_barrier
	s_waitcnt lgkmcnt(0)
	v_mfma_f32_16x16x32_bf16 v[116:119], v[210:213], v[160:163], v[116:119]
	v_mfma_f32_16x16x32_bf16 v[112:115], v[218:221], v[160:163], v[112:115]
	v_mfma_f32_16x16x32_bf16 v[100:103], v[210:213], v[168:171], v[100:103]
	v_mfma_f32_16x16x32_bf16 v[96:99], v[218:221], v[168:171], v[96:99]
	v_mfma_f32_16x16x32_bf16 v[84:87], v[210:213], v[176:179], v[84:87]
	v_mfma_f32_16x16x32_bf16 v[80:83], v[218:221], v[176:179], v[80:83]
	v_mfma_f32_16x16x32_bf16 v[68:71], v[210:213], v[202:205], v[68:71]
	v_mfma_f32_16x16x32_bf16 v[64:67], v[218:221], v[202:205], v[64:67]
	v_mfma_f32_16x16x32_bf16 v[116:119], v[214:217], v[164:167], v[116:119]
	v_mfma_f32_16x16x32_bf16 v[112:115], v[222:225], v[164:167], v[112:115]
	v_mfma_f32_16x16x32_bf16 v[100:103], v[214:217], v[172:175], v[100:103]
	v_mfma_f32_16x16x32_bf16 v[96:99], v[222:225], v[172:175], v[96:99]
	v_mfma_f32_16x16x32_bf16 v[84:87], v[214:217], v[198:201], v[84:87]
	v_mfma_f32_16x16x32_bf16 v[80:83], v[222:225], v[198:201], v[80:83]
	v_mfma_f32_16x16x32_bf16 v[68:71], v[214:217], v[206:209], v[68:71]
	v_mfma_f32_16x16x32_bf16 v[64:67], v[222:225], v[206:209], v[64:67]
	s_mov_b32 m0, s10
	s_add_u32 s100, s74, s58
	s_addc_u32 s101, s75, s59
	s_barrier
	ds_read_b128 v[160:163], v191 offset:16384
	ds_read_b128 v[164:167], v191 offset:17408
	ds_read_b128 v[168:171], v191 offset:18432
	ds_read_b128 v[172:175], v191 offset:19456
	ds_read_b128 v[176:179], v191 offset:20480
	ds_read_b128 v[198:201], v191 offset:21504
	ds_read_b128 v[202:205], v191 offset:22528
	ds_read_b128 v[206:209], v191 offset:23552
	global_load_lds_dwordx4 v136, s[74:75]
	s_mov_b32 m0, s11
	s_nop 0
	global_load_lds_dwordx4 v140, s[74:75]
	s_waitcnt vmcnt(10)
	s_barrier
	s_waitcnt lgkmcnt(0)
	v_mfma_f32_16x16x32_bf16 v[60:63], v[128:131], v[160:163], v[60:63]
	v_mfma_f32_16x16x32_bf16 v[56:59], v[152:155], v[160:163], v[56:59]
	v_mfma_f32_16x16x32_bf16 v[44:47], v[128:131], v[168:171], v[44:47]
	v_mfma_f32_16x16x32_bf16 v[40:43], v[152:155], v[168:171], v[40:43]
	v_mfma_f32_16x16x32_bf16 v[28:31], v[128:131], v[176:179], v[28:31]
	v_mfma_f32_16x16x32_bf16 v[24:27], v[152:155], v[176:179], v[24:27]
	v_mfma_f32_16x16x32_bf16 v[12:15], v[128:131], v[202:205], v[12:15]
	v_mfma_f32_16x16x32_bf16 v[8:11], v[152:155], v[202:205], v[8:11]
	v_mfma_f32_16x16x32_bf16 v[60:63], v[132:135], v[164:167], v[60:63]
	v_mfma_f32_16x16x32_bf16 v[56:59], v[156:159], v[164:167], v[56:59]
	v_mfma_f32_16x16x32_bf16 v[44:47], v[132:135], v[172:175], v[44:47]
	v_mfma_f32_16x16x32_bf16 v[40:43], v[156:159], v[172:175], v[40:43]
	v_mfma_f32_16x16x32_bf16 v[28:31], v[132:135], v[198:201], v[28:31]
	v_mfma_f32_16x16x32_bf16 v[24:27], v[156:159], v[198:201], v[24:27]
	v_mfma_f32_16x16x32_bf16 v[12:15], v[132:135], v[206:209], v[12:15]
	v_mfma_f32_16x16x32_bf16 v[8:11], v[156:159], v[206:209], v[8:11]
	s_barrier
	s_add_u32 s40, s72, 0x80000
	s_addc_u32 s41, s73, 0
	s_add_i32 s39, s24, s9
	s_mov_b32 m0, s39
	s_nop 0
	global_load_lds_dwordx4 v138, s[40:41]
	s_add_i32 m0, s39, 0x2000
	s_nop 0
	global_load_lds_dwordx4 v142, s[40:41]
	s_add_i32 s39, 0, 0x18000
	v_add_u32_e32 v156, s39, v184
	ds_read_b128 v[128:131], v156
	ds_read_b128 v[132:135], v156 offset:1024
	ds_read_b128 v[152:155], v156 offset:2048
	ds_read_b128 v[156:159], v156 offset:3072
	s_waitcnt vmcnt(6)
	s_barrier
; #define PG8_STAGE(bufoff, gbase, voff) do { _Pragma("unroll") for (int _i = 0; _i < 2; ++_i) \
;         __builtin_amdgcn_global_load_lds((const unsigned*)((const char*)(gbase) + (voff)[_i]), (LAS unsigned*)(lds + (bufoff) + ldsw + _i * 8192), 16, 0, 0); } while (0)
; #define PG8_LDA(dst, b, h) do { _Pragma("unroll") for (int m = 0; m < 4; ++m) _Pragma("unroll") for (int k = 0; k < 2; ++k) dst[m][k] = *(const LAS bf16x8*)(lds + PG8_SA(b, h) + aoff + m * 2048 + k * 1024); } while (0)
; #define PG8_LDB(dst, b, h) do { _Pragma("unroll") for (int n = 0; n < 2; ++n) _Pragma("unroll") for (int k = 0; k < 2; ++k) dst[n][k] = *(const LAS bf16x8*)(lds + PG8_SB(b, h) + boff + n * 2048 + k * 1024); } while (0)
; #define PG8_MMA(ai, bj, At, Bt) do { __builtin_amdgcn_s_setprio(1); _Pragma("unroll") for (int m = 0; m < 4; ++m) _Pragma("unroll") for (int n = 0; n < 2; ++n) _Pragma("unroll") for (int k = 0; k < 2; ++k) \
;         acc[ai][bj][m][n] = __builtin_amdgcn_mfma_f32_16x16x32_bf16(Bt[n][k], At[m][k], acc[ai][bj][m][n], 0, 0, 0); __builtin_amdgcn_s_setprio(0); } while (0)
; #define PG8_WAIT_V(n) asm volatile("s_waitcnt vmcnt(" #n ")" ::: "memory")
; #define PG8_WAIT_L(n) asm volatile("s_waitcnt lgkmcnt(" #n ")" ::: "memory")
; #define PG8_BAR __builtin_amdgcn_s_barrier()
; #define PG8_SCHED __builtin_amdgcn_sched_barrier(0)
; template <class Epi>
; __device__ __forceinline__ void gemm_phase(LAS unsigned char* lds, const Gemm g, const StaticOrder& S, const Epi& E, int wv) {
;     ...
;             PG8_LDB(B0, 0, 0); PG8_SCHED; PG8_LDA(At, 0, 0); PG8_STAGE(PG8_SA(1, 1), a1 + hstepA, voffA);
;     ...
;             PG8_LDB(B0, 1, 0); PG8_SCHED; PG8_LDA(At, 1, 0); PG8_STAGE(PG8_SA(0, 1), a2 + hstepA, voffA);
;             PG8_WAIT_L(8); PG8_BAR; PG8_WAIT_L(0); PG8_MMA(0, 0, At, B0); PG8_BAR; PG8_SCHED;
;             PG8_LDB(B1, 1, 1); PG8_STAGE(PG8_SB(1, 0), b3, voffB);
;             PG8_BAR; PG8_WAIT_L(0); PG8_MMA(0, 1, At, B1); PG8_BAR;
;             PG8_LDA(At, 1, 1); PG8_STAGE(PG8_SA(1, 0), a3, voffA);
;             PG8_BAR; PG8_WAIT_L(0); PG8_MMA(1, 0, At, B0); PG8_BAR; PG8_SCHED;
;             PG8_STAGE(PG8_SB(1, 1), b3 + hstepB, voffB);
;             PG8_WAIT_V(6); PG8_BAR; PG8_MMA(1, 1, At, B1); PG8_BAR;
	v_mfma_f32_16x16x32_bf16 v[52:55], v[210:213], v[160:163], v[52:55]
	v_mfma_f32_16x16x32_bf16 v[48:51], v[218:221], v[160:163], v[48:51]
	v_mfma_f32_16x16x32_bf16 v[36:39], v[210:213], v[168:171], v[36:39]
	v_mfma_f32_16x16x32_bf16 v[32:35], v[218:221], v[168:171], v[32:35]
	v_mfma_f32_16x16x32_bf16 v[20:23], v[210:213], v[176:179], v[20:23]
	v_mfma_f32_16x16x32_bf16 v[16:19], v[218:221], v[176:179], v[16:19]
	v_mfma_f32_16x16x32_bf16 v[4:7], v[210:213], v[202:205], v[4:7]
	v_mfma_f32_16x16x32_bf16 v[0:3], v[218:221], v[202:205], v[0:3]
	v_mfma_f32_16x16x32_bf16 v[52:55], v[214:217], v[164:167], v[52:55]
	v_mfma_f32_16x16x32_bf16 v[48:51], v[222:225], v[164:167], v[48:51]
	v_mfma_f32_16x16x32_bf16 v[36:39], v[214:217], v[172:175], v[36:39]
	v_mfma_f32_16x16x32_bf16 v[32:35], v[222:225], v[172:175], v[32:35]
	v_mfma_f32_16x16x32_bf16 v[20:23], v[214:217], v[198:201], v[20:23]
	v_mfma_f32_16x16x32_bf16 v[16:19], v[222:225], v[198:201], v[16:19]
	v_mfma_f32_16x16x32_bf16 v[4:7], v[214:217], v[206:209], v[4:7]
	v_mfma_f32_16x16x32_bf16 v[0:3], v[222:225], v[206:209], v[0:3]
	s_waitcnt lgkmcnt(0)
	s_barrier
	s_add_u32 s40, s74, 0x80000
	s_addc_u32 s41, s75, 0
	s_mov_b32 m0, s12
	ds_read_b128 v[160:163], v191 offset:32768
	ds_read_b128 v[164:167], v191 offset:33792
	ds_read_b128 v[168:171], v191 offset:34816
	ds_read_b128 v[172:175], v191 offset:35840
	ds_read_b128 v[176:179], v191 offset:36864
	ds_read_b128 v[198:201], v191 offset:37888
	ds_read_b128 v[202:205], v191 offset:38912
	ds_read_b128 v[206:209], v191 offset:39936
	global_load_lds_dwordx4 v136, s[40:41]
	s_mov_b32 m0, s13
	s_nop 0
	global_load_lds_dwordx4 v140, s[40:41]
	s_waitcnt lgkmcnt(8)
	s_barrier
	s_waitcnt lgkmcnt(0)
	v_mfma_f32_16x16x32_bf16 v[124:127], v[128:131], v[160:163], v[124:127]
	v_mfma_f32_16x16x32_bf16 v[120:123], v[152:155], v[160:163], v[120:123]
	v_mfma_f32_16x16x32_bf16 v[108:111], v[128:131], v[168:171], v[108:111]
	v_mfma_f32_16x16x32_bf16 v[104:107], v[152:155], v[168:171], v[104:107]
	v_mfma_f32_16x16x32_bf16 v[92:95], v[128:131], v[176:179], v[92:95]
	v_mfma_f32_16x16x32_bf16 v[88:91], v[152:155], v[176:179], v[88:91]
	v_mfma_f32_16x16x32_bf16 v[76:79], v[128:131], v[202:205], v[76:79]
	v_mfma_f32_16x16x32_bf16 v[72:75], v[152:155], v[202:205], v[72:75]
	v_mfma_f32_16x16x32_bf16 v[124:127], v[132:135], v[164:167], v[124:127]
	v_mfma_f32_16x16x32_bf16 v[120:123], v[156:159], v[164:167], v[120:123]
	v_mfma_f32_16x16x32_bf16 v[108:111], v[132:135], v[172:175], v[108:111]
	v_mfma_f32_16x16x32_bf16 v[104:107], v[156:159], v[172:175], v[104:107]
	v_mfma_f32_16x16x32_bf16 v[92:95], v[132:135], v[198:201], v[92:95]
	v_mfma_f32_16x16x32_bf16 v[88:91], v[156:159], v[198:201], v[88:91]
	v_mfma_f32_16x16x32_bf16 v[76:79], v[132:135], v[206:209], v[76:79]
	v_mfma_f32_16x16x32_bf16 v[72:75], v[156:159], v[206:209], v[72:75]
	s_barrier
	s_add_i32 s42, 0, 0x1c000
	s_add_i32 s39, s39, s9
	v_add_u32_e32 v197, s42, v184
	s_mov_b32 m0, s39
	ds_read_b128 v[210:213], v197
	ds_read_b128 v[214:217], v197 offset:1024
	ds_read_b128 v[218:221], v197 offset:2048
	ds_read_b128 v[222:225], v197 offset:3072
	global_load_lds_dwordx4 v138, s[98:99]
	s_add_i32 m0, s39, 0x2000
	s_nop 0
	global_load_lds_dwordx4 v142, s[98:99]
	s_barrier
	s_waitcnt lgkmcnt(0)
	v_mfma_f32_16x16x32_bf16 v[116:119], v[210:213], v[160:163], v[116:119]
	v_mfma_f32_16x16x32_bf16 v[112:115], v[218:221], v[160:163], v[112:115]
	v_mfma_f32_16x16x32_bf16 v[100:103], v[210:213], v[168:171], v[100:103]
	v_mfma_f32_16x16x32_bf16 v[96:99], v[218:221], v[168:171], v[96:99]
	v_mfma_f32_16x16x32_bf16 v[84:87], v[210:213], v[176:179], v[84:87]
	v_mfma_f32_16x16x32_bf16 v[80:83], v[218:221], v[176:179], v[80:83]
	v_mfma_f32_16x16x32_bf16 v[68:71], v[210:213], v[202:205], v[68:71]
	v_mfma_f32_16x16x32_bf16 v[64:67], v[218:221], v[202:205], v[64:67]
	v_mfma_f32_16x16x32_bf16 v[116:119], v[214:217], v[164:167], v[116:119]
	v_mfma_f32_16x16x32_bf16 v[112:115], v[222:225], v[164:167], v[112:115]
	v_mfma_f32_16x16x32_bf16 v[100:103], v[214:217], v[172:175], v[100:103]
	v_mfma_f32_16x16x32_bf16 v[96:99], v[222:225], v[172:175], v[96:99]
	v_mfma_f32_16x16x32_bf16 v[84:87], v[214:217], v[198:201], v[84:87]
	v_mfma_f32_16x16x32_bf16 v[80:83], v[222:225], v[198:201], v[80:83]
	v_mfma_f32_16x16x32_bf16 v[68:71], v[214:217], v[206:209], v[68:71]
	v_mfma_f32_16x16x32_bf16 v[64:67], v[222:225], v[206:209], v[64:67]
	s_mov_b32 m0, s15
	s_barrier
	ds_read_b128 v[160:163], v191 offset:49152
	ds_read_b128 v[164:167], v191 offset:50176
	ds_read_b128 v[168:171], v191 offset:51200
	ds_read_b128 v[172:175], v191 offset:52224
	ds_read_b128 v[176:179], v191 offset:53248
	ds_read_b128 v[198:201], v191 offset:54272
	ds_read_b128 v[202:205], v191 offset:55296
	ds_read_b128 v[206:209], v191 offset:56320
	global_load_lds_dwordx4 v136, s[100:101]
	s_mov_b32 m0, s22
	s_nop 0
	global_load_lds_dwordx4 v140, s[100:101]
	s_waitcnt vmcnt(10)
	s_barrier
	s_waitcnt lgkmcnt(0)
	v_mfma_f32_16x16x32_bf16 v[60:63], v[128:131], v[160:163], v[60:63]
	v_mfma_f32_16x16x32_bf16 v[56:59], v[152:155], v[160:163], v[56:59]
	v_mfma_f32_16x16x32_bf16 v[44:47], v[128:131], v[168:171], v[44:47]
	v_mfma_f32_16x16x32_bf16 v[40:43], v[152:155], v[168:171], v[40:43]
	v_mfma_f32_16x16x32_bf16 v[28:31], v[128:131], v[176:179], v[28:31]
	v_mfma_f32_16x16x32_bf16 v[24:27], v[152:155], v[176:179], v[24:27]
	v_mfma_f32_16x16x32_bf16 v[12:15], v[128:131], v[202:205], v[12:15]
	v_mfma_f32_16x16x32_bf16 v[8:11], v[152:155], v[202:205], v[8:11]
	v_mfma_f32_16x16x32_bf16 v[60:63], v[132:135], v[164:167], v[60:63]
	v_mfma_f32_16x16x32_bf16 v[56:59], v[156:159], v[164:167], v[56:59]
	v_mfma_f32_16x16x32_bf16 v[44:47], v[132:135], v[172:175], v[44:47]
	v_mfma_f32_16x16x32_bf16 v[40:43], v[156:159], v[172:175], v[40:43]
	v_mfma_f32_16x16x32_bf16 v[28:31], v[132:135], v[198:201], v[28:31]
	v_mfma_f32_16x16x32_bf16 v[24:27], v[156:159], v[198:201], v[24:27]
	v_mfma_f32_16x16x32_bf16 v[12:15], v[132:135], v[206:209], v[12:15]
	v_mfma_f32_16x16x32_bf16 v[8:11], v[156:159], v[206:209], v[8:11]
	s_barrier
	s_add_u32 s40, s72, 0x80080
	s_addc_u32 s41, s73, 0
	s_add_i32 s39, s42, s9
	s_mov_b32 m0, s39
	s_nop 0
	global_load_lds_dwordx4 v138, s[40:41]
	s_add_i32 m0, s39, 0x2000
	s_nop 0
	global_load_lds_dwordx4 v142, s[40:41]
	ds_read_b128 v[128:131], v190
	ds_read_b128 v[132:135], v190 offset:1024
	ds_read_b128 v[152:155], v190 offset:2048
	ds_read_b128 v[156:159], v190 offset:3072
	s_waitcnt vmcnt(6)
	s_branch .LBB0_208

; #define PG8_STAGE(bufoff, gbase, voff) do { _Pragma("unroll") for (int _i = 0; _i < 2; ++_i) \
;         __builtin_amdgcn_global_load_lds((const unsigned*)((const char*)(gbase) + (voff)[_i]), (LAS unsigned*)(lds + (bufoff) + ldsw + _i * 8192), 16, 0, 0); } while (0)
; #define PG8_LDA(dst, b, h) do { _Pragma("unroll") for (int m = 0; m < 4; ++m) _Pragma("unroll") for (int k = 0; k < 2; ++k) dst[m][k] = *(const LAS bf16x8*)(lds + PG8_SA(b, h) + aoff + m * 2048 + k * 1024); } while (0)
; #define PG8_LDB(dst, b, h) do { _Pragma("unroll") for (int n = 0; n < 2; ++n) _Pragma("unroll") for (int k = 0; k < 2; ++k) dst[n][k] = *(const LAS bf16x8*)(lds + PG8_SB(b, h) + boff + n * 2048 + k * 1024); } while (0)
; #define PG8_MMA(ai, bj, At, Bt) do { __builtin_amdgcn_s_setprio(1); _Pragma("unroll") for (int m = 0; m < 4; ++m) _Pragma("unroll") for (int n = 0; n < 2; ++n) _Pragma("unroll") for (int k = 0; k < 2; ++k) \
;         acc[ai][bj][m][n] = __builtin_amdgcn_mfma_f32_16x16x32_bf16(Bt[n][k], At[m][k], acc[ai][bj][m][n], 0, 0, 0); __builtin_amdgcn_s_setprio(0); } while (0)
; #define PG8_WAIT_V(n) asm volatile("s_waitcnt vmcnt(" #n ")" ::: "memory")
; #define PG8_WAIT_L(n) asm volatile("s_waitcnt lgkmcnt(" #n ")" ::: "memory")
; #define PG8_BAR __builtin_amdgcn_s_barrier()
; template <class Epi>
; __device__ __forceinline__ void gemm_phase(LAS unsigned char* lds, const Gemm g, const StaticOrder& S, const Epi& E, int wv) {
;     ...
;             const bool last = (t == nt - 2);
;             const char* a1 = cA + (ptrdiff_t)(t + 1) * kstep;
;             const char* a2 = last ? nA : cA + (ptrdiff_t)(t + 2) * kstep; const char* b2 = last ? nB : cB + (ptrdiff_t)(t + 2) * kstep;
;             const char* a3 = a2 + kstep; const char* b3 = b2 + kstep;
;             PG8_LDB(B0, 0, 0); PG8_SCHED; PG8_LDA(At, 0, 0); PG8_STAGE(PG8_SA(1, 1), a1 + hstepA, voffA);
;             PG8_WAIT_L(8); PG8_BAR; PG8_WAIT_L(0); PG8_MMA(0, 0, At, B0); PG8_BAR; PG8_SCHED;
;             PG8_LDB(B1, 0, 1); PG8_STAGE(PG8_SB(0, 0), b2, voffB);
;             PG8_BAR; PG8_WAIT_L(0); PG8_MMA(0, 1, At, B1); PG8_BAR;
;             PG8_LDA(At, 0, 1); PG8_STAGE(PG8_SA(0, 0), a2, voffA);
;             PG8_BAR; PG8_WAIT_L(0); PG8_MMA(1, 0, At, B0); PG8_BAR; PG8_SCHED;
;             PG8_STAGE(PG8_SB(0, 1), b2 + hstepB, voffB);
;             PG8_WAIT_V(6); PG8_BAR; PG8_MMA(1, 1, At, B1); PG8_BAR;
.Lrot_in_259:
	s_add_u32 s43, s66, 0xfff80080
	s_addc_u32 s44, s67, -1
	s_cmp_eq_u32 s42, 28
	s_cselect_b32 s71, s34, s44
	s_cselect_b32 s70, s35, s43
	s_cselect_b32 s69, s38, s41
	s_cselect_b32 s68, s39, s40
	s_add_i32 m0, s10, 0xc000
	ds_read_b128 v[172:175], v168
	ds_read_b128 v[176:179], v168 offset:1024
	ds_read_b128 v[184:187], v168 offset:2048
	ds_read_b128 v[188:191], v168 offset:3072
	ds_read_b128 v[192:195], v168 offset:4096
	ds_read_b128 v[196:199], v168 offset:5120
	ds_read_b128 v[200:203], v168 offset:6144
	ds_read_b128 v[204:207], v168 offset:7168
	global_load_lds_dwordx4 v138, s[66:67]
	s_add_i32 m0, s10, 0xe000
	s_nop 0
	global_load_lds_dwordx4 v140, s[66:67]
	s_waitcnt lgkmcnt(8)
	s_barrier
	s_waitcnt lgkmcnt(0)
	v_mfma_f32_16x16x32_bf16 v[124:127], v[146:149], v[172:175], v[124:127]
	v_mfma_f32_16x16x32_bf16 v[120:123], v[154:157], v[172:175], v[120:123]
	v_mfma_f32_16x16x32_bf16 v[112:115], v[146:149], v[184:187], v[112:115]
	v_mfma_f32_16x16x32_bf16 v[104:107], v[154:157], v[184:187], v[104:107]
	v_mfma_f32_16x16x32_bf16 v[96:99], v[146:149], v[192:195], v[96:99]
	v_mfma_f32_16x16x32_bf16 v[88:91], v[154:157], v[192:195], v[88:91]
	v_mfma_f32_16x16x32_bf16 v[80:83], v[146:149], v[200:203], v[80:83]
	v_mfma_f32_16x16x32_bf16 v[72:75], v[154:157], v[200:203], v[72:75]
	v_mfma_f32_16x16x32_bf16 v[124:127], v[150:153], v[176:179], v[124:127]
	v_mfma_f32_16x16x32_bf16 v[120:123], v[158:161], v[176:179], v[120:123]
	v_mfma_f32_16x16x32_bf16 v[112:115], v[150:153], v[188:191], v[112:115]
	v_mfma_f32_16x16x32_bf16 v[104:107], v[158:161], v[188:191], v[104:107]
	v_mfma_f32_16x16x32_bf16 v[96:99], v[150:153], v[196:199], v[96:99]
	v_mfma_f32_16x16x32_bf16 v[88:91], v[158:161], v[196:199], v[88:91]
	v_mfma_f32_16x16x32_bf16 v[80:83], v[150:153], v[204:207], v[80:83]
	v_mfma_f32_16x16x32_bf16 v[72:75], v[158:161], v[204:207], v[72:75]
	s_barrier
	s_add_i32 s43, s23, s9
	s_add_u32 s98, s68, s20
	s_addc_u32 s99, s69, s21
	s_mov_b32 m0, s43
	ds_read_b128 v[208:211], v169
	ds_read_b128 v[212:215], v169 offset:1024
	ds_read_b128 v[216:219], v169 offset:2048
	ds_read_b128 v[220:223], v169 offset:3072
	global_load_lds_dwordx4 v130, s[68:69]
	s_add_i32 m0, s43, 0x2000
	s_nop 0
	global_load_lds_dwordx4 v134, s[68:69]
	s_barrier
	s_waitcnt lgkmcnt(0)
	v_mfma_f32_16x16x32_bf16 v[116:119], v[208:211], v[172:175], v[116:119]
	v_mfma_f32_16x16x32_bf16 v[108:111], v[216:219], v[172:175], v[108:111]
	v_mfma_f32_16x16x32_bf16 v[100:103], v[208:211], v[184:187], v[100:103]
	v_mfma_f32_16x16x32_bf16 v[92:95], v[216:219], v[184:187], v[92:95]
	v_mfma_f32_16x16x32_bf16 v[84:87], v[208:211], v[192:195], v[84:87]
	v_mfma_f32_16x16x32_bf16 v[76:79], v[216:219], v[192:195], v[76:79]
	v_mfma_f32_16x16x32_bf16 v[68:71], v[208:211], v[200:203], v[68:71]
	v_mfma_f32_16x16x32_bf16 v[64:67], v[216:219], v[200:203], v[64:67]
	v_mfma_f32_16x16x32_bf16 v[116:119], v[212:215], v[176:179], v[116:119]
	v_mfma_f32_16x16x32_bf16 v[108:111], v[220:223], v[176:179], v[108:111]
	v_mfma_f32_16x16x32_bf16 v[100:103], v[212:215], v[188:191], v[100:103]
	v_mfma_f32_16x16x32_bf16 v[92:95], v[220:223], v[188:191], v[92:95]
	v_mfma_f32_16x16x32_bf16 v[84:87], v[212:215], v[196:199], v[84:87]
	v_mfma_f32_16x16x32_bf16 v[76:79], v[220:223], v[196:199], v[76:79]
	v_mfma_f32_16x16x32_bf16 v[68:71], v[212:215], v[204:207], v[68:71]
	v_mfma_f32_16x16x32_bf16 v[64:67], v[220:223], v[204:207], v[64:67]
	s_mov_b32 m0, s10
	s_add_u32 s100, s70, s20
	s_addc_u32 s101, s71, s21
	s_barrier
	ds_read_b128 v[172:175], v168 offset:16384
	ds_read_b128 v[176:179], v168 offset:17408
	ds_read_b128 v[184:187], v168 offset:18432
	ds_read_b128 v[188:191], v168 offset:19456
	ds_read_b128 v[192:195], v168 offset:20480
	ds_read_b128 v[196:199], v168 offset:21504
	ds_read_b128 v[200:203], v168 offset:22528
	ds_read_b128 v[204:207], v168 offset:23552
	global_load_lds_dwordx4 v128, s[70:71]
	s_mov_b32 m0, s11
	s_nop 0
	global_load_lds_dwordx4 v132, s[70:71]
	s_waitcnt vmcnt(10)
	s_barrier
	s_waitcnt lgkmcnt(0)
	v_mfma_f32_16x16x32_bf16 v[60:63], v[146:149], v[172:175], v[60:63]
	v_mfma_f32_16x16x32_bf16 v[56:59], v[154:157], v[172:175], v[56:59]
	v_mfma_f32_16x16x32_bf16 v[52:55], v[146:149], v[184:187], v[52:55]
	v_mfma_f32_16x16x32_bf16 v[44:47], v[154:157], v[184:187], v[44:47]
	v_mfma_f32_16x16x32_bf16 v[36:39], v[146:149], v[192:195], v[36:39]
	v_mfma_f32_16x16x32_bf16 v[28:31], v[154:157], v[192:195], v[28:31]
	v_mfma_f32_16x16x32_bf16 v[20:23], v[146:149], v[200:203], v[20:23]
	v_mfma_f32_16x16x32_bf16 v[12:15], v[154:157], v[200:203], v[12:15]
	v_mfma_f32_16x16x32_bf16 v[60:63], v[150:153], v[176:179], v[60:63]
	v_mfma_f32_16x16x32_bf16 v[56:59], v[158:161], v[176:179], v[56:59]
	v_mfma_f32_16x16x32_bf16 v[52:55], v[150:153], v[188:191], v[52:55]
	v_mfma_f32_16x16x32_bf16 v[44:47], v[158:161], v[188:191], v[44:47]
	v_mfma_f32_16x16x32_bf16 v[36:39], v[150:153], v[196:199], v[36:39]
	v_mfma_f32_16x16x32_bf16 v[28:31], v[158:161], v[196:199], v[28:31]
	v_mfma_f32_16x16x32_bf16 v[20:23], v[150:153], v[204:207], v[20:23]
	v_mfma_f32_16x16x32_bf16 v[12:15], v[158:161], v[204:207], v[12:15]
	s_barrier
	s_add_u32 s44, s68, 0x80000
	s_addc_u32 s45, s69, 0
	s_add_i32 s43, s24, s9
	s_mov_b32 m0, s43
	s_nop 0
	global_load_lds_dwordx4 v130, s[44:45]
	s_add_i32 m0, s43, 0x2000
	s_nop 0
	global_load_lds_dwordx4 v134, s[44:45]
	s_add_i32 s43, 0, 0x18000
	v_add_u32_e32 v158, s43, v165
	ds_read_b128 v[146:149], v158
	ds_read_b128 v[150:153], v158 offset:1024
	ds_read_b128 v[154:157], v158 offset:2048
	ds_read_b128 v[158:161], v158 offset:3072
	s_waitcnt vmcnt(6)
	s_barrier
; #define PG8_STAGE(bufoff, gbase, voff) do { _Pragma("unroll") for (int _i = 0; _i < 2; ++_i) \
;         __builtin_amdgcn_global_load_lds((const unsigned*)((const char*)(gbase) + (voff)[_i]), (LAS unsigned*)(lds + (bufoff) + ldsw + _i * 8192), 16, 0, 0); } while (0)
; #define PG8_LDA(dst, b, h) do { _Pragma("unroll") for (int m = 0; m < 4; ++m) _Pragma("unroll") for (int k = 0; k < 2; ++k) dst[m][k] = *(const LAS bf16x8*)(lds + PG8_SA(b, h) + aoff + m * 2048 + k * 1024); } while (0)
; #define PG8_LDB(dst, b, h) do { _Pragma("unroll") for (int n = 0; n < 2; ++n) _Pragma("unroll") for (int k = 0; k < 2; ++k) dst[n][k] = *(const LAS bf16x8*)(lds + PG8_SB(b, h) + boff + n * 2048 + k * 1024); } while (0)
; #define PG8_MMA(ai, bj, At, Bt) do { __builtin_amdgcn_s_setprio(1); _Pragma("unroll") for (int m = 0; m < 4; ++m) _Pragma("unroll") for (int n = 0; n < 2; ++n) _Pragma("unroll") for (int k = 0; k < 2; ++k) \
;         acc[ai][bj][m][n] = __builtin_amdgcn_mfma_f32_16x16x32_bf16(Bt[n][k], At[m][k], acc[ai][bj][m][n], 0, 0, 0); __builtin_amdgcn_s_setprio(0); } while (0)
; #define PG8_WAIT_V(n) asm volatile("s_waitcnt vmcnt(" #n ")" ::: "memory")
; #define PG8_WAIT_L(n) asm volatile("s_waitcnt lgkmcnt(" #n ")" ::: "memory")
; #define PG8_BAR __builtin_amdgcn_s_barrier()
; #define PG8_SCHED __builtin_amdgcn_sched_barrier(0)
; template <class Epi>
; __device__ __forceinline__ void gemm_phase(LAS unsigned char* lds, const Gemm g, const StaticOrder& S, const Epi& E, int wv) {
;     ...
;             PG8_LDB(B0, 0, 0); PG8_SCHED; PG8_LDA(At, 0, 0); PG8_STAGE(PG8_SA(1, 1), a1 + hstepA, voffA);
;     ...
;             PG8_LDB(B0, 1, 0); PG8_SCHED; PG8_LDA(At, 1, 0); PG8_STAGE(PG8_SA(0, 1), a2 + hstepA, voffA);
;             PG8_WAIT_L(8); PG8_BAR; PG8_WAIT_L(0); PG8_MMA(0, 0, At, B0); PG8_BAR; PG8_SCHED;
;             PG8_LDB(B1, 1, 1); PG8_STAGE(PG8_SB(1, 0), b3, voffB);
;             PG8_BAR; PG8_WAIT_L(0); PG8_MMA(0, 1, At, B1); PG8_BAR;
;             PG8_LDA(At, 1, 1); PG8_STAGE(PG8_SA(1, 0), a3, voffA);
;             PG8_BAR; PG8_WAIT_L(0); PG8_MMA(1, 0, At, B0); PG8_BAR; PG8_SCHED;
;             PG8_STAGE(PG8_SB(1, 1), b3 + hstepB, voffB);
;             PG8_WAIT_V(6); PG8_BAR; PG8_MMA(1, 1, At, B1); PG8_BAR;
	v_mfma_f32_16x16x32_bf16 v[48:51], v[208:211], v[172:175], v[48:51]
	v_mfma_f32_16x16x32_bf16 v[40:43], v[216:219], v[172:175], v[40:43]
	v_mfma_f32_16x16x32_bf16 v[32:35], v[208:211], v[184:187], v[32:35]
	v_mfma_f32_16x16x32_bf16 v[24:27], v[216:219], v[184:187], v[24:27]
	v_mfma_f32_16x16x32_bf16 v[16:19], v[208:211], v[192:195], v[16:19]
	v_mfma_f32_16x16x32_bf16 v[8:11], v[216:219], v[192:195], v[8:11]
	v_mfma_f32_16x16x32_bf16 v[4:7], v[208:211], v[200:203], v[4:7]
	v_mfma_f32_16x16x32_bf16 v[0:3], v[216:219], v[200:203], v[0:3]
	v_mfma_f32_16x16x32_bf16 v[48:51], v[212:215], v[176:179], v[48:51]
	v_mfma_f32_16x16x32_bf16 v[40:43], v[220:223], v[176:179], v[40:43]
	v_mfma_f32_16x16x32_bf16 v[32:35], v[212:215], v[188:191], v[32:35]
	v_mfma_f32_16x16x32_bf16 v[24:27], v[220:223], v[188:191], v[24:27]
	v_mfma_f32_16x16x32_bf16 v[16:19], v[212:215], v[196:199], v[16:19]
	v_mfma_f32_16x16x32_bf16 v[8:11], v[220:223], v[196:199], v[8:11]
	v_mfma_f32_16x16x32_bf16 v[4:7], v[212:215], v[204:207], v[4:7]
	v_mfma_f32_16x16x32_bf16 v[0:3], v[220:223], v[204:207], v[0:3]
	s_waitcnt lgkmcnt(0)
	s_barrier
	s_add_u32 s44, s70, 0x80000
	s_addc_u32 s45, s71, 0
	s_mov_b32 m0, s12
	ds_read_b128 v[172:175], v168 offset:32768
	ds_read_b128 v[176:179], v168 offset:33792
	ds_read_b128 v[184:187], v168 offset:34816
	ds_read_b128 v[188:191], v168 offset:35840
	ds_read_b128 v[192:195], v168 offset:36864
	ds_read_b128 v[196:199], v168 offset:37888
	ds_read_b128 v[200:203], v168 offset:38912
	ds_read_b128 v[204:207], v168 offset:39936
	global_load_lds_dwordx4 v128, s[44:45]
	s_mov_b32 m0, s13
	s_nop 0
	global_load_lds_dwordx4 v132, s[44:45]
	s_waitcnt lgkmcnt(8)
	s_barrier
	s_waitcnt lgkmcnt(0)
	v_mfma_f32_16x16x32_bf16 v[124:127], v[146:149], v[172:175], v[124:127]
	v_mfma_f32_16x16x32_bf16 v[120:123], v[154:157], v[172:175], v[120:123]
	v_mfma_f32_16x16x32_bf16 v[112:115], v[146:149], v[184:187], v[112:115]
	v_mfma_f32_16x16x32_bf16 v[104:107], v[154:157], v[184:187], v[104:107]
	v_mfma_f32_16x16x32_bf16 v[96:99], v[146:149], v[192:195], v[96:99]
	v_mfma_f32_16x16x32_bf16 v[88:91], v[154:157], v[192:195], v[88:91]
	v_mfma_f32_16x16x32_bf16 v[80:83], v[146:149], v[200:203], v[80:83]
	v_mfma_f32_16x16x32_bf16 v[72:75], v[154:157], v[200:203], v[72:75]
	v_mfma_f32_16x16x32_bf16 v[124:127], v[150:153], v[176:179], v[124:127]
	v_mfma_f32_16x16x32_bf16 v[120:123], v[158:161], v[176:179], v[120:123]
	v_mfma_f32_16x16x32_bf16 v[112:115], v[150:153], v[188:191], v[112:115]
	v_mfma_f32_16x16x32_bf16 v[104:107], v[158:161], v[188:191], v[104:107]
	v_mfma_f32_16x16x32_bf16 v[96:99], v[150:153], v[196:199], v[96:99]
	v_mfma_f32_16x16x32_bf16 v[88:91], v[158:161], v[196:199], v[88:91]
	v_mfma_f32_16x16x32_bf16 v[80:83], v[150:153], v[204:207], v[80:83]
	v_mfma_f32_16x16x32_bf16 v[72:75], v[158:161], v[204:207], v[72:75]
	s_barrier
	s_add_i32 s46, 0, 0x1c000
	s_add_i32 s43, s43, s9
	v_add_u32_e32 v171, s46, v165
	s_mov_b32 m0, s43
	ds_read_b128 v[208:211], v171
	ds_read_b128 v[212:215], v171 offset:1024
	ds_read_b128 v[216:219], v171 offset:2048
	ds_read_b128 v[220:223], v171 offset:3072
	global_load_lds_dwordx4 v130, s[98:99]
	s_add_i32 m0, s43, 0x2000
	s_nop 0
	global_load_lds_dwordx4 v134, s[98:99]
	s_barrier
	s_waitcnt lgkmcnt(0)
	v_mfma_f32_16x16x32_bf16 v[116:119], v[208:211], v[172:175], v[116:119]
	v_mfma_f32_16x16x32_bf16 v[108:111], v[216:219], v[172:175], v[108:111]
	v_mfma_f32_16x16x32_bf16 v[100:103], v[208:211], v[184:187], v[100:103]
	v_mfma_f32_16x16x32_bf16 v[92:95], v[216:219], v[184:187], v[92:95]
	v_mfma_f32_16x16x32_bf16 v[84:87], v[208:211], v[192:195], v[84:87]
	v_mfma_f32_16x16x32_bf16 v[76:79], v[216:219], v[192:195], v[76:79]
	v_mfma_f32_16x16x32_bf16 v[68:71], v[208:211], v[200:203], v[68:71]
	v_mfma_f32_16x16x32_bf16 v[64:67], v[216:219], v[200:203], v[64:67]
	v_mfma_f32_16x16x32_bf16 v[116:119], v[212:215], v[176:179], v[116:119]
	v_mfma_f32_16x16x32_bf16 v[108:111], v[220:223], v[176:179], v[108:111]
	v_mfma_f32_16x16x32_bf16 v[100:103], v[212:215], v[188:191], v[100:103]
	v_mfma_f32_16x16x32_bf16 v[92:95], v[220:223], v[188:191], v[92:95]
	v_mfma_f32_16x16x32_bf16 v[84:87], v[212:215], v[196:199], v[84:87]
	v_mfma_f32_16x16x32_bf16 v[76:79], v[220:223], v[196:199], v[76:79]
	v_mfma_f32_16x16x32_bf16 v[68:71], v[212:215], v[204:207], v[68:71]
	v_mfma_f32_16x16x32_bf16 v[64:67], v[220:223], v[204:207], v[64:67]
	s_mov_b32 m0, s15
	s_barrier
	ds_read_b128 v[172:175], v168 offset:49152
	ds_read_b128 v[176:179], v168 offset:50176
	ds_read_b128 v[184:187], v168 offset:51200
	ds_read_b128 v[188:191], v168 offset:52224
	ds_read_b128 v[192:195], v168 offset:53248
	ds_read_b128 v[196:199], v168 offset:54272
	ds_read_b128 v[200:203], v168 offset:55296
	ds_read_b128 v[204:207], v168 offset:56320
	global_load_lds_dwordx4 v128, s[100:101]
	s_mov_b32 m0, s22
	s_nop 0
	global_load_lds_dwordx4 v132, s[100:101]
	s_waitcnt vmcnt(10)
	s_barrier
	s_waitcnt lgkmcnt(0)
	v_mfma_f32_16x16x32_bf16 v[60:63], v[146:149], v[172:175], v[60:63]
	v_mfma_f32_16x16x32_bf16 v[56:59], v[154:157], v[172:175], v[56:59]
	v_mfma_f32_16x16x32_bf16 v[52:55], v[146:149], v[184:187], v[52:55]
	v_mfma_f32_16x16x32_bf16 v[44:47], v[154:157], v[184:187], v[44:47]
	v_mfma_f32_16x16x32_bf16 v[36:39], v[146:149], v[192:195], v[36:39]
	v_mfma_f32_16x16x32_bf16 v[28:31], v[154:157], v[192:195], v[28:31]
	v_mfma_f32_16x16x32_bf16 v[20:23], v[146:149], v[200:203], v[20:23]
	v_mfma_f32_16x16x32_bf16 v[12:15], v[154:157], v[200:203], v[12:15]
	v_mfma_f32_16x16x32_bf16 v[60:63], v[150:153], v[176:179], v[60:63]
	v_mfma_f32_16x16x32_bf16 v[56:59], v[158:161], v[176:179], v[56:59]
	v_mfma_f32_16x16x32_bf16 v[52:55], v[150:153], v[188:191], v[52:55]
	v_mfma_f32_16x16x32_bf16 v[44:47], v[158:161], v[188:191], v[44:47]
	v_mfma_f32_16x16x32_bf16 v[36:39], v[150:153], v[196:199], v[36:39]
	v_mfma_f32_16x16x32_bf16 v[28:31], v[158:161], v[196:199], v[28:31]
	v_mfma_f32_16x16x32_bf16 v[20:23], v[150:153], v[204:207], v[20:23]
	v_mfma_f32_16x16x32_bf16 v[12:15], v[158:161], v[204:207], v[12:15]
	s_barrier
	s_add_u32 s44, s68, 0x80080
	s_addc_u32 s45, s69, 0
	s_add_i32 s43, s46, s9
	s_mov_b32 m0, s43
	s_nop 0
	global_load_lds_dwordx4 v130, s[44:45]
	s_add_i32 m0, s43, 0x2000
	s_nop 0
	global_load_lds_dwordx4 v134, s[44:45]
	ds_read_b128 v[146:149], v167
	ds_read_b128 v[150:153], v167 offset:1024
	ds_read_b128 v[154:157], v167 offset:2048
	ds_read_b128 v[158:161], v167 offset:3072
	s_waitcnt vmcnt(6)
	s_branch .LBB0_259

; #define PG8_STAGE(bufoff, gbase, voff) do { _Pragma("unroll") for (int _i = 0; _i < 2; ++_i) \
;         __builtin_amdgcn_global_load_lds((const unsigned*)((const char*)(gbase) + (voff)[_i]), (LAS unsigned*)(lds + (bufoff) + ldsw + _i * 8192), 16, 0, 0); } while (0)
; #define PG8_LDA(dst, b, h) do { _Pragma("unroll") for (int m = 0; m < 4; ++m) _Pragma("unroll") for (int k = 0; k < 2; ++k) dst[m][k] = *(const LAS bf16x8*)(lds + PG8_SA(b, h) + aoff + m * 2048 + k * 1024); } while (0)
; #define PG8_LDB(dst, b, h) do { _Pragma("unroll") for (int n = 0; n < 2; ++n) _Pragma("unroll") for (int k = 0; k < 2; ++k) dst[n][k] = *(const LAS bf16x8*)(lds + PG8_SB(b, h) + boff + n * 2048 + k * 1024); } while (0)
; #define PG8_MMA(ai, bj, At, Bt) do { __builtin_amdgcn_s_setprio(1); _Pragma("unroll") for (int m = 0; m < 4; ++m) _Pragma("unroll") for (int n = 0; n < 2; ++n) _Pragma("unroll") for (int k = 0; k < 2; ++k) \
;         acc[ai][bj][m][n] = __builtin_amdgcn_mfma_f32_16x16x32_bf16(Bt[n][k], At[m][k], acc[ai][bj][m][n], 0, 0, 0); __builtin_amdgcn_s_setprio(0); } while (0)
; #define PG8_WAIT_V(n) asm volatile("s_waitcnt vmcnt(" #n ")" ::: "memory")
; #define PG8_WAIT_L(n) asm volatile("s_waitcnt lgkmcnt(" #n ")" ::: "memory")
; #define PG8_BAR __builtin_amdgcn_s_barrier()
; template <class Epi>
; __device__ __forceinline__ void gemm_phase(LAS unsigned char* lds, const Gemm g, const StaticOrder& S, const Epi& E, int wv) {
;     ...
;             const bool last = (t == nt - 2);
;             const char* a1 = cA + (ptrdiff_t)(t + 1) * kstep;
;             const char* a2 = last ? nA : cA + (ptrdiff_t)(t + 2) * kstep; const char* b2 = last ? nB : cB + (ptrdiff_t)(t + 2) * kstep;
;             const char* a3 = a2 + kstep; const char* b3 = b2 + kstep;
;             PG8_LDB(B0, 0, 0); PG8_SCHED; PG8_LDA(At, 0, 0); PG8_STAGE(PG8_SA(1, 1), a1 + hstepA, voffA);
;             PG8_WAIT_L(8); PG8_BAR; PG8_WAIT_L(0); PG8_MMA(0, 0, At, B0); PG8_BAR; PG8_SCHED;
;             PG8_LDB(B1, 0, 1); PG8_STAGE(PG8_SB(0, 0), b2, voffB);
;             PG8_BAR; PG8_WAIT_L(0); PG8_MMA(0, 1, At, B1); PG8_BAR;
;             PG8_LDA(At, 0, 1); PG8_STAGE(PG8_SA(0, 0), a2, voffA);
;             PG8_BAR; PG8_WAIT_L(0); PG8_MMA(1, 0, At, B0); PG8_BAR; PG8_SCHED;
;             PG8_STAGE(PG8_SB(0, 1), b2 + hstepB, voffB);
;             PG8_WAIT_V(6); PG8_BAR; PG8_MMA(1, 1, At, B1); PG8_BAR;
.Lrot_in_443:
	s_add_u32 s42, s70, 0xfff80080
	s_addc_u32 s43, s71, -1
	s_cmp_eq_u32 s41, 28
	s_cselect_b32 s75, s33, s43
	s_cselect_b32 s74, s34, s42
	s_cselect_b32 s73, s35, s40
	s_cselect_b32 s72, s38, s39
	s_add_i32 m0, s10, 0xc000
	ds_read_b128 v[160:163], v180
	ds_read_b128 v[164:167], v180 offset:1024
	ds_read_b128 v[168:171], v180 offset:2048
	ds_read_b128 v[172:175], v180 offset:3072
	ds_read_b128 v[182:185], v180 offset:4096
	ds_read_b128 v[186:189], v180 offset:5120
	ds_read_b128 v[190:193], v180 offset:6144
	ds_read_b128 v[194:197], v180 offset:7168
	global_load_lds_dwordx4 v154, s[70:71]
	s_add_i32 m0, s10, 0xe000
	s_nop 0
	global_load_lds_dwordx4 v152, s[70:71]
	s_waitcnt lgkmcnt(8)
	s_barrier
	s_waitcnt lgkmcnt(0)
	v_mfma_f32_16x16x32_bf16 v[124:127], v[128:131], v[160:163], v[124:127]
	v_mfma_f32_16x16x32_bf16 v[120:123], v[136:139], v[160:163], v[120:123]
	v_mfma_f32_16x16x32_bf16 v[108:111], v[128:131], v[168:171], v[108:111]
	v_mfma_f32_16x16x32_bf16 v[104:107], v[136:139], v[168:171], v[104:107]
	v_mfma_f32_16x16x32_bf16 v[92:95], v[128:131], v[182:185], v[92:95]
	v_mfma_f32_16x16x32_bf16 v[88:91], v[136:139], v[182:185], v[88:91]
	v_mfma_f32_16x16x32_bf16 v[76:79], v[128:131], v[190:193], v[76:79]
	v_mfma_f32_16x16x32_bf16 v[72:75], v[136:139], v[190:193], v[72:75]
	v_mfma_f32_16x16x32_bf16 v[124:127], v[132:135], v[164:167], v[124:127]
	v_mfma_f32_16x16x32_bf16 v[120:123], v[140:143], v[164:167], v[120:123]
	v_mfma_f32_16x16x32_bf16 v[108:111], v[132:135], v[172:175], v[108:111]
	v_mfma_f32_16x16x32_bf16 v[104:107], v[140:143], v[172:175], v[104:107]
	v_mfma_f32_16x16x32_bf16 v[92:95], v[132:135], v[186:189], v[92:95]
	v_mfma_f32_16x16x32_bf16 v[88:91], v[140:143], v[186:189], v[88:91]
	v_mfma_f32_16x16x32_bf16 v[76:79], v[132:135], v[194:197], v[76:79]
	v_mfma_f32_16x16x32_bf16 v[72:75], v[140:143], v[194:197], v[72:75]
	s_barrier
	s_add_i32 s42, s23, s9
	s_add_u32 s98, s72, s54
	s_addc_u32 s99, s73, s55
	s_mov_b32 m0, s42
	ds_read_b128 v[198:201], v181
	ds_read_b128 v[202:205], v181 offset:1024
	ds_read_b128 v[206:209], v181 offset:2048
	ds_read_b128 v[210:213], v181 offset:3072
	global_load_lds_dwordx4 v146, s[72:73]
	s_add_i32 m0, s42, 0x2000
	s_nop 0
	global_load_lds_dwordx4 v150, s[72:73]
	s_barrier
	s_waitcnt lgkmcnt(0)
	v_mfma_f32_16x16x32_bf16 v[116:119], v[198:201], v[160:163], v[116:119]
	v_mfma_f32_16x16x32_bf16 v[112:115], v[206:209], v[160:163], v[112:115]
	v_mfma_f32_16x16x32_bf16 v[100:103], v[198:201], v[168:171], v[100:103]
	v_mfma_f32_16x16x32_bf16 v[96:99], v[206:209], v[168:171], v[96:99]
	v_mfma_f32_16x16x32_bf16 v[84:87], v[198:201], v[182:185], v[84:87]
	v_mfma_f32_16x16x32_bf16 v[80:83], v[206:209], v[182:185], v[80:83]
	v_mfma_f32_16x16x32_bf16 v[68:71], v[198:201], v[190:193], v[68:71]
	v_mfma_f32_16x16x32_bf16 v[64:67], v[206:209], v[190:193], v[64:67]
	v_mfma_f32_16x16x32_bf16 v[116:119], v[202:205], v[164:167], v[116:119]
	v_mfma_f32_16x16x32_bf16 v[112:115], v[210:213], v[164:167], v[112:115]
	v_mfma_f32_16x16x32_bf16 v[100:103], v[202:205], v[172:175], v[100:103]
	v_mfma_f32_16x16x32_bf16 v[96:99], v[210:213], v[172:175], v[96:99]
	v_mfma_f32_16x16x32_bf16 v[84:87], v[202:205], v[186:189], v[84:87]
	v_mfma_f32_16x16x32_bf16 v[80:83], v[210:213], v[186:189], v[80:83]
	v_mfma_f32_16x16x32_bf16 v[68:71], v[202:205], v[194:197], v[68:71]
	v_mfma_f32_16x16x32_bf16 v[64:67], v[210:213], v[194:197], v[64:67]
	s_mov_b32 m0, s10
	s_add_u32 s100, s74, s54
	s_addc_u32 s101, s75, s55
	s_barrier
	ds_read_b128 v[160:163], v180 offset:16384
	ds_read_b128 v[164:167], v180 offset:17408
	ds_read_b128 v[168:171], v180 offset:18432
	ds_read_b128 v[172:175], v180 offset:19456
	ds_read_b128 v[182:185], v180 offset:20480
	ds_read_b128 v[186:189], v180 offset:21504
	ds_read_b128 v[190:193], v180 offset:22528
	ds_read_b128 v[194:197], v180 offset:23552
	global_load_lds_dwordx4 v144, s[74:75]
	s_mov_b32 m0, s11
	s_nop 0
	global_load_lds_dwordx4 v148, s[74:75]
	s_waitcnt vmcnt(10)
	s_barrier
	s_waitcnt lgkmcnt(0)
	v_mfma_f32_16x16x32_bf16 v[60:63], v[128:131], v[160:163], v[60:63]
	v_mfma_f32_16x16x32_bf16 v[56:59], v[136:139], v[160:163], v[56:59]
	v_mfma_f32_16x16x32_bf16 v[44:47], v[128:131], v[168:171], v[44:47]
	v_mfma_f32_16x16x32_bf16 v[40:43], v[136:139], v[168:171], v[40:43]
	v_mfma_f32_16x16x32_bf16 v[28:31], v[128:131], v[182:185], v[28:31]
	v_mfma_f32_16x16x32_bf16 v[24:27], v[136:139], v[182:185], v[24:27]
	v_mfma_f32_16x16x32_bf16 v[12:15], v[128:131], v[190:193], v[12:15]
	v_mfma_f32_16x16x32_bf16 v[8:11], v[136:139], v[190:193], v[8:11]
	v_mfma_f32_16x16x32_bf16 v[60:63], v[132:135], v[164:167], v[60:63]
	v_mfma_f32_16x16x32_bf16 v[56:59], v[140:143], v[164:167], v[56:59]
	v_mfma_f32_16x16x32_bf16 v[44:47], v[132:135], v[172:175], v[44:47]
	v_mfma_f32_16x16x32_bf16 v[40:43], v[140:143], v[172:175], v[40:43]
	v_mfma_f32_16x16x32_bf16 v[28:31], v[132:135], v[186:189], v[28:31]
	v_mfma_f32_16x16x32_bf16 v[24:27], v[140:143], v[186:189], v[24:27]
	v_mfma_f32_16x16x32_bf16 v[12:15], v[132:135], v[194:197], v[12:15]
	v_mfma_f32_16x16x32_bf16 v[8:11], v[140:143], v[194:197], v[8:11]
	s_barrier
	s_add_u32 s42, s72, 0x80000
	s_addc_u32 s43, s73, 0
	s_add_i32 s44, s24, s9
	s_mov_b32 m0, s44
	s_nop 0
	global_load_lds_dwordx4 v146, s[42:43]
	s_add_i32 m0, s44, 0x2000
	s_nop 0
	global_load_lds_dwordx4 v150, s[42:43]
	s_add_i32 s44, 0, 0x18000
	v_add_u32_e32 v140, s44, v177
	ds_read_b128 v[128:131], v140
	ds_read_b128 v[132:135], v140 offset:1024
	ds_read_b128 v[136:139], v140 offset:2048
	ds_read_b128 v[140:143], v140 offset:3072
	s_waitcnt vmcnt(6)
	s_barrier
; #define PG8_STAGE(bufoff, gbase, voff) do { _Pragma("unroll") for (int _i = 0; _i < 2; ++_i) \
;         __builtin_amdgcn_global_load_lds((const unsigned*)((const char*)(gbase) + (voff)[_i]), (LAS unsigned*)(lds + (bufoff) + ldsw + _i * 8192), 16, 0, 0); } while (0)
; #define PG8_LDA(dst, b, h) do { _Pragma("unroll") for (int m = 0; m < 4; ++m) _Pragma("unroll") for (int k = 0; k < 2; ++k) dst[m][k] = *(const LAS bf16x8*)(lds + PG8_SA(b, h) + aoff + m * 2048 + k * 1024); } while (0)
; #define PG8_LDB(dst, b, h) do { _Pragma("unroll") for (int n = 0; n < 2; ++n) _Pragma("unroll") for (int k = 0; k < 2; ++k) dst[n][k] = *(const LAS bf16x8*)(lds + PG8_SB(b, h) + boff + n * 2048 + k * 1024); } while (0)
; #define PG8_MMA(ai, bj, At, Bt) do { __builtin_amdgcn_s_setprio(1); _Pragma("unroll") for (int m = 0; m < 4; ++m) _Pragma("unroll") for (int n = 0; n < 2; ++n) _Pragma("unroll") for (int k = 0; k < 2; ++k) \
;         acc[ai][bj][m][n] = __builtin_amdgcn_mfma_f32_16x16x32_bf16(Bt[n][k], At[m][k], acc[ai][bj][m][n], 0, 0, 0); __builtin_amdgcn_s_setprio(0); } while (0)
; #define PG8_WAIT_V(n) asm volatile("s_waitcnt vmcnt(" #n ")" ::: "memory")
; #define PG8_WAIT_L(n) asm volatile("s_waitcnt lgkmcnt(" #n ")" ::: "memory")
; #define PG8_BAR __builtin_amdgcn_s_barrier()
; #define PG8_SCHED __builtin_amdgcn_sched_barrier(0)
; template <class Epi>
; __device__ __forceinline__ void gemm_phase(LAS unsigned char* lds, const Gemm g, const StaticOrder& S, const Epi& E, int wv) {
;     ...
;             PG8_LDB(B0, 0, 0); PG8_SCHED; PG8_LDA(At, 0, 0); PG8_STAGE(PG8_SA(1, 1), a1 + hstepA, voffA);
;     ...
;             PG8_LDB(B0, 1, 0); PG8_SCHED; PG8_LDA(At, 1, 0); PG8_STAGE(PG8_SA(0, 1), a2 + hstepA, voffA);
;             PG8_WAIT_L(8); PG8_BAR; PG8_WAIT_L(0); PG8_MMA(0, 0, At, B0); PG8_BAR; PG8_SCHED;
;             PG8_LDB(B1, 1, 1); PG8_STAGE(PG8_SB(1, 0), b3, voffB);
;             PG8_BAR; PG8_WAIT_L(0); PG8_MMA(0, 1, At, B1); PG8_BAR;
;             PG8_LDA(At, 1, 1); PG8_STAGE(PG8_SA(1, 0), a3, voffA);
;             PG8_BAR; PG8_WAIT_L(0); PG8_MMA(1, 0, At, B0); PG8_BAR; PG8_SCHED;
;             PG8_STAGE(PG8_SB(1, 1), b3 + hstepB, voffB);
;             PG8_WAIT_V(6); PG8_BAR; PG8_MMA(1, 1, At, B1); PG8_BAR;
	v_mfma_f32_16x16x32_bf16 v[52:55], v[198:201], v[160:163], v[52:55]
	v_mfma_f32_16x16x32_bf16 v[48:51], v[206:209], v[160:163], v[48:51]
	v_mfma_f32_16x16x32_bf16 v[36:39], v[198:201], v[168:171], v[36:39]
	v_mfma_f32_16x16x32_bf16 v[32:35], v[206:209], v[168:171], v[32:35]
	v_mfma_f32_16x16x32_bf16 v[20:23], v[198:201], v[182:185], v[20:23]
	v_mfma_f32_16x16x32_bf16 v[16:19], v[206:209], v[182:185], v[16:19]
	v_mfma_f32_16x16x32_bf16 v[4:7], v[198:201], v[190:193], v[4:7]
	v_mfma_f32_16x16x32_bf16 v[0:3], v[206:209], v[190:193], v[0:3]
	v_mfma_f32_16x16x32_bf16 v[52:55], v[202:205], v[164:167], v[52:55]
	v_mfma_f32_16x16x32_bf16 v[48:51], v[210:213], v[164:167], v[48:51]
	v_mfma_f32_16x16x32_bf16 v[36:39], v[202:205], v[172:175], v[36:39]
	v_mfma_f32_16x16x32_bf16 v[32:35], v[210:213], v[172:175], v[32:35]
	v_mfma_f32_16x16x32_bf16 v[20:23], v[202:205], v[186:189], v[20:23]
	v_mfma_f32_16x16x32_bf16 v[16:19], v[210:213], v[186:189], v[16:19]
	v_mfma_f32_16x16x32_bf16 v[4:7], v[202:205], v[194:197], v[4:7]
	v_mfma_f32_16x16x32_bf16 v[0:3], v[210:213], v[194:197], v[0:3]
	s_waitcnt lgkmcnt(0)
	s_barrier
	s_add_u32 s42, s74, 0x80000
	s_addc_u32 s43, s75, 0
	s_mov_b32 m0, s12
	ds_read_b128 v[160:163], v180 offset:32768
	ds_read_b128 v[164:167], v180 offset:33792
	ds_read_b128 v[168:171], v180 offset:34816
	ds_read_b128 v[172:175], v180 offset:35840
	ds_read_b128 v[182:185], v180 offset:36864
	ds_read_b128 v[186:189], v180 offset:37888
	ds_read_b128 v[190:193], v180 offset:38912
	ds_read_b128 v[194:197], v180 offset:39936
	global_load_lds_dwordx4 v144, s[42:43]
	s_mov_b32 m0, s13
	s_nop 0
	global_load_lds_dwordx4 v148, s[42:43]
	s_waitcnt lgkmcnt(8)
	s_barrier
	s_waitcnt lgkmcnt(0)
	v_mfma_f32_16x16x32_bf16 v[124:127], v[128:131], v[160:163], v[124:127]
	v_mfma_f32_16x16x32_bf16 v[120:123], v[136:139], v[160:163], v[120:123]
	v_mfma_f32_16x16x32_bf16 v[108:111], v[128:131], v[168:171], v[108:111]
	v_mfma_f32_16x16x32_bf16 v[104:107], v[136:139], v[168:171], v[104:107]
	v_mfma_f32_16x16x32_bf16 v[92:95], v[128:131], v[182:185], v[92:95]
	v_mfma_f32_16x16x32_bf16 v[88:91], v[136:139], v[182:185], v[88:91]
	v_mfma_f32_16x16x32_bf16 v[76:79], v[128:131], v[190:193], v[76:79]
	v_mfma_f32_16x16x32_bf16 v[72:75], v[136:139], v[190:193], v[72:75]
	v_mfma_f32_16x16x32_bf16 v[124:127], v[132:135], v[164:167], v[124:127]
	v_mfma_f32_16x16x32_bf16 v[120:123], v[140:143], v[164:167], v[120:123]
	v_mfma_f32_16x16x32_bf16 v[108:111], v[132:135], v[172:175], v[108:111]
	v_mfma_f32_16x16x32_bf16 v[104:107], v[140:143], v[172:175], v[104:107]
	v_mfma_f32_16x16x32_bf16 v[92:95], v[132:135], v[186:189], v[92:95]
	v_mfma_f32_16x16x32_bf16 v[88:91], v[140:143], v[186:189], v[88:91]
	v_mfma_f32_16x16x32_bf16 v[76:79], v[132:135], v[194:197], v[76:79]
	v_mfma_f32_16x16x32_bf16 v[72:75], v[140:143], v[194:197], v[72:75]
	s_barrier
	s_add_i32 s45, 0, 0x1c000
	s_add_i32 s42, s44, s9
	v_add_u32_e32 v210, s45, v177
	s_mov_b32 m0, s42
	ds_read_b128 v[198:201], v210
	ds_read_b128 v[202:205], v210 offset:1024
	ds_read_b128 v[206:209], v210 offset:2048
	ds_read_b128 v[210:213], v210 offset:3072
	global_load_lds_dwordx4 v146, s[98:99]
	s_add_i32 m0, s42, 0x2000
	s_nop 0
	global_load_lds_dwordx4 v150, s[98:99]
	s_barrier
	s_waitcnt lgkmcnt(0)
	v_mfma_f32_16x16x32_bf16 v[116:119], v[198:201], v[160:163], v[116:119]
	v_mfma_f32_16x16x32_bf16 v[112:115], v[206:209], v[160:163], v[112:115]
	v_mfma_f32_16x16x32_bf16 v[100:103], v[198:201], v[168:171], v[100:103]
	v_mfma_f32_16x16x32_bf16 v[96:99], v[206:209], v[168:171], v[96:99]
	v_mfma_f32_16x16x32_bf16 v[84:87], v[198:201], v[182:185], v[84:87]
	v_mfma_f32_16x16x32_bf16 v[80:83], v[206:209], v[182:185], v[80:83]
	v_mfma_f32_16x16x32_bf16 v[68:71], v[198:201], v[190:193], v[68:71]
	v_mfma_f32_16x16x32_bf16 v[64:67], v[206:209], v[190:193], v[64:67]
	v_mfma_f32_16x16x32_bf16 v[116:119], v[202:205], v[164:167], v[116:119]
	v_mfma_f32_16x16x32_bf16 v[112:115], v[210:213], v[164:167], v[112:115]
	v_mfma_f32_16x16x32_bf16 v[100:103], v[202:205], v[172:175], v[100:103]
	v_mfma_f32_16x16x32_bf16 v[96:99], v[210:213], v[172:175], v[96:99]
	v_mfma_f32_16x16x32_bf16 v[84:87], v[202:205], v[186:189], v[84:87]
	v_mfma_f32_16x16x32_bf16 v[80:83], v[210:213], v[186:189], v[80:83]
	v_mfma_f32_16x16x32_bf16 v[68:71], v[202:205], v[194:197], v[68:71]
	v_mfma_f32_16x16x32_bf16 v[64:67], v[210:213], v[194:197], v[64:67]
	s_mov_b32 m0, s15
	s_barrier
	ds_read_b128 v[160:163], v180 offset:49152
	ds_read_b128 v[164:167], v180 offset:50176
	ds_read_b128 v[168:171], v180 offset:51200
	ds_read_b128 v[172:175], v180 offset:52224
	ds_read_b128 v[182:185], v180 offset:53248
	ds_read_b128 v[186:189], v180 offset:54272
	ds_read_b128 v[190:193], v180 offset:55296
	ds_read_b128 v[194:197], v180 offset:56320
	global_load_lds_dwordx4 v144, s[100:101]
	s_mov_b32 m0, s22
	s_nop 0
	global_load_lds_dwordx4 v148, s[100:101]
	s_waitcnt vmcnt(10)
	s_barrier
	s_waitcnt lgkmcnt(0)
	v_mfma_f32_16x16x32_bf16 v[60:63], v[128:131], v[160:163], v[60:63]
	v_mfma_f32_16x16x32_bf16 v[56:59], v[136:139], v[160:163], v[56:59]
	v_mfma_f32_16x16x32_bf16 v[44:47], v[128:131], v[168:171], v[44:47]
	v_mfma_f32_16x16x32_bf16 v[40:43], v[136:139], v[168:171], v[40:43]
	v_mfma_f32_16x16x32_bf16 v[28:31], v[128:131], v[182:185], v[28:31]
	v_mfma_f32_16x16x32_bf16 v[24:27], v[136:139], v[182:185], v[24:27]
	v_mfma_f32_16x16x32_bf16 v[12:15], v[128:131], v[190:193], v[12:15]
	v_mfma_f32_16x16x32_bf16 v[8:11], v[136:139], v[190:193], v[8:11]
	v_mfma_f32_16x16x32_bf16 v[60:63], v[132:135], v[164:167], v[60:63]
	v_mfma_f32_16x16x32_bf16 v[56:59], v[140:143], v[164:167], v[56:59]
	v_mfma_f32_16x16x32_bf16 v[44:47], v[132:135], v[172:175], v[44:47]
	v_mfma_f32_16x16x32_bf16 v[40:43], v[140:143], v[172:175], v[40:43]
	v_mfma_f32_16x16x32_bf16 v[28:31], v[132:135], v[186:189], v[28:31]
	v_mfma_f32_16x16x32_bf16 v[24:27], v[140:143], v[186:189], v[24:27]
	v_mfma_f32_16x16x32_bf16 v[12:15], v[132:135], v[194:197], v[12:15]
	v_mfma_f32_16x16x32_bf16 v[8:11], v[140:143], v[194:197], v[8:11]
	s_barrier
	s_add_u32 s42, s72, 0x80080
	s_addc_u32 s43, s73, 0
	s_add_i32 s44, s45, s9
	s_mov_b32 m0, s44
	s_nop 0
	global_load_lds_dwordx4 v146, s[42:43]
	s_add_i32 m0, s44, 0x2000
	s_nop 0
	global_load_lds_dwordx4 v150, s[42:43]
	ds_read_b128 v[128:131], v179
	ds_read_b128 v[132:135], v179 offset:1024
	ds_read_b128 v[136:139], v179 offset:2048
	ds_read_b128 v[140:143], v179 offset:3072
	s_waitcnt vmcnt(6)
	s_branch .LBB0_443

; #define PG8_STAGE(bufoff, gbase, voff) do { _Pragma("unroll") for (int _i = 0; _i < 2; ++_i) \
;         __builtin_amdgcn_global_load_lds((const unsigned*)((const char*)(gbase) + (voff)[_i]), (LAS unsigned*)(lds + (bufoff) + ldsw + _i * 8192), 16, 0, 0); } while (0)
; #define PG8_LDA(dst, b, h) do { _Pragma("unroll") for (int m = 0; m < 4; ++m) _Pragma("unroll") for (int k = 0; k < 2; ++k) dst[m][k] = *(const LAS bf16x8*)(lds + PG8_SA(b, h) + aoff + m * 2048 + k * 1024); } while (0)
; #define PG8_LDB(dst, b, h) do { _Pragma("unroll") for (int n = 0; n < 2; ++n) _Pragma("unroll") for (int k = 0; k < 2; ++k) dst[n][k] = *(const LAS bf16x8*)(lds + PG8_SB(b, h) + boff + n * 2048 + k * 1024); } while (0)
; #define PG8_MMA(ai, bj, At, Bt) do { __builtin_amdgcn_s_setprio(1); _Pragma("unroll") for (int m = 0; m < 4; ++m) _Pragma("unroll") for (int n = 0; n < 2; ++n) _Pragma("unroll") for (int k = 0; k < 2; ++k) \
;         acc[ai][bj][m][n] = __builtin_amdgcn_mfma_f32_16x16x32_bf16(Bt[n][k], At[m][k], acc[ai][bj][m][n], 0, 0, 0); __builtin_amdgcn_s_setprio(0); } while (0)
; #define PG8_WAIT_V(n) asm volatile("s_waitcnt vmcnt(" #n ")" ::: "memory")
; #define PG8_WAIT_L(n) asm volatile("s_waitcnt lgkmcnt(" #n ")" ::: "memory")
; #define PG8_BAR __builtin_amdgcn_s_barrier()
; template <class Epi>
; __device__ __forceinline__ void gemm_phase(LAS unsigned char* lds, const Gemm g, const StaticOrder& S, const Epi& E, int wv) {
;     ...
;             const bool last = (t == nt - 2);
;             const char* a1 = cA + (ptrdiff_t)(t + 1) * kstep;
;             const char* a2 = last ? nA : cA + (ptrdiff_t)(t + 2) * kstep; const char* b2 = last ? nB : cB + (ptrdiff_t)(t + 2) * kstep;
;             const char* a3 = a2 + kstep; const char* b3 = b2 + kstep;
;             PG8_LDB(B0, 0, 0); PG8_SCHED; PG8_LDA(At, 0, 0); PG8_STAGE(PG8_SA(1, 1), a1 + hstepA, voffA);
;             PG8_WAIT_L(8); PG8_BAR; PG8_WAIT_L(0); PG8_MMA(0, 0, At, B0); PG8_BAR; PG8_SCHED;
;             PG8_LDB(B1, 0, 1); PG8_STAGE(PG8_SB(0, 0), b2, voffB);
;             PG8_BAR; PG8_WAIT_L(0); PG8_MMA(0, 1, At, B1); PG8_BAR;
;             PG8_LDA(At, 0, 1); PG8_STAGE(PG8_SA(0, 0), a2, voffA);
;             PG8_BAR; PG8_WAIT_L(0); PG8_MMA(1, 0, At, B0); PG8_BAR; PG8_SCHED;
;             PG8_STAGE(PG8_SB(0, 1), b2 + hstepB, voffB);
;             PG8_WAIT_V(6); PG8_BAR; PG8_MMA(1, 1, At, B1); PG8_BAR;
.Lrot_in_530:
	s_add_u32 s44, s66, 0xfff80080
	s_addc_u32 s45, s67, -1
	s_cmp_eq_u32 s43, 28
	s_cselect_b32 s71, s35, s45
	s_cselect_b32 s70, s38, s44
	s_cselect_b32 s69, s39, s42
	s_cselect_b32 s68, s40, s41
	s_add_i32 m0, s10, 0xc000
	ds_read_b128 v[170:173], v154
	ds_read_b128 v[174:177], v154 offset:1024
	ds_read_b128 v[178:181], v154 offset:2048
	ds_read_b128 v[182:185], v154 offset:3072
	ds_read_b128 v[186:189], v154 offset:4096
	ds_read_b128 v[190:193], v154 offset:5120
	ds_read_b128 v[194:197], v154 offset:6144
	ds_read_b128 v[198:201], v154 offset:7168
	global_load_lds_dwordx4 v138, s[66:67]
	s_add_i32 m0, s10, 0xe000
	s_nop 0
	global_load_lds_dwordx4 v136, s[66:67]
	s_waitcnt lgkmcnt(8)
	s_barrier
	s_waitcnt lgkmcnt(0)
	v_mfma_f32_16x16x32_bf16 v[124:127], v[144:147], v[170:173], v[124:127]
	v_mfma_f32_16x16x32_bf16 v[120:123], v[162:165], v[170:173], v[120:123]
	v_mfma_f32_16x16x32_bf16 v[116:119], v[144:147], v[178:181], v[116:119]
	v_mfma_f32_16x16x32_bf16 v[112:115], v[162:165], v[178:181], v[112:115]
	v_mfma_f32_16x16x32_bf16 v[92:95], v[144:147], v[186:189], v[92:95]
	v_mfma_f32_16x16x32_bf16 v[88:91], v[162:165], v[186:189], v[88:91]
	v_mfma_f32_16x16x32_bf16 v[76:79], v[144:147], v[194:197], v[76:79]
	v_mfma_f32_16x16x32_bf16 v[72:75], v[162:165], v[194:197], v[72:75]
	v_mfma_f32_16x16x32_bf16 v[124:127], v[158:161], v[174:177], v[124:127]
	v_mfma_f32_16x16x32_bf16 v[120:123], v[166:169], v[174:177], v[120:123]
	v_mfma_f32_16x16x32_bf16 v[116:119], v[158:161], v[182:185], v[116:119]
	v_mfma_f32_16x16x32_bf16 v[112:115], v[166:169], v[182:185], v[112:115]
	v_mfma_f32_16x16x32_bf16 v[92:95], v[158:161], v[190:193], v[92:95]
	v_mfma_f32_16x16x32_bf16 v[88:91], v[166:169], v[190:193], v[88:91]
	v_mfma_f32_16x16x32_bf16 v[76:79], v[158:161], v[198:201], v[76:79]
	v_mfma_f32_16x16x32_bf16 v[72:75], v[166:169], v[198:201], v[72:75]
	s_barrier
	s_add_i32 s44, s23, s9
	s_add_u32 s98, s68, s52
	s_addc_u32 s99, s69, s53
	s_mov_b32 m0, s44
	ds_read_b128 v[202:205], v155
	ds_read_b128 v[206:209], v155 offset:1024
	ds_read_b128 v[210:213], v155 offset:2048
	ds_read_b128 v[214:217], v155 offset:3072
	global_load_lds_dwordx4 v130, s[68:69]
	s_add_i32 m0, s44, 0x2000
	s_nop 0
	global_load_lds_dwordx4 v134, s[68:69]
	s_barrier
	s_waitcnt lgkmcnt(0)
	v_mfma_f32_16x16x32_bf16 v[108:111], v[202:205], v[170:173], v[108:111]
	v_mfma_f32_16x16x32_bf16 v[104:107], v[210:213], v[170:173], v[104:107]
	v_mfma_f32_16x16x32_bf16 v[100:103], v[202:205], v[178:181], v[100:103]
	v_mfma_f32_16x16x32_bf16 v[96:99], v[210:213], v[178:181], v[96:99]
	v_mfma_f32_16x16x32_bf16 v[84:87], v[202:205], v[186:189], v[84:87]
	v_mfma_f32_16x16x32_bf16 v[80:83], v[210:213], v[186:189], v[80:83]
	v_mfma_f32_16x16x32_bf16 v[68:71], v[202:205], v[194:197], v[68:71]
	v_mfma_f32_16x16x32_bf16 v[64:67], v[210:213], v[194:197], v[64:67]
	v_mfma_f32_16x16x32_bf16 v[108:111], v[206:209], v[174:177], v[108:111]
	v_mfma_f32_16x16x32_bf16 v[104:107], v[214:217], v[174:177], v[104:107]
	v_mfma_f32_16x16x32_bf16 v[100:103], v[206:209], v[182:185], v[100:103]
	v_mfma_f32_16x16x32_bf16 v[96:99], v[214:217], v[182:185], v[96:99]
	v_mfma_f32_16x16x32_bf16 v[84:87], v[206:209], v[190:193], v[84:87]
	v_mfma_f32_16x16x32_bf16 v[80:83], v[214:217], v[190:193], v[80:83]
	v_mfma_f32_16x16x32_bf16 v[68:71], v[206:209], v[198:201], v[68:71]
	v_mfma_f32_16x16x32_bf16 v[64:67], v[214:217], v[198:201], v[64:67]
	s_mov_b32 m0, s10
	s_add_u32 s100, s70, s52
	s_addc_u32 s101, s71, s53
	s_barrier
	ds_read_b128 v[170:173], v154 offset:16384
	ds_read_b128 v[174:177], v154 offset:17408
	ds_read_b128 v[178:181], v154 offset:18432
	ds_read_b128 v[182:185], v154 offset:19456
	ds_read_b128 v[186:189], v154 offset:20480
	ds_read_b128 v[190:193], v154 offset:21504
	ds_read_b128 v[194:197], v154 offset:22528
	ds_read_b128 v[198:201], v154 offset:23552
	global_load_lds_dwordx4 v128, s[70:71]
	s_mov_b32 m0, s11
	s_nop 0
	global_load_lds_dwordx4 v132, s[70:71]
	s_waitcnt vmcnt(10)
	s_barrier
	s_waitcnt lgkmcnt(0)
	v_mfma_f32_16x16x32_bf16 v[60:63], v[144:147], v[170:173], v[60:63]
	v_mfma_f32_16x16x32_bf16 v[56:59], v[162:165], v[170:173], v[56:59]
	v_mfma_f32_16x16x32_bf16 v[44:47], v[144:147], v[178:181], v[44:47]
	v_mfma_f32_16x16x32_bf16 v[40:43], v[162:165], v[178:181], v[40:43]
	v_mfma_f32_16x16x32_bf16 v[28:31], v[144:147], v[186:189], v[28:31]
	v_mfma_f32_16x16x32_bf16 v[24:27], v[162:165], v[186:189], v[24:27]
	v_mfma_f32_16x16x32_bf16 v[12:15], v[144:147], v[194:197], v[12:15]
	v_mfma_f32_16x16x32_bf16 v[8:11], v[162:165], v[194:197], v[8:11]
	v_mfma_f32_16x16x32_bf16 v[60:63], v[158:161], v[174:177], v[60:63]
	v_mfma_f32_16x16x32_bf16 v[56:59], v[166:169], v[174:177], v[56:59]
	v_mfma_f32_16x16x32_bf16 v[44:47], v[158:161], v[182:185], v[44:47]
	v_mfma_f32_16x16x32_bf16 v[40:43], v[166:169], v[182:185], v[40:43]
	v_mfma_f32_16x16x32_bf16 v[28:31], v[158:161], v[190:193], v[28:31]
	v_mfma_f32_16x16x32_bf16 v[24:27], v[166:169], v[190:193], v[24:27]
	v_mfma_f32_16x16x32_bf16 v[12:15], v[158:161], v[198:201], v[12:15]
	v_mfma_f32_16x16x32_bf16 v[8:11], v[166:169], v[198:201], v[8:11]
	s_barrier
	s_add_u32 s44, s68, 0x80000
	s_addc_u32 s45, s69, 0
	s_add_i32 s46, s24, s9
	s_mov_b32 m0, s46
	s_nop 0
	global_load_lds_dwordx4 v130, s[44:45]
	s_add_i32 m0, s46, 0x2000
	s_nop 0
	global_load_lds_dwordx4 v134, s[44:45]
	s_add_i32 s46, 0, 0x18000
	v_add_u32_e32 v157, s46, v151
	ds_read_b128 v[144:147], v157
	ds_read_b128 v[158:161], v157 offset:1024
	ds_read_b128 v[162:165], v157 offset:2048
	ds_read_b128 v[166:169], v157 offset:3072
	s_waitcnt vmcnt(6)
	s_barrier
; #define PG8_STAGE(bufoff, gbase, voff) do { _Pragma("unroll") for (int _i = 0; _i < 2; ++_i) \
;         __builtin_amdgcn_global_load_lds((const unsigned*)((const char*)(gbase) + (voff)[_i]), (LAS unsigned*)(lds + (bufoff) + ldsw + _i * 8192), 16, 0, 0); } while (0)
; #define PG8_LDA(dst, b, h) do { _Pragma("unroll") for (int m = 0; m < 4; ++m) _Pragma("unroll") for (int k = 0; k < 2; ++k) dst[m][k] = *(const LAS bf16x8*)(lds + PG8_SA(b, h) + aoff + m * 2048 + k * 1024); } while (0)
; #define PG8_LDB(dst, b, h) do { _Pragma("unroll") for (int n = 0; n < 2; ++n) _Pragma("unroll") for (int k = 0; k < 2; ++k) dst[n][k] = *(const LAS bf16x8*)(lds + PG8_SB(b, h) + boff + n * 2048 + k * 1024); } while (0)
; #define PG8_MMA(ai, bj, At, Bt) do { __builtin_amdgcn_s_setprio(1); _Pragma("unroll") for (int m = 0; m < 4; ++m) _Pragma("unroll") for (int n = 0; n < 2; ++n) _Pragma("unroll") for (int k = 0; k < 2; ++k) \
;         acc[ai][bj][m][n] = __builtin_amdgcn_mfma_f32_16x16x32_bf16(Bt[n][k], At[m][k], acc[ai][bj][m][n], 0, 0, 0); __builtin_amdgcn_s_setprio(0); } while (0)
; #define PG8_WAIT_V(n) asm volatile("s_waitcnt vmcnt(" #n ")" ::: "memory")
; #define PG8_WAIT_L(n) asm volatile("s_waitcnt lgkmcnt(" #n ")" ::: "memory")
; #define PG8_BAR __builtin_amdgcn_s_barrier()
; #define PG8_SCHED __builtin_amdgcn_sched_barrier(0)
; template <class Epi>
; __device__ __forceinline__ void gemm_phase(LAS unsigned char* lds, const Gemm g, const StaticOrder& S, const Epi& E, int wv) {
;     ...
;             PG8_LDB(B0, 0, 0); PG8_SCHED; PG8_LDA(At, 0, 0); PG8_STAGE(PG8_SA(1, 1), a1 + hstepA, voffA);
;     ...
;             PG8_LDB(B0, 1, 0); PG8_SCHED; PG8_LDA(At, 1, 0); PG8_STAGE(PG8_SA(0, 1), a2 + hstepA, voffA);
;             PG8_WAIT_L(8); PG8_BAR; PG8_WAIT_L(0); PG8_MMA(0, 0, At, B0); PG8_BAR; PG8_SCHED;
;             PG8_LDB(B1, 1, 1); PG8_STAGE(PG8_SB(1, 0), b3, voffB);
;             PG8_BAR; PG8_WAIT_L(0); PG8_MMA(0, 1, At, B1); PG8_BAR;
;             PG8_LDA(At, 1, 1); PG8_STAGE(PG8_SA(1, 0), a3, voffA);
;             PG8_BAR; PG8_WAIT_L(0); PG8_MMA(1, 0, At, B0); PG8_BAR; PG8_SCHED;
;             PG8_STAGE(PG8_SB(1, 1), b3 + hstepB, voffB);
;             PG8_WAIT_V(6); PG8_BAR; PG8_MMA(1, 1, At, B1); PG8_BAR;
	v_mfma_f32_16x16x32_bf16 v[52:55], v[202:205], v[170:173], v[52:55]
	v_mfma_f32_16x16x32_bf16 v[48:51], v[210:213], v[170:173], v[48:51]
	v_mfma_f32_16x16x32_bf16 v[36:39], v[202:205], v[178:181], v[36:39]
	v_mfma_f32_16x16x32_bf16 v[32:35], v[210:213], v[178:181], v[32:35]
	v_mfma_f32_16x16x32_bf16 v[20:23], v[202:205], v[186:189], v[20:23]
	v_mfma_f32_16x16x32_bf16 v[16:19], v[210:213], v[186:189], v[16:19]
	v_mfma_f32_16x16x32_bf16 v[4:7], v[202:205], v[194:197], v[4:7]
	v_mfma_f32_16x16x32_bf16 v[0:3], v[210:213], v[194:197], v[0:3]
	v_mfma_f32_16x16x32_bf16 v[52:55], v[206:209], v[174:177], v[52:55]
	v_mfma_f32_16x16x32_bf16 v[48:51], v[214:217], v[174:177], v[48:51]
	v_mfma_f32_16x16x32_bf16 v[36:39], v[206:209], v[182:185], v[36:39]
	v_mfma_f32_16x16x32_bf16 v[32:35], v[214:217], v[182:185], v[32:35]
	v_mfma_f32_16x16x32_bf16 v[20:23], v[206:209], v[190:193], v[20:23]
	v_mfma_f32_16x16x32_bf16 v[16:19], v[214:217], v[190:193], v[16:19]
	v_mfma_f32_16x16x32_bf16 v[4:7], v[206:209], v[198:201], v[4:7]
	v_mfma_f32_16x16x32_bf16 v[0:3], v[214:217], v[198:201], v[0:3]
	s_waitcnt lgkmcnt(0)
	s_barrier
	s_add_u32 s44, s70, 0x80000
	s_addc_u32 s45, s71, 0
	s_mov_b32 m0, s12
	ds_read_b128 v[170:173], v154 offset:32768
	ds_read_b128 v[174:177], v154 offset:33792
	ds_read_b128 v[178:181], v154 offset:34816
	ds_read_b128 v[182:185], v154 offset:35840
	ds_read_b128 v[186:189], v154 offset:36864
	ds_read_b128 v[190:193], v154 offset:37888
	ds_read_b128 v[194:197], v154 offset:38912
	ds_read_b128 v[198:201], v154 offset:39936
	global_load_lds_dwordx4 v128, s[44:45]
	s_mov_b32 m0, s13
	s_nop 0
	global_load_lds_dwordx4 v132, s[44:45]
	s_waitcnt lgkmcnt(8)
	s_barrier
	s_waitcnt lgkmcnt(0)
	v_mfma_f32_16x16x32_bf16 v[124:127], v[144:147], v[170:173], v[124:127]
	v_mfma_f32_16x16x32_bf16 v[120:123], v[162:165], v[170:173], v[120:123]
	v_mfma_f32_16x16x32_bf16 v[116:119], v[144:147], v[178:181], v[116:119]
	v_mfma_f32_16x16x32_bf16 v[112:115], v[162:165], v[178:181], v[112:115]
	v_mfma_f32_16x16x32_bf16 v[92:95], v[144:147], v[186:189], v[92:95]
	v_mfma_f32_16x16x32_bf16 v[88:91], v[162:165], v[186:189], v[88:91]
	v_mfma_f32_16x16x32_bf16 v[76:79], v[144:147], v[194:197], v[76:79]
	v_mfma_f32_16x16x32_bf16 v[72:75], v[162:165], v[194:197], v[72:75]
	v_mfma_f32_16x16x32_bf16 v[124:127], v[158:161], v[174:177], v[124:127]
	v_mfma_f32_16x16x32_bf16 v[120:123], v[166:169], v[174:177], v[120:123]
	v_mfma_f32_16x16x32_bf16 v[116:119], v[158:161], v[182:185], v[116:119]
	v_mfma_f32_16x16x32_bf16 v[112:115], v[166:169], v[182:185], v[112:115]
	v_mfma_f32_16x16x32_bf16 v[92:95], v[158:161], v[190:193], v[92:95]
	v_mfma_f32_16x16x32_bf16 v[88:91], v[166:169], v[190:193], v[88:91]
	v_mfma_f32_16x16x32_bf16 v[76:79], v[158:161], v[198:201], v[76:79]
	v_mfma_f32_16x16x32_bf16 v[72:75], v[166:169], v[198:201], v[72:75]
	s_barrier
	s_add_i32 s47, 0, 0x1c000
	s_add_i32 s44, s46, s9
	v_add_u32_e32 v157, s47, v151
	s_mov_b32 m0, s44
	ds_read_b128 v[202:205], v157
	ds_read_b128 v[206:209], v157 offset:1024
	ds_read_b128 v[210:213], v157 offset:2048
	ds_read_b128 v[214:217], v157 offset:3072
	global_load_lds_dwordx4 v130, s[98:99]
	s_add_i32 m0, s44, 0x2000
	s_nop 0
	global_load_lds_dwordx4 v134, s[98:99]
	s_barrier
	s_waitcnt lgkmcnt(0)
	v_mfma_f32_16x16x32_bf16 v[108:111], v[202:205], v[170:173], v[108:111]
	v_mfma_f32_16x16x32_bf16 v[104:107], v[210:213], v[170:173], v[104:107]
	v_mfma_f32_16x16x32_bf16 v[100:103], v[202:205], v[178:181], v[100:103]
	v_mfma_f32_16x16x32_bf16 v[96:99], v[210:213], v[178:181], v[96:99]
	v_mfma_f32_16x16x32_bf16 v[84:87], v[202:205], v[186:189], v[84:87]
	v_mfma_f32_16x16x32_bf16 v[80:83], v[210:213], v[186:189], v[80:83]
	v_mfma_f32_16x16x32_bf16 v[68:71], v[202:205], v[194:197], v[68:71]
	v_mfma_f32_16x16x32_bf16 v[64:67], v[210:213], v[194:197], v[64:67]
	v_mfma_f32_16x16x32_bf16 v[108:111], v[206:209], v[174:177], v[108:111]
	v_mfma_f32_16x16x32_bf16 v[104:107], v[214:217], v[174:177], v[104:107]
	v_mfma_f32_16x16x32_bf16 v[100:103], v[206:209], v[182:185], v[100:103]
	v_mfma_f32_16x16x32_bf16 v[96:99], v[214:217], v[182:185], v[96:99]
	v_mfma_f32_16x16x32_bf16 v[84:87], v[206:209], v[190:193], v[84:87]
	v_mfma_f32_16x16x32_bf16 v[80:83], v[214:217], v[190:193], v[80:83]
	v_mfma_f32_16x16x32_bf16 v[68:71], v[206:209], v[198:201], v[68:71]
	v_mfma_f32_16x16x32_bf16 v[64:67], v[214:217], v[198:201], v[64:67]
	s_mov_b32 m0, s15
	s_barrier
	ds_read_b128 v[170:173], v154 offset:49152
	ds_read_b128 v[174:177], v154 offset:50176
	ds_read_b128 v[178:181], v154 offset:51200
	ds_read_b128 v[182:185], v154 offset:52224
	ds_read_b128 v[186:189], v154 offset:53248
	ds_read_b128 v[190:193], v154 offset:54272
	ds_read_b128 v[194:197], v154 offset:55296
	ds_read_b128 v[198:201], v154 offset:56320
	global_load_lds_dwordx4 v128, s[100:101]
	s_mov_b32 m0, s22
	s_nop 0
	global_load_lds_dwordx4 v132, s[100:101]
	s_waitcnt vmcnt(10)
	s_barrier
	s_waitcnt lgkmcnt(0)
	v_mfma_f32_16x16x32_bf16 v[60:63], v[144:147], v[170:173], v[60:63]
	v_mfma_f32_16x16x32_bf16 v[56:59], v[162:165], v[170:173], v[56:59]
	v_mfma_f32_16x16x32_bf16 v[44:47], v[144:147], v[178:181], v[44:47]
	v_mfma_f32_16x16x32_bf16 v[40:43], v[162:165], v[178:181], v[40:43]
	v_mfma_f32_16x16x32_bf16 v[28:31], v[144:147], v[186:189], v[28:31]
	v_mfma_f32_16x16x32_bf16 v[24:27], v[162:165], v[186:189], v[24:27]
	v_mfma_f32_16x16x32_bf16 v[12:15], v[144:147], v[194:197], v[12:15]
	v_mfma_f32_16x16x32_bf16 v[8:11], v[162:165], v[194:197], v[8:11]
	v_mfma_f32_16x16x32_bf16 v[60:63], v[158:161], v[174:177], v[60:63]
	v_mfma_f32_16x16x32_bf16 v[56:59], v[166:169], v[174:177], v[56:59]
	v_mfma_f32_16x16x32_bf16 v[44:47], v[158:161], v[182:185], v[44:47]
	v_mfma_f32_16x16x32_bf16 v[40:43], v[166:169], v[182:185], v[40:43]
	v_mfma_f32_16x16x32_bf16 v[28:31], v[158:161], v[190:193], v[28:31]
	v_mfma_f32_16x16x32_bf16 v[24:27], v[166:169], v[190:193], v[24:27]
	v_mfma_f32_16x16x32_bf16 v[12:15], v[158:161], v[198:201], v[12:15]
	v_mfma_f32_16x16x32_bf16 v[8:11], v[166:169], v[198:201], v[8:11]
	s_barrier
	s_add_u32 s44, s68, 0x80080
	s_addc_u32 s45, s69, 0
	s_add_i32 s46, s47, s9
	s_mov_b32 m0, s46
	s_nop 0
	global_load_lds_dwordx4 v130, s[44:45]
	s_add_i32 m0, s46, 0x2000
	s_nop 0
	global_load_lds_dwordx4 v134, s[44:45]
	ds_read_b128 v[144:147], v153
	ds_read_b128 v[158:161], v153 offset:1024
	ds_read_b128 v[162:165], v153 offset:2048
	ds_read_b128 v[166:169], v153 offset:3072
	s_waitcnt vmcnt(6)
	s_branch .LBB0_530

; #define PG8_STAGE(bufoff, gbase, voff) do { _Pragma("unroll") for (int _i = 0; _i < 2; ++_i) \
;         __builtin_amdgcn_global_load_lds((const unsigned*)((const char*)(gbase) + (voff)[_i]), (LAS unsigned*)(lds + (bufoff) + ldsw + _i * 8192), 16, 0, 0); } while (0)
; #define PG8_LDA(dst, b, h) do { _Pragma("unroll") for (int m = 0; m < 4; ++m) _Pragma("unroll") for (int k = 0; k < 2; ++k) dst[m][k] = *(const LAS bf16x8*)(lds + PG8_SA(b, h) + aoff + m * 2048 + k * 1024); } while (0)
; #define PG8_LDB(dst, b, h) do { _Pragma("unroll") for (int n = 0; n < 2; ++n) _Pragma("unroll") for (int k = 0; k < 2; ++k) dst[n][k] = *(const LAS bf16x8*)(lds + PG8_SB(b, h) + boff + n * 2048 + k * 1024); } while (0)
; #define PG8_MMA(ai, bj, At, Bt) do { __builtin_amdgcn_s_setprio(1); _Pragma("unroll") for (int m = 0; m < 4; ++m) _Pragma("unroll") for (int n = 0; n < 2; ++n) _Pragma("unroll") for (int k = 0; k < 2; ++k) \
;         acc[ai][bj][m][n] = __builtin_amdgcn_mfma_f32_16x16x32_bf16(Bt[n][k], At[m][k], acc[ai][bj][m][n], 0, 0, 0); __builtin_amdgcn_s_setprio(0); } while (0)
; #define PG8_WAIT_V(n) asm volatile("s_waitcnt vmcnt(" #n ")" ::: "memory")
; #define PG8_WAIT_L(n) asm volatile("s_waitcnt lgkmcnt(" #n ")" ::: "memory")
; #define PG8_BAR __builtin_amdgcn_s_barrier()
; #define PG8_SCHED __builtin_amdgcn_sched_barrier(0)
; template <class Epi>
; __device__ __forceinline__ void gemm_phase(LAS unsigned char* lds, const Gemm g, const StaticOrder& S, const Epi& E, int wv) {
;     ...
;             const char* a1 = cA + (ptrdiff_t)(t + 1) * kstep;
;             const char* a2 = last ? nA : cA + (ptrdiff_t)(t + 2) * kstep; const char* b2 = last ? nB : cB + (ptrdiff_t)(t + 2) * kstep;
;             const char* a3 = a2 + kstep; const char* b3 = b2 + kstep;
;             PG8_LDB(B0, 0, 0); PG8_SCHED; PG8_LDA(At, 0, 0); PG8_STAGE(PG8_SA(1, 1), a1 + hstepA, voffA);
;             PG8_WAIT_L(8); PG8_BAR; PG8_WAIT_L(0); PG8_MMA(0, 0, At, B0); PG8_BAR; PG8_SCHED;
;             PG8_LDB(B1, 0, 1); PG8_STAGE(PG8_SB(0, 0), b2, voffB);
;             PG8_BAR; PG8_WAIT_L(0); PG8_MMA(0, 1, At, B1); PG8_BAR;
;             PG8_LDA(At, 0, 1); PG8_STAGE(PG8_SA(0, 0), a2, voffA);
;             PG8_BAR; PG8_WAIT_L(0); PG8_MMA(1, 0, At, B0); PG8_BAR; PG8_SCHED;
;             PG8_STAGE(PG8_SB(0, 1), b2 + hstepB, voffB);
;             PG8_WAIT_V(6); PG8_BAR; PG8_MMA(1, 1, At, B1); PG8_BAR;
.LBB0_605:
	s_or_b32 s50, s35, 1
	s_lshl_b64 s[38:39], s[50:51], 7
	s_sub_u32 s38, 0, s38
	s_subb_u32 s39, 0, s39
	s_add_u32 s38, s33, s38
	s_addc_u32 s39, s34, s39
	s_add_i32 m0, s8, 0xc000
	ds_read_b128 v[156:159], v175
	ds_read_b128 v[160:163], v175 offset:1024
	ds_read_b128 v[164:167], v175 offset:2048
	ds_read_b128 v[168:171], v175 offset:3072
	ds_read_b128 v[176:179], v175 offset:4096
	ds_read_b128 v[180:183], v175 offset:5120
	ds_read_b128 v[184:187], v175 offset:6144
	ds_read_b128 v[188:191], v175 offset:7168
	global_load_lds_dwordx4 v144, s[38:39]
	s_add_i32 m0, s8, 0xe000
	s_nop 0
	global_load_lds_dwordx4 v148, s[38:39]
	s_waitcnt lgkmcnt(8)
	s_barrier
	s_waitcnt lgkmcnt(0)
	v_mfma_f32_16x16x32_bf16 v[124:127], v[128:131], v[156:159], v[124:127]
	v_mfma_f32_16x16x32_bf16 v[120:123], v[136:139], v[156:159], v[120:123]
	v_mfma_f32_16x16x32_bf16 v[108:111], v[128:131], v[164:167], v[108:111]
	v_mfma_f32_16x16x32_bf16 v[104:107], v[136:139], v[164:167], v[104:107]
	v_mfma_f32_16x16x32_bf16 v[92:95], v[128:131], v[176:179], v[92:95]
	v_mfma_f32_16x16x32_bf16 v[88:91], v[136:139], v[176:179], v[88:91]
	v_mfma_f32_16x16x32_bf16 v[76:79], v[128:131], v[184:187], v[76:79]
	v_mfma_f32_16x16x32_bf16 v[72:75], v[136:139], v[184:187], v[72:75]
	v_mfma_f32_16x16x32_bf16 v[124:127], v[132:135], v[160:163], v[124:127]
	v_mfma_f32_16x16x32_bf16 v[120:123], v[140:143], v[160:163], v[120:123]
	v_mfma_f32_16x16x32_bf16 v[108:111], v[132:135], v[168:171], v[108:111]
	v_mfma_f32_16x16x32_bf16 v[104:107], v[140:143], v[168:171], v[104:107]
	v_mfma_f32_16x16x32_bf16 v[92:95], v[132:135], v[180:183], v[92:95]
	v_mfma_f32_16x16x32_bf16 v[88:91], v[140:143], v[180:183], v[88:91]
	v_mfma_f32_16x16x32_bf16 v[76:79], v[132:135], v[188:191], v[76:79]
	v_mfma_f32_16x16x32_bf16 v[72:75], v[140:143], v[188:191], v[72:75]
	s_barrier
	s_add_i32 s38, s22, s7
	v_add_u32_e32 v204, s23, v173
	s_add_u32 s98, s82, s58
	s_addc_u32 s99, s83, s59
	s_mov_b32 m0, s38
	ds_read_b128 v[192:195], v204
	ds_read_b128 v[196:199], v204 offset:1024
	ds_read_b128 v[200:203], v204 offset:2048
	ds_read_b128 v[204:207], v204 offset:3072
	global_load_lds_dwordx4 v146, s[82:83]
	s_add_i32 m0, s38, 0x2000
	s_nop 0
	global_load_lds_dwordx4 v150, s[82:83]
	s_barrier
	s_waitcnt lgkmcnt(0)
	v_mfma_f32_16x16x32_bf16 v[116:119], v[192:195], v[156:159], v[116:119]
	v_mfma_f32_16x16x32_bf16 v[112:115], v[200:203], v[156:159], v[112:115]
	v_mfma_f32_16x16x32_bf16 v[100:103], v[192:195], v[164:167], v[100:103]
	v_mfma_f32_16x16x32_bf16 v[96:99], v[200:203], v[164:167], v[96:99]
	v_mfma_f32_16x16x32_bf16 v[84:87], v[192:195], v[176:179], v[84:87]
	v_mfma_f32_16x16x32_bf16 v[80:83], v[200:203], v[176:179], v[80:83]
	v_mfma_f32_16x16x32_bf16 v[68:71], v[192:195], v[184:187], v[68:71]
	v_mfma_f32_16x16x32_bf16 v[64:67], v[200:203], v[184:187], v[64:67]
	v_mfma_f32_16x16x32_bf16 v[116:119], v[196:199], v[160:163], v[116:119]
	v_mfma_f32_16x16x32_bf16 v[112:115], v[204:207], v[160:163], v[112:115]
	v_mfma_f32_16x16x32_bf16 v[100:103], v[196:199], v[168:171], v[100:103]
	v_mfma_f32_16x16x32_bf16 v[96:99], v[204:207], v[168:171], v[96:99]
	v_mfma_f32_16x16x32_bf16 v[84:87], v[196:199], v[180:183], v[84:87]
	v_mfma_f32_16x16x32_bf16 v[80:83], v[204:207], v[180:183], v[80:83]
	v_mfma_f32_16x16x32_bf16 v[68:71], v[196:199], v[188:191], v[68:71]
	v_mfma_f32_16x16x32_bf16 v[64:67], v[204:207], v[188:191], v[64:67]
	s_mov_b32 m0, s8
	s_add_u32 s100, s84, s58
	s_addc_u32 s101, s85, s59
	s_barrier
	ds_read_b128 v[156:159], v175 offset:16384
	ds_read_b128 v[160:163], v175 offset:17408
	ds_read_b128 v[164:167], v175 offset:18432
	ds_read_b128 v[168:171], v175 offset:19456
	ds_read_b128 v[176:179], v175 offset:20480
	ds_read_b128 v[180:183], v175 offset:21504
	ds_read_b128 v[184:187], v175 offset:22528
	ds_read_b128 v[188:191], v175 offset:23552
	global_load_lds_dwordx4 v144, s[84:85]
	s_mov_b32 m0, s9
	s_nop 0
	global_load_lds_dwordx4 v148, s[84:85]
	s_waitcnt vmcnt(10)
	s_barrier
	s_waitcnt lgkmcnt(0)
	v_mfma_f32_16x16x32_bf16 v[60:63], v[128:131], v[156:159], v[60:63]
	v_mfma_f32_16x16x32_bf16 v[56:59], v[136:139], v[156:159], v[56:59]
	v_mfma_f32_16x16x32_bf16 v[44:47], v[128:131], v[164:167], v[44:47]
	v_mfma_f32_16x16x32_bf16 v[40:43], v[136:139], v[164:167], v[40:43]
	v_mfma_f32_16x16x32_bf16 v[28:31], v[128:131], v[176:179], v[28:31]
	v_mfma_f32_16x16x32_bf16 v[24:27], v[136:139], v[176:179], v[24:27]
	v_mfma_f32_16x16x32_bf16 v[12:15], v[128:131], v[184:187], v[12:15]
	v_mfma_f32_16x16x32_bf16 v[8:11], v[136:139], v[184:187], v[8:11]
	v_mfma_f32_16x16x32_bf16 v[60:63], v[132:135], v[160:163], v[60:63]
	v_mfma_f32_16x16x32_bf16 v[56:59], v[140:143], v[160:163], v[56:59]
	v_mfma_f32_16x16x32_bf16 v[44:47], v[132:135], v[168:171], v[44:47]
	v_mfma_f32_16x16x32_bf16 v[40:43], v[140:143], v[168:171], v[40:43]
	v_mfma_f32_16x16x32_bf16 v[28:31], v[132:135], v[180:183], v[28:31]
	v_mfma_f32_16x16x32_bf16 v[24:27], v[140:143], v[180:183], v[24:27]
	v_mfma_f32_16x16x32_bf16 v[12:15], v[132:135], v[188:191], v[12:15]
	v_mfma_f32_16x16x32_bf16 v[8:11], v[140:143], v[188:191], v[8:11]
	s_barrier
	s_add_u32 s38, s82, 0x200000
	s_addc_u32 s39, s83, 0
	s_add_i32 s40, s23, s7
	s_mov_b32 m0, s40
	s_nop 0
	global_load_lds_dwordx4 v146, s[38:39]
	s_add_i32 m0, s40, 0x2000
	s_nop 0
	global_load_lds_dwordx4 v150, s[38:39]
	s_add_i32 s40, 0, 0x18000
	v_add_u32_e32 v140, s40, v173
	ds_read_b128 v[128:131], v140
	ds_read_b128 v[132:135], v140 offset:1024
	ds_read_b128 v[136:139], v140 offset:2048
	ds_read_b128 v[140:143], v140 offset:3072
	s_waitcnt vmcnt(6)
	s_barrier
; #define PG8_STAGE(bufoff, gbase, voff) do { _Pragma("unroll") for (int _i = 0; _i < 2; ++_i) \
;         __builtin_amdgcn_global_load_lds((const unsigned*)((const char*)(gbase) + (voff)[_i]), (LAS unsigned*)(lds + (bufoff) + ldsw + _i * 8192), 16, 0, 0); } while (0)
; #define PG8_LDA(dst, b, h) do { _Pragma("unroll") for (int m = 0; m < 4; ++m) _Pragma("unroll") for (int k = 0; k < 2; ++k) dst[m][k] = *(const LAS bf16x8*)(lds + PG8_SA(b, h) + aoff + m * 2048 + k * 1024); } while (0)
; #define PG8_LDB(dst, b, h) do { _Pragma("unroll") for (int n = 0; n < 2; ++n) _Pragma("unroll") for (int k = 0; k < 2; ++k) dst[n][k] = *(const LAS bf16x8*)(lds + PG8_SB(b, h) + boff + n * 2048 + k * 1024); } while (0)
; #define PG8_MMA(ai, bj, At, Bt) do { __builtin_amdgcn_s_setprio(1); _Pragma("unroll") for (int m = 0; m < 4; ++m) _Pragma("unroll") for (int n = 0; n < 2; ++n) _Pragma("unroll") for (int k = 0; k < 2; ++k) \
;         acc[ai][bj][m][n] = __builtin_amdgcn_mfma_f32_16x16x32_bf16(Bt[n][k], At[m][k], acc[ai][bj][m][n], 0, 0, 0); __builtin_amdgcn_s_setprio(0); } while (0)
; #define PG8_WAIT_V(n) asm volatile("s_waitcnt vmcnt(" #n ")" ::: "memory")
; #define PG8_WAIT_L(n) asm volatile("s_waitcnt lgkmcnt(" #n ")" ::: "memory")
; #define PG8_BAR __builtin_amdgcn_s_barrier()
; #define PG8_SCHED __builtin_amdgcn_sched_barrier(0)
; template <class Epi>
; __device__ __forceinline__ void gemm_phase(LAS unsigned char* lds, const Gemm g, const StaticOrder& S, const Epi& E, int wv) {
;     ...
;             PG8_WAIT_V(6); PG8_BAR; PG8_MMA(1, 1, At, B1); PG8_BAR;
;             PG8_LDB(B0, 1, 0); PG8_SCHED; PG8_LDA(At, 1, 0); PG8_STAGE(PG8_SA(0, 1), a2 + hstepA, voffA);
;             PG8_WAIT_L(8); PG8_BAR; PG8_WAIT_L(0); PG8_MMA(0, 0, At, B0); PG8_BAR; PG8_SCHED;
;             PG8_LDB(B1, 1, 1); PG8_STAGE(PG8_SB(1, 0), b3, voffB);
;             PG8_BAR; PG8_WAIT_L(0); PG8_MMA(0, 1, At, B1); PG8_BAR;
;             PG8_LDA(At, 1, 1); PG8_STAGE(PG8_SA(1, 0), a3, voffA);
;             PG8_BAR; PG8_WAIT_L(0); PG8_MMA(1, 0, At, B0); PG8_BAR; PG8_SCHED;
	v_mfma_f32_16x16x32_bf16 v[52:55], v[192:195], v[156:159], v[52:55]
	v_mfma_f32_16x16x32_bf16 v[48:51], v[200:203], v[156:159], v[48:51]
	v_mfma_f32_16x16x32_bf16 v[36:39], v[192:195], v[164:167], v[36:39]
	v_mfma_f32_16x16x32_bf16 v[32:35], v[200:203], v[164:167], v[32:35]
	v_mfma_f32_16x16x32_bf16 v[20:23], v[192:195], v[176:179], v[20:23]
	v_mfma_f32_16x16x32_bf16 v[16:19], v[200:203], v[176:179], v[16:19]
	v_mfma_f32_16x16x32_bf16 v[4:7], v[192:195], v[184:187], v[4:7]
	v_mfma_f32_16x16x32_bf16 v[0:3], v[200:203], v[184:187], v[0:3]
	v_mfma_f32_16x16x32_bf16 v[52:55], v[196:199], v[160:163], v[52:55]
	v_mfma_f32_16x16x32_bf16 v[48:51], v[204:207], v[160:163], v[48:51]
	v_mfma_f32_16x16x32_bf16 v[36:39], v[196:199], v[168:171], v[36:39]
	v_mfma_f32_16x16x32_bf16 v[32:35], v[204:207], v[168:171], v[32:35]
	v_mfma_f32_16x16x32_bf16 v[20:23], v[196:199], v[180:183], v[20:23]
	v_mfma_f32_16x16x32_bf16 v[16:19], v[204:207], v[180:183], v[16:19]
	v_mfma_f32_16x16x32_bf16 v[4:7], v[196:199], v[188:191], v[4:7]
	v_mfma_f32_16x16x32_bf16 v[0:3], v[204:207], v[188:191], v[0:3]
	s_waitcnt lgkmcnt(0)
	s_barrier
	s_add_u32 s38, s84, 0x200000
	s_addc_u32 s39, s85, 0
	s_mov_b32 m0, s10
	ds_read_b128 v[156:159], v175 offset:32768
	ds_read_b128 v[160:163], v175 offset:33792
	ds_read_b128 v[164:167], v175 offset:34816
	ds_read_b128 v[168:171], v175 offset:35840
	ds_read_b128 v[176:179], v175 offset:36864
	ds_read_b128 v[180:183], v175 offset:37888
	ds_read_b128 v[184:187], v175 offset:38912
	ds_read_b128 v[188:191], v175 offset:39936
	global_load_lds_dwordx4 v144, s[38:39]
	s_mov_b32 m0, s11
	s_nop 0
	global_load_lds_dwordx4 v148, s[38:39]
	s_waitcnt lgkmcnt(8)
	s_barrier
	s_waitcnt lgkmcnt(0)
	v_mfma_f32_16x16x32_bf16 v[124:127], v[128:131], v[156:159], v[124:127]
	v_mfma_f32_16x16x32_bf16 v[120:123], v[136:139], v[156:159], v[120:123]
	v_mfma_f32_16x16x32_bf16 v[108:111], v[128:131], v[164:167], v[108:111]
	v_mfma_f32_16x16x32_bf16 v[104:107], v[136:139], v[164:167], v[104:107]
	v_mfma_f32_16x16x32_bf16 v[92:95], v[128:131], v[176:179], v[92:95]
	v_mfma_f32_16x16x32_bf16 v[88:91], v[136:139], v[176:179], v[88:91]
	v_mfma_f32_16x16x32_bf16 v[76:79], v[128:131], v[184:187], v[76:79]
	v_mfma_f32_16x16x32_bf16 v[72:75], v[136:139], v[184:187], v[72:75]
	v_mfma_f32_16x16x32_bf16 v[124:127], v[132:135], v[160:163], v[124:127]
	v_mfma_f32_16x16x32_bf16 v[120:123], v[140:143], v[160:163], v[120:123]
	v_mfma_f32_16x16x32_bf16 v[108:111], v[132:135], v[168:171], v[108:111]
	v_mfma_f32_16x16x32_bf16 v[104:107], v[140:143], v[168:171], v[104:107]
	v_mfma_f32_16x16x32_bf16 v[92:95], v[132:135], v[180:183], v[92:95]
	v_mfma_f32_16x16x32_bf16 v[88:91], v[140:143], v[180:183], v[88:91]
	v_mfma_f32_16x16x32_bf16 v[76:79], v[132:135], v[188:191], v[76:79]
	v_mfma_f32_16x16x32_bf16 v[72:75], v[140:143], v[188:191], v[72:75]
	s_barrier
	s_add_i32 s41, 0, 0x1c000
	s_add_i32 s38, s40, s7
	v_add_u32_e32 v204, s41, v173
	s_mov_b32 m0, s38
	ds_read_b128 v[192:195], v204
	ds_read_b128 v[196:199], v204 offset:1024
	ds_read_b128 v[200:203], v204 offset:2048
	ds_read_b128 v[204:207], v204 offset:3072
	global_load_lds_dwordx4 v146, s[98:99]
	s_add_i32 m0, s38, 0x2000
	s_nop 0
	global_load_lds_dwordx4 v150, s[98:99]
	s_barrier
	s_waitcnt lgkmcnt(0)
	v_mfma_f32_16x16x32_bf16 v[116:119], v[192:195], v[156:159], v[116:119]
	v_mfma_f32_16x16x32_bf16 v[112:115], v[200:203], v[156:159], v[112:115]
	v_mfma_f32_16x16x32_bf16 v[100:103], v[192:195], v[164:167], v[100:103]
	v_mfma_f32_16x16x32_bf16 v[96:99], v[200:203], v[164:167], v[96:99]
	v_mfma_f32_16x16x32_bf16 v[84:87], v[192:195], v[176:179], v[84:87]
	v_mfma_f32_16x16x32_bf16 v[80:83], v[200:203], v[176:179], v[80:83]
	v_mfma_f32_16x16x32_bf16 v[68:71], v[192:195], v[184:187], v[68:71]
	v_mfma_f32_16x16x32_bf16 v[64:67], v[200:203], v[184:187], v[64:67]
	v_mfma_f32_16x16x32_bf16 v[116:119], v[196:199], v[160:163], v[116:119]
	v_mfma_f32_16x16x32_bf16 v[112:115], v[204:207], v[160:163], v[112:115]
	v_mfma_f32_16x16x32_bf16 v[100:103], v[196:199], v[168:171], v[100:103]
	v_mfma_f32_16x16x32_bf16 v[96:99], v[204:207], v[168:171], v[96:99]
	v_mfma_f32_16x16x32_bf16 v[84:87], v[196:199], v[180:183], v[84:87]
	v_mfma_f32_16x16x32_bf16 v[80:83], v[204:207], v[180:183], v[80:83]
	v_mfma_f32_16x16x32_bf16 v[68:71], v[196:199], v[188:191], v[68:71]
	v_mfma_f32_16x16x32_bf16 v[64:67], v[204:207], v[188:191], v[64:67]
	s_mov_b32 m0, s12
	s_barrier
; #define PG8_STAGE(bufoff, gbase, voff) do { _Pragma("unroll") for (int _i = 0; _i < 2; ++_i) \
;         __builtin_amdgcn_global_load_lds((const unsigned*)((const char*)(gbase) + (voff)[_i]), (LAS unsigned*)(lds + (bufoff) + ldsw + _i * 8192), 16, 0, 0); } while (0)
; #define PG8_LDA(dst, b, h) do { _Pragma("unroll") for (int m = 0; m < 4; ++m) _Pragma("unroll") for (int k = 0; k < 2; ++k) dst[m][k] = *(const LAS bf16x8*)(lds + PG8_SA(b, h) + aoff + m * 2048 + k * 1024); } while (0)
; #define PG8_LDB(dst, b, h) do { _Pragma("unroll") for (int n = 0; n < 2; ++n) _Pragma("unroll") for (int k = 0; k < 2; ++k) dst[n][k] = *(const LAS bf16x8*)(lds + PG8_SB(b, h) + boff + n * 2048 + k * 1024); } while (0)
; #define PG8_MMA(ai, bj, At, Bt) do { __builtin_amdgcn_s_setprio(1); _Pragma("unroll") for (int m = 0; m < 4; ++m) _Pragma("unroll") for (int n = 0; n < 2; ++n) _Pragma("unroll") for (int k = 0; k < 2; ++k) \
;         acc[ai][bj][m][n] = __builtin_amdgcn_mfma_f32_16x16x32_bf16(Bt[n][k], At[m][k], acc[ai][bj][m][n], 0, 0, 0); __builtin_amdgcn_s_setprio(0); } while (0)
; #define PG8_WAIT_V(n) asm volatile("s_waitcnt vmcnt(" #n ")" ::: "memory")
; #define PG8_WAIT_L(n) asm volatile("s_waitcnt lgkmcnt(" #n ")" ::: "memory")
; #define PG8_BAR __builtin_amdgcn_s_barrier()
; #define PG8_SCHED __builtin_amdgcn_sched_barrier(0)
; template <class Epi>
; __device__ __forceinline__ void gemm_phase(LAS unsigned char* lds, const Gemm g, const StaticOrder& S, const Epi& E, int wv) {
;     ...
;         for (int t = 0; t < nt; t += 2) {
;     ...
;             PG8_LDB(B0, 1, 0); PG8_SCHED; PG8_LDA(At, 1, 0); PG8_STAGE(PG8_SA(0, 1), a2 + hstepA, voffA);
;             PG8_WAIT_L(8); PG8_BAR; PG8_WAIT_L(0); PG8_MMA(0, 0, At, B0); PG8_BAR; PG8_SCHED;
;             PG8_LDB(B1, 1, 1); PG8_STAGE(PG8_SB(1, 0), b3, voffB);
;             PG8_BAR; PG8_WAIT_L(0); PG8_MMA(0, 1, At, B1); PG8_BAR;
;             PG8_LDA(At, 1, 1); PG8_STAGE(PG8_SA(1, 0), a3, voffA);
;             PG8_BAR; PG8_WAIT_L(0); PG8_MMA(1, 0, At, B0); PG8_BAR; PG8_SCHED;
;             PG8_STAGE(PG8_SB(1, 1), b3 + hstepB, voffB);
;             PG8_WAIT_V(6); PG8_BAR; PG8_MMA(1, 1, At, B1); PG8_BAR;
	ds_read_b128 v[156:159], v175 offset:49152
	ds_read_b128 v[160:163], v175 offset:50176
	ds_read_b128 v[164:167], v175 offset:51200
	ds_read_b128 v[168:171], v175 offset:52224
	ds_read_b128 v[176:179], v175 offset:53248
	ds_read_b128 v[180:183], v175 offset:54272
	ds_read_b128 v[184:187], v175 offset:55296
	ds_read_b128 v[188:191], v175 offset:56320
	global_load_lds_dwordx4 v144, s[100:101]
	s_mov_b32 m0, s13
	s_nop 0
	global_load_lds_dwordx4 v148, s[100:101]
	s_waitcnt vmcnt(10)
	s_barrier
	s_waitcnt lgkmcnt(0)
	v_mfma_f32_16x16x32_bf16 v[60:63], v[128:131], v[156:159], v[60:63]
	v_mfma_f32_16x16x32_bf16 v[56:59], v[136:139], v[156:159], v[56:59]
	v_mfma_f32_16x16x32_bf16 v[44:47], v[128:131], v[164:167], v[44:47]
	v_mfma_f32_16x16x32_bf16 v[40:43], v[136:139], v[164:167], v[40:43]
	v_mfma_f32_16x16x32_bf16 v[28:31], v[128:131], v[176:179], v[28:31]
	v_mfma_f32_16x16x32_bf16 v[24:27], v[136:139], v[176:179], v[24:27]
	v_mfma_f32_16x16x32_bf16 v[12:15], v[128:131], v[184:187], v[12:15]
	v_mfma_f32_16x16x32_bf16 v[8:11], v[136:139], v[184:187], v[8:11]
	v_mfma_f32_16x16x32_bf16 v[60:63], v[132:135], v[160:163], v[60:63]
	v_mfma_f32_16x16x32_bf16 v[56:59], v[140:143], v[160:163], v[56:59]
	v_mfma_f32_16x16x32_bf16 v[44:47], v[132:135], v[168:171], v[44:47]
	v_mfma_f32_16x16x32_bf16 v[40:43], v[140:143], v[168:171], v[40:43]
	v_mfma_f32_16x16x32_bf16 v[28:31], v[132:135], v[180:183], v[28:31]
	v_mfma_f32_16x16x32_bf16 v[24:27], v[140:143], v[180:183], v[24:27]
	v_mfma_f32_16x16x32_bf16 v[12:15], v[132:135], v[188:191], v[12:15]
	v_mfma_f32_16x16x32_bf16 v[8:11], v[140:143], v[188:191], v[8:11]
	s_barrier
	s_add_u32 s38, s82, 0x1fff80
	s_addc_u32 s39, s83, 0
	s_add_i32 s40, s41, s7
	s_mov_b32 m0, s40
	s_nop 0
	global_load_lds_dwordx4 v146, s[38:39]
	s_add_i32 m0, s40, 0x2000
	s_nop 0
	global_load_lds_dwordx4 v150, s[38:39]
	v_add_u32_e32 v140, s22, v173
	ds_read_b128 v[128:131], v140
	ds_read_b128 v[132:135], v140 offset:1024
	ds_read_b128 v[136:139], v140 offset:2048
	ds_read_b128 v[140:143], v140 offset:3072
	s_waitcnt vmcnt(6)
	s_barrier
	v_mfma_f32_16x16x32_bf16 v[52:55], v[192:195], v[156:159], v[52:55]
	v_mfma_f32_16x16x32_bf16 v[48:51], v[200:203], v[156:159], v[48:51]
	v_mfma_f32_16x16x32_bf16 v[36:39], v[192:195], v[164:167], v[36:39]
	v_mfma_f32_16x16x32_bf16 v[32:35], v[200:203], v[164:167], v[32:35]
	v_mfma_f32_16x16x32_bf16 v[20:23], v[192:195], v[176:179], v[20:23]
	v_mfma_f32_16x16x32_bf16 v[16:19], v[200:203], v[176:179], v[16:19]
	v_mfma_f32_16x16x32_bf16 v[4:7], v[192:195], v[184:187], v[4:7]
	v_mfma_f32_16x16x32_bf16 v[0:3], v[200:203], v[184:187], v[0:3]
	v_mfma_f32_16x16x32_bf16 v[52:55], v[196:199], v[160:163], v[52:55]
	v_mfma_f32_16x16x32_bf16 v[48:51], v[204:207], v[160:163], v[48:51]
	v_mfma_f32_16x16x32_bf16 v[36:39], v[196:199], v[168:171], v[36:39]
	v_mfma_f32_16x16x32_bf16 v[32:35], v[204:207], v[168:171], v[32:35]
	v_mfma_f32_16x16x32_bf16 v[20:23], v[196:199], v[180:183], v[20:23]
	v_mfma_f32_16x16x32_bf16 v[16:19], v[204:207], v[180:183], v[16:19]
	v_mfma_f32_16x16x32_bf16 v[4:7], v[196:199], v[188:191], v[4:7]
	v_mfma_f32_16x16x32_bf16 v[0:3], v[204:207], v[188:191], v[0:3]
	s_waitcnt lgkmcnt(0)
	s_cmpk_gt_u32 s35, 0x7d
	s_mov_b32 s35, s80
	s_barrier
	s_cbranch_scc1 .LBB0_610

; #define PG8_STAGE(bufoff, gbase, voff) do { _Pragma("unroll") for (int _i = 0; _i < 2; ++_i) \
;         __builtin_amdgcn_global_load_lds((const unsigned*)((const char*)(gbase) + (voff)[_i]), (LAS unsigned*)(lds + (bufoff) + ldsw + _i * 8192), 16, 0, 0); } while (0)
; #define PG8_LDA(dst, b, h) do { _Pragma("unroll") for (int m = 0; m < 4; ++m) _Pragma("unroll") for (int k = 0; k < 2; ++k) dst[m][k] = *(const LAS bf16x8*)(lds + PG8_SA(b, h) + aoff + m * 2048 + k * 1024); } while (0)
; #define PG8_LDB(dst, b, h) do { _Pragma("unroll") for (int n = 0; n < 2; ++n) _Pragma("unroll") for (int k = 0; k < 2; ++k) dst[n][k] = *(const LAS bf16x8*)(lds + PG8_SB(b, h) + boff + n * 2048 + k * 1024); } while (0)
; #define PG8_MMA(ai, bj, At, Bt) do { __builtin_amdgcn_s_setprio(1); _Pragma("unroll") for (int m = 0; m < 4; ++m) _Pragma("unroll") for (int n = 0; n < 2; ++n) _Pragma("unroll") for (int k = 0; k < 2; ++k) \
;         acc[ai][bj][m][n] = __builtin_amdgcn_mfma_f32_16x16x32_bf16(Bt[n][k], At[m][k], acc[ai][bj][m][n], 0, 0, 0); __builtin_amdgcn_s_setprio(0); } while (0)
; template <class Epi>
; __device__ __forceinline__ void gemm_phase(LAS unsigned char* lds, const Gemm g, const StaticOrder& S, const Epi& E, int wv) {
;     ...
;         const bool has_next = S.next(ui + 1, nxt);
;         const char* nA = has_next ? (const char*)g.A + (size_t)nxt.pm * tstepA + ((g.adiag & 1) ? (size_t)(nxt.pn >> 1) * K * 2 : 0) + kbeg : cA;
;         const char* nB = has_next ? (const char*)g.Bt + (size_t)nxt.pn * tstepB + kbeg : cB;
;         for (int t = 0; t < nt; t += 2) {
;             const bool last = (t == nt - 2);
;             const char* a1 = cA + (ptrdiff_t)(t + 1) * kstep;
;             const char* a2 = last ? nA : cA + (ptrdiff_t)(t + 2) * kstep; const char* b2 = last ? nB : cB + (ptrdiff_t)(t + 2) * kstep;
;             const char* a3 = a2 + kstep; const char* b3 = b2 + kstep;
;             PG8_LDB(B0, 0, 0); PG8_SCHED; PG8_LDA(At, 0, 0); PG8_STAGE(PG8_SA(1, 1), a1 + hstepA, voffA);
;             PG8_WAIT_L(8); PG8_BAR; PG8_WAIT_L(0); PG8_MMA(0, 0, At, B0); PG8_BAR; PG8_SCHED;
;             PG8_LDB(B1, 0, 1); PG8_STAGE(PG8_SB(0, 0), b2, voffB);
;             PG8_BAR; PG8_WAIT_L(0); PG8_MMA(0, 1, At, B1); PG8_BAR;
;             PG8_LDA(At, 0, 1); PG8_STAGE(PG8_SA(0, 0), a2, voffA);
;             PG8_BAR; PG8_WAIT_L(0); PG8_MMA(1, 0, At, B0); PG8_BAR; PG8_SCHED;
.LBB0_638:
	s_ashr_i32 s63, s62, 31
	s_lshl_b64 s[38:39], s[62:63], 17
	s_add_u32 s64, s5, s38
	v_cmp_lt_i64_e32 vcc, s[56:57], v[8:9]
	s_addc_u32 s65, s6, s39
	ds_read_b128 v[18:21], v15
	ds_read_b128 v[22:25], v15 offset:1024
	ds_read_b128 v[26:29], v15 offset:2048
	ds_read_b128 v[30:33], v15 offset:3072
	s_and_b64 s[38:39], vcc, exec
	s_cselect_b32 s75, s65, s69
	s_cselect_b32 s74, s64, s68
	s_ashr_i32 s61, s60, 31
	s_lshl_b64 s[38:39], s[60:61], 17
	s_add_u32 s66, s7, s38
	s_addc_u32 s67, s8, s39
	s_and_b64 s[38:39], vcc, exec
	s_cselect_b32 s73, s67, s71
	s_cselect_b32 s72, s66, s70
	s_add_u32 s38, s68, 0x10080
	s_addc_u32 s39, s69, 0
	s_mov_b32 m0, s23
	v_lshl_add_u64 v[66:67], s[38:39], 0, v[0:1]
	ds_read_b128 v[34:37], v16
	ds_read_b128 v[38:41], v16 offset:1024
	ds_read_b128 v[42:45], v16 offset:2048
	ds_read_b128 v[46:49], v16 offset:3072
	ds_read_b128 v[50:53], v16 offset:4096
	ds_read_b128 v[54:57], v16 offset:5120
	ds_read_b128 v[58:61], v16 offset:6144
	ds_read_b128 v[62:65], v16 offset:7168
	global_load_lds_dwordx4 v[66:67], off
	v_lshl_add_u64 v[66:67], s[38:39], 0, v[4:5]
	s_mov_b32 m0, s24
	s_nop 0
	global_load_lds_dwordx4 v[66:67], off
	s_waitcnt lgkmcnt(8)
	s_barrier
	s_waitcnt lgkmcnt(0)
	v_mfma_f32_16x16x32_bf16 v[66:69], v[18:21], v[34:37], 0
	v_mfma_f32_16x16x32_bf16 v[70:73], v[26:29], v[34:37], 0
	v_mfma_f32_16x16x32_bf16 v[74:77], v[18:21], v[42:45], 0
	v_mfma_f32_16x16x32_bf16 v[78:81], v[26:29], v[42:45], 0
	v_mfma_f32_16x16x32_bf16 v[82:85], v[18:21], v[50:53], 0
	v_mfma_f32_16x16x32_bf16 v[86:89], v[26:29], v[50:53], 0
	v_mfma_f32_16x16x32_bf16 v[90:93], v[18:21], v[58:61], 0
	v_mfma_f32_16x16x32_bf16 v[94:97], v[26:29], v[58:61], 0
	v_mfma_f32_16x16x32_bf16 v[66:69], v[22:25], v[38:41], v[66:69]
	v_mfma_f32_16x16x32_bf16 v[70:73], v[30:33], v[38:41], v[70:73]
	v_mfma_f32_16x16x32_bf16 v[74:77], v[22:25], v[46:49], v[74:77]
	v_mfma_f32_16x16x32_bf16 v[78:81], v[30:33], v[46:49], v[78:81]
	v_mfma_f32_16x16x32_bf16 v[82:85], v[22:25], v[54:57], v[82:85]
	v_mfma_f32_16x16x32_bf16 v[86:89], v[30:33], v[54:57], v[86:89]
	v_mfma_f32_16x16x32_bf16 v[90:93], v[22:25], v[62:65], v[90:93]
	v_mfma_f32_16x16x32_bf16 v[94:97], v[30:33], v[62:65], v[94:97]
	s_barrier
	v_lshl_add_u64 v[210:211], s[70:71], 0, v[2:3]
	s_add_i32 s39, s22, s9
	v_lshl_add_u64 v[114:115], v[210:211], 0, s[52:53]
	s_mov_b32 m0, s39
	v_lshl_add_u64 v[212:213], s[70:71], 0, v[6:7]
	s_add_i32 s35, s39, 0x2000
	ds_read_b128 v[98:101], v17
	ds_read_b128 v[102:105], v17 offset:1024
	ds_read_b128 v[106:109], v17 offset:2048
	ds_read_b128 v[110:113], v17 offset:3072
	global_load_lds_dwordx4 v[114:115], off
	v_lshl_add_u64 v[114:115], v[212:213], 0, s[52:53]
	s_mov_b32 m0, s35
	s_nop 0
	global_load_lds_dwordx4 v[114:115], off
	s_barrier
	s_waitcnt lgkmcnt(0)
	v_mfma_f32_16x16x32_bf16 v[114:117], v[98:101], v[34:37], 0
	v_mfma_f32_16x16x32_bf16 v[34:37], v[106:109], v[34:37], 0
	v_mfma_f32_16x16x32_bf16 v[114:117], v[102:105], v[38:41], v[114:117]
	v_mfma_f32_16x16x32_bf16 v[34:37], v[110:113], v[38:41], v[34:37]
	v_mfma_f32_16x16x32_bf16 v[38:41], v[98:101], v[42:45], 0
	v_mfma_f32_16x16x32_bf16 v[42:45], v[106:109], v[42:45], 0
	v_mfma_f32_16x16x32_bf16 v[38:41], v[102:105], v[46:49], v[38:41]
	v_mfma_f32_16x16x32_bf16 v[42:45], v[110:113], v[46:49], v[42:45]
	v_mfma_f32_16x16x32_bf16 v[46:49], v[98:101], v[50:53], 0
	v_mfma_f32_16x16x32_bf16 v[50:53], v[106:109], v[50:53], 0
	v_mfma_f32_16x16x32_bf16 v[46:49], v[102:105], v[54:57], v[46:49]
	v_mfma_f32_16x16x32_bf16 v[50:53], v[110:113], v[54:57], v[50:53]
	v_mfma_f32_16x16x32_bf16 v[54:57], v[98:101], v[58:61], 0
	v_mfma_f32_16x16x32_bf16 v[58:61], v[106:109], v[58:61], 0
	v_mfma_f32_16x16x32_bf16 v[54:57], v[102:105], v[62:65], v[54:57]
	v_mfma_f32_16x16x32_bf16 v[58:61], v[110:113], v[62:65], v[58:61]
	v_lshl_add_u64 v[214:215], s[68:69], 0, v[0:1]
	s_mov_b32 m0, s10
	v_lshl_add_u64 v[146:147], v[214:215], 0, s[52:53]
	v_lshl_add_u64 v[216:217], s[68:69], 0, v[4:5]
	s_barrier
	ds_read_b128 v[62:65], v16 offset:16384
	ds_read_b128 v[118:121], v16 offset:17408
	ds_read_b128 v[122:125], v16 offset:18432
	ds_read_b128 v[126:129], v16 offset:19456
	ds_read_b128 v[130:133], v16 offset:20480
	ds_read_b128 v[134:137], v16 offset:21504
	ds_read_b128 v[138:141], v16 offset:22528
	ds_read_b128 v[142:145], v16 offset:23552
	global_load_lds_dwordx4 v[146:147], off
	v_lshl_add_u64 v[146:147], v[216:217], 0, s[52:53]
	s_mov_b32 m0, s11
	s_nop 0
	global_load_lds_dwordx4 v[146:147], off
	s_barrier
	s_waitcnt lgkmcnt(0)
	v_mfma_f32_16x16x32_bf16 v[146:149], v[18:21], v[62:65], 0
	v_mfma_f32_16x16x32_bf16 v[154:157], v[18:21], v[122:125], 0
	v_mfma_f32_16x16x32_bf16 v[162:165], v[18:21], v[130:133], 0
	v_mfma_f32_16x16x32_bf16 v[18:21], v[18:21], v[138:141], 0
	v_mfma_f32_16x16x32_bf16 v[146:149], v[22:25], v[118:121], v[146:149]
	v_mfma_f32_16x16x32_bf16 v[150:153], v[26:29], v[62:65], 0
	v_mfma_f32_16x16x32_bf16 v[154:157], v[22:25], v[126:129], v[154:157]
	v_mfma_f32_16x16x32_bf16 v[158:161], v[26:29], v[122:125], 0
	v_mfma_f32_16x16x32_bf16 v[162:165], v[22:25], v[134:137], v[162:165]
	v_mfma_f32_16x16x32_bf16 v[166:169], v[26:29], v[130:133], 0
	v_mfma_f32_16x16x32_bf16 v[18:21], v[22:25], v[142:145], v[18:21]
	v_mfma_f32_16x16x32_bf16 v[22:25], v[26:29], v[138:141], 0
	v_mfma_f32_16x16x32_bf16 v[150:153], v[30:33], v[118:121], v[150:153]
	v_mfma_f32_16x16x32_bf16 v[158:161], v[30:33], v[126:129], v[158:161]
	v_mfma_f32_16x16x32_bf16 v[166:169], v[30:33], v[134:137], v[166:169]
	v_mfma_f32_16x16x32_bf16 v[22:25], v[30:33], v[142:145], v[22:25]
	s_barrier
; #define PG8_STAGE(bufoff, gbase, voff) do { _Pragma("unroll") for (int _i = 0; _i < 2; ++_i) \
;         __builtin_amdgcn_global_load_lds((const unsigned*)((const char*)(gbase) + (voff)[_i]), (LAS unsigned*)(lds + (bufoff) + ldsw + _i * 8192), 16, 0, 0); } while (0)
; #define PG8_LDA(dst, b, h) do { _Pragma("unroll") for (int m = 0; m < 4; ++m) _Pragma("unroll") for (int k = 0; k < 2; ++k) dst[m][k] = *(const LAS bf16x8*)(lds + PG8_SA(b, h) + aoff + m * 2048 + k * 1024); } while (0)
; #define PG8_LDB(dst, b, h) do { _Pragma("unroll") for (int n = 0; n < 2; ++n) _Pragma("unroll") for (int k = 0; k < 2; ++k) dst[n][k] = *(const LAS bf16x8*)(lds + PG8_SB(b, h) + boff + n * 2048 + k * 1024); } while (0)
; #define PG8_MMA(ai, bj, At, Bt) do { __builtin_amdgcn_s_setprio(1); _Pragma("unroll") for (int m = 0; m < 4; ++m) _Pragma("unroll") for (int n = 0; n < 2; ++n) _Pragma("unroll") for (int k = 0; k < 2; ++k) \
;         acc[ai][bj][m][n] = __builtin_amdgcn_mfma_f32_16x16x32_bf16(Bt[n][k], At[m][k], acc[ai][bj][m][n], 0, 0, 0); __builtin_amdgcn_s_setprio(0); } while (0)
; #define PG8_WAIT_V(n) asm volatile("s_waitcnt vmcnt(" #n ")" ::: "memory")
; #define PG8_WAIT_L(n) asm volatile("s_waitcnt lgkmcnt(" #n ")" ::: "memory")
; #define PG8_BAR __builtin_amdgcn_s_barrier()
; #define PG8_SCHED __builtin_amdgcn_sched_barrier(0)
; template <class Epi>
; __device__ __forceinline__ void gemm_phase(LAS unsigned char* lds, const Gemm g, const StaticOrder& S, const Epi& E, int wv) {
;     ...
;             PG8_STAGE(PG8_SB(0, 1), b2 + hstepB, voffB);
;             PG8_WAIT_V(6); PG8_BAR; PG8_MMA(1, 1, At, B1); PG8_BAR;
;             PG8_LDB(B0, 1, 0); PG8_SCHED; PG8_LDA(At, 1, 0); PG8_STAGE(PG8_SA(0, 1), a2 + hstepA, voffA);
;             PG8_WAIT_L(8); PG8_BAR; PG8_WAIT_L(0); PG8_MMA(0, 0, At, B0); PG8_BAR; PG8_SCHED;
;             PG8_LDB(B1, 1, 1); PG8_STAGE(PG8_SB(1, 0), b3, voffB);
;             PG8_BAR; PG8_WAIT_L(0); PG8_MMA(0, 1, At, B1); PG8_BAR;
;             PG8_LDA(At, 1, 1); PG8_STAGE(PG8_SA(1, 0), a3, voffA);
;             PG8_BAR; PG8_WAIT_L(0); PG8_MMA(1, 0, At, B0); PG8_BAR; PG8_SCHED;
	s_add_u32 s42, s70, 0x10100
	s_addc_u32 s43, s71, 0
	s_add_i32 s40, s25, s9
	v_lshl_add_u64 v[26:27], s[42:43], 0, v[2:3]
	s_mov_b32 m0, s40
	s_add_i32 s38, s40, 0x2000
	global_load_lds_dwordx4 v[26:27], off
	v_lshl_add_u64 v[26:27], s[42:43], 0, v[6:7]
	s_mov_b32 m0, s38
	s_nop 0
	global_load_lds_dwordx4 v[26:27], off
	s_waitcnt vmcnt(6)
	s_barrier
	v_mfma_f32_16x16x32_bf16 v[26:29], v[98:101], v[62:65], 0
	v_mfma_f32_16x16x32_bf16 v[30:33], v[106:109], v[62:65], 0
	v_mfma_f32_16x16x32_bf16 v[26:29], v[102:105], v[118:121], v[26:29]
	v_mfma_f32_16x16x32_bf16 v[30:33], v[110:113], v[118:121], v[30:33]
	v_mfma_f32_16x16x32_bf16 v[62:65], v[98:101], v[122:125], 0
	v_mfma_f32_16x16x32_bf16 v[118:121], v[106:109], v[122:125], 0
	v_mfma_f32_16x16x32_bf16 v[122:125], v[98:101], v[130:133], 0
	v_mfma_f32_16x16x32_bf16 v[98:101], v[98:101], v[138:141], 0
	v_mfma_f32_16x16x32_bf16 v[62:65], v[102:105], v[126:129], v[62:65]
	v_mfma_f32_16x16x32_bf16 v[118:121], v[110:113], v[126:129], v[118:121]
	v_mfma_f32_16x16x32_bf16 v[122:125], v[102:105], v[134:137], v[122:125]
	v_mfma_f32_16x16x32_bf16 v[126:129], v[106:109], v[130:133], 0
	v_mfma_f32_16x16x32_bf16 v[98:101], v[102:105], v[142:145], v[98:101]
	v_mfma_f32_16x16x32_bf16 v[102:105], v[106:109], v[138:141], 0
	v_mfma_f32_16x16x32_bf16 v[126:129], v[110:113], v[134:137], v[126:129]
	v_mfma_f32_16x16x32_bf16 v[102:105], v[110:113], v[142:145], v[102:105]
	s_add_i32 s41, 0, 0x18000
	v_add_u32_e32 v218, s41, v13
	s_barrier
	ds_read_b128 v[106:109], v218
	ds_read_b128 v[110:113], v218 offset:1024
	ds_read_b128 v[130:133], v218 offset:2048
	ds_read_b128 v[134:137], v218 offset:3072
	s_add_u32 s42, s68, 0x10100
	s_addc_u32 s43, s69, 0
	s_mov_b32 m0, s12
	v_lshl_add_u64 v[194:195], s[42:43], 0, v[0:1]
	ds_read_b128 v[138:141], v16 offset:32768
	ds_read_b128 v[142:145], v16 offset:33792
	ds_read_b128 v[170:173], v16 offset:34816
	ds_read_b128 v[174:177], v16 offset:35840
	ds_read_b128 v[178:181], v16 offset:36864
	ds_read_b128 v[182:185], v16 offset:37888
	ds_read_b128 v[186:189], v16 offset:38912
	ds_read_b128 v[190:193], v16 offset:39936
	global_load_lds_dwordx4 v[194:195], off
	v_lshl_add_u64 v[194:195], s[42:43], 0, v[4:5]
	s_mov_b32 m0, s13
	s_nop 0
	global_load_lds_dwordx4 v[194:195], off
	s_waitcnt lgkmcnt(8)
	s_barrier
	s_waitcnt lgkmcnt(0)
	v_mfma_f32_16x16x32_bf16 v[66:69], v[106:109], v[138:141], v[66:69]
	v_mfma_f32_16x16x32_bf16 v[70:73], v[130:133], v[138:141], v[70:73]
	v_mfma_f32_16x16x32_bf16 v[74:77], v[106:109], v[170:173], v[74:77]
	v_mfma_f32_16x16x32_bf16 v[78:81], v[130:133], v[170:173], v[78:81]
	v_mfma_f32_16x16x32_bf16 v[82:85], v[106:109], v[178:181], v[82:85]
	v_mfma_f32_16x16x32_bf16 v[86:89], v[130:133], v[178:181], v[86:89]
	v_mfma_f32_16x16x32_bf16 v[90:93], v[106:109], v[186:189], v[90:93]
	v_mfma_f32_16x16x32_bf16 v[94:97], v[130:133], v[186:189], v[94:97]
	v_mfma_f32_16x16x32_bf16 v[66:69], v[110:113], v[142:145], v[66:69]
	v_mfma_f32_16x16x32_bf16 v[70:73], v[134:137], v[142:145], v[70:73]
	v_mfma_f32_16x16x32_bf16 v[74:77], v[110:113], v[174:177], v[74:77]
	v_mfma_f32_16x16x32_bf16 v[78:81], v[134:137], v[174:177], v[78:81]
	v_mfma_f32_16x16x32_bf16 v[82:85], v[110:113], v[182:185], v[82:85]
	v_mfma_f32_16x16x32_bf16 v[86:89], v[134:137], v[182:185], v[86:89]
	v_mfma_f32_16x16x32_bf16 v[90:93], v[110:113], v[190:193], v[90:93]
	v_mfma_f32_16x16x32_bf16 v[94:97], v[134:137], v[190:193], v[94:97]
	s_barrier
	s_add_i32 s44, 0, 0x1c000
	s_add_i32 s43, s41, s9
	v_add_u32_e32 v219, s44, v13
	v_lshl_add_u64 v[210:211], v[210:211], 0, s[54:55]
	s_mov_b32 m0, s43
	s_add_i32 s41, s43, 0x2000
	ds_read_b128 v[194:197], v219
	ds_read_b128 v[198:201], v219 offset:1024
	ds_read_b128 v[202:205], v219 offset:2048
	ds_read_b128 v[206:209], v219 offset:3072
	global_load_lds_dwordx4 v[210:211], off
	v_lshl_add_u64 v[210:211], v[212:213], 0, s[54:55]
	s_mov_b32 m0, s41
	s_nop 0
	global_load_lds_dwordx4 v[210:211], off
	s_barrier
	s_waitcnt lgkmcnt(0)
	v_mfma_f32_16x16x32_bf16 v[114:117], v[194:197], v[138:141], v[114:117]
	v_mfma_f32_16x16x32_bf16 v[34:37], v[202:205], v[138:141], v[34:37]
	v_mfma_f32_16x16x32_bf16 v[38:41], v[194:197], v[170:173], v[38:41]
	v_mfma_f32_16x16x32_bf16 v[42:45], v[202:205], v[170:173], v[42:45]
	v_mfma_f32_16x16x32_bf16 v[46:49], v[194:197], v[178:181], v[46:49]
	v_mfma_f32_16x16x32_bf16 v[50:53], v[202:205], v[178:181], v[50:53]
	v_mfma_f32_16x16x32_bf16 v[54:57], v[194:197], v[186:189], v[54:57]
	v_mfma_f32_16x16x32_bf16 v[58:61], v[202:205], v[186:189], v[58:61]
	v_mfma_f32_16x16x32_bf16 v[114:117], v[198:201], v[142:145], v[114:117]
	v_mfma_f32_16x16x32_bf16 v[34:37], v[206:209], v[142:145], v[34:37]
	v_mfma_f32_16x16x32_bf16 v[38:41], v[198:201], v[174:177], v[38:41]
	v_mfma_f32_16x16x32_bf16 v[42:45], v[206:209], v[174:177], v[42:45]
	v_mfma_f32_16x16x32_bf16 v[46:49], v[198:201], v[182:185], v[46:49]
	v_mfma_f32_16x16x32_bf16 v[50:53], v[206:209], v[182:185], v[50:53]
	v_mfma_f32_16x16x32_bf16 v[54:57], v[198:201], v[190:193], v[54:57]
	v_mfma_f32_16x16x32_bf16 v[58:61], v[206:209], v[190:193], v[58:61]
	s_mov_b32 m0, s14
	v_lshl_add_u64 v[210:211], v[214:215], 0, s[54:55]
	s_barrier
	ds_read_b128 v[138:141], v16 offset:49152
	ds_read_b128 v[142:145], v16 offset:50176
	ds_read_b128 v[170:173], v16 offset:51200
	ds_read_b128 v[174:177], v16 offset:52224
	ds_read_b128 v[178:181], v16 offset:53248
	ds_read_b128 v[182:185], v16 offset:54272
	ds_read_b128 v[186:189], v16 offset:55296
	ds_read_b128 v[190:193], v16 offset:56320
	global_load_lds_dwordx4 v[210:211], off
	v_lshl_add_u64 v[210:211], v[216:217], 0, s[54:55]
	s_mov_b32 m0, s15
	s_nop 0
	global_load_lds_dwordx4 v[210:211], off
	s_barrier
; #define PG8_STAGE(bufoff, gbase, voff) do { _Pragma("unroll") for (int _i = 0; _i < 2; ++_i) \
;         __builtin_amdgcn_global_load_lds((const unsigned*)((const char*)(gbase) + (voff)[_i]), (LAS unsigned*)(lds + (bufoff) + ldsw + _i * 8192), 16, 0, 0); } while (0)
; #define PG8_LDA(dst, b, h) do { _Pragma("unroll") for (int m = 0; m < 4; ++m) _Pragma("unroll") for (int k = 0; k < 2; ++k) dst[m][k] = *(const LAS bf16x8*)(lds + PG8_SA(b, h) + aoff + m * 2048 + k * 1024); } while (0)
; #define PG8_LDB(dst, b, h) do { _Pragma("unroll") for (int n = 0; n < 2; ++n) _Pragma("unroll") for (int k = 0; k < 2; ++k) dst[n][k] = *(const LAS bf16x8*)(lds + PG8_SB(b, h) + boff + n * 2048 + k * 1024); } while (0)
; #define PG8_MMA(ai, bj, At, Bt) do { __builtin_amdgcn_s_setprio(1); _Pragma("unroll") for (int m = 0; m < 4; ++m) _Pragma("unroll") for (int n = 0; n < 2; ++n) _Pragma("unroll") for (int k = 0; k < 2; ++k) \
;         acc[ai][bj][m][n] = __builtin_amdgcn_mfma_f32_16x16x32_bf16(Bt[n][k], At[m][k], acc[ai][bj][m][n], 0, 0, 0); __builtin_amdgcn_s_setprio(0); } while (0)
; #define PG8_WAIT_V(n) asm volatile("s_waitcnt vmcnt(" #n ")" ::: "memory")
; #define PG8_WAIT_L(n) asm volatile("s_waitcnt lgkmcnt(" #n ")" ::: "memory")
; #define PG8_BAR __builtin_amdgcn_s_barrier()
; #define PG8_SCHED __builtin_amdgcn_sched_barrier(0)
; template <class Epi>
; __device__ __forceinline__ void gemm_phase(LAS unsigned char* lds, const Gemm g, const StaticOrder& S, const Epi& E, int wv) {
;     ...
;             PG8_LDB(B0, 0, 0); PG8_SCHED; PG8_LDA(At, 0, 0); PG8_STAGE(PG8_SA(1, 1), a1 + hstepA, voffA);
;             PG8_WAIT_L(8); PG8_BAR; PG8_WAIT_L(0); PG8_MMA(0, 0, At, B0); PG8_BAR; PG8_SCHED;
;             PG8_LDB(B1, 0, 1); PG8_STAGE(PG8_SB(0, 0), b2, voffB);
;             PG8_BAR; PG8_WAIT_L(0); PG8_MMA(0, 1, At, B1); PG8_BAR;
;     ...
;             PG8_BAR; PG8_WAIT_L(0); PG8_MMA(1, 0, At, B0); PG8_BAR; PG8_SCHED;
;             PG8_STAGE(PG8_SB(1, 1), b3 + hstepB, voffB);
;             PG8_WAIT_V(6); PG8_BAR; PG8_MMA(1, 1, At, B1); PG8_BAR;
	s_waitcnt lgkmcnt(0)
	v_mfma_f32_16x16x32_bf16 v[146:149], v[106:109], v[138:141], v[146:149]
	v_mfma_f32_16x16x32_bf16 v[150:153], v[130:133], v[138:141], v[150:153]
	v_mfma_f32_16x16x32_bf16 v[154:157], v[106:109], v[170:173], v[154:157]
	v_mfma_f32_16x16x32_bf16 v[158:161], v[130:133], v[170:173], v[158:161]
	v_mfma_f32_16x16x32_bf16 v[162:165], v[106:109], v[178:181], v[162:165]
	v_mfma_f32_16x16x32_bf16 v[166:169], v[130:133], v[178:181], v[166:169]
	v_mfma_f32_16x16x32_bf16 v[18:21], v[106:109], v[186:189], v[18:21]
	v_mfma_f32_16x16x32_bf16 v[22:25], v[130:133], v[186:189], v[22:25]
	v_mfma_f32_16x16x32_bf16 v[146:149], v[110:113], v[142:145], v[146:149]
	v_mfma_f32_16x16x32_bf16 v[150:153], v[134:137], v[142:145], v[150:153]
	v_mfma_f32_16x16x32_bf16 v[154:157], v[110:113], v[174:177], v[154:157]
	v_mfma_f32_16x16x32_bf16 v[158:161], v[134:137], v[174:177], v[158:161]
	v_mfma_f32_16x16x32_bf16 v[162:165], v[110:113], v[182:185], v[162:165]
	v_mfma_f32_16x16x32_bf16 v[166:169], v[134:137], v[182:185], v[166:169]
	v_mfma_f32_16x16x32_bf16 v[18:21], v[110:113], v[190:193], v[18:21]
	v_mfma_f32_16x16x32_bf16 v[22:25], v[134:137], v[190:193], v[22:25]
	s_barrier
	s_add_u32 s46, s70, 0x10180
	s_addc_u32 s47, s71, 0
	s_add_i32 s44, s44, s9
	v_lshl_add_u64 v[106:107], s[46:47], 0, v[2:3]
	s_mov_b32 m0, s44
	s_add_i32 s42, s44, 0x2000
	global_load_lds_dwordx4 v[106:107], off
	v_lshl_add_u64 v[106:107], s[46:47], 0, v[6:7]
	s_mov_b32 m0, s42
	s_nop 0
	global_load_lds_dwordx4 v[106:107], off
	s_waitcnt vmcnt(6)
	s_barrier
	v_mfma_f32_16x16x32_bf16 v[26:29], v[194:197], v[138:141], v[26:29]
	v_mfma_f32_16x16x32_bf16 v[30:33], v[202:205], v[138:141], v[30:33]
	v_mfma_f32_16x16x32_bf16 v[62:65], v[194:197], v[170:173], v[62:65]
	v_mfma_f32_16x16x32_bf16 v[106:109], v[202:205], v[170:173], v[118:121]
	v_mfma_f32_16x16x32_bf16 v[110:113], v[194:197], v[178:181], v[122:125]
	v_mfma_f32_16x16x32_bf16 v[118:121], v[202:205], v[178:181], v[126:129]
	v_mfma_f32_16x16x32_bf16 v[98:101], v[194:197], v[186:189], v[98:101]
	v_mfma_f32_16x16x32_bf16 v[102:105], v[202:205], v[186:189], v[102:105]
	v_mfma_f32_16x16x32_bf16 v[26:29], v[198:201], v[142:145], v[26:29]
	v_mfma_f32_16x16x32_bf16 v[30:33], v[206:209], v[142:145], v[30:33]
	v_mfma_f32_16x16x32_bf16 v[62:65], v[198:201], v[174:177], v[62:65]
	v_mfma_f32_16x16x32_bf16 v[106:109], v[206:209], v[174:177], v[106:109]
	v_mfma_f32_16x16x32_bf16 v[110:113], v[198:201], v[182:185], v[110:113]
	v_mfma_f32_16x16x32_bf16 v[118:121], v[206:209], v[182:185], v[118:121]
	v_mfma_f32_16x16x32_bf16 v[98:101], v[198:201], v[190:193], v[98:101]
	v_mfma_f32_16x16x32_bf16 v[102:105], v[206:209], v[190:193], v[102:105]
	s_barrier
	ds_read_b128 v[122:125], v15
	ds_read_b128 v[126:129], v15 offset:1024
	ds_read_b128 v[130:133], v15 offset:2048
	ds_read_b128 v[134:137], v15 offset:3072
	s_add_u32 s46, s68, 0x10180
	s_addc_u32 s47, s69, 0
	s_mov_b32 m0, s23
	v_lshl_add_u64 v[194:195], s[46:47], 0, v[0:1]
	ds_read_b128 v[138:141], v16
	ds_read_b128 v[142:145], v16 offset:1024
	ds_read_b128 v[170:173], v16 offset:2048
	ds_read_b128 v[174:177], v16 offset:3072
	ds_read_b128 v[178:181], v16 offset:4096
	ds_read_b128 v[182:185], v16 offset:5120
	ds_read_b128 v[186:189], v16 offset:6144
	ds_read_b128 v[190:193], v16 offset:7168
	global_load_lds_dwordx4 v[194:195], off
	v_lshl_add_u64 v[194:195], s[46:47], 0, v[4:5]
	s_mov_b32 m0, s24
	s_nop 0
	global_load_lds_dwordx4 v[194:195], off
	s_waitcnt lgkmcnt(8)
	s_barrier
	s_waitcnt lgkmcnt(0)
	v_mfma_f32_16x16x32_bf16 v[66:69], v[122:125], v[138:141], v[66:69]
	v_mfma_f32_16x16x32_bf16 v[70:73], v[130:133], v[138:141], v[70:73]
	v_mfma_f32_16x16x32_bf16 v[74:77], v[122:125], v[170:173], v[74:77]
	v_mfma_f32_16x16x32_bf16 v[78:81], v[130:133], v[170:173], v[78:81]
	v_mfma_f32_16x16x32_bf16 v[82:85], v[122:125], v[178:181], v[82:85]
	v_mfma_f32_16x16x32_bf16 v[86:89], v[130:133], v[178:181], v[86:89]
	v_mfma_f32_16x16x32_bf16 v[90:93], v[122:125], v[186:189], v[90:93]
	v_mfma_f32_16x16x32_bf16 v[94:97], v[130:133], v[186:189], v[94:97]
	v_mfma_f32_16x16x32_bf16 v[66:69], v[126:129], v[142:145], v[66:69]
	v_mfma_f32_16x16x32_bf16 v[70:73], v[134:137], v[142:145], v[70:73]
	v_mfma_f32_16x16x32_bf16 v[74:77], v[126:129], v[174:177], v[74:77]
	v_mfma_f32_16x16x32_bf16 v[78:81], v[134:137], v[174:177], v[78:81]
	v_mfma_f32_16x16x32_bf16 v[82:85], v[126:129], v[182:185], v[82:85]
	v_mfma_f32_16x16x32_bf16 v[86:89], v[134:137], v[182:185], v[86:89]
	v_mfma_f32_16x16x32_bf16 v[90:93], v[126:129], v[190:193], v[90:93]
	v_mfma_f32_16x16x32_bf16 v[94:97], v[134:137], v[190:193], v[94:97]
	s_barrier
	s_mov_b32 m0, s39
	v_lshl_add_u64 v[210:211], s[72:73], 0, v[2:3]
	ds_read_b128 v[194:197], v17
	ds_read_b128 v[198:201], v17 offset:1024
	ds_read_b128 v[202:205], v17 offset:2048
	ds_read_b128 v[206:209], v17 offset:3072
	global_load_lds_dwordx4 v[210:211], off
	v_lshl_add_u64 v[212:213], s[72:73], 0, v[6:7]
	s_mov_b32 m0, s35
	s_nop 0
	global_load_lds_dwordx4 v[212:213], off
	s_barrier
	s_waitcnt lgkmcnt(0)
	v_mfma_f32_16x16x32_bf16 v[114:117], v[194:197], v[138:141], v[114:117]
	v_mfma_f32_16x16x32_bf16 v[34:37], v[202:205], v[138:141], v[34:37]
	v_mfma_f32_16x16x32_bf16 v[38:41], v[194:197], v[170:173], v[38:41]
	v_mfma_f32_16x16x32_bf16 v[42:45], v[202:205], v[170:173], v[42:45]
	v_mfma_f32_16x16x32_bf16 v[46:49], v[194:197], v[178:181], v[46:49]
	v_mfma_f32_16x16x32_bf16 v[50:53], v[202:205], v[178:181], v[50:53]
	v_mfma_f32_16x16x32_bf16 v[54:57], v[194:197], v[186:189], v[54:57]
	v_mfma_f32_16x16x32_bf16 v[58:61], v[202:205], v[186:189], v[58:61]
	v_mfma_f32_16x16x32_bf16 v[114:117], v[198:201], v[142:145], v[114:117]
	v_mfma_f32_16x16x32_bf16 v[34:37], v[206:209], v[142:145], v[34:37]
	v_mfma_f32_16x16x32_bf16 v[38:41], v[198:201], v[174:177], v[38:41]
	v_mfma_f32_16x16x32_bf16 v[42:45], v[206:209], v[174:177], v[42:45]
	v_mfma_f32_16x16x32_bf16 v[46:49], v[198:201], v[182:185], v[46:49]
	v_mfma_f32_16x16x32_bf16 v[50:53], v[206:209], v[182:185], v[50:53]
	v_mfma_f32_16x16x32_bf16 v[54:57], v[198:201], v[190:193], v[54:57]
	v_mfma_f32_16x16x32_bf16 v[58:61], v[206:209], v[190:193], v[58:61]
	s_mov_b32 m0, s10
	v_lshl_add_u64 v[214:215], s[74:75], 0, v[0:1]
	s_barrier
; #define PG8_STAGE(bufoff, gbase, voff) do { _Pragma("unroll") for (int _i = 0; _i < 2; ++_i) \
;         __builtin_amdgcn_global_load_lds((const unsigned*)((const char*)(gbase) + (voff)[_i]), (LAS unsigned*)(lds + (bufoff) + ldsw + _i * 8192), 16, 0, 0); } while (0)
; #define PG8_LDA(dst, b, h) do { _Pragma("unroll") for (int m = 0; m < 4; ++m) _Pragma("unroll") for (int k = 0; k < 2; ++k) dst[m][k] = *(const LAS bf16x8*)(lds + PG8_SA(b, h) + aoff + m * 2048 + k * 1024); } while (0)
; #define PG8_LDB(dst, b, h) do { _Pragma("unroll") for (int n = 0; n < 2; ++n) _Pragma("unroll") for (int k = 0; k < 2; ++k) dst[n][k] = *(const LAS bf16x8*)(lds + PG8_SB(b, h) + boff + n * 2048 + k * 1024); } while (0)
; #define PG8_MMA(ai, bj, At, Bt) do { __builtin_amdgcn_s_setprio(1); _Pragma("unroll") for (int m = 0; m < 4; ++m) _Pragma("unroll") for (int n = 0; n < 2; ++n) _Pragma("unroll") for (int k = 0; k < 2; ++k) \
;         acc[ai][bj][m][n] = __builtin_amdgcn_mfma_f32_16x16x32_bf16(Bt[n][k], At[m][k], acc[ai][bj][m][n], 0, 0, 0); __builtin_amdgcn_s_setprio(0); } while (0)
; #define PG8_WAIT_V(n) asm volatile("s_waitcnt vmcnt(" #n ")" ::: "memory")
; #define PG8_WAIT_L(n) asm volatile("s_waitcnt lgkmcnt(" #n ")" ::: "memory")
; #define PG8_BAR __builtin_amdgcn_s_barrier()
; #define PG8_SCHED __builtin_amdgcn_sched_barrier(0)
; template <class Epi>
; __device__ __forceinline__ void gemm_phase(LAS unsigned char* lds, const Gemm g, const StaticOrder& S, const Epi& E, int wv) {
;     ...
;             PG8_LDA(At, 0, 1); PG8_STAGE(PG8_SA(0, 0), a2, voffA);
;             PG8_BAR; PG8_WAIT_L(0); PG8_MMA(1, 0, At, B0); PG8_BAR; PG8_SCHED;
;             PG8_STAGE(PG8_SB(0, 1), b2 + hstepB, voffB);
;             PG8_WAIT_V(6); PG8_BAR; PG8_MMA(1, 1, At, B1); PG8_BAR;
;             PG8_LDB(B0, 1, 0); PG8_SCHED; PG8_LDA(At, 1, 0); PG8_STAGE(PG8_SA(0, 1), a2 + hstepA, voffA);
;             PG8_WAIT_L(8); PG8_BAR; PG8_WAIT_L(0); PG8_MMA(0, 0, At, B0); PG8_BAR; PG8_SCHED;
;             PG8_LDB(B1, 1, 1); PG8_STAGE(PG8_SB(1, 0), b3, voffB);
;             PG8_BAR; PG8_WAIT_L(0); PG8_MMA(0, 1, At, B1); PG8_BAR;
	ds_read_b128 v[138:141], v16 offset:16384
	ds_read_b128 v[142:145], v16 offset:17408
	ds_read_b128 v[170:173], v16 offset:18432
	ds_read_b128 v[174:177], v16 offset:19456
	ds_read_b128 v[178:181], v16 offset:20480
	ds_read_b128 v[182:185], v16 offset:21504
	ds_read_b128 v[186:189], v16 offset:22528
	ds_read_b128 v[190:193], v16 offset:23552
	global_load_lds_dwordx4 v[214:215], off
	v_lshl_add_u64 v[216:217], s[74:75], 0, v[4:5]
	s_mov_b32 m0, s11
	s_nop 0
	global_load_lds_dwordx4 v[216:217], off
	s_barrier
	s_waitcnt lgkmcnt(0)
	v_mfma_f32_16x16x32_bf16 v[146:149], v[122:125], v[138:141], v[146:149]
	v_mfma_f32_16x16x32_bf16 v[150:153], v[130:133], v[138:141], v[150:153]
	v_mfma_f32_16x16x32_bf16 v[154:157], v[122:125], v[170:173], v[154:157]
	v_mfma_f32_16x16x32_bf16 v[158:161], v[130:133], v[170:173], v[158:161]
	v_mfma_f32_16x16x32_bf16 v[162:165], v[122:125], v[178:181], v[162:165]
	v_mfma_f32_16x16x32_bf16 v[166:169], v[130:133], v[178:181], v[166:169]
	v_mfma_f32_16x16x32_bf16 v[18:21], v[122:125], v[186:189], v[18:21]
	v_mfma_f32_16x16x32_bf16 v[22:25], v[130:133], v[186:189], v[22:25]
	v_mfma_f32_16x16x32_bf16 v[146:149], v[126:129], v[142:145], v[146:149]
	v_mfma_f32_16x16x32_bf16 v[150:153], v[134:137], v[142:145], v[150:153]
	v_mfma_f32_16x16x32_bf16 v[154:157], v[126:129], v[174:177], v[154:157]
	v_mfma_f32_16x16x32_bf16 v[158:161], v[134:137], v[174:177], v[158:161]
	v_mfma_f32_16x16x32_bf16 v[162:165], v[126:129], v[182:185], v[162:165]
	v_mfma_f32_16x16x32_bf16 v[166:169], v[134:137], v[182:185], v[166:169]
	v_mfma_f32_16x16x32_bf16 v[18:21], v[126:129], v[190:193], v[18:21]
	v_mfma_f32_16x16x32_bf16 v[22:25], v[134:137], v[190:193], v[22:25]
	s_barrier
	s_add_u32 s46, s72, 0x10000
	s_addc_u32 s47, s73, 0
	s_mov_b32 m0, s40
	v_lshl_add_u64 v[122:123], s[46:47], 0, v[2:3]
	global_load_lds_dwordx4 v[122:123], off
	v_lshl_add_u64 v[122:123], s[46:47], 0, v[6:7]
	s_mov_b32 m0, s38
	s_nop 0
	global_load_lds_dwordx4 v[122:123], off
	s_waitcnt vmcnt(6)
	s_barrier
	v_mfma_f32_16x16x32_bf16 v[26:29], v[194:197], v[138:141], v[26:29]
	v_mfma_f32_16x16x32_bf16 v[30:33], v[202:205], v[138:141], v[30:33]
	v_mfma_f32_16x16x32_bf16 v[62:65], v[194:197], v[170:173], v[62:65]
	v_mfma_f32_16x16x32_bf16 v[106:109], v[202:205], v[170:173], v[106:109]
	v_mfma_f32_16x16x32_bf16 v[110:113], v[194:197], v[178:181], v[110:113]
	v_mfma_f32_16x16x32_bf16 v[118:121], v[202:205], v[178:181], v[118:121]
	v_mfma_f32_16x16x32_bf16 v[98:101], v[194:197], v[186:189], v[98:101]
	v_mfma_f32_16x16x32_bf16 v[102:105], v[202:205], v[186:189], v[102:105]
	v_mfma_f32_16x16x32_bf16 v[26:29], v[198:201], v[142:145], v[26:29]
	v_mfma_f32_16x16x32_bf16 v[30:33], v[206:209], v[142:145], v[30:33]
	v_mfma_f32_16x16x32_bf16 v[62:65], v[198:201], v[174:177], v[62:65]
	v_mfma_f32_16x16x32_bf16 v[106:109], v[206:209], v[174:177], v[106:109]
	v_mfma_f32_16x16x32_bf16 v[110:113], v[198:201], v[182:185], v[110:113]
	v_mfma_f32_16x16x32_bf16 v[118:121], v[206:209], v[182:185], v[118:121]
	v_mfma_f32_16x16x32_bf16 v[98:101], v[198:201], v[190:193], v[98:101]
	v_mfma_f32_16x16x32_bf16 v[102:105], v[206:209], v[190:193], v[102:105]
	s_barrier
	ds_read_b128 v[122:125], v218
	ds_read_b128 v[126:129], v218 offset:1024
	ds_read_b128 v[130:133], v218 offset:2048
	ds_read_b128 v[134:137], v218 offset:3072
	s_add_u32 s38, s74, 0x10000
	s_addc_u32 s39, s75, 0
	s_mov_b32 m0, s12
	v_lshl_add_u64 v[194:195], s[38:39], 0, v[0:1]
	ds_read_b128 v[138:141], v16 offset:32768
	ds_read_b128 v[142:145], v16 offset:33792
	ds_read_b128 v[170:173], v16 offset:34816
	ds_read_b128 v[174:177], v16 offset:35840
	ds_read_b128 v[178:181], v16 offset:36864
	ds_read_b128 v[182:185], v16 offset:37888
	ds_read_b128 v[186:189], v16 offset:38912
	ds_read_b128 v[190:193], v16 offset:39936
	global_load_lds_dwordx4 v[194:195], off
	v_lshl_add_u64 v[194:195], s[38:39], 0, v[4:5]
	s_mov_b32 m0, s13
	s_nop 0
	global_load_lds_dwordx4 v[194:195], off
	s_waitcnt lgkmcnt(8)
	s_barrier
	s_waitcnt lgkmcnt(0)
	v_mfma_f32_16x16x32_bf16 v[66:69], v[122:125], v[138:141], v[66:69]
	v_mfma_f32_16x16x32_bf16 v[70:73], v[130:133], v[138:141], v[70:73]
	v_mfma_f32_16x16x32_bf16 v[74:77], v[122:125], v[170:173], v[74:77]
	v_mfma_f32_16x16x32_bf16 v[78:81], v[130:133], v[170:173], v[78:81]
	v_mfma_f32_16x16x32_bf16 v[82:85], v[122:125], v[178:181], v[82:85]
	v_mfma_f32_16x16x32_bf16 v[86:89], v[130:133], v[178:181], v[86:89]
	v_mfma_f32_16x16x32_bf16 v[90:93], v[122:125], v[186:189], v[90:93]
	v_mfma_f32_16x16x32_bf16 v[94:97], v[130:133], v[186:189], v[94:97]
	v_mfma_f32_16x16x32_bf16 v[66:69], v[126:129], v[142:145], v[66:69]
	v_mfma_f32_16x16x32_bf16 v[70:73], v[134:137], v[142:145], v[70:73]
	v_mfma_f32_16x16x32_bf16 v[74:77], v[126:129], v[174:177], v[74:77]
	v_mfma_f32_16x16x32_bf16 v[78:81], v[134:137], v[174:177], v[78:81]
	v_mfma_f32_16x16x32_bf16 v[82:85], v[126:129], v[182:185], v[82:85]
	v_mfma_f32_16x16x32_bf16 v[86:89], v[134:137], v[182:185], v[86:89]
	v_mfma_f32_16x16x32_bf16 v[90:93], v[126:129], v[190:193], v[90:93]
	v_mfma_f32_16x16x32_bf16 v[94:97], v[134:137], v[190:193], v[94:97]
	s_barrier
	s_mov_b32 m0, s43
	v_lshl_add_u64 v[210:211], v[210:211], 0, s[50:51]
	ds_read_b128 v[194:197], v219
	ds_read_b128 v[198:201], v219 offset:1024
	ds_read_b128 v[202:205], v219 offset:2048
	ds_read_b128 v[206:209], v219 offset:3072
	global_load_lds_dwordx4 v[210:211], off
	v_lshl_add_u64 v[210:211], v[212:213], 0, s[50:51]
	s_mov_b32 m0, s41
	s_nop 0
	global_load_lds_dwordx4 v[210:211], off
	s_barrier
; #define PG8_STAGE(bufoff, gbase, voff) do { _Pragma("unroll") for (int _i = 0; _i < 2; ++_i) \
;         __builtin_amdgcn_global_load_lds((const unsigned*)((const char*)(gbase) + (voff)[_i]), (LAS unsigned*)(lds + (bufoff) + ldsw + _i * 8192), 16, 0, 0); } while (0)
; #define PG8_LDA(dst, b, h) do { _Pragma("unroll") for (int m = 0; m < 4; ++m) _Pragma("unroll") for (int k = 0; k < 2; ++k) dst[m][k] = *(const LAS bf16x8*)(lds + PG8_SA(b, h) + aoff + m * 2048 + k * 1024); } while (0)
; #define PG8_MMA(ai, bj, At, Bt) do { __builtin_amdgcn_s_setprio(1); _Pragma("unroll") for (int m = 0; m < 4; ++m) _Pragma("unroll") for (int n = 0; n < 2; ++n) _Pragma("unroll") for (int k = 0; k < 2; ++k) \
;         acc[ai][bj][m][n] = __builtin_amdgcn_mfma_f32_16x16x32_bf16(Bt[n][k], At[m][k], acc[ai][bj][m][n], 0, 0, 0); __builtin_amdgcn_s_setprio(0); } while (0)
; #define PG8_WAIT_V(n) asm volatile("s_waitcnt vmcnt(" #n ")" ::: "memory")
; #define PG8_WAIT_L(n) asm volatile("s_waitcnt lgkmcnt(" #n ")" ::: "memory")
; #define PG8_BAR __builtin_amdgcn_s_barrier()
; #define PG8_SCHED __builtin_amdgcn_sched_barrier(0)
;     __device__ __forceinline__ const CAS char* base() const { const CAS char* ka = (const CAS char*)__builtin_amdgcn_kernarg_segment_ptr(); asm volatile("" : "+s"(ka)); return ka; }
; template <class Epi>
; __device__ __forceinline__ void gemm_phase(LAS unsigned char* lds, const Gemm g, const StaticOrder& S, const Epi& E, int wv) {
;     ...
;             PG8_BAR; PG8_WAIT_L(0); PG8_MMA(0, 1, At, B1); PG8_BAR;
;             PG8_LDA(At, 1, 1); PG8_STAGE(PG8_SA(1, 0), a3, voffA);
;             PG8_BAR; PG8_WAIT_L(0); PG8_MMA(1, 0, At, B0); PG8_BAR; PG8_SCHED;
;             PG8_STAGE(PG8_SB(1, 1), b3 + hstepB, voffB);
;             PG8_WAIT_V(6); PG8_BAR; PG8_MMA(1, 1, At, B1); PG8_BAR;
;     __device__ __forceinline__ void operator()(const f32x4 (&acc)[2][2][4][2], const Unit& u, int wr, int wc, int fr, int fq) const {
;         const int row0 = u.pm * BM + wr * 64 + fr; int colt = u.pn * BM; bf16_t* base = O; int tsel = 0;
;         if (split_cols) { tsel = colt / split_cols; base += (size_t)tsel * split_stride; colt -= tsel * split_cols; }
;         const int col0 = colt + wc * 32 + 8 * fq;
	s_waitcnt lgkmcnt(0)
	v_mfma_f32_16x16x32_bf16 v[114:117], v[194:197], v[138:141], v[114:117]
	v_mfma_f32_16x16x32_bf16 v[34:37], v[202:205], v[138:141], v[34:37]
	v_mfma_f32_16x16x32_bf16 v[38:41], v[194:197], v[170:173], v[38:41]
	v_mfma_f32_16x16x32_bf16 v[42:45], v[202:205], v[170:173], v[42:45]
	v_mfma_f32_16x16x32_bf16 v[46:49], v[194:197], v[178:181], v[46:49]
	v_mfma_f32_16x16x32_bf16 v[50:53], v[202:205], v[178:181], v[50:53]
	v_mfma_f32_16x16x32_bf16 v[54:57], v[194:197], v[186:189], v[54:57]
	v_mfma_f32_16x16x32_bf16 v[58:61], v[202:205], v[186:189], v[58:61]
	v_mfma_f32_16x16x32_bf16 v[114:117], v[198:201], v[142:145], v[114:117]
	v_mfma_f32_16x16x32_bf16 v[34:37], v[206:209], v[142:145], v[34:37]
	v_mfma_f32_16x16x32_bf16 v[38:41], v[198:201], v[174:177], v[38:41]
	v_mfma_f32_16x16x32_bf16 v[42:45], v[206:209], v[174:177], v[42:45]
	v_mfma_f32_16x16x32_bf16 v[46:49], v[198:201], v[182:185], v[46:49]
	v_mfma_f32_16x16x32_bf16 v[50:53], v[206:209], v[182:185], v[50:53]
	v_mfma_f32_16x16x32_bf16 v[54:57], v[198:201], v[190:193], v[54:57]
	v_mfma_f32_16x16x32_bf16 v[58:61], v[206:209], v[190:193], v[58:61]
	s_mov_b32 m0, s14
	v_lshl_add_u64 v[210:211], v[214:215], 0, s[50:51]
	s_barrier
	ds_read_b128 v[138:141], v16 offset:49152
	ds_read_b128 v[142:145], v16 offset:50176
	ds_read_b128 v[170:173], v16 offset:51200
	ds_read_b128 v[174:177], v16 offset:52224
	ds_read_b128 v[178:181], v16 offset:53248
	ds_read_b128 v[182:185], v16 offset:54272
	ds_read_b128 v[186:189], v16 offset:55296
	ds_read_b128 v[190:193], v16 offset:56320
	global_load_lds_dwordx4 v[210:211], off
	v_lshl_add_u64 v[210:211], v[216:217], 0, s[50:51]
	s_mov_b32 m0, s15
	s_nop 0
	global_load_lds_dwordx4 v[210:211], off
	s_barrier
	s_waitcnt lgkmcnt(0)
	v_mfma_f32_16x16x32_bf16 v[146:149], v[122:125], v[138:141], v[146:149]
	v_mfma_f32_16x16x32_bf16 v[150:153], v[130:133], v[138:141], v[150:153]
	v_mfma_f32_16x16x32_bf16 v[154:157], v[122:125], v[170:173], v[154:157]
	v_mfma_f32_16x16x32_bf16 v[158:161], v[130:133], v[170:173], v[158:161]
	v_mfma_f32_16x16x32_bf16 v[162:165], v[122:125], v[178:181], v[162:165]
	v_mfma_f32_16x16x32_bf16 v[166:169], v[130:133], v[178:181], v[166:169]
	v_mfma_f32_16x16x32_bf16 v[18:21], v[122:125], v[186:189], v[18:21]
	v_mfma_f32_16x16x32_bf16 v[22:25], v[130:133], v[186:189], v[22:25]
	v_mfma_f32_16x16x32_bf16 v[146:149], v[126:129], v[142:145], v[146:149]
	v_mfma_f32_16x16x32_bf16 v[150:153], v[134:137], v[142:145], v[150:153]
	v_mfma_f32_16x16x32_bf16 v[154:157], v[126:129], v[174:177], v[154:157]
	v_mfma_f32_16x16x32_bf16 v[158:161], v[134:137], v[174:177], v[158:161]
	v_mfma_f32_16x16x32_bf16 v[162:165], v[126:129], v[182:185], v[162:165]
	v_mfma_f32_16x16x32_bf16 v[166:169], v[134:137], v[182:185], v[166:169]
	v_mfma_f32_16x16x32_bf16 v[18:21], v[126:129], v[190:193], v[18:21]
	v_mfma_f32_16x16x32_bf16 v[22:25], v[134:137], v[190:193], v[22:25]
	s_barrier
	s_add_u32 s38, s72, 0x10080
	s_addc_u32 s39, s73, 0
	s_mov_b32 m0, s44
	v_lshl_add_u64 v[122:123], s[38:39], 0, v[2:3]
	global_load_lds_dwordx4 v[122:123], off
	v_lshl_add_u64 v[122:123], s[38:39], 0, v[6:7]
	s_mov_b32 m0, s42
	s_nop 0
	global_load_lds_dwordx4 v[122:123], off
	s_waitcnt vmcnt(6)
	s_barrier
	v_mfma_f32_16x16x32_bf16 v[26:29], v[194:197], v[138:141], v[26:29]
	v_mfma_f32_16x16x32_bf16 v[30:33], v[202:205], v[138:141], v[30:33]
	v_mfma_f32_16x16x32_bf16 v[62:65], v[194:197], v[170:173], v[62:65]
	v_mfma_f32_16x16x32_bf16 v[106:109], v[202:205], v[170:173], v[106:109]
	v_mfma_f32_16x16x32_bf16 v[110:113], v[194:197], v[178:181], v[110:113]
	v_mfma_f32_16x16x32_bf16 v[118:121], v[202:205], v[178:181], v[118:121]
	v_mfma_f32_16x16x32_bf16 v[98:101], v[194:197], v[186:189], v[98:101]
	v_mfma_f32_16x16x32_bf16 v[102:105], v[202:205], v[186:189], v[102:105]
	v_mfma_f32_16x16x32_bf16 v[26:29], v[198:201], v[142:145], v[26:29]
	v_mfma_f32_16x16x32_bf16 v[30:33], v[206:209], v[142:145], v[30:33]
	v_mfma_f32_16x16x32_bf16 v[62:65], v[198:201], v[174:177], v[62:65]
	v_mfma_f32_16x16x32_bf16 v[106:109], v[206:209], v[174:177], v[106:109]
	v_mfma_f32_16x16x32_bf16 v[110:113], v[198:201], v[182:185], v[110:113]
	v_mfma_f32_16x16x32_bf16 v[118:121], v[206:209], v[182:185], v[118:121]
	v_mfma_f32_16x16x32_bf16 v[98:101], v[198:201], v[190:193], v[98:101]
	v_mfma_f32_16x16x32_bf16 v[102:105], v[206:209], v[190:193], v[102:105]
	v_lshl_add_u32 v122, s58, 8, v12
	v_lshl_or_b32 v124, s34, 8, v14
	v_ashrrev_i32_e32 v125, 31, v124
	v_ashrrev_i32_e32 v123, 31, v122
	v_lshl_add_u64 v[124:125], v[124:125], 1, s[18:19]
	v_lshlrev_b64 v[126:127], 12, v[122:123]
	v_lshl_add_u64 v[126:127], v[124:125], 0, v[126:127]
	v_cvt_pk_bf16_f32 v66, v66, v67
	v_cvt_pk_bf16_f32 v67, v68, v69
	v_cvt_pk_bf16_f32 v68, v70, v71
	v_cvt_pk_bf16_f32 v69, v72, v73
	s_barrier
; __device__ __forceinline__ float fast_sigmoid(float x) { return __builtin_amdgcn_rcpf(1.0f + __builtin_amdgcn_exp2f(-x * LOG2E)); }
;     __device__ __forceinline__ const CAS char* base() const { const CAS char* ka = (const CAS char*)__builtin_amdgcn_kernarg_segment_ptr(); asm volatile("" : "+s"(ka)); return ka; }
; template <class Epi>
; __device__ __forceinline__ void gemm_phase(LAS unsigned char* lds, const Gemm g, const StaticOrder& S, const Epi& E, int wv) {
;     ...
;         cur = nxt; cA = nA; cB = nB; ++ui;
;     __device__ __forceinline__ void operator()(const f32x4 (&acc)[2][2][4][2], const Unit& u, int wr, int wc, int fr, int fq) const {
;     ...
;                 bf16_t* rowp = base + (size_t)row * ldc + col0;
; #pragma unroll
;                 for (int bj = 0; bj < 2; ++bj) { f32x4 v0 = acc[ai][bj][m][0], v1 = acc[ai][bj][m][1];
;                     if (SM == 1) { v0 *= rs; v1 *= rs; }
;                     if (SM == 2) { v0 *= cs[bj][0]; v1 *= cs[bj][1]; }
;                     if (ACT == 1) {
; #pragma unroll
;                         for (int j = 0; j < 4; ++j) { const float a = fmaxf(v0[j], 0.f), b = fmaxf(v1[j], 0.f); v0[j] = a * a; v1[j] = b * b; } }
;                     if (ACT == 2) { if (tsel == 0) {
; #pragma unroll
;                         for (int j = 0; j < 4; ++j) { const float a = v0[j], b = v1[j];
;                             v0[j] = a * fast_sigmoid(1.5957691216057308f * (a + 0.044715f * a * a * a)); v1[j] = b * fast_sigmoid(1.5957691216057308f * (b + 0.044715f * b * b * b)); } } }
;                     u32x4 w; w.x = pk_bf16(v0[0], v0[1]); w.y = pk_bf16(v0[2], v0[3]); w.z = pk_bf16(v1[0], v1[1]); w.w = pk_bf16(v1[2], v1[3]);
;                     *(u32x4*)(rowp + bj * HALF) = w; } }
	global_store_dwordx4 v[126:127], v[66:69], off
	s_mov_b64 s[34:35], 0x80000
	v_cvt_pk_bf16_f32 v26, v26, v27
	v_cvt_pk_bf16_f32 v68, v34, v35
	v_or_b32_e32 v34, 16, v122
	v_ashrrev_i32_e32 v35, 31, v34
	v_cvt_pk_bf16_f32 v66, v114, v115
	v_cvt_pk_bf16_f32 v67, v116, v117
	v_cvt_pk_bf16_f32 v69, v36, v37
	v_lshlrev_b64 v[34:35], 12, v[34:35]
	global_store_dwordx4 v[126:127], v[66:69], off offset:256
	v_cvt_pk_bf16_f32 v36, v78, v79
	v_cvt_pk_bf16_f32 v37, v80, v81
	v_lshl_add_u64 v[66:67], v[124:125], 0, v[34:35]
	v_cvt_pk_bf16_f32 v34, v74, v75
	v_cvt_pk_bf16_f32 v35, v76, v77
	global_store_dwordx4 v[66:67], v[34:37], off
	v_cvt_pk_bf16_f32 v27, v28, v29
	v_cvt_pk_bf16_f32 v28, v30, v31
	v_cvt_pk_bf16_f32 v34, v38, v39
	v_cvt_pk_bf16_f32 v35, v40, v41
	v_cvt_pk_bf16_f32 v36, v42, v43
	v_cvt_pk_bf16_f32 v37, v44, v45
	global_store_dwordx4 v[66:67], v[34:37], off offset:256
	v_cvt_pk_bf16_f32 v29, v32, v33
	v_cvt_pk_bf16_f32 v18, v18, v19
	v_or_b32_e32 v34, 32, v122
	v_ashrrev_i32_e32 v35, 31, v34
	v_lshlrev_b64 v[34:35], 12, v[34:35]
	v_lshl_add_u64 v[38:39], v[124:125], 0, v[34:35]
	v_cvt_pk_bf16_f32 v34, v82, v83
	v_cvt_pk_bf16_f32 v35, v84, v85
	v_cvt_pk_bf16_f32 v36, v86, v87
	v_cvt_pk_bf16_f32 v37, v88, v89
	global_store_dwordx4 v[38:39], v[34:37], off
	v_cvt_pk_bf16_f32 v19, v20, v21
	v_cvt_pk_bf16_f32 v20, v22, v23
	v_cvt_pk_bf16_f32 v34, v46, v47
	v_cvt_pk_bf16_f32 v35, v48, v49
	v_cvt_pk_bf16_f32 v36, v50, v51
	v_cvt_pk_bf16_f32 v37, v52, v53
	global_store_dwordx4 v[38:39], v[34:37], off offset:256
	v_cvt_pk_bf16_f32 v21, v24, v25
	s_add_i32 s33, s33, s28
	v_or_b32_e32 v34, 48, v122
	v_ashrrev_i32_e32 v35, 31, v34
	v_lshlrev_b64 v[34:35], 12, v[34:35]
	v_lshl_add_u64 v[38:39], v[124:125], 0, v[34:35]
	v_cvt_pk_bf16_f32 v34, v90, v91
	v_cvt_pk_bf16_f32 v35, v92, v93
	v_cvt_pk_bf16_f32 v36, v94, v95
	v_cvt_pk_bf16_f32 v37, v96, v97
	global_store_dwordx4 v[38:39], v[34:37], off
	s_mov_b32 s58, s62
	s_mov_b64 s[70:71], s[66:67]
	v_cvt_pk_bf16_f32 v34, v54, v55
	v_cvt_pk_bf16_f32 v35, v56, v57
	v_cvt_pk_bf16_f32 v36, v58, v59
	v_cvt_pk_bf16_f32 v37, v60, v61
	global_store_dwordx4 v[38:39], v[34:37], off offset:256
	v_lshl_add_u64 v[38:39], v[126:127], 0, s[34:35]
	s_mov_b32 s34, 0x80000
	v_add_co_u32_e32 v40, vcc, s34, v126
	s_mov_b64 s[34:35], 0x90000
	s_nop 0
	v_addc_co_u32_e32 v41, vcc, 0, v127, vcc
	v_lshl_add_u64 v[30:31], v[126:127], 0, s[34:35]
	s_mov_b32 s34, 0x90000
	v_add_co_u32_e32 v32, vcc, s34, v126
	global_store_dwordx4 v[38:39], v[26:29], off offset:256
	s_nop 0
	v_addc_co_u32_e32 v33, vcc, 0, v127, vcc
	v_cvt_pk_bf16_f32 v26, v154, v155
	v_cvt_pk_bf16_f32 v27, v156, v157
	v_cvt_pk_bf16_f32 v28, v158, v159
	v_cvt_pk_bf16_f32 v29, v160, v161
	global_store_dwordx4 v[32:33], v[26:29], off
	s_mov_b64 s[34:35], 0xa0000
	v_cvt_pk_bf16_f32 v34, v146, v147
	v_cvt_pk_bf16_f32 v26, v62, v63
	v_cvt_pk_bf16_f32 v27, v64, v65
	v_cvt_pk_bf16_f32 v28, v106, v107
	v_cvt_pk_bf16_f32 v29, v108, v109
	global_store_dwordx4 v[30:31], v[26:29], off offset:256
	v_lshl_add_u64 v[30:31], v[126:127], 0, s[34:35]
	s_mov_b32 s34, 0xa0000
	v_add_co_u32_e32 v32, vcc, s34, v126
	v_cvt_pk_bf16_f32 v26, v162, v163
	v_cvt_pk_bf16_f32 v27, v164, v165
	v_cvt_pk_bf16_f32 v28, v166, v167
	v_cvt_pk_bf16_f32 v29, v168, v169
	v_addc_co_u32_e32 v33, vcc, 0, v127, vcc
	global_store_dwordx4 v[32:33], v[26:29], off
	s_mov_b64 s[34:35], 0xb0000
	v_cvt_pk_bf16_f32 v35, v148, v149
	v_cvt_pk_bf16_f32 v26, v110, v111
	v_cvt_pk_bf16_f32 v27, v112, v113
	v_cvt_pk_bf16_f32 v28, v118, v119
	v_cvt_pk_bf16_f32 v29, v120, v121
	global_store_dwordx4 v[30:31], v[26:29], off offset:256
	v_cvt_pk_bf16_f32 v36, v150, v151
	v_cvt_pk_bf16_f32 v37, v152, v153
	v_lshl_add_u64 v[26:27], v[126:127], 0, s[34:35]
	s_mov_b32 s34, 0xb0000
	v_add_co_u32_e32 v22, vcc, s34, v126
	s_mov_b32 s34, s60
	s_nop 0
	v_addc_co_u32_e32 v23, vcc, 0, v127, vcc
	global_store_dwordx4 v[22:23], v[18:21], off
	s_andn2_b64 vcc, exec, s[16:17]
	s_mov_b64 s[68:69], s[64:65]
	v_cvt_pk_bf16_f32 v18, v98, v99
	v_cvt_pk_bf16_f32 v19, v100, v101
	v_cvt_pk_bf16_f32 v20, v102, v103
	v_cvt_pk_bf16_f32 v21, v104, v105
	global_store_dwordx4 v[40:41], v[34:37], off
	global_store_dwordx4 v[26:27], v[18:21], off offset:256
	s_cbranch_vccz .LBB0_644

; #define PG8_STAGE(bufoff, gbase, voff) do { _Pragma("unroll") for (int _i = 0; _i < 2; ++_i) \
;         __builtin_amdgcn_global_load_lds((const unsigned*)((const char*)(gbase) + (voff)[_i]), (LAS unsigned*)(lds + (bufoff) + ldsw + _i * 8192), 16, 0, 0); } while (0)
; #define PG8_LDA(dst, b, h) do { _Pragma("unroll") for (int m = 0; m < 4; ++m) _Pragma("unroll") for (int k = 0; k < 2; ++k) dst[m][k] = *(const LAS bf16x8*)(lds + PG8_SA(b, h) + aoff + m * 2048 + k * 1024); } while (0)
; #define PG8_LDB(dst, b, h) do { _Pragma("unroll") for (int n = 0; n < 2; ++n) _Pragma("unroll") for (int k = 0; k < 2; ++k) dst[n][k] = *(const LAS bf16x8*)(lds + PG8_SB(b, h) + boff + n * 2048 + k * 1024); } while (0)
; #define PG8_MMA(ai, bj, At, Bt) do { __builtin_amdgcn_s_setprio(1); _Pragma("unroll") for (int m = 0; m < 4; ++m) _Pragma("unroll") for (int n = 0; n < 2; ++n) _Pragma("unroll") for (int k = 0; k < 2; ++k) \
;         acc[ai][bj][m][n] = __builtin_amdgcn_mfma_f32_16x16x32_bf16(Bt[n][k], At[m][k], acc[ai][bj][m][n], 0, 0, 0); __builtin_amdgcn_s_setprio(0); } while (0)
; #define PG8_WAIT_V(n) asm volatile("s_waitcnt vmcnt(" #n ")" ::: "memory")
; #define PG8_WAIT_L(n) asm volatile("s_waitcnt lgkmcnt(" #n ")" ::: "memory")
; #define PG8_BAR __builtin_amdgcn_s_barrier()
; template <class Epi>
; __device__ __forceinline__ void gemm_phase(LAS unsigned char* lds, const Gemm g, const StaticOrder& S, const Epi& E, int wv) {
;     ...
;             const bool last = (t == nt - 2);
;             const char* a1 = cA + (ptrdiff_t)(t + 1) * kstep;
;             const char* a2 = last ? nA : cA + (ptrdiff_t)(t + 2) * kstep; const char* b2 = last ? nB : cB + (ptrdiff_t)(t + 2) * kstep;
;             const char* a3 = a2 + kstep; const char* b3 = b2 + kstep;
;             PG8_LDB(B0, 0, 0); PG8_SCHED; PG8_LDA(At, 0, 0); PG8_STAGE(PG8_SA(1, 1), a1 + hstepA, voffA);
;             PG8_WAIT_L(8); PG8_BAR; PG8_WAIT_L(0); PG8_MMA(0, 0, At, B0); PG8_BAR; PG8_SCHED;
;             PG8_LDB(B1, 0, 1); PG8_STAGE(PG8_SB(0, 0), b2, voffB);
;             PG8_BAR; PG8_WAIT_L(0); PG8_MMA(0, 1, At, B1); PG8_BAR;
;             PG8_LDA(At, 0, 1); PG8_STAGE(PG8_SA(0, 0), a2, voffA);
;             PG8_BAR; PG8_WAIT_L(0); PG8_MMA(1, 0, At, B0); PG8_BAR; PG8_SCHED;
;             PG8_STAGE(PG8_SB(0, 1), b2 + hstepB, voffB);
;             PG8_WAIT_V(6); PG8_BAR; PG8_MMA(1, 1, At, B1); PG8_BAR;
.Lrot_in_717:
	s_add_u32 s42, s74, 0xfff80080
	s_addc_u32 s43, s75, -1
	s_cmp_eq_u32 s41, 28
	s_cselect_b32 s79, s33, s43
	s_cselect_b32 s78, s34, s42
	s_cselect_b32 s77, s35, s40
	s_cselect_b32 s76, s38, s39
	s_add_i32 m0, s10, 0xc000
	ds_read_b128 v[144:147], v194
	ds_read_b128 v[148:151], v194 offset:1024
	ds_read_b128 v[152:155], v194 offset:2048
	ds_read_b128 v[156:159], v194 offset:3072
	ds_read_b128 v[176:179], v194 offset:4096
	ds_read_b128 v[180:183], v194 offset:5120
	ds_read_b128 v[184:187], v194 offset:6144
	ds_read_b128 v[198:201], v194 offset:7168
	global_load_lds_dwordx4 v170, s[74:75]
	s_add_i32 m0, s10, 0xe000
	s_nop 0
	global_load_lds_dwordx4 v168, s[74:75]
	s_waitcnt lgkmcnt(8)
	s_barrier
	s_waitcnt lgkmcnt(0)
	v_mfma_f32_16x16x32_bf16 v[124:127], v[128:131], v[144:147], v[124:127]
	v_mfma_f32_16x16x32_bf16 v[120:123], v[136:139], v[144:147], v[120:123]
	v_mfma_f32_16x16x32_bf16 v[108:111], v[128:131], v[152:155], v[108:111]
	v_mfma_f32_16x16x32_bf16 v[104:107], v[136:139], v[152:155], v[104:107]
	v_mfma_f32_16x16x32_bf16 v[92:95], v[128:131], v[176:179], v[92:95]
	v_mfma_f32_16x16x32_bf16 v[88:91], v[136:139], v[176:179], v[88:91]
	v_mfma_f32_16x16x32_bf16 v[76:79], v[128:131], v[184:187], v[76:79]
	v_mfma_f32_16x16x32_bf16 v[72:75], v[136:139], v[184:187], v[72:75]
	v_mfma_f32_16x16x32_bf16 v[124:127], v[132:135], v[148:151], v[124:127]
	v_mfma_f32_16x16x32_bf16 v[120:123], v[140:143], v[148:151], v[120:123]
	v_mfma_f32_16x16x32_bf16 v[108:111], v[132:135], v[156:159], v[108:111]
	v_mfma_f32_16x16x32_bf16 v[104:107], v[140:143], v[156:159], v[104:107]
	v_mfma_f32_16x16x32_bf16 v[92:95], v[132:135], v[180:183], v[92:95]
	v_mfma_f32_16x16x32_bf16 v[88:91], v[140:143], v[180:183], v[88:91]
	v_mfma_f32_16x16x32_bf16 v[76:79], v[132:135], v[198:201], v[76:79]
	v_mfma_f32_16x16x32_bf16 v[72:75], v[140:143], v[198:201], v[72:75]
	s_barrier
	s_add_i32 s42, s23, s9
	s_add_u32 s98, s76, s60
	s_addc_u32 s99, s77, s61
	s_mov_b32 m0, s42
	ds_read_b128 v[202:205], v195
	ds_read_b128 v[206:209], v195 offset:1024
	ds_read_b128 v[210:213], v195 offset:2048
	ds_read_b128 v[214:217], v195 offset:3072
	global_load_lds_dwordx4 v162, s[76:77]
	s_add_i32 m0, s42, 0x2000
	s_nop 0
	global_load_lds_dwordx4 v166, s[76:77]
	s_barrier
	s_waitcnt lgkmcnt(0)
	v_mfma_f32_16x16x32_bf16 v[116:119], v[202:205], v[144:147], v[116:119]
	v_mfma_f32_16x16x32_bf16 v[112:115], v[210:213], v[144:147], v[112:115]
	v_mfma_f32_16x16x32_bf16 v[100:103], v[202:205], v[152:155], v[100:103]
	v_mfma_f32_16x16x32_bf16 v[96:99], v[210:213], v[152:155], v[96:99]
	v_mfma_f32_16x16x32_bf16 v[84:87], v[202:205], v[176:179], v[84:87]
	v_mfma_f32_16x16x32_bf16 v[80:83], v[210:213], v[176:179], v[80:83]
	v_mfma_f32_16x16x32_bf16 v[68:71], v[202:205], v[184:187], v[68:71]
	v_mfma_f32_16x16x32_bf16 v[64:67], v[210:213], v[184:187], v[64:67]
	v_mfma_f32_16x16x32_bf16 v[116:119], v[206:209], v[148:151], v[116:119]
	v_mfma_f32_16x16x32_bf16 v[112:115], v[214:217], v[148:151], v[112:115]
	v_mfma_f32_16x16x32_bf16 v[100:103], v[206:209], v[156:159], v[100:103]
	v_mfma_f32_16x16x32_bf16 v[96:99], v[214:217], v[156:159], v[96:99]
	v_mfma_f32_16x16x32_bf16 v[84:87], v[206:209], v[180:183], v[84:87]
	v_mfma_f32_16x16x32_bf16 v[80:83], v[214:217], v[180:183], v[80:83]
	v_mfma_f32_16x16x32_bf16 v[68:71], v[206:209], v[198:201], v[68:71]
	v_mfma_f32_16x16x32_bf16 v[64:67], v[214:217], v[198:201], v[64:67]
	s_mov_b32 m0, s10
	s_add_u32 s100, s78, s60
	s_addc_u32 s101, s79, s61
	s_barrier
	ds_read_b128 v[144:147], v194 offset:16384
	ds_read_b128 v[148:151], v194 offset:17408
	ds_read_b128 v[152:155], v194 offset:18432
	ds_read_b128 v[156:159], v194 offset:19456
	ds_read_b128 v[176:179], v194 offset:20480
	ds_read_b128 v[180:183], v194 offset:21504
	ds_read_b128 v[184:187], v194 offset:22528
	ds_read_b128 v[198:201], v194 offset:23552
	global_load_lds_dwordx4 v160, s[78:79]
	s_mov_b32 m0, s11
	s_nop 0
	global_load_lds_dwordx4 v164, s[78:79]
	s_waitcnt vmcnt(10)
	s_barrier
	s_waitcnt lgkmcnt(0)
	v_mfma_f32_16x16x32_bf16 v[60:63], v[128:131], v[144:147], v[60:63]
	v_mfma_f32_16x16x32_bf16 v[56:59], v[136:139], v[144:147], v[56:59]
	v_mfma_f32_16x16x32_bf16 v[44:47], v[128:131], v[152:155], v[44:47]
	v_mfma_f32_16x16x32_bf16 v[40:43], v[136:139], v[152:155], v[40:43]
	v_mfma_f32_16x16x32_bf16 v[28:31], v[128:131], v[176:179], v[28:31]
	v_mfma_f32_16x16x32_bf16 v[24:27], v[136:139], v[176:179], v[24:27]
	v_mfma_f32_16x16x32_bf16 v[12:15], v[128:131], v[184:187], v[12:15]
	v_mfma_f32_16x16x32_bf16 v[8:11], v[136:139], v[184:187], v[8:11]
	v_mfma_f32_16x16x32_bf16 v[60:63], v[132:135], v[148:151], v[60:63]
	v_mfma_f32_16x16x32_bf16 v[56:59], v[140:143], v[148:151], v[56:59]
	v_mfma_f32_16x16x32_bf16 v[44:47], v[132:135], v[156:159], v[44:47]
	v_mfma_f32_16x16x32_bf16 v[40:43], v[140:143], v[156:159], v[40:43]
	v_mfma_f32_16x16x32_bf16 v[28:31], v[132:135], v[180:183], v[28:31]
	v_mfma_f32_16x16x32_bf16 v[24:27], v[140:143], v[180:183], v[24:27]
	v_mfma_f32_16x16x32_bf16 v[12:15], v[132:135], v[198:201], v[12:15]
	v_mfma_f32_16x16x32_bf16 v[8:11], v[140:143], v[198:201], v[8:11]
	s_barrier
	s_add_u32 s42, s76, 0x80000
	s_addc_u32 s43, s77, 0
	s_add_i32 s44, s24, s9
	s_mov_b32 m0, s44
	s_nop 0
	global_load_lds_dwordx4 v162, s[42:43]
	s_add_i32 m0, s44, 0x2000
	s_nop 0
	global_load_lds_dwordx4 v166, s[42:43]
	s_add_i32 s44, 0, 0x18000
	v_add_u32_e32 v140, s44, v191
	ds_read_b128 v[128:131], v140
	ds_read_b128 v[132:135], v140 offset:1024
	ds_read_b128 v[136:139], v140 offset:2048
	ds_read_b128 v[140:143], v140 offset:3072
	s_waitcnt vmcnt(6)
	s_barrier
; #define PG8_STAGE(bufoff, gbase, voff) do { _Pragma("unroll") for (int _i = 0; _i < 2; ++_i) \
;         __builtin_amdgcn_global_load_lds((const unsigned*)((const char*)(gbase) + (voff)[_i]), (LAS unsigned*)(lds + (bufoff) + ldsw + _i * 8192), 16, 0, 0); } while (0)
; #define PG8_LDA(dst, b, h) do { _Pragma("unroll") for (int m = 0; m < 4; ++m) _Pragma("unroll") for (int k = 0; k < 2; ++k) dst[m][k] = *(const LAS bf16x8*)(lds + PG8_SA(b, h) + aoff + m * 2048 + k * 1024); } while (0)
; #define PG8_LDB(dst, b, h) do { _Pragma("unroll") for (int n = 0; n < 2; ++n) _Pragma("unroll") for (int k = 0; k < 2; ++k) dst[n][k] = *(const LAS bf16x8*)(lds + PG8_SB(b, h) + boff + n * 2048 + k * 1024); } while (0)
; #define PG8_MMA(ai, bj, At, Bt) do { __builtin_amdgcn_s_setprio(1); _Pragma("unroll") for (int m = 0; m < 4; ++m) _Pragma("unroll") for (int n = 0; n < 2; ++n) _Pragma("unroll") for (int k = 0; k < 2; ++k) \
;         acc[ai][bj][m][n] = __builtin_amdgcn_mfma_f32_16x16x32_bf16(Bt[n][k], At[m][k], acc[ai][bj][m][n], 0, 0, 0); __builtin_amdgcn_s_setprio(0); } while (0)
; #define PG8_WAIT_V(n) asm volatile("s_waitcnt vmcnt(" #n ")" ::: "memory")
; #define PG8_WAIT_L(n) asm volatile("s_waitcnt lgkmcnt(" #n ")" ::: "memory")
; #define PG8_BAR __builtin_amdgcn_s_barrier()
; #define PG8_SCHED __builtin_amdgcn_sched_barrier(0)
; template <class Epi>
; __device__ __forceinline__ void gemm_phase(LAS unsigned char* lds, const Gemm g, const StaticOrder& S, const Epi& E, int wv) {
;     ...
;             PG8_LDB(B0, 0, 0); PG8_SCHED; PG8_LDA(At, 0, 0); PG8_STAGE(PG8_SA(1, 1), a1 + hstepA, voffA);
;     ...
;             PG8_LDB(B0, 1, 0); PG8_SCHED; PG8_LDA(At, 1, 0); PG8_STAGE(PG8_SA(0, 1), a2 + hstepA, voffA);
;             PG8_WAIT_L(8); PG8_BAR; PG8_WAIT_L(0); PG8_MMA(0, 0, At, B0); PG8_BAR; PG8_SCHED;
;             PG8_LDB(B1, 1, 1); PG8_STAGE(PG8_SB(1, 0), b3, voffB);
;             PG8_BAR; PG8_WAIT_L(0); PG8_MMA(0, 1, At, B1); PG8_BAR;
;             PG8_LDA(At, 1, 1); PG8_STAGE(PG8_SA(1, 0), a3, voffA);
;             PG8_BAR; PG8_WAIT_L(0); PG8_MMA(1, 0, At, B0); PG8_BAR; PG8_SCHED;
;             PG8_STAGE(PG8_SB(1, 1), b3 + hstepB, voffB);
;             PG8_WAIT_V(6); PG8_BAR; PG8_MMA(1, 1, At, B1); PG8_BAR;
	v_mfma_f32_16x16x32_bf16 v[52:55], v[202:205], v[144:147], v[52:55]
	v_mfma_f32_16x16x32_bf16 v[48:51], v[210:213], v[144:147], v[48:51]
	v_mfma_f32_16x16x32_bf16 v[36:39], v[202:205], v[152:155], v[36:39]
	v_mfma_f32_16x16x32_bf16 v[32:35], v[210:213], v[152:155], v[32:35]
	v_mfma_f32_16x16x32_bf16 v[20:23], v[202:205], v[176:179], v[20:23]
	v_mfma_f32_16x16x32_bf16 v[16:19], v[210:213], v[176:179], v[16:19]
	v_mfma_f32_16x16x32_bf16 v[4:7], v[202:205], v[184:187], v[4:7]
	v_mfma_f32_16x16x32_bf16 v[0:3], v[210:213], v[184:187], v[0:3]
	v_mfma_f32_16x16x32_bf16 v[52:55], v[206:209], v[148:151], v[52:55]
	v_mfma_f32_16x16x32_bf16 v[48:51], v[214:217], v[148:151], v[48:51]
	v_mfma_f32_16x16x32_bf16 v[36:39], v[206:209], v[156:159], v[36:39]
	v_mfma_f32_16x16x32_bf16 v[32:35], v[214:217], v[156:159], v[32:35]
	v_mfma_f32_16x16x32_bf16 v[20:23], v[206:209], v[180:183], v[20:23]
	v_mfma_f32_16x16x32_bf16 v[16:19], v[214:217], v[180:183], v[16:19]
	v_mfma_f32_16x16x32_bf16 v[4:7], v[206:209], v[198:201], v[4:7]
	v_mfma_f32_16x16x32_bf16 v[0:3], v[214:217], v[198:201], v[0:3]
	s_waitcnt lgkmcnt(0)
	s_barrier
	s_add_u32 s42, s78, 0x80000
	s_addc_u32 s43, s79, 0
	s_mov_b32 m0, s12
	ds_read_b128 v[144:147], v194 offset:32768
	ds_read_b128 v[148:151], v194 offset:33792
	ds_read_b128 v[152:155], v194 offset:34816
	ds_read_b128 v[156:159], v194 offset:35840
	ds_read_b128 v[176:179], v194 offset:36864
	ds_read_b128 v[180:183], v194 offset:37888
	ds_read_b128 v[184:187], v194 offset:38912
	ds_read_b128 v[198:201], v194 offset:39936
	global_load_lds_dwordx4 v160, s[42:43]
	s_mov_b32 m0, s13
	s_nop 0
	global_load_lds_dwordx4 v164, s[42:43]
	s_waitcnt lgkmcnt(8)
	s_barrier
	s_waitcnt lgkmcnt(0)
	v_mfma_f32_16x16x32_bf16 v[124:127], v[128:131], v[144:147], v[124:127]
	v_mfma_f32_16x16x32_bf16 v[120:123], v[136:139], v[144:147], v[120:123]
	v_mfma_f32_16x16x32_bf16 v[108:111], v[128:131], v[152:155], v[108:111]
	v_mfma_f32_16x16x32_bf16 v[104:107], v[136:139], v[152:155], v[104:107]
	v_mfma_f32_16x16x32_bf16 v[92:95], v[128:131], v[176:179], v[92:95]
	v_mfma_f32_16x16x32_bf16 v[88:91], v[136:139], v[176:179], v[88:91]
	v_mfma_f32_16x16x32_bf16 v[76:79], v[128:131], v[184:187], v[76:79]
	v_mfma_f32_16x16x32_bf16 v[72:75], v[136:139], v[184:187], v[72:75]
	v_mfma_f32_16x16x32_bf16 v[124:127], v[132:135], v[148:151], v[124:127]
	v_mfma_f32_16x16x32_bf16 v[120:123], v[140:143], v[148:151], v[120:123]
	v_mfma_f32_16x16x32_bf16 v[108:111], v[132:135], v[156:159], v[108:111]
	v_mfma_f32_16x16x32_bf16 v[104:107], v[140:143], v[156:159], v[104:107]
	v_mfma_f32_16x16x32_bf16 v[92:95], v[132:135], v[180:183], v[92:95]
	v_mfma_f32_16x16x32_bf16 v[88:91], v[140:143], v[180:183], v[88:91]
	v_mfma_f32_16x16x32_bf16 v[76:79], v[132:135], v[198:201], v[76:79]
	v_mfma_f32_16x16x32_bf16 v[72:75], v[140:143], v[198:201], v[72:75]
	s_barrier
	s_add_i32 s45, 0, 0x1c000
	s_add_i32 s42, s44, s9
	v_add_u32_e32 v197, s45, v191
	s_mov_b32 m0, s42
	ds_read_b128 v[202:205], v197
	ds_read_b128 v[206:209], v197 offset:1024
	ds_read_b128 v[210:213], v197 offset:2048
	ds_read_b128 v[214:217], v197 offset:3072
	global_load_lds_dwordx4 v162, s[98:99]
	s_add_i32 m0, s42, 0x2000
	s_nop 0
	global_load_lds_dwordx4 v166, s[98:99]
	s_barrier
	s_waitcnt lgkmcnt(0)
	v_mfma_f32_16x16x32_bf16 v[116:119], v[202:205], v[144:147], v[116:119]
	v_mfma_f32_16x16x32_bf16 v[112:115], v[210:213], v[144:147], v[112:115]
	v_mfma_f32_16x16x32_bf16 v[100:103], v[202:205], v[152:155], v[100:103]
	v_mfma_f32_16x16x32_bf16 v[96:99], v[210:213], v[152:155], v[96:99]
	v_mfma_f32_16x16x32_bf16 v[84:87], v[202:205], v[176:179], v[84:87]
	v_mfma_f32_16x16x32_bf16 v[80:83], v[210:213], v[176:179], v[80:83]
	v_mfma_f32_16x16x32_bf16 v[68:71], v[202:205], v[184:187], v[68:71]
	v_mfma_f32_16x16x32_bf16 v[64:67], v[210:213], v[184:187], v[64:67]
	v_mfma_f32_16x16x32_bf16 v[116:119], v[206:209], v[148:151], v[116:119]
	v_mfma_f32_16x16x32_bf16 v[112:115], v[214:217], v[148:151], v[112:115]
	v_mfma_f32_16x16x32_bf16 v[100:103], v[206:209], v[156:159], v[100:103]
	v_mfma_f32_16x16x32_bf16 v[96:99], v[214:217], v[156:159], v[96:99]
	v_mfma_f32_16x16x32_bf16 v[84:87], v[206:209], v[180:183], v[84:87]
	v_mfma_f32_16x16x32_bf16 v[80:83], v[214:217], v[180:183], v[80:83]
	v_mfma_f32_16x16x32_bf16 v[68:71], v[206:209], v[198:201], v[68:71]
	v_mfma_f32_16x16x32_bf16 v[64:67], v[214:217], v[198:201], v[64:67]
	s_mov_b32 m0, s15
	s_barrier
	ds_read_b128 v[144:147], v194 offset:49152
	ds_read_b128 v[148:151], v194 offset:50176
	ds_read_b128 v[152:155], v194 offset:51200
	ds_read_b128 v[156:159], v194 offset:52224
	ds_read_b128 v[176:179], v194 offset:53248
	ds_read_b128 v[180:183], v194 offset:54272
	ds_read_b128 v[184:187], v194 offset:55296
	ds_read_b128 v[198:201], v194 offset:56320
	global_load_lds_dwordx4 v160, s[100:101]
	s_mov_b32 m0, s22
	s_nop 0
	global_load_lds_dwordx4 v164, s[100:101]
	s_waitcnt vmcnt(10)
	s_barrier
	s_waitcnt lgkmcnt(0)
	v_mfma_f32_16x16x32_bf16 v[60:63], v[128:131], v[144:147], v[60:63]
	v_mfma_f32_16x16x32_bf16 v[56:59], v[136:139], v[144:147], v[56:59]
	v_mfma_f32_16x16x32_bf16 v[44:47], v[128:131], v[152:155], v[44:47]
	v_mfma_f32_16x16x32_bf16 v[40:43], v[136:139], v[152:155], v[40:43]
	v_mfma_f32_16x16x32_bf16 v[28:31], v[128:131], v[176:179], v[28:31]
	v_mfma_f32_16x16x32_bf16 v[24:27], v[136:139], v[176:179], v[24:27]
	v_mfma_f32_16x16x32_bf16 v[12:15], v[128:131], v[184:187], v[12:15]
	v_mfma_f32_16x16x32_bf16 v[8:11], v[136:139], v[184:187], v[8:11]
	v_mfma_f32_16x16x32_bf16 v[60:63], v[132:135], v[148:151], v[60:63]
	v_mfma_f32_16x16x32_bf16 v[56:59], v[140:143], v[148:151], v[56:59]
	v_mfma_f32_16x16x32_bf16 v[44:47], v[132:135], v[156:159], v[44:47]
	v_mfma_f32_16x16x32_bf16 v[40:43], v[140:143], v[156:159], v[40:43]
	v_mfma_f32_16x16x32_bf16 v[28:31], v[132:135], v[180:183], v[28:31]
	v_mfma_f32_16x16x32_bf16 v[24:27], v[140:143], v[180:183], v[24:27]
	v_mfma_f32_16x16x32_bf16 v[12:15], v[132:135], v[198:201], v[12:15]
	v_mfma_f32_16x16x32_bf16 v[8:11], v[140:143], v[198:201], v[8:11]
	s_barrier
	s_add_u32 s42, s76, 0x80080
	s_addc_u32 s43, s77, 0
	s_add_i32 s44, s45, s9
	s_mov_b32 m0, s44
	s_nop 0
	global_load_lds_dwordx4 v162, s[42:43]
	s_add_i32 m0, s44, 0x2000
	s_nop 0
	global_load_lds_dwordx4 v166, s[42:43]
	ds_read_b128 v[128:131], v193
	ds_read_b128 v[132:135], v193 offset:1024
	ds_read_b128 v[136:139], v193 offset:2048
	ds_read_b128 v[140:143], v193 offset:3072
	s_waitcnt vmcnt(6)
	s_branch .LBB0_717

; #define PG8_STAGE(bufoff, gbase, voff) do { _Pragma("unroll") for (int _i = 0; _i < 2; ++_i) \
;         __builtin_amdgcn_global_load_lds((const unsigned*)((const char*)(gbase) + (voff)[_i]), (LAS unsigned*)(lds + (bufoff) + ldsw + _i * 8192), 16, 0, 0); } while (0)
; #define PG8_LDA(dst, b, h) do { _Pragma("unroll") for (int m = 0; m < 4; ++m) _Pragma("unroll") for (int k = 0; k < 2; ++k) dst[m][k] = *(const LAS bf16x8*)(lds + PG8_SA(b, h) + aoff + m * 2048 + k * 1024); } while (0)
; #define PG8_LDB(dst, b, h) do { _Pragma("unroll") for (int n = 0; n < 2; ++n) _Pragma("unroll") for (int k = 0; k < 2; ++k) dst[n][k] = *(const LAS bf16x8*)(lds + PG8_SB(b, h) + boff + n * 2048 + k * 1024); } while (0)
; #define PG8_MMA(ai, bj, At, Bt) do { __builtin_amdgcn_s_setprio(1); _Pragma("unroll") for (int m = 0; m < 4; ++m) _Pragma("unroll") for (int n = 0; n < 2; ++n) _Pragma("unroll") for (int k = 0; k < 2; ++k) \
;         acc[ai][bj][m][n] = __builtin_amdgcn_mfma_f32_16x16x32_bf16(Bt[n][k], At[m][k], acc[ai][bj][m][n], 0, 0, 0); __builtin_amdgcn_s_setprio(0); } while (0)
; #define PG8_WAIT_V(n) asm volatile("s_waitcnt vmcnt(" #n ")" ::: "memory")
; #define PG8_WAIT_L(n) asm volatile("s_waitcnt lgkmcnt(" #n ")" ::: "memory")
; #define PG8_BAR __builtin_amdgcn_s_barrier()
; template <class Epi>
; __device__ __forceinline__ void gemm_phase(LAS unsigned char* lds, const Gemm g, const StaticOrder& S, const Epi& E, int wv) {
;     ...
;             const bool last = (t == nt - 2);
;             const char* a1 = cA + (ptrdiff_t)(t + 1) * kstep;
;             const char* a2 = last ? nA : cA + (ptrdiff_t)(t + 2) * kstep; const char* b2 = last ? nB : cB + (ptrdiff_t)(t + 2) * kstep;
;             const char* a3 = a2 + kstep; const char* b3 = b2 + kstep;
;             PG8_LDB(B0, 0, 0); PG8_SCHED; PG8_LDA(At, 0, 0); PG8_STAGE(PG8_SA(1, 1), a1 + hstepA, voffA);
;             PG8_WAIT_L(8); PG8_BAR; PG8_WAIT_L(0); PG8_MMA(0, 0, At, B0); PG8_BAR; PG8_SCHED;
;             PG8_LDB(B1, 0, 1); PG8_STAGE(PG8_SB(0, 0), b2, voffB);
;             PG8_BAR; PG8_WAIT_L(0); PG8_MMA(0, 1, At, B1); PG8_BAR;
;             PG8_LDA(At, 0, 1); PG8_STAGE(PG8_SA(0, 0), a2, voffA);
;             PG8_BAR; PG8_WAIT_L(0); PG8_MMA(1, 0, At, B0); PG8_BAR; PG8_SCHED;
;             PG8_STAGE(PG8_SB(0, 1), b2 + hstepB, voffB);
;             PG8_WAIT_V(6); PG8_BAR; PG8_MMA(1, 1, At, B1); PG8_BAR;
.Lrot_in_958:
	s_add_u32 s50, s48, 0xfff80080
	s_addc_u32 s51, s49, -1
	s_cmp_eq_u32 s70, 28
	s_cselect_b32 s53, s11, s51
	s_cselect_b32 s52, s41, s50
	s_cselect_b32 s51, s39, s69
	s_cselect_b32 s50, s47, s68
	s_add_i32 m0, s24, 0xc000
	ds_read_b128 v[168:171], v156
	ds_read_b128 v[172:175], v156 offset:1024
	ds_read_b128 v[176:179], v156 offset:2048
	ds_read_b128 v[180:183], v156 offset:3072
	ds_read_b128 v[184:187], v156 offset:4096
	ds_read_b128 v[188:191], v156 offset:5120
	ds_read_b128 v[192:195], v156 offset:6144
	ds_read_b128 v[196:199], v156 offset:7168
	global_load_lds_dwordx4 v138, s[48:49]
	s_add_i32 m0, s24, 0xe000
	s_nop 0
	global_load_lds_dwordx4 v136, s[48:49]
	s_waitcnt lgkmcnt(8)
	s_barrier
	s_waitcnt lgkmcnt(0)
	v_mfma_f32_16x16x32_bf16 v[124:127], v[144:147], v[168:171], v[124:127]
	v_mfma_f32_16x16x32_bf16 v[120:123], v[160:163], v[168:171], v[120:123]
	v_mfma_f32_16x16x32_bf16 v[108:111], v[144:147], v[176:179], v[108:111]
	v_mfma_f32_16x16x32_bf16 v[104:107], v[160:163], v[176:179], v[104:107]
	v_mfma_f32_16x16x32_bf16 v[92:95], v[144:147], v[184:187], v[92:95]
	v_mfma_f32_16x16x32_bf16 v[88:91], v[160:163], v[184:187], v[88:91]
	v_mfma_f32_16x16x32_bf16 v[76:79], v[144:147], v[192:195], v[76:79]
	v_mfma_f32_16x16x32_bf16 v[72:75], v[160:163], v[192:195], v[72:75]
	v_mfma_f32_16x16x32_bf16 v[124:127], v[148:151], v[172:175], v[124:127]
	v_mfma_f32_16x16x32_bf16 v[120:123], v[164:167], v[172:175], v[120:123]
	v_mfma_f32_16x16x32_bf16 v[108:111], v[148:151], v[180:183], v[108:111]
	v_mfma_f32_16x16x32_bf16 v[104:107], v[164:167], v[180:183], v[104:107]
	v_mfma_f32_16x16x32_bf16 v[92:95], v[148:151], v[188:191], v[92:95]
	v_mfma_f32_16x16x32_bf16 v[88:91], v[164:167], v[188:191], v[88:91]
	v_mfma_f32_16x16x32_bf16 v[76:79], v[148:151], v[196:199], v[76:79]
	v_mfma_f32_16x16x32_bf16 v[72:75], v[164:167], v[196:199], v[72:75]
	s_barrier
	s_add_i32 s71, s60, s23
	s_add_u32 s98, s50, s16
	s_addc_u32 s99, s51, s17
	s_mov_b32 m0, s71
	ds_read_b128 v[200:203], v157
	ds_read_b128 v[204:207], v157 offset:1024
	ds_read_b128 v[208:211], v157 offset:2048
	ds_read_b128 v[212:215], v157 offset:3072
	global_load_lds_dwordx4 v130, s[50:51]
	s_add_i32 m0, s71, 0x2000
	s_nop 0
	global_load_lds_dwordx4 v134, s[50:51]
	s_barrier
	s_waitcnt lgkmcnt(0)
	v_mfma_f32_16x16x32_bf16 v[116:119], v[200:203], v[168:171], v[116:119]
	v_mfma_f32_16x16x32_bf16 v[112:115], v[208:211], v[168:171], v[112:115]
	v_mfma_f32_16x16x32_bf16 v[100:103], v[200:203], v[176:179], v[100:103]
	v_mfma_f32_16x16x32_bf16 v[96:99], v[208:211], v[176:179], v[96:99]
	v_mfma_f32_16x16x32_bf16 v[84:87], v[200:203], v[184:187], v[84:87]
	v_mfma_f32_16x16x32_bf16 v[80:83], v[208:211], v[184:187], v[80:83]
	v_mfma_f32_16x16x32_bf16 v[68:71], v[200:203], v[192:195], v[68:71]
	v_mfma_f32_16x16x32_bf16 v[64:67], v[208:211], v[192:195], v[64:67]
	v_mfma_f32_16x16x32_bf16 v[116:119], v[204:207], v[172:175], v[116:119]
	v_mfma_f32_16x16x32_bf16 v[112:115], v[212:215], v[172:175], v[112:115]
	v_mfma_f32_16x16x32_bf16 v[100:103], v[204:207], v[180:183], v[100:103]
	v_mfma_f32_16x16x32_bf16 v[96:99], v[212:215], v[180:183], v[96:99]
	v_mfma_f32_16x16x32_bf16 v[84:87], v[204:207], v[188:191], v[84:87]
	v_mfma_f32_16x16x32_bf16 v[80:83], v[212:215], v[188:191], v[80:83]
	v_mfma_f32_16x16x32_bf16 v[68:71], v[204:207], v[196:199], v[68:71]
	v_mfma_f32_16x16x32_bf16 v[64:67], v[212:215], v[196:199], v[64:67]
	s_mov_b32 m0, s24
	s_add_u32 s100, s52, s16
	s_addc_u32 s101, s53, s17
	s_barrier
	ds_read_b128 v[168:171], v156 offset:16384
	ds_read_b128 v[172:175], v156 offset:17408
	ds_read_b128 v[176:179], v156 offset:18432
	ds_read_b128 v[180:183], v156 offset:19456
	ds_read_b128 v[184:187], v156 offset:20480
	ds_read_b128 v[188:191], v156 offset:21504
	ds_read_b128 v[192:195], v156 offset:22528
	ds_read_b128 v[196:199], v156 offset:23552
	global_load_lds_dwordx4 v128, s[52:53]
	s_mov_b32 m0, s25
	s_nop 0
	global_load_lds_dwordx4 v132, s[52:53]
	s_waitcnt vmcnt(10)
	s_barrier
	s_waitcnt lgkmcnt(0)
	v_mfma_f32_16x16x32_bf16 v[60:63], v[144:147], v[168:171], v[60:63]
	v_mfma_f32_16x16x32_bf16 v[56:59], v[160:163], v[168:171], v[56:59]
	v_mfma_f32_16x16x32_bf16 v[44:47], v[144:147], v[176:179], v[44:47]
	v_mfma_f32_16x16x32_bf16 v[40:43], v[160:163], v[176:179], v[40:43]
	v_mfma_f32_16x16x32_bf16 v[28:31], v[144:147], v[184:187], v[28:31]
	v_mfma_f32_16x16x32_bf16 v[24:27], v[160:163], v[184:187], v[24:27]
	v_mfma_f32_16x16x32_bf16 v[12:15], v[144:147], v[192:195], v[12:15]
	v_mfma_f32_16x16x32_bf16 v[8:11], v[160:163], v[192:195], v[8:11]
	v_mfma_f32_16x16x32_bf16 v[60:63], v[148:151], v[172:175], v[60:63]
	v_mfma_f32_16x16x32_bf16 v[56:59], v[164:167], v[172:175], v[56:59]
	v_mfma_f32_16x16x32_bf16 v[44:47], v[148:151], v[180:183], v[44:47]
	v_mfma_f32_16x16x32_bf16 v[40:43], v[164:167], v[180:183], v[40:43]
	v_mfma_f32_16x16x32_bf16 v[28:31], v[148:151], v[188:191], v[28:31]
	v_mfma_f32_16x16x32_bf16 v[24:27], v[164:167], v[188:191], v[24:27]
	v_mfma_f32_16x16x32_bf16 v[12:15], v[148:151], v[196:199], v[12:15]
	v_mfma_f32_16x16x32_bf16 v[8:11], v[164:167], v[196:199], v[8:11]
	s_barrier
	s_add_u32 s72, s50, 0x80000
	s_addc_u32 s73, s51, 0
	s_add_i32 s71, s61, s23
	s_mov_b32 m0, s71
	s_nop 0
	global_load_lds_dwordx4 v130, s[72:73]
	s_add_i32 m0, s71, 0x2000
	s_nop 0
	global_load_lds_dwordx4 v134, s[72:73]
	s_add_i32 s71, 0, 0x18000
	v_add_u32_e32 v159, s71, v153
	ds_read_b128 v[144:147], v159
	ds_read_b128 v[148:151], v159 offset:1024
	ds_read_b128 v[160:163], v159 offset:2048
	ds_read_b128 v[164:167], v159 offset:3072
	s_waitcnt vmcnt(6)
	s_barrier
; #define PG8_STAGE(bufoff, gbase, voff) do { _Pragma("unroll") for (int _i = 0; _i < 2; ++_i) \
;         __builtin_amdgcn_global_load_lds((const unsigned*)((const char*)(gbase) + (voff)[_i]), (LAS unsigned*)(lds + (bufoff) + ldsw + _i * 8192), 16, 0, 0); } while (0)
; #define PG8_LDA(dst, b, h) do { _Pragma("unroll") for (int m = 0; m < 4; ++m) _Pragma("unroll") for (int k = 0; k < 2; ++k) dst[m][k] = *(const LAS bf16x8*)(lds + PG8_SA(b, h) + aoff + m * 2048 + k * 1024); } while (0)
; #define PG8_LDB(dst, b, h) do { _Pragma("unroll") for (int n = 0; n < 2; ++n) _Pragma("unroll") for (int k = 0; k < 2; ++k) dst[n][k] = *(const LAS bf16x8*)(lds + PG8_SB(b, h) + boff + n * 2048 + k * 1024); } while (0)
; #define PG8_MMA(ai, bj, At, Bt) do { __builtin_amdgcn_s_setprio(1); _Pragma("unroll") for (int m = 0; m < 4; ++m) _Pragma("unroll") for (int n = 0; n < 2; ++n) _Pragma("unroll") for (int k = 0; k < 2; ++k) \
;         acc[ai][bj][m][n] = __builtin_amdgcn_mfma_f32_16x16x32_bf16(Bt[n][k], At[m][k], acc[ai][bj][m][n], 0, 0, 0); __builtin_amdgcn_s_setprio(0); } while (0)
; #define PG8_WAIT_V(n) asm volatile("s_waitcnt vmcnt(" #n ")" ::: "memory")
; #define PG8_WAIT_L(n) asm volatile("s_waitcnt lgkmcnt(" #n ")" ::: "memory")
; #define PG8_BAR __builtin_amdgcn_s_barrier()
; #define PG8_SCHED __builtin_amdgcn_sched_barrier(0)
; template <class Epi>
; __device__ __forceinline__ void gemm_phase(LAS unsigned char* lds, const Gemm g, const StaticOrder& S, const Epi& E, int wv) {
;     ...
;             PG8_WAIT_V(6); PG8_BAR; PG8_MMA(1, 1, At, B1); PG8_BAR;
;             PG8_LDB(B0, 1, 0); PG8_SCHED; PG8_LDA(At, 1, 0); PG8_STAGE(PG8_SA(0, 1), a2 + hstepA, voffA);
;             PG8_WAIT_L(8); PG8_BAR; PG8_WAIT_L(0); PG8_MMA(0, 0, At, B0); PG8_BAR; PG8_SCHED;
;             PG8_LDB(B1, 1, 1); PG8_STAGE(PG8_SB(1, 0), b3, voffB);
;             PG8_BAR; PG8_WAIT_L(0); PG8_MMA(0, 1, At, B1); PG8_BAR;
;             PG8_LDA(At, 1, 1); PG8_STAGE(PG8_SA(1, 0), a3, voffA);
;             PG8_BAR; PG8_WAIT_L(0); PG8_MMA(1, 0, At, B0); PG8_BAR; PG8_SCHED;
;             PG8_STAGE(PG8_SB(1, 1), b3 + hstepB, voffB);
;             PG8_WAIT_V(6); PG8_BAR; PG8_MMA(1, 1, At, B1); PG8_BAR;
	v_mfma_f32_16x16x32_bf16 v[52:55], v[200:203], v[168:171], v[52:55]
	v_mfma_f32_16x16x32_bf16 v[48:51], v[208:211], v[168:171], v[48:51]
	v_mfma_f32_16x16x32_bf16 v[36:39], v[200:203], v[176:179], v[36:39]
	v_mfma_f32_16x16x32_bf16 v[32:35], v[208:211], v[176:179], v[32:35]
	v_mfma_f32_16x16x32_bf16 v[20:23], v[200:203], v[184:187], v[20:23]
	v_mfma_f32_16x16x32_bf16 v[16:19], v[208:211], v[184:187], v[16:19]
	v_mfma_f32_16x16x32_bf16 v[4:7], v[200:203], v[192:195], v[4:7]
	v_mfma_f32_16x16x32_bf16 v[0:3], v[208:211], v[192:195], v[0:3]
	v_mfma_f32_16x16x32_bf16 v[52:55], v[204:207], v[172:175], v[52:55]
	v_mfma_f32_16x16x32_bf16 v[48:51], v[212:215], v[172:175], v[48:51]
	v_mfma_f32_16x16x32_bf16 v[36:39], v[204:207], v[180:183], v[36:39]
	v_mfma_f32_16x16x32_bf16 v[32:35], v[212:215], v[180:183], v[32:35]
	v_mfma_f32_16x16x32_bf16 v[20:23], v[204:207], v[188:191], v[20:23]
	v_mfma_f32_16x16x32_bf16 v[16:19], v[212:215], v[188:191], v[16:19]
	v_mfma_f32_16x16x32_bf16 v[4:7], v[204:207], v[196:199], v[4:7]
	v_mfma_f32_16x16x32_bf16 v[0:3], v[212:215], v[196:199], v[0:3]
	s_waitcnt lgkmcnt(0)
	s_barrier
	s_add_u32 s52, s52, 0x80000
	s_addc_u32 s53, s53, 0
	s_mov_b32 m0, s33
	ds_read_b128 v[168:171], v156 offset:32768
	ds_read_b128 v[172:175], v156 offset:33792
	ds_read_b128 v[176:179], v156 offset:34816
	ds_read_b128 v[180:183], v156 offset:35840
	ds_read_b128 v[184:187], v156 offset:36864
	ds_read_b128 v[188:191], v156 offset:37888
	ds_read_b128 v[192:195], v156 offset:38912
	ds_read_b128 v[196:199], v156 offset:39936
	global_load_lds_dwordx4 v128, s[52:53]
	s_mov_b32 m0, s54
	s_nop 0
	global_load_lds_dwordx4 v132, s[52:53]
	s_waitcnt lgkmcnt(8)
	s_barrier
	s_waitcnt lgkmcnt(0)
	v_mfma_f32_16x16x32_bf16 v[124:127], v[144:147], v[168:171], v[124:127]
	v_mfma_f32_16x16x32_bf16 v[120:123], v[160:163], v[168:171], v[120:123]
	v_mfma_f32_16x16x32_bf16 v[108:111], v[144:147], v[176:179], v[108:111]
	v_mfma_f32_16x16x32_bf16 v[104:107], v[160:163], v[176:179], v[104:107]
	v_mfma_f32_16x16x32_bf16 v[92:95], v[144:147], v[184:187], v[92:95]
	v_mfma_f32_16x16x32_bf16 v[88:91], v[160:163], v[184:187], v[88:91]
	v_mfma_f32_16x16x32_bf16 v[76:79], v[144:147], v[192:195], v[76:79]
	v_mfma_f32_16x16x32_bf16 v[72:75], v[160:163], v[192:195], v[72:75]
	v_mfma_f32_16x16x32_bf16 v[124:127], v[148:151], v[172:175], v[124:127]
	v_mfma_f32_16x16x32_bf16 v[120:123], v[164:167], v[172:175], v[120:123]
	v_mfma_f32_16x16x32_bf16 v[108:111], v[148:151], v[180:183], v[108:111]
	v_mfma_f32_16x16x32_bf16 v[104:107], v[164:167], v[180:183], v[104:107]
	v_mfma_f32_16x16x32_bf16 v[92:95], v[148:151], v[188:191], v[92:95]
	v_mfma_f32_16x16x32_bf16 v[88:91], v[164:167], v[188:191], v[88:91]
	v_mfma_f32_16x16x32_bf16 v[76:79], v[148:151], v[196:199], v[76:79]
	v_mfma_f32_16x16x32_bf16 v[72:75], v[164:167], v[196:199], v[72:75]
	s_barrier
	s_add_i32 s52, 0, 0x1c000
	s_add_i32 s53, s71, s23
	v_add_u32_e32 v159, s52, v153
	s_mov_b32 m0, s53
	ds_read_b128 v[200:203], v159
	ds_read_b128 v[204:207], v159 offset:1024
	ds_read_b128 v[208:211], v159 offset:2048
	ds_read_b128 v[212:215], v159 offset:3072
	global_load_lds_dwordx4 v130, s[98:99]
	s_add_i32 m0, s53, 0x2000
	s_nop 0
	global_load_lds_dwordx4 v134, s[98:99]
	s_barrier
	s_waitcnt lgkmcnt(0)
	v_mfma_f32_16x16x32_bf16 v[116:119], v[200:203], v[168:171], v[116:119]
	v_mfma_f32_16x16x32_bf16 v[112:115], v[208:211], v[168:171], v[112:115]
	v_mfma_f32_16x16x32_bf16 v[100:103], v[200:203], v[176:179], v[100:103]
	v_mfma_f32_16x16x32_bf16 v[96:99], v[208:211], v[176:179], v[96:99]
	v_mfma_f32_16x16x32_bf16 v[84:87], v[200:203], v[184:187], v[84:87]
	v_mfma_f32_16x16x32_bf16 v[80:83], v[208:211], v[184:187], v[80:83]
	v_mfma_f32_16x16x32_bf16 v[68:71], v[200:203], v[192:195], v[68:71]
	v_mfma_f32_16x16x32_bf16 v[64:67], v[208:211], v[192:195], v[64:67]
	v_mfma_f32_16x16x32_bf16 v[116:119], v[204:207], v[172:175], v[116:119]
	v_mfma_f32_16x16x32_bf16 v[112:115], v[212:215], v[172:175], v[112:115]
	v_mfma_f32_16x16x32_bf16 v[100:103], v[204:207], v[180:183], v[100:103]
	v_mfma_f32_16x16x32_bf16 v[96:99], v[212:215], v[180:183], v[96:99]
	v_mfma_f32_16x16x32_bf16 v[84:87], v[204:207], v[188:191], v[84:87]
	v_mfma_f32_16x16x32_bf16 v[80:83], v[212:215], v[188:191], v[80:83]
	v_mfma_f32_16x16x32_bf16 v[68:71], v[204:207], v[196:199], v[68:71]
	v_mfma_f32_16x16x32_bf16 v[64:67], v[212:215], v[196:199], v[64:67]
	s_mov_b32 m0, s58
	s_barrier
	ds_read_b128 v[168:171], v156 offset:49152
	ds_read_b128 v[172:175], v156 offset:50176
	ds_read_b128 v[176:179], v156 offset:51200
	ds_read_b128 v[180:183], v156 offset:52224
	ds_read_b128 v[184:187], v156 offset:53248
	ds_read_b128 v[188:191], v156 offset:54272
	ds_read_b128 v[192:195], v156 offset:55296
	ds_read_b128 v[196:199], v156 offset:56320
	global_load_lds_dwordx4 v128, s[100:101]
	s_mov_b32 m0, s59
	s_nop 0
	global_load_lds_dwordx4 v132, s[100:101]
	s_waitcnt vmcnt(10)
	s_barrier
	s_waitcnt lgkmcnt(0)
	v_mfma_f32_16x16x32_bf16 v[60:63], v[144:147], v[168:171], v[60:63]
	v_mfma_f32_16x16x32_bf16 v[56:59], v[160:163], v[168:171], v[56:59]
	v_mfma_f32_16x16x32_bf16 v[44:47], v[144:147], v[176:179], v[44:47]
	v_mfma_f32_16x16x32_bf16 v[40:43], v[160:163], v[176:179], v[40:43]
	v_mfma_f32_16x16x32_bf16 v[28:31], v[144:147], v[184:187], v[28:31]
	v_mfma_f32_16x16x32_bf16 v[24:27], v[160:163], v[184:187], v[24:27]
	v_mfma_f32_16x16x32_bf16 v[12:15], v[144:147], v[192:195], v[12:15]
	v_mfma_f32_16x16x32_bf16 v[8:11], v[160:163], v[192:195], v[8:11]
	v_mfma_f32_16x16x32_bf16 v[60:63], v[148:151], v[172:175], v[60:63]
	v_mfma_f32_16x16x32_bf16 v[56:59], v[164:167], v[172:175], v[56:59]
	v_mfma_f32_16x16x32_bf16 v[44:47], v[148:151], v[180:183], v[44:47]
	v_mfma_f32_16x16x32_bf16 v[40:43], v[164:167], v[180:183], v[40:43]
	v_mfma_f32_16x16x32_bf16 v[28:31], v[148:151], v[188:191], v[28:31]
	v_mfma_f32_16x16x32_bf16 v[24:27], v[164:167], v[188:191], v[24:27]
	v_mfma_f32_16x16x32_bf16 v[12:15], v[148:151], v[196:199], v[12:15]
	v_mfma_f32_16x16x32_bf16 v[8:11], v[164:167], v[196:199], v[8:11]
	s_barrier
	s_add_u32 s50, s50, 0x80080
	s_addc_u32 s51, s51, 0
	s_add_i32 s52, s52, s23
	s_mov_b32 m0, s52
	s_nop 0
	global_load_lds_dwordx4 v130, s[50:51]
	s_add_i32 m0, s52, 0x2000
	s_nop 0
	global_load_lds_dwordx4 v134, s[50:51]
	ds_read_b128 v[144:147], v155
	ds_read_b128 v[148:151], v155 offset:1024
	ds_read_b128 v[160:163], v155 offset:2048
	ds_read_b128 v[164:167], v155 offset:3072
	s_waitcnt vmcnt(6)
	s_branch .LBB0_958

; #define PG8_STAGE(bufoff, gbase, voff) do { _Pragma("unroll") for (int _i = 0; _i < 2; ++_i) \
;         __builtin_amdgcn_global_load_lds((const unsigned*)((const char*)(gbase) + (voff)[_i]), (LAS unsigned*)(lds + (bufoff) + ldsw + _i * 8192), 16, 0, 0); } while (0)
; #define PG8_LDA(dst, b, h) do { _Pragma("unroll") for (int m = 0; m < 4; ++m) _Pragma("unroll") for (int k = 0; k < 2; ++k) dst[m][k] = *(const LAS bf16x8*)(lds + PG8_SA(b, h) + aoff + m * 2048 + k * 1024); } while (0)
; #define PG8_LDB(dst, b, h) do { _Pragma("unroll") for (int n = 0; n < 2; ++n) _Pragma("unroll") for (int k = 0; k < 2; ++k) dst[n][k] = *(const LAS bf16x8*)(lds + PG8_SB(b, h) + boff + n * 2048 + k * 1024); } while (0)
; #define PG8_MMA(ai, bj, At, Bt) do { __builtin_amdgcn_s_setprio(1); _Pragma("unroll") for (int m = 0; m < 4; ++m) _Pragma("unroll") for (int n = 0; n < 2; ++n) _Pragma("unroll") for (int k = 0; k < 2; ++k) \
;         acc[ai][bj][m][n] = __builtin_amdgcn_mfma_f32_16x16x32_bf16(Bt[n][k], At[m][k], acc[ai][bj][m][n], 0, 0, 0); __builtin_amdgcn_s_setprio(0); } while (0)
; template <class Epi>
; __device__ __forceinline__ void gemm_phase(LAS unsigned char* lds, const Gemm g, const StaticOrder& S, const Epi& E, int wv) {
;     ...
;         const bool has_next = S.next(ui + 1, nxt);
;         const char* nA = has_next ? (const char*)g.A + (size_t)nxt.pm * tstepA + ((g.adiag & 1) ? (size_t)(nxt.pn >> 1) * K * 2 : 0) + kbeg : cA;
;         const char* nB = has_next ? (const char*)g.Bt + (size_t)nxt.pn * tstepB + kbeg : cB;
;         for (int t = 0; t < nt; t += 2) {
;             const bool last = (t == nt - 2);
;             const char* a1 = cA + (ptrdiff_t)(t + 1) * kstep;
;             const char* a2 = last ? nA : cA + (ptrdiff_t)(t + 2) * kstep; const char* b2 = last ? nB : cB + (ptrdiff_t)(t + 2) * kstep;
;             const char* a3 = a2 + kstep; const char* b3 = b2 + kstep;
;             PG8_LDB(B0, 0, 0); PG8_SCHED; PG8_LDA(At, 0, 0); PG8_STAGE(PG8_SA(1, 1), a1 + hstepA, voffA);
;             PG8_WAIT_L(8); PG8_BAR; PG8_WAIT_L(0); PG8_MMA(0, 0, At, B0); PG8_BAR; PG8_SCHED;
;             PG8_LDB(B1, 0, 1); PG8_STAGE(PG8_SB(0, 0), b2, voffB);
;             PG8_BAR; PG8_WAIT_L(0); PG8_MMA(0, 1, At, B1); PG8_BAR;
;             PG8_LDA(At, 0, 1); PG8_STAGE(PG8_SA(0, 0), a2, voffA);
;             PG8_BAR; PG8_WAIT_L(0); PG8_MMA(1, 0, At, B0); PG8_BAR; PG8_SCHED;
.LBB0_1126:
	s_ashr_i32 s51, s50, 31
	s_lshl_b64 s[52:53], s[50:51], 20
	s_add_u32 s49, s69, s52
	s_addc_u32 s51, s70, s53
	s_ashr_i32 s52, s48, 1
	s_ashr_i32 s53, s52, 31
	s_lshl_b64 s[52:53], s[52:53], 9
	s_add_u32 s52, s49, s52
	v_cmp_lt_i64_e32 vcc, s[46:47], v[148:149]
	s_addc_u32 s53, s51, s53
	ds_read_b128 v[0:3], v205
	ds_read_b128 v[4:7], v205 offset:1024
	ds_read_b128 v[8:11], v205 offset:2048
	ds_read_b128 v[12:15], v205 offset:3072
	s_and_b64 s[54:55], vcc, exec
	s_cselect_b32 s67, s53, s61
	s_cselect_b32 s66, s52, s60
	s_ashr_i32 s49, s48, 31
	s_lshl_b64 s[54:55], s[48:49], 17
	s_add_u32 s54, s71, s54
	s_addc_u32 s55, s72, s55
	s_and_b64 s[64:65], vcc, exec
	s_cselect_b32 s65, s55, s63
	s_cselect_b32 s64, s54, s62
	s_add_u32 s76, s60, 0x80080
	s_addc_u32 s77, s61, 0
	s_add_i32 s79, s4, 0xc000
	v_lshl_add_u64 v[48:49], s[76:77], 0, v[140:141]
	s_mov_b32 m0, s79
	s_add_i32 s49, s4, 0xe000
	ds_read_b128 v[16:19], v206
	ds_read_b128 v[20:23], v206 offset:1024
	ds_read_b128 v[24:27], v206 offset:2048
	ds_read_b128 v[28:31], v206 offset:3072
	ds_read_b128 v[32:35], v206 offset:4096
	ds_read_b128 v[36:39], v206 offset:5120
	ds_read_b128 v[40:43], v206 offset:6144
	ds_read_b128 v[44:47], v206 offset:7168
	global_load_lds_dwordx4 v[48:49], off
	v_lshl_add_u64 v[48:49], s[76:77], 0, v[144:145]
	s_mov_b32 m0, s49
	s_nop 0
	global_load_lds_dwordx4 v[48:49], off
	s_waitcnt lgkmcnt(8)
	s_barrier
	s_waitcnt lgkmcnt(0)
	v_mfma_f32_16x16x32_bf16 v[48:51], v[0:3], v[16:19], 0
	v_mfma_f32_16x16x32_bf16 v[52:55], v[8:11], v[16:19], 0
	v_mfma_f32_16x16x32_bf16 v[56:59], v[0:3], v[24:27], 0
	v_mfma_f32_16x16x32_bf16 v[60:63], v[8:11], v[24:27], 0
	v_mfma_f32_16x16x32_bf16 v[64:67], v[0:3], v[32:35], 0
	v_mfma_f32_16x16x32_bf16 v[68:71], v[8:11], v[32:35], 0
	v_mfma_f32_16x16x32_bf16 v[72:75], v[0:3], v[40:43], 0
	v_mfma_f32_16x16x32_bf16 v[76:79], v[8:11], v[40:43], 0
	v_mfma_f32_16x16x32_bf16 v[48:51], v[4:7], v[20:23], v[48:51]
	v_mfma_f32_16x16x32_bf16 v[52:55], v[12:15], v[20:23], v[52:55]
	v_mfma_f32_16x16x32_bf16 v[56:59], v[4:7], v[28:31], v[56:59]
	v_mfma_f32_16x16x32_bf16 v[60:63], v[12:15], v[28:31], v[60:63]
	v_mfma_f32_16x16x32_bf16 v[64:67], v[4:7], v[36:39], v[64:67]
	v_mfma_f32_16x16x32_bf16 v[68:71], v[12:15], v[36:39], v[68:71]
	v_mfma_f32_16x16x32_bf16 v[72:75], v[4:7], v[44:47], v[72:75]
	v_mfma_f32_16x16x32_bf16 v[76:79], v[12:15], v[44:47], v[76:79]
	s_barrier
	v_lshl_add_u64 v[200:201], s[62:63], 0, v[142:143]
	s_add_i32 s76, s33, s73
	v_lshl_add_u64 v[96:97], v[200:201], 0, s[36:37]
	s_mov_b32 m0, s76
	v_lshl_add_u64 v[214:215], s[62:63], 0, v[146:147]
	s_add_i32 s51, s76, 0x2000
	ds_read_b128 v[80:83], v207
	ds_read_b128 v[84:87], v207 offset:1024
	ds_read_b128 v[88:91], v207 offset:2048
	ds_read_b128 v[92:95], v207 offset:3072
	global_load_lds_dwordx4 v[96:97], off
	v_lshl_add_u64 v[96:97], v[214:215], 0, s[36:37]
	s_mov_b32 m0, s51
	s_nop 0
	global_load_lds_dwordx4 v[96:97], off
	s_barrier
	s_waitcnt lgkmcnt(0)
	v_mfma_f32_16x16x32_bf16 v[96:99], v[80:83], v[16:19], 0
	v_mfma_f32_16x16x32_bf16 v[16:19], v[88:91], v[16:19], 0
	v_mfma_f32_16x16x32_bf16 v[96:99], v[84:87], v[20:23], v[96:99]
	v_mfma_f32_16x16x32_bf16 v[16:19], v[92:95], v[20:23], v[16:19]
	v_mfma_f32_16x16x32_bf16 v[20:23], v[80:83], v[24:27], 0
	v_mfma_f32_16x16x32_bf16 v[24:27], v[88:91], v[24:27], 0
	v_mfma_f32_16x16x32_bf16 v[20:23], v[84:87], v[28:31], v[20:23]
	v_mfma_f32_16x16x32_bf16 v[24:27], v[92:95], v[28:31], v[24:27]
	v_mfma_f32_16x16x32_bf16 v[28:31], v[80:83], v[32:35], 0
	v_mfma_f32_16x16x32_bf16 v[32:35], v[88:91], v[32:35], 0
	v_mfma_f32_16x16x32_bf16 v[28:31], v[84:87], v[36:39], v[28:31]
	v_mfma_f32_16x16x32_bf16 v[32:35], v[92:95], v[36:39], v[32:35]
	v_mfma_f32_16x16x32_bf16 v[36:39], v[80:83], v[40:43], 0
	v_mfma_f32_16x16x32_bf16 v[40:43], v[88:91], v[40:43], 0
	v_mfma_f32_16x16x32_bf16 v[36:39], v[84:87], v[44:47], v[36:39]
	v_mfma_f32_16x16x32_bf16 v[40:43], v[92:95], v[44:47], v[40:43]
	v_lshl_add_u64 v[216:217], s[60:61], 0, v[140:141]
	s_mov_b32 m0, s4
	v_lshl_add_u64 v[128:129], v[216:217], 0, s[36:37]
	v_lshl_add_u64 v[218:219], s[60:61], 0, v[144:145]
	s_barrier
	ds_read_b128 v[44:47], v206 offset:16384
	ds_read_b128 v[100:103], v206 offset:17408
	ds_read_b128 v[104:107], v206 offset:18432
	ds_read_b128 v[108:111], v206 offset:19456
	ds_read_b128 v[112:115], v206 offset:20480
	ds_read_b128 v[116:119], v206 offset:21504
	ds_read_b128 v[120:123], v206 offset:22528
	ds_read_b128 v[124:127], v206 offset:23552
	global_load_lds_dwordx4 v[128:129], off
	v_lshl_add_u64 v[128:129], v[218:219], 0, s[36:37]
	s_mov_b32 m0, s5
	s_nop 0
	global_load_lds_dwordx4 v[128:129], off
	s_barrier
	s_waitcnt lgkmcnt(0)
	v_mfma_f32_16x16x32_bf16 v[128:131], v[0:3], v[44:47], 0
	v_mfma_f32_16x16x32_bf16 v[136:139], v[0:3], v[104:107], 0
	v_mfma_f32_16x16x32_bf16 v[156:159], v[0:3], v[112:115], 0
	v_mfma_f32_16x16x32_bf16 v[0:3], v[0:3], v[120:123], 0
	v_mfma_f32_16x16x32_bf16 v[128:131], v[4:7], v[100:103], v[128:131]
	v_mfma_f32_16x16x32_bf16 v[132:135], v[8:11], v[44:47], 0
	v_mfma_f32_16x16x32_bf16 v[136:139], v[4:7], v[108:111], v[136:139]
	v_mfma_f32_16x16x32_bf16 v[152:155], v[8:11], v[104:107], 0
	v_mfma_f32_16x16x32_bf16 v[156:159], v[4:7], v[116:119], v[156:159]
	v_mfma_f32_16x16x32_bf16 v[160:163], v[8:11], v[112:115], 0
	v_mfma_f32_16x16x32_bf16 v[0:3], v[4:7], v[124:127], v[0:3]
	v_mfma_f32_16x16x32_bf16 v[4:7], v[8:11], v[120:123], 0
	v_mfma_f32_16x16x32_bf16 v[132:135], v[12:15], v[100:103], v[132:135]
	v_mfma_f32_16x16x32_bf16 v[152:155], v[12:15], v[108:111], v[152:155]
	v_mfma_f32_16x16x32_bf16 v[160:163], v[12:15], v[116:119], v[160:163]
	v_mfma_f32_16x16x32_bf16 v[4:7], v[12:15], v[124:127], v[4:7]
	s_barrier
; #define PG8_STAGE(bufoff, gbase, voff) do { _Pragma("unroll") for (int _i = 0; _i < 2; ++_i) \
;         __builtin_amdgcn_global_load_lds((const unsigned*)((const char*)(gbase) + (voff)[_i]), (LAS unsigned*)(lds + (bufoff) + ldsw + _i * 8192), 16, 0, 0); } while (0)
; #define PG8_LDA(dst, b, h) do { _Pragma("unroll") for (int m = 0; m < 4; ++m) _Pragma("unroll") for (int k = 0; k < 2; ++k) dst[m][k] = *(const LAS bf16x8*)(lds + PG8_SA(b, h) + aoff + m * 2048 + k * 1024); } while (0)
; #define PG8_LDB(dst, b, h) do { _Pragma("unroll") for (int n = 0; n < 2; ++n) _Pragma("unroll") for (int k = 0; k < 2; ++k) dst[n][k] = *(const LAS bf16x8*)(lds + PG8_SB(b, h) + boff + n * 2048 + k * 1024); } while (0)
; #define PG8_MMA(ai, bj, At, Bt) do { __builtin_amdgcn_s_setprio(1); _Pragma("unroll") for (int m = 0; m < 4; ++m) _Pragma("unroll") for (int n = 0; n < 2; ++n) _Pragma("unroll") for (int k = 0; k < 2; ++k) \
;         acc[ai][bj][m][n] = __builtin_amdgcn_mfma_f32_16x16x32_bf16(Bt[n][k], At[m][k], acc[ai][bj][m][n], 0, 0, 0); __builtin_amdgcn_s_setprio(0); } while (0)
; #define PG8_WAIT_V(n) asm volatile("s_waitcnt vmcnt(" #n ")" ::: "memory")
; #define PG8_WAIT_L(n) asm volatile("s_waitcnt lgkmcnt(" #n ")" ::: "memory")
; #define PG8_BAR __builtin_amdgcn_s_barrier()
; #define PG8_SCHED __builtin_amdgcn_sched_barrier(0)
; template <class Epi>
; __device__ __forceinline__ void gemm_phase(LAS unsigned char* lds, const Gemm g, const StaticOrder& S, const Epi& E, int wv) {
;     ...
;             PG8_STAGE(PG8_SB(0, 1), b2 + hstepB, voffB);
;             PG8_WAIT_V(6); PG8_BAR; PG8_MMA(1, 1, At, B1); PG8_BAR;
;             PG8_LDB(B0, 1, 0); PG8_SCHED; PG8_LDA(At, 1, 0); PG8_STAGE(PG8_SA(0, 1), a2 + hstepA, voffA);
;             PG8_WAIT_L(8); PG8_BAR; PG8_WAIT_L(0); PG8_MMA(0, 0, At, B0); PG8_BAR; PG8_SCHED;
;             PG8_LDB(B1, 1, 1); PG8_STAGE(PG8_SB(1, 0), b3, voffB);
;             PG8_BAR; PG8_WAIT_L(0); PG8_MMA(0, 1, At, B1); PG8_BAR;
	s_add_u32 s80, s62, 0x10100
	s_addc_u32 s81, s63, 0
	s_add_i32 s77, s59, s73
	v_lshl_add_u64 v[8:9], s[80:81], 0, v[142:143]
	s_mov_b32 m0, s77
	s_add_i32 s57, s77, 0x2000
	global_load_lds_dwordx4 v[8:9], off
	v_lshl_add_u64 v[8:9], s[80:81], 0, v[146:147]
	s_mov_b32 m0, s57
	s_nop 0
	global_load_lds_dwordx4 v[8:9], off
	s_waitcnt vmcnt(6)
	s_barrier
	v_mfma_f32_16x16x32_bf16 v[8:11], v[80:83], v[44:47], 0
	v_mfma_f32_16x16x32_bf16 v[12:15], v[88:91], v[44:47], 0
	v_mfma_f32_16x16x32_bf16 v[8:11], v[84:87], v[100:103], v[8:11]
	v_mfma_f32_16x16x32_bf16 v[12:15], v[92:95], v[100:103], v[12:15]
	v_mfma_f32_16x16x32_bf16 v[44:47], v[80:83], v[104:107], 0
	v_mfma_f32_16x16x32_bf16 v[100:103], v[88:91], v[104:107], 0
	v_mfma_f32_16x16x32_bf16 v[104:107], v[80:83], v[112:115], 0
	v_mfma_f32_16x16x32_bf16 v[80:83], v[80:83], v[120:123], 0
	v_mfma_f32_16x16x32_bf16 v[44:47], v[84:87], v[108:111], v[44:47]
	v_mfma_f32_16x16x32_bf16 v[100:103], v[92:95], v[108:111], v[100:103]
	v_mfma_f32_16x16x32_bf16 v[104:107], v[84:87], v[116:119], v[104:107]
	v_mfma_f32_16x16x32_bf16 v[108:111], v[88:91], v[112:115], 0
	v_mfma_f32_16x16x32_bf16 v[80:83], v[84:87], v[124:127], v[80:83]
	v_mfma_f32_16x16x32_bf16 v[84:87], v[88:91], v[120:123], 0
	v_mfma_f32_16x16x32_bf16 v[108:111], v[92:95], v[116:119], v[108:111]
	v_mfma_f32_16x16x32_bf16 v[84:87], v[92:95], v[124:127], v[84:87]
	s_add_i32 s78, 0, 0x18000
	v_add_u32_e32 v209, s78, v203
	s_barrier
	ds_read_b128 v[88:91], v209
	ds_read_b128 v[92:95], v209 offset:1024
	ds_read_b128 v[112:115], v209 offset:2048
	ds_read_b128 v[116:119], v209 offset:3072
	s_add_u32 s80, s60, 0x80100
	s_addc_u32 s81, s61, 0
	s_mov_b32 m0, s22
	v_lshl_add_u64 v[188:189], s[80:81], 0, v[140:141]
	ds_read_b128 v[120:123], v206 offset:32768
	ds_read_b128 v[124:127], v206 offset:33792
	ds_read_b128 v[164:167], v206 offset:34816
	ds_read_b128 v[168:171], v206 offset:35840
	ds_read_b128 v[172:175], v206 offset:36864
	ds_read_b128 v[176:179], v206 offset:37888
	ds_read_b128 v[180:183], v206 offset:38912
	ds_read_b128 v[184:187], v206 offset:39936
	global_load_lds_dwordx4 v[188:189], off
	v_lshl_add_u64 v[188:189], s[80:81], 0, v[144:145]
	s_mov_b32 m0, s23
	s_nop 0
	global_load_lds_dwordx4 v[188:189], off
	s_waitcnt lgkmcnt(8)
	s_barrier
	s_waitcnt lgkmcnt(0)
	v_mfma_f32_16x16x32_bf16 v[48:51], v[88:91], v[120:123], v[48:51]
	v_mfma_f32_16x16x32_bf16 v[52:55], v[112:115], v[120:123], v[52:55]
	v_mfma_f32_16x16x32_bf16 v[56:59], v[88:91], v[164:167], v[56:59]
	v_mfma_f32_16x16x32_bf16 v[60:63], v[112:115], v[164:167], v[60:63]
	v_mfma_f32_16x16x32_bf16 v[64:67], v[88:91], v[172:175], v[64:67]
	v_mfma_f32_16x16x32_bf16 v[68:71], v[112:115], v[172:175], v[68:71]
	v_mfma_f32_16x16x32_bf16 v[72:75], v[88:91], v[180:183], v[72:75]
	v_mfma_f32_16x16x32_bf16 v[76:79], v[112:115], v[180:183], v[76:79]
	v_mfma_f32_16x16x32_bf16 v[48:51], v[92:95], v[124:127], v[48:51]
	v_mfma_f32_16x16x32_bf16 v[52:55], v[116:119], v[124:127], v[52:55]
	v_mfma_f32_16x16x32_bf16 v[56:59], v[92:95], v[168:171], v[56:59]
	v_mfma_f32_16x16x32_bf16 v[60:63], v[116:119], v[168:171], v[60:63]
	v_mfma_f32_16x16x32_bf16 v[64:67], v[92:95], v[176:179], v[64:67]
	v_mfma_f32_16x16x32_bf16 v[68:71], v[116:119], v[176:179], v[68:71]
	v_mfma_f32_16x16x32_bf16 v[72:75], v[92:95], v[184:187], v[72:75]
	v_mfma_f32_16x16x32_bf16 v[76:79], v[116:119], v[184:187], v[76:79]
	s_barrier
	s_add_i32 s81, 0, 0x1c000
	s_add_i32 s80, s78, s73
	v_add_u32_e32 v250, s81, v203
	v_lshl_add_u64 v[200:201], v[200:201], 0, s[38:39]
	s_mov_b32 m0, s80
	s_add_i32 s78, s80, 0x2000
	ds_read_b128 v[188:191], v250
	ds_read_b128 v[192:195], v250 offset:1024
	ds_read_b128 v[196:199], v250 offset:2048
	ds_read_b128 v[210:213], v250 offset:3072
	global_load_lds_dwordx4 v[200:201], off
	v_lshl_add_u64 v[200:201], v[214:215], 0, s[38:39]
	s_mov_b32 m0, s78
	s_nop 0
	global_load_lds_dwordx4 v[200:201], off
	s_barrier
	s_waitcnt lgkmcnt(0)
	v_mfma_f32_16x16x32_bf16 v[96:99], v[188:191], v[120:123], v[96:99]
	v_mfma_f32_16x16x32_bf16 v[16:19], v[196:199], v[120:123], v[16:19]
	v_mfma_f32_16x16x32_bf16 v[20:23], v[188:191], v[164:167], v[20:23]
	v_mfma_f32_16x16x32_bf16 v[24:27], v[196:199], v[164:167], v[24:27]
	v_mfma_f32_16x16x32_bf16 v[28:31], v[188:191], v[172:175], v[28:31]
	v_mfma_f32_16x16x32_bf16 v[32:35], v[196:199], v[172:175], v[32:35]
	v_mfma_f32_16x16x32_bf16 v[36:39], v[188:191], v[180:183], v[36:39]
	v_mfma_f32_16x16x32_bf16 v[40:43], v[196:199], v[180:183], v[40:43]
	v_mfma_f32_16x16x32_bf16 v[96:99], v[192:195], v[124:127], v[96:99]
	v_mfma_f32_16x16x32_bf16 v[16:19], v[210:213], v[124:127], v[16:19]
	v_mfma_f32_16x16x32_bf16 v[20:23], v[192:195], v[168:171], v[20:23]
	v_mfma_f32_16x16x32_bf16 v[24:27], v[210:213], v[168:171], v[24:27]
	v_mfma_f32_16x16x32_bf16 v[28:31], v[192:195], v[176:179], v[28:31]
	v_mfma_f32_16x16x32_bf16 v[32:35], v[210:213], v[176:179], v[32:35]
	v_mfma_f32_16x16x32_bf16 v[36:39], v[192:195], v[184:187], v[36:39]
	v_mfma_f32_16x16x32_bf16 v[40:43], v[210:213], v[184:187], v[40:43]
	s_mov_b32 m0, s24
	v_lshl_add_u64 v[200:201], v[216:217], 0, s[38:39]
	s_barrier
	ds_read_b128 v[120:123], v206 offset:49152
	ds_read_b128 v[124:127], v206 offset:50176
	ds_read_b128 v[164:167], v206 offset:51200
	ds_read_b128 v[168:171], v206 offset:52224
	ds_read_b128 v[172:175], v206 offset:53248
	ds_read_b128 v[176:179], v206 offset:54272
	ds_read_b128 v[180:183], v206 offset:55296
	ds_read_b128 v[184:187], v206 offset:56320
	global_load_lds_dwordx4 v[200:201], off
	v_lshl_add_u64 v[200:201], v[218:219], 0, s[38:39]
	s_mov_b32 m0, s25
	s_nop 0
	global_load_lds_dwordx4 v[200:201], off
	s_barrier
; #define PG8_STAGE(bufoff, gbase, voff) do { _Pragma("unroll") for (int _i = 0; _i < 2; ++_i) \
;         __builtin_amdgcn_global_load_lds((const unsigned*)((const char*)(gbase) + (voff)[_i]), (LAS unsigned*)(lds + (bufoff) + ldsw + _i * 8192), 16, 0, 0); } while (0)
; #define PG8_LDA(dst, b, h) do { _Pragma("unroll") for (int m = 0; m < 4; ++m) _Pragma("unroll") for (int k = 0; k < 2; ++k) dst[m][k] = *(const LAS bf16x8*)(lds + PG8_SA(b, h) + aoff + m * 2048 + k * 1024); } while (0)
; #define PG8_LDB(dst, b, h) do { _Pragma("unroll") for (int n = 0; n < 2; ++n) _Pragma("unroll") for (int k = 0; k < 2; ++k) dst[n][k] = *(const LAS bf16x8*)(lds + PG8_SB(b, h) + boff + n * 2048 + k * 1024); } while (0)
; #define PG8_MMA(ai, bj, At, Bt) do { __builtin_amdgcn_s_setprio(1); _Pragma("unroll") for (int m = 0; m < 4; ++m) _Pragma("unroll") for (int n = 0; n < 2; ++n) _Pragma("unroll") for (int k = 0; k < 2; ++k) \
;         acc[ai][bj][m][n] = __builtin_amdgcn_mfma_f32_16x16x32_bf16(Bt[n][k], At[m][k], acc[ai][bj][m][n], 0, 0, 0); __builtin_amdgcn_s_setprio(0); } while (0)
; #define PG8_WAIT_V(n) asm volatile("s_waitcnt vmcnt(" #n ")" ::: "memory")
; #define PG8_WAIT_L(n) asm volatile("s_waitcnt lgkmcnt(" #n ")" ::: "memory")
; #define PG8_BAR __builtin_amdgcn_s_barrier()
; #define PG8_SCHED __builtin_amdgcn_sched_barrier(0)
; template <class Epi>
; __device__ __forceinline__ void gemm_phase(LAS unsigned char* lds, const Gemm g, const StaticOrder& S, const Epi& E, int wv) {
;     ...
;             PG8_LDB(B0, 0, 0); PG8_SCHED; PG8_LDA(At, 0, 0); PG8_STAGE(PG8_SA(1, 1), a1 + hstepA, voffA);
;             PG8_WAIT_L(8); PG8_BAR; PG8_WAIT_L(0); PG8_MMA(0, 0, At, B0); PG8_BAR; PG8_SCHED;
;             PG8_LDB(B1, 0, 1); PG8_STAGE(PG8_SB(0, 0), b2, voffB);
;             PG8_BAR; PG8_WAIT_L(0); PG8_MMA(0, 1, At, B1); PG8_BAR;
;     ...
;             PG8_BAR; PG8_WAIT_L(0); PG8_MMA(0, 1, At, B1); PG8_BAR;
;             PG8_LDA(At, 1, 1); PG8_STAGE(PG8_SA(1, 0), a3, voffA);
;             PG8_BAR; PG8_WAIT_L(0); PG8_MMA(1, 0, At, B0); PG8_BAR; PG8_SCHED;
;             PG8_STAGE(PG8_SB(1, 1), b3 + hstepB, voffB);
;             PG8_WAIT_V(6); PG8_BAR; PG8_MMA(1, 1, At, B1); PG8_BAR;
	s_waitcnt lgkmcnt(0)
	v_mfma_f32_16x16x32_bf16 v[128:131], v[88:91], v[120:123], v[128:131]
	v_mfma_f32_16x16x32_bf16 v[132:135], v[112:115], v[120:123], v[132:135]
	v_mfma_f32_16x16x32_bf16 v[136:139], v[88:91], v[164:167], v[136:139]
	v_mfma_f32_16x16x32_bf16 v[152:155], v[112:115], v[164:167], v[152:155]
	v_mfma_f32_16x16x32_bf16 v[156:159], v[88:91], v[172:175], v[156:159]
	v_mfma_f32_16x16x32_bf16 v[160:163], v[112:115], v[172:175], v[160:163]
	v_mfma_f32_16x16x32_bf16 v[0:3], v[88:91], v[180:183], v[0:3]
	v_mfma_f32_16x16x32_bf16 v[4:7], v[112:115], v[180:183], v[4:7]
	v_mfma_f32_16x16x32_bf16 v[128:131], v[92:95], v[124:127], v[128:131]
	v_mfma_f32_16x16x32_bf16 v[132:135], v[116:119], v[124:127], v[132:135]
	v_mfma_f32_16x16x32_bf16 v[136:139], v[92:95], v[168:171], v[136:139]
	v_mfma_f32_16x16x32_bf16 v[152:155], v[116:119], v[168:171], v[152:155]
	v_mfma_f32_16x16x32_bf16 v[156:159], v[92:95], v[176:179], v[156:159]
	v_mfma_f32_16x16x32_bf16 v[160:163], v[116:119], v[176:179], v[160:163]
	v_mfma_f32_16x16x32_bf16 v[0:3], v[92:95], v[184:187], v[0:3]
	v_mfma_f32_16x16x32_bf16 v[4:7], v[116:119], v[184:187], v[4:7]
	s_barrier
	s_add_u32 s82, s62, 0x10180
	s_addc_u32 s83, s63, 0
	s_add_i32 s63, s81, s73
	v_lshl_add_u64 v[88:89], s[82:83], 0, v[142:143]
	s_mov_b32 m0, s63
	s_add_i32 s62, s63, 0x2000
	global_load_lds_dwordx4 v[88:89], off
	v_lshl_add_u64 v[88:89], s[82:83], 0, v[146:147]
	s_mov_b32 m0, s62
	s_nop 0
	global_load_lds_dwordx4 v[88:89], off
	s_waitcnt vmcnt(6)
	s_barrier
	v_mfma_f32_16x16x32_bf16 v[8:11], v[188:191], v[120:123], v[8:11]
	v_mfma_f32_16x16x32_bf16 v[12:15], v[196:199], v[120:123], v[12:15]
	v_mfma_f32_16x16x32_bf16 v[44:47], v[188:191], v[164:167], v[44:47]
	v_mfma_f32_16x16x32_bf16 v[88:91], v[196:199], v[164:167], v[100:103]
	v_mfma_f32_16x16x32_bf16 v[92:95], v[188:191], v[172:175], v[104:107]
	v_mfma_f32_16x16x32_bf16 v[100:103], v[196:199], v[172:175], v[108:111]
	v_mfma_f32_16x16x32_bf16 v[80:83], v[188:191], v[180:183], v[80:83]
	v_mfma_f32_16x16x32_bf16 v[84:87], v[196:199], v[180:183], v[84:87]
	v_mfma_f32_16x16x32_bf16 v[8:11], v[192:195], v[124:127], v[8:11]
	v_mfma_f32_16x16x32_bf16 v[12:15], v[210:213], v[124:127], v[12:15]
	v_mfma_f32_16x16x32_bf16 v[44:47], v[192:195], v[168:171], v[44:47]
	v_mfma_f32_16x16x32_bf16 v[88:91], v[210:213], v[168:171], v[88:91]
	v_mfma_f32_16x16x32_bf16 v[92:95], v[192:195], v[176:179], v[92:95]
	v_mfma_f32_16x16x32_bf16 v[100:103], v[210:213], v[176:179], v[100:103]
	v_mfma_f32_16x16x32_bf16 v[80:83], v[192:195], v[184:187], v[80:83]
	v_mfma_f32_16x16x32_bf16 v[84:87], v[210:213], v[184:187], v[84:87]
	s_barrier
	ds_read_b128 v[104:107], v205
	ds_read_b128 v[108:111], v205 offset:1024
	ds_read_b128 v[112:115], v205 offset:2048
	ds_read_b128 v[116:119], v205 offset:3072
	s_add_u32 s60, s60, 0x80180
	s_addc_u32 s61, s61, 0
	s_mov_b32 m0, s79
	v_lshl_add_u64 v[188:189], s[60:61], 0, v[140:141]
	ds_read_b128 v[120:123], v206
	ds_read_b128 v[124:127], v206 offset:1024
	ds_read_b128 v[164:167], v206 offset:2048
	ds_read_b128 v[168:171], v206 offset:3072
	ds_read_b128 v[172:175], v206 offset:4096
	ds_read_b128 v[176:179], v206 offset:5120
	ds_read_b128 v[180:183], v206 offset:6144
	ds_read_b128 v[184:187], v206 offset:7168
	global_load_lds_dwordx4 v[188:189], off
	v_lshl_add_u64 v[188:189], s[60:61], 0, v[144:145]
	s_mov_b32 m0, s49
	s_nop 0
	global_load_lds_dwordx4 v[188:189], off
	s_waitcnt lgkmcnt(8)
	s_barrier
	s_waitcnt lgkmcnt(0)
	v_mfma_f32_16x16x32_bf16 v[60:63], v[112:115], v[164:167], v[60:63]
	v_mfma_f32_16x16x32_bf16 v[188:191], v[116:119], v[168:171], v[60:63]
	v_mfma_f32_16x16x32_bf16 v[60:63], v[104:107], v[172:175], v[64:67]
	v_mfma_f32_16x16x32_bf16 v[64:67], v[108:111], v[176:179], v[60:63]
	v_mfma_f32_16x16x32_bf16 v[60:63], v[112:115], v[172:175], v[68:71]
	v_mfma_f32_16x16x32_bf16 v[68:71], v[116:119], v[176:179], v[60:63]
	v_mfma_f32_16x16x32_bf16 v[60:63], v[104:107], v[180:183], v[72:75]
	v_mfma_f32_16x16x32_bf16 v[48:51], v[104:107], v[120:123], v[48:51]
	v_mfma_f32_16x16x32_bf16 v[52:55], v[112:115], v[120:123], v[52:55]
	v_mfma_f32_16x16x32_bf16 v[56:59], v[104:107], v[164:167], v[56:59]
	v_mfma_f32_16x16x32_bf16 v[72:75], v[108:111], v[184:187], v[60:63]
	v_mfma_f32_16x16x32_bf16 v[60:63], v[112:115], v[180:183], v[76:79]
	v_mfma_f32_16x16x32_bf16 v[48:51], v[108:111], v[124:127], v[48:51]
	v_mfma_f32_16x16x32_bf16 v[52:55], v[116:119], v[124:127], v[52:55]
	v_mfma_f32_16x16x32_bf16 v[56:59], v[108:111], v[168:171], v[56:59]
	v_mfma_f32_16x16x32_bf16 v[76:79], v[116:119], v[184:187], v[60:63]
	s_barrier
	s_mov_b32 m0, s76
	v_lshl_add_u64 v[200:201], s[64:65], 0, v[142:143]
	ds_read_b128 v[60:63], v207
	ds_read_b128 v[192:195], v207 offset:1024
	ds_read_b128 v[196:199], v207 offset:2048
	ds_read_b128 v[210:213], v207 offset:3072
	global_load_lds_dwordx4 v[200:201], off
	v_lshl_add_u64 v[242:243], s[64:65], 0, v[146:147]
	s_mov_b32 m0, s51
	s_nop 0
	global_load_lds_dwordx4 v[242:243], off
	s_barrier
	s_waitcnt lgkmcnt(0)
	v_mfma_f32_16x16x32_bf16 v[36:39], v[60:63], v[180:183], v[36:39]
	v_mfma_f32_16x16x32_bf16 v[96:99], v[60:63], v[120:123], v[96:99]
	v_mfma_f32_16x16x32_bf16 v[16:19], v[196:199], v[120:123], v[16:19]
	v_mfma_f32_16x16x32_bf16 v[20:23], v[60:63], v[164:167], v[20:23]
	v_mfma_f32_16x16x32_bf16 v[24:27], v[196:199], v[164:167], v[24:27]
	v_mfma_f32_16x16x32_bf16 v[28:31], v[60:63], v[172:175], v[28:31]
	v_mfma_f32_16x16x32_bf16 v[32:35], v[196:199], v[172:175], v[32:35]
	v_mfma_f32_16x16x32_bf16 v[164:167], v[192:195], v[184:187], v[36:39]
	v_mfma_f32_16x16x32_bf16 v[36:39], v[196:199], v[180:183], v[40:43]
	v_mfma_f32_16x16x32_bf16 v[96:99], v[192:195], v[124:127], v[96:99]
	v_mfma_f32_16x16x32_bf16 v[16:19], v[210:213], v[124:127], v[16:19]
	v_mfma_f32_16x16x32_bf16 v[20:23], v[192:195], v[168:171], v[20:23]
	v_mfma_f32_16x16x32_bf16 v[24:27], v[210:213], v[168:171], v[24:27]
	v_mfma_f32_16x16x32_bf16 v[28:31], v[192:195], v[176:179], v[28:31]
	v_mfma_f32_16x16x32_bf16 v[32:35], v[210:213], v[176:179], v[32:35]
	v_mfma_f32_16x16x32_bf16 v[168:171], v[210:213], v[184:187], v[36:39]
	s_mov_b32 m0, s4
	v_lshl_add_u64 v[246:247], s[66:67], 0, v[140:141]
	s_barrier
; #define PG8_STAGE(bufoff, gbase, voff) do { _Pragma("unroll") for (int _i = 0; _i < 2; ++_i) \
;         __builtin_amdgcn_global_load_lds((const unsigned*)((const char*)(gbase) + (voff)[_i]), (LAS unsigned*)(lds + (bufoff) + ldsw + _i * 8192), 16, 0, 0); } while (0)
; #define PG8_LDA(dst, b, h) do { _Pragma("unroll") for (int m = 0; m < 4; ++m) _Pragma("unroll") for (int k = 0; k < 2; ++k) dst[m][k] = *(const LAS bf16x8*)(lds + PG8_SA(b, h) + aoff + m * 2048 + k * 1024); } while (0)
; #define PG8_LDB(dst, b, h) do { _Pragma("unroll") for (int n = 0; n < 2; ++n) _Pragma("unroll") for (int k = 0; k < 2; ++k) dst[n][k] = *(const LAS bf16x8*)(lds + PG8_SB(b, h) + boff + n * 2048 + k * 1024); } while (0)
; #define PG8_MMA(ai, bj, At, Bt) do { __builtin_amdgcn_s_setprio(1); _Pragma("unroll") for (int m = 0; m < 4; ++m) _Pragma("unroll") for (int n = 0; n < 2; ++n) _Pragma("unroll") for (int k = 0; k < 2; ++k) \
;         acc[ai][bj][m][n] = __builtin_amdgcn_mfma_f32_16x16x32_bf16(Bt[n][k], At[m][k], acc[ai][bj][m][n], 0, 0, 0); __builtin_amdgcn_s_setprio(0); } while (0)
; #define PG8_WAIT_V(n) asm volatile("s_waitcnt vmcnt(" #n ")" ::: "memory")
; #define PG8_WAIT_L(n) asm volatile("s_waitcnt lgkmcnt(" #n ")" ::: "memory")
; #define PG8_BAR __builtin_amdgcn_s_barrier()
; #define PG8_SCHED __builtin_amdgcn_sched_barrier(0)
; template <class Epi>
; __device__ __forceinline__ void gemm_phase(LAS unsigned char* lds, const Gemm g, const StaticOrder& S, const Epi& E, int wv) {
;     ...
;             PG8_LDA(At, 0, 1); PG8_STAGE(PG8_SA(0, 0), a2, voffA);
;             PG8_BAR; PG8_WAIT_L(0); PG8_MMA(1, 0, At, B0); PG8_BAR; PG8_SCHED;
;             PG8_STAGE(PG8_SB(0, 1), b2 + hstepB, voffB);
;             PG8_WAIT_V(6); PG8_BAR; PG8_MMA(1, 1, At, B1); PG8_BAR;
;             PG8_LDB(B0, 1, 0); PG8_SCHED; PG8_LDA(At, 1, 0); PG8_STAGE(PG8_SA(0, 1), a2 + hstepA, voffA);
;             PG8_WAIT_L(8); PG8_BAR; PG8_WAIT_L(0); PG8_MMA(0, 0, At, B0); PG8_BAR; PG8_SCHED;
	ds_read_b128 v[36:39], v206 offset:16384
	ds_read_b128 v[40:43], v206 offset:17408
	ds_read_b128 v[120:123], v206 offset:18432
	ds_read_b128 v[124:127], v206 offset:19456
	ds_read_b128 v[172:175], v206 offset:20480
	ds_read_b128 v[176:179], v206 offset:21504
	ds_read_b128 v[180:183], v206 offset:22528
	ds_read_b128 v[184:187], v206 offset:23552
	global_load_lds_dwordx4 v[246:247], off
	v_lshl_add_u64 v[248:249], s[66:67], 0, v[144:145]
	s_mov_b32 m0, s5
	s_nop 0
	global_load_lds_dwordx4 v[248:249], off
	s_barrier
	s_waitcnt lgkmcnt(0)
	v_mfma_f32_16x16x32_bf16 v[128:131], v[104:107], v[36:39], v[128:131]
	v_mfma_f32_16x16x32_bf16 v[214:217], v[108:111], v[40:43], v[128:131]
	v_mfma_f32_16x16x32_bf16 v[128:131], v[112:115], v[36:39], v[132:135]
	v_mfma_f32_16x16x32_bf16 v[218:221], v[116:119], v[40:43], v[128:131]
	v_mfma_f32_16x16x32_bf16 v[128:131], v[104:107], v[120:123], v[136:139]
	v_mfma_f32_16x16x32_bf16 v[222:225], v[108:111], v[124:127], v[128:131]
	v_mfma_f32_16x16x32_bf16 v[128:131], v[112:115], v[120:123], v[152:155]
	v_mfma_f32_16x16x32_bf16 v[152:155], v[116:119], v[124:127], v[128:131]
	v_mfma_f32_16x16x32_bf16 v[128:131], v[104:107], v[172:175], v[156:159]
	v_mfma_f32_16x16x32_bf16 v[156:159], v[108:111], v[176:179], v[128:131]
	v_mfma_f32_16x16x32_bf16 v[128:131], v[112:115], v[172:175], v[160:163]
	v_mfma_f32_16x16x32_bf16 v[0:3], v[104:107], v[180:183], v[0:3]
	v_mfma_f32_16x16x32_bf16 v[4:7], v[112:115], v[180:183], v[4:7]
	v_mfma_f32_16x16x32_bf16 v[160:163], v[116:119], v[176:179], v[128:131]
	v_mfma_f32_16x16x32_bf16 v[0:3], v[108:111], v[184:187], v[0:3]
	v_mfma_f32_16x16x32_bf16 v[4:7], v[116:119], v[184:187], v[4:7]
	s_barrier
	s_add_u32 s60, s64, 0x10000
	s_addc_u32 s61, s65, 0
	s_mov_b32 m0, s77
	v_lshl_add_u64 v[104:105], s[60:61], 0, v[142:143]
	global_load_lds_dwordx4 v[104:105], off
	v_lshl_add_u64 v[104:105], s[60:61], 0, v[146:147]
	s_mov_b32 m0, s57
	s_nop 0
	global_load_lds_dwordx4 v[104:105], off
	s_waitcnt vmcnt(6)
	s_barrier
	v_mfma_f32_16x16x32_bf16 v[12:15], v[196:199], v[36:39], v[12:15]
	v_mfma_f32_16x16x32_bf16 v[226:229], v[210:213], v[40:43], v[12:15]
	v_mfma_f32_16x16x32_bf16 v[12:15], v[60:63], v[120:123], v[44:47]
	v_mfma_f32_16x16x32_bf16 v[230:233], v[192:195], v[124:127], v[12:15]
	v_mfma_f32_16x16x32_bf16 v[12:15], v[196:199], v[120:123], v[88:91]
	v_mfma_f32_16x16x32_bf16 v[234:237], v[210:213], v[124:127], v[12:15]
	v_mfma_f32_16x16x32_bf16 v[12:15], v[60:63], v[172:175], v[92:95]
	v_mfma_f32_16x16x32_bf16 v[238:241], v[192:195], v[176:179], v[12:15]
	v_mfma_f32_16x16x32_bf16 v[12:15], v[196:199], v[172:175], v[100:103]
	v_mfma_f32_16x16x32_bf16 v[172:175], v[210:213], v[176:179], v[12:15]
	v_mfma_f32_16x16x32_bf16 v[12:15], v[60:63], v[180:183], v[80:83]
	v_mfma_f32_16x16x32_bf16 v[8:11], v[60:63], v[36:39], v[8:11]
	v_mfma_f32_16x16x32_bf16 v[80:83], v[192:195], v[184:187], v[12:15]
	v_mfma_f32_16x16x32_bf16 v[12:15], v[196:199], v[180:183], v[84:87]
	v_mfma_f32_16x16x32_bf16 v[8:11], v[192:195], v[40:43], v[8:11]
	v_mfma_f32_16x16x32_bf16 v[176:179], v[210:213], v[184:187], v[12:15]
	s_barrier
	ds_read_b128 v[84:87], v209
	ds_read_b128 v[92:95], v209 offset:1024
	ds_read_b128 v[100:103], v209 offset:2048
	ds_read_b128 v[180:183], v209 offset:3072
	s_add_u32 s60, s66, 0x80000
	s_addc_u32 s61, s67, 0
	s_mov_b32 m0, s22
	v_lshl_add_u64 v[36:37], s[60:61], 0, v[140:141]
	ds_read_b128 v[12:15], v206 offset:32768
	ds_read_b128 v[40:43], v206 offset:33792
	ds_read_b128 v[88:91], v206 offset:34816
	ds_read_b128 v[104:107], v206 offset:35840
	ds_read_b128 v[108:111], v206 offset:36864
	ds_read_b128 v[184:187], v206 offset:37888
	ds_read_b128 v[192:195], v206 offset:38912
	ds_read_b128 v[196:199], v206 offset:39936
	global_load_lds_dwordx4 v[36:37], off
	v_lshl_add_u64 v[36:37], s[60:61], 0, v[144:145]
	s_mov_b32 m0, s23
	s_nop 0
	global_load_lds_dwordx4 v[36:37], off
	s_waitcnt lgkmcnt(8)
	s_barrier
	s_waitcnt lgkmcnt(0)
	v_mfma_f32_16x16x32_bf16 v[36:39], v[84:87], v[12:15], v[48:51]
	v_mfma_f32_16x16x32_bf16 v[136:139], v[92:95], v[40:43], v[36:39]
	v_mfma_f32_16x16x32_bf16 v[36:39], v[100:103], v[12:15], v[52:55]
	v_mfma_f32_16x16x32_bf16 v[60:63], v[180:183], v[40:43], v[36:39]
	v_mfma_f32_16x16x32_bf16 v[36:39], v[84:87], v[88:91], v[56:59]
	v_mfma_f32_16x16x32_bf16 v[128:131], v[92:95], v[104:107], v[36:39]
	v_mfma_f32_16x16x32_bf16 v[36:39], v[100:103], v[88:91], v[188:191]
	v_mfma_f32_16x16x32_bf16 v[52:55], v[180:183], v[104:107], v[36:39]
	v_mfma_f32_16x16x32_bf16 v[36:39], v[84:87], v[108:111], v[64:67]
	v_mfma_f32_16x16x32_bf16 v[120:123], v[92:95], v[184:187], v[36:39]
	v_mfma_f32_16x16x32_bf16 v[36:39], v[100:103], v[108:111], v[68:71]
	v_mfma_f32_16x16x32_bf16 v[44:47], v[180:183], v[184:187], v[36:39]
	v_mfma_f32_16x16x32_bf16 v[36:39], v[84:87], v[192:195], v[72:75]
	v_mfma_f32_16x16x32_bf16 v[112:115], v[92:95], v[196:199], v[36:39]
	v_mfma_f32_16x16x32_bf16 v[36:39], v[100:103], v[192:195], v[76:79]
	v_mfma_f32_16x16x32_bf16 v[36:39], v[180:183], v[196:199], v[36:39]
	s_barrier
	s_mov_b32 m0, s80
	v_lshl_add_u64 v[48:49], v[200:201], 0, s[34:35]
	ds_read_b128 v[64:67], v250
	ds_read_b128 v[68:71], v250 offset:1024
	ds_read_b128 v[76:79], v250 offset:2048
	ds_read_b128 v[188:191], v250 offset:3072
	global_load_lds_dwordx4 v[48:49], off
	v_lshl_add_u64 v[48:49], v[242:243], 0, s[34:35]
	s_mov_b32 m0, s78
	s_nop 0
	global_load_lds_dwordx4 v[48:49], off
	s_barrier
; #define PG8_STAGE(bufoff, gbase, voff) do { _Pragma("unroll") for (int _i = 0; _i < 2; ++_i) \
;         __builtin_amdgcn_global_load_lds((const unsigned*)((const char*)(gbase) + (voff)[_i]), (LAS unsigned*)(lds + (bufoff) + ldsw + _i * 8192), 16, 0, 0); } while (0)
; #define PG8_LDA(dst, b, h) do { _Pragma("unroll") for (int m = 0; m < 4; ++m) _Pragma("unroll") for (int k = 0; k < 2; ++k) dst[m][k] = *(const LAS bf16x8*)(lds + PG8_SA(b, h) + aoff + m * 2048 + k * 1024); } while (0)
; #define PG8_LDB(dst, b, h) do { _Pragma("unroll") for (int n = 0; n < 2; ++n) _Pragma("unroll") for (int k = 0; k < 2; ++k) dst[n][k] = *(const LAS bf16x8*)(lds + PG8_SB(b, h) + boff + n * 2048 + k * 1024); } while (0)
; #define PG8_MMA(ai, bj, At, Bt) do { __builtin_amdgcn_s_setprio(1); _Pragma("unroll") for (int m = 0; m < 4; ++m) _Pragma("unroll") for (int n = 0; n < 2; ++n) _Pragma("unroll") for (int k = 0; k < 2; ++k) \
;         acc[ai][bj][m][n] = __builtin_amdgcn_mfma_f32_16x16x32_bf16(Bt[n][k], At[m][k], acc[ai][bj][m][n], 0, 0, 0); __builtin_amdgcn_s_setprio(0); } while (0)
; #define PG8_WAIT_V(n) asm volatile("s_waitcnt vmcnt(" #n ")" ::: "memory")
; #define PG8_WAIT_L(n) asm volatile("s_waitcnt lgkmcnt(" #n ")" ::: "memory")
; #define PG8_BAR __builtin_amdgcn_s_barrier()
; template <class Epi>
; __device__ __forceinline__ void gemm_phase(LAS unsigned char* lds, const Gemm g, const StaticOrder& S, const Epi& E, int wv) {
;     ...
;             PG8_WAIT_L(8); PG8_BAR; PG8_WAIT_L(0); PG8_MMA(0, 0, At, B0); PG8_BAR; PG8_SCHED;
;             PG8_LDB(B1, 1, 1); PG8_STAGE(PG8_SB(1, 0), b3, voffB);
;             PG8_BAR; PG8_WAIT_L(0); PG8_MMA(0, 1, At, B1); PG8_BAR;
;             PG8_LDA(At, 1, 1); PG8_STAGE(PG8_SA(1, 0), a3, voffA);
;             PG8_BAR; PG8_WAIT_L(0); PG8_MMA(1, 0, At, B0); PG8_BAR; PG8_SCHED;
;             PG8_STAGE(PG8_SB(1, 1), b3 + hstepB, voffB);
;             PG8_WAIT_V(6); PG8_BAR; PG8_MMA(1, 1, At, B1); PG8_BAR;
;     __device__ __forceinline__ void operator()(const f32x4 (&acc)[2][2][4][2], const Unit& u, int wr, int wc, int fr, int fq) const {
;         const int row0 = u.pm * BM + wr * 64 + fr, ch0 = u.pn * HALF + wc * 32 + 4 * fq;
; #pragma unroll
;         for (int n = 0; n < 2; ++n) {
;             const f32x4 ba = *(const f32x4*)(b_ga + ch0 + n * 16), bx = *(const f32x4*)(b_gx + ch0 + n * 16), sp = *(const f32x4*)(lam + ch0 + n * 16);
	s_waitcnt lgkmcnt(0)
	v_mfma_f32_16x16x32_bf16 v[48:51], v[64:67], v[12:15], v[96:99]
	v_mfma_f32_16x16x32_bf16 v[12:15], v[76:79], v[12:15], v[16:19]
	v_mfma_f32_16x16x32_bf16 v[56:59], v[188:191], v[40:43], v[12:15]
	v_mfma_f32_16x16x32_bf16 v[12:15], v[64:67], v[88:91], v[20:23]
	v_mfma_f32_16x16x32_bf16 v[124:127], v[68:71], v[104:107], v[12:15]
	v_mfma_f32_16x16x32_bf16 v[12:15], v[76:79], v[88:91], v[24:27]
	v_mfma_f32_16x16x32_bf16 v[132:135], v[68:71], v[40:43], v[48:51]
	v_mfma_f32_16x16x32_bf16 v[48:51], v[188:191], v[104:107], v[12:15]
	v_mfma_f32_16x16x32_bf16 v[12:15], v[64:67], v[108:111], v[28:31]
	v_mfma_f32_16x16x32_bf16 v[116:119], v[68:71], v[184:187], v[12:15]
	v_mfma_f32_16x16x32_bf16 v[12:15], v[76:79], v[108:111], v[32:35]
	v_mfma_f32_16x16x32_bf16 v[40:43], v[188:191], v[184:187], v[12:15]
	v_mfma_f32_16x16x32_bf16 v[12:15], v[64:67], v[192:195], v[164:167]
	v_mfma_f32_16x16x32_bf16 v[108:111], v[68:71], v[196:199], v[12:15]
	v_mfma_f32_16x16x32_bf16 v[12:15], v[76:79], v[192:195], v[168:171]
	v_mfma_f32_16x16x32_bf16 v[32:35], v[188:191], v[196:199], v[12:15]
	s_mov_b32 m0, s24
	s_nop 4
	v_lshl_add_u64 v[12:13], v[246:247], 0, s[34:35]
	s_barrier
	ds_read_b128 v[16:19], v206 offset:49152
	ds_read_b128 v[24:27], v206 offset:50176
	ds_read_b128 v[164:167], v206 offset:51200
	ds_read_b128 v[168:171], v206 offset:52224
	ds_read_b128 v[184:187], v206 offset:53248
	ds_read_b128 v[192:195], v206 offset:54272
	ds_read_b128 v[196:199], v206 offset:55296
	ds_read_b128 v[210:213], v206 offset:56320
	global_load_lds_dwordx4 v[12:13], off
	v_lshl_add_u64 v[12:13], v[248:249], 0, s[34:35]
	s_mov_b32 m0, s25
	s_nop 0
	global_load_lds_dwordx4 v[12:13], off
	s_barrier
	s_waitcnt lgkmcnt(0)
	v_mfma_f32_16x16x32_bf16 v[12:15], v[84:87], v[16:19], v[214:217]
	v_mfma_f32_16x16x32_bf16 v[104:107], v[92:95], v[24:27], v[12:15]
	v_mfma_f32_16x16x32_bf16 v[12:15], v[100:103], v[16:19], v[218:221]
	v_mfma_f32_16x16x32_bf16 v[28:31], v[180:183], v[24:27], v[12:15]
	v_mfma_f32_16x16x32_bf16 v[12:15], v[84:87], v[164:167], v[222:225]
	v_mfma_f32_16x16x32_bf16 v[96:99], v[92:95], v[168:171], v[12:15]
	v_mfma_f32_16x16x32_bf16 v[12:15], v[100:103], v[164:167], v[152:155]
	v_mfma_f32_16x16x32_bf16 v[20:23], v[180:183], v[168:171], v[12:15]
	v_mfma_f32_16x16x32_bf16 v[12:15], v[84:87], v[184:187], v[156:159]
	v_mfma_f32_16x16x32_bf16 v[0:3], v[84:87], v[196:199], v[0:3]
	v_mfma_f32_16x16x32_bf16 v[88:91], v[92:95], v[192:195], v[12:15]
	v_mfma_f32_16x16x32_bf16 v[12:15], v[100:103], v[184:187], v[160:163]
	v_mfma_f32_16x16x32_bf16 v[72:75], v[92:95], v[210:213], v[0:3]
	v_mfma_f32_16x16x32_bf16 v[0:3], v[100:103], v[196:199], v[4:7]
	v_mfma_f32_16x16x32_bf16 v[12:15], v[180:183], v[192:195], v[12:15]
	v_mfma_f32_16x16x32_bf16 v[4:7], v[180:183], v[210:213], v[0:3]
	s_barrier
	s_add_u32 s60, s64, 0x10080
	s_addc_u32 s61, s65, 0
	s_mov_b32 m0, s63
	s_nop 0
	v_lshl_add_u64 v[0:1], s[60:61], 0, v[142:143]
	global_load_lds_dwordx4 v[0:1], off
	v_lshl_add_u64 v[0:1], s[60:61], 0, v[146:147]
	s_mov_b32 m0, s62
	s_nop 0
	global_load_lds_dwordx4 v[0:1], off
	s_waitcnt vmcnt(6)
	s_barrier
	v_mfma_f32_16x16x32_bf16 v[0:3], v[64:67], v[16:19], v[8:11]
	v_mfma_f32_16x16x32_bf16 v[100:103], v[68:71], v[24:27], v[0:3]
	v_mfma_f32_16x16x32_bf16 v[0:3], v[76:79], v[16:19], v[226:229]
	v_mfma_f32_16x16x32_bf16 v[24:27], v[188:191], v[24:27], v[0:3]
	v_mfma_f32_16x16x32_bf16 v[0:3], v[64:67], v[164:167], v[230:233]
	v_mfma_f32_16x16x32_bf16 v[92:95], v[68:71], v[168:171], v[0:3]
	v_mfma_f32_16x16x32_bf16 v[0:3], v[76:79], v[164:167], v[234:237]
	v_mfma_f32_16x16x32_bf16 v[16:19], v[188:191], v[168:171], v[0:3]
	v_mfma_f32_16x16x32_bf16 v[0:3], v[64:67], v[184:187], v[238:241]
	v_mfma_f32_16x16x32_bf16 v[84:87], v[68:71], v[192:195], v[0:3]
	v_mfma_f32_16x16x32_bf16 v[0:3], v[76:79], v[184:187], v[172:175]
	v_mfma_f32_16x16x32_bf16 v[8:11], v[188:191], v[192:195], v[0:3]
	v_mfma_f32_16x16x32_bf16 v[0:3], v[64:67], v[196:199], v[80:83]
	v_mfma_f32_16x16x32_bf16 v[64:67], v[68:71], v[210:213], v[0:3]
	v_mfma_f32_16x16x32_bf16 v[0:3], v[76:79], v[196:199], v[176:179]
	v_mfma_f32_16x16x32_bf16 v[0:3], v[188:191], v[210:213], v[0:3]
	v_lshl_or_b32 v152, s58, 7, v204
	v_ashrrev_i32_e32 v153, 31, v152
	v_lshlrev_b64 v[76:77], 2, v[152:153]
	v_lshl_add_u64 v[154:155], s[8:9], 0, v[76:77]
	s_barrier
; __device__ __forceinline__ float bf_lo(unsigned w) { return __uint_as_float(w << 16); }
; __device__ __forceinline__ float bf_hi(unsigned w) { return __uint_as_float(w & 0xffff0000u); }
; __device__ __forceinline__ float fast_sigmoid(float x) { return __builtin_amdgcn_rcpf(1.0f + __builtin_amdgcn_exp2f(-x * LOG2E)); }
;     __device__ __forceinline__ void operator()(const f32x4 (&acc)[2][2][4][2], const Unit& u, int wr, int wc, int fr, int fq) const {
;         const int row0 = u.pm * BM + wr * 64 + fr, ch0 = u.pn * HALF + wc * 32 + 4 * fq;
; #pragma unroll
;         for (int n = 0; n < 2; ++n) {
;             const f32x4 ba = *(const f32x4*)(b_ga + ch0 + n * 16), bx = *(const f32x4*)(b_gx + ch0 + n * 16), sp = *(const f32x4*)(lam + ch0 + n * 16);
;             u32x2 xall[8];
; #pragma unroll
;             for (int it = 0; it < 8; ++it) xall[it] = *(const u32x2*)(xc + (size_t)(row0 + (it >> 2) * HALF + (it & 3) * 16) * DM + ch0 + n * 16);
;             asm volatile("" ::: "memory");
; #pragma unroll
;             for (int ai = 0; ai < 2; ++ai)
; #pragma unroll
;                 for (int m = 0; m < 4; ++m) { const int row = row0 + ai * HALF + m * 16; const size_t off = (size_t)row * DM + ch0 + n * 16;
;                     const u32x2 xw = xall[ai * 4 + m];
;                     const float xv[4] = {bf_lo(xw.x), bf_hi(xw.x), bf_lo(xw.y), bf_hi(xw.y)};
;                     f32x4 av; float bv[4];
; #pragma unroll
;                     for (int j = 0; j < 4; ++j) { const float r = fast_sigmoid(acc[ai][0][m][n][j] + ba[j]), ig = fast_sigmoid(acc[ai][1][m][n][j] + bx[j]);
;                         const float la = sp[j] * r; const float la2 = __uint_as_float(pk_bf16(la * LOG2E, 0.f) << 16);
;                         const float a = __builtin_amdgcn_exp2f(la2); const float x2 = 2.0f * la2 * 0.6931471805599453f; av[j] = la2;
;                         const float om = (x2 > -0.03f) ? -(x2 * (1.0f + x2 * (0.5f + x2 * (1.0f / 6.0f + x2 * (1.0f / 24.0f))))) : (1.0f - a * a);
;                         bv[j] = __builtin_amdgcn_sqrtf(om) * (ig * xv[j]); }
;                     { u32x2 wa; wa.x = pk_bf16(av[0], av[1]); wa.y = pk_bf16(av[2], av[3]); *(u32x2*)(aout + off) = wa; }
;                     u32x2 w; w.x = pk_bf16(bv[0], bv[1]); w.y = pk_bf16(bv[2], bv[3]); *(u32x2*)(bout + off) = w; }
	global_load_dwordx4 v[80:83], v[154:155], off
	v_lshl_add_u64 v[158:159], s[14:15], 0, v[76:77]
	v_lshl_add_u32 v164, s56, 8, v202
	v_lshl_add_u64 v[156:157], s[10:11], 0, v[76:77]
	global_load_dwordx4 v[76:79], v[158:159], off
	v_add_u32_e32 v184, 0x80, v164
	v_ashrrev_i32_e32 v165, 31, v164
	v_or_b32_e32 v196, 16, v164
	v_or_b32_e32 v192, 32, v164
	v_or_b32_e32 v188, 48, v164
	v_ashrrev_i32_e32 v185, 31, v184
	v_add_u32_e32 v172, 0x90, v164
	v_add_u32_e32 v174, 0xa0, v164
	v_add_u32_e32 v178, 0xb0, v164
	v_lshl_add_u64 v[176:177], v[152:153], 1, s[12:13]
	v_lshlrev_b64 v[160:161], 12, v[164:165]
	v_ashrrev_i32_e32 v197, 31, v196
	v_ashrrev_i32_e32 v193, 31, v192
	v_ashrrev_i32_e32 v189, 31, v188
	v_lshlrev_b64 v[170:171], 12, v[184:185]
	v_ashrrev_i32_e32 v173, 31, v172
	v_ashrrev_i32_e32 v175, 31, v174
	v_ashrrev_i32_e32 v179, 31, v178
	v_lshl_add_u64 v[160:161], v[176:177], 0, v[160:161]
	v_lshlrev_b64 v[162:163], 12, v[196:197]
	v_lshlrev_b64 v[166:167], 12, v[192:193]
	v_lshlrev_b64 v[168:169], 12, v[188:189]
	v_lshl_add_u64 v[170:171], v[176:177], 0, v[170:171]
	v_lshlrev_b64 v[172:173], 12, v[172:173]
	v_lshlrev_b64 v[174:175], 12, v[174:175]
	v_lshlrev_b64 v[178:179], 12, v[178:179]
	global_load_dwordx4 v[68:71], v[156:157], off
	v_lshl_add_u64 v[162:163], v[176:177], 0, v[162:163]
	v_lshl_add_u64 v[166:167], v[176:177], 0, v[166:167]
	v_lshl_add_u64 v[168:169], v[176:177], 0, v[168:169]
	global_load_dwordx2 v[200:201], v[160:161], off
	global_load_dwordx2 v[198:199], v[162:163], off
	global_load_dwordx2 v[194:195], v[166:167], off
	global_load_dwordx2 v[190:191], v[168:169], off
	v_lshl_add_u64 v[172:173], v[176:177], 0, v[172:173]
	v_lshl_add_u64 v[174:175], v[176:177], 0, v[174:175]
	v_lshl_add_u64 v[176:177], v[176:177], 0, v[178:179]
	global_load_dwordx2 v[186:187], v[170:171], off
	global_load_dwordx2 v[182:183], v[172:173], off
	global_load_dwordx2 v[180:181], v[174:175], off
	global_load_dwordx2 v[178:179], v[176:177], off
	s_waitcnt vmcnt(0)
	v_add_f32_e32 v136, v136, v80
	v_mul_f32_e32 v136, 0xbfb8aa3b, v136
	v_exp_f32_e32 v136, v136
	s_nop 0
	v_add_f32_e32 v136, 1.0, v136
	v_rcp_f32_e32 v136, v136
	s_nop 0
	v_mul_f32_e32 v136, v76, v136
	v_mul_f32_e32 v136, 0x3fb8aa3b, v136
	v_cvt_pk_bf16_f32 v136, v136, 0
	v_lshlrev_b32_e32 v136, 16, v136
	v_add_f32_e32 v209, v136, v136
	v_mul_f32_e32 v210, 0x3f317218, v209
	v_cmp_nlt_f32_e32 vcc, s74, v210
	s_and_saveexec_b64 s[56:57], vcc
	s_xor_b64 s[56:57], exec, s[56:57]
	v_exp_f32_e32 v209, v136
	s_nop 0
	v_fma_f32 v209, -v209, v209, 1.0
	s_andn2_saveexec_b64 s[56:57], s[56:57]
	v_fmamk_f32 v209, v210, 0x3d2aaaab, v208
	v_fma_f32 v209, v210, v209, 0.5
	v_fma_f32 v209, v210, v209, 1.0
	v_mul_f32_e64 v209, v210, -v209
	s_or_b64 exec, exec, s[56:57]
	v_add_f32_e32 v137, v137, v81
	v_mul_f32_e32 v137, 0xbfb8aa3b, v137
	v_exp_f32_e32 v137, v137
	s_nop 0
	v_add_f32_e32 v137, 1.0, v137
	v_rcp_f32_e32 v137, v137
	s_nop 0
	v_mul_f32_e32 v137, v77, v137
	v_mul_f32_e32 v137, 0x3fb8aa3b, v137
	v_cvt_pk_bf16_f32 v137, v137, 0
	v_lshlrev_b32_e32 v137, 16, v137
	v_add_f32_e32 v210, v137, v137
	v_mul_f32_e32 v211, 0x3f317218, v210
	v_cmp_nlt_f32_e32 vcc, s74, v211
	s_and_saveexec_b64 s[56:57], vcc
	s_xor_b64 s[56:57], exec, s[56:57]
	v_exp_f32_e32 v210, v137
	s_nop 0
	v_fma_f32 v210, -v210, v210, 1.0
	s_andn2_saveexec_b64 s[56:57], s[56:57]
	v_fmamk_f32 v210, v211, 0x3d2aaaab, v208
	v_fma_f32 v210, v211, v210, 0.5
	v_fma_f32 v210, v211, v210, 1.0
	v_mul_f32_e64 v210, v211, -v210
	s_or_b64 exec, exec, s[56:57]
	v_add_f32_e32 v138, v138, v82
	v_mul_f32_e32 v138, 0xbfb8aa3b, v138
	v_exp_f32_e32 v138, v138
	s_nop 0
	v_add_f32_e32 v138, 1.0, v138
	v_rcp_f32_e32 v138, v138
	s_nop 0
	v_mul_f32_e32 v138, v78, v138
	v_mul_f32_e32 v138, 0x3fb8aa3b, v138
	v_cvt_pk_bf16_f32 v138, v138, 0
	v_lshlrev_b32_e32 v138, 16, v138
	v_add_f32_e32 v211, v138, v138
	v_mul_f32_e32 v212, 0x3f317218, v211
	v_cmp_nlt_f32_e32 vcc, s74, v212
	s_and_saveexec_b64 s[56:57], vcc
	s_xor_b64 s[56:57], exec, s[56:57]
	v_exp_f32_e32 v211, v138
	s_nop 0
	v_fma_f32 v211, -v211, v211, 1.0
	s_andn2_saveexec_b64 s[56:57], s[56:57]
	v_fmamk_f32 v211, v212, 0x3d2aaaab, v208
	v_fma_f32 v211, v212, v211, 0.5
	v_fma_f32 v211, v212, v211, 1.0
	v_mul_f32_e64 v211, v212, -v211
	s_or_b64 exec, exec, s[56:57]
	v_add_f32_e32 v139, v139, v83
	v_mul_f32_e32 v139, 0xbfb8aa3b, v139
	v_exp_f32_e32 v139, v139
	s_nop 0
	v_add_f32_e32 v139, 1.0, v139
	v_rcp_f32_e32 v139, v139
	s_nop 0
	v_mul_f32_e32 v139, v79, v139
	v_mul_f32_e32 v139, 0x3fb8aa3b, v139
	v_cvt_pk_bf16_f32 v139, v139, 0
	v_lshlrev_b32_e32 v139, 16, v139
	v_add_f32_e32 v212, v139, v139
	v_mul_f32_e32 v213, 0x3f317218, v212
	v_cmp_nlt_f32_e32 vcc, s74, v213
	s_and_saveexec_b64 s[56:57], vcc
	s_xor_b64 s[56:57], exec, s[56:57]
	v_exp_f32_e32 v212, v139
	s_nop 0
	v_fma_f32 v212, -v212, v212, 1.0
	s_andn2_saveexec_b64 s[56:57], s[56:57]
	v_fmamk_f32 v212, v213, 0x3d2aaaab, v208
	v_fma_f32 v212, v213, v212, 0.5
	v_fma_f32 v212, v213, v212, 1.0
	v_mul_f32_e64 v212, v213, -v212
	s_or_b64 exec, exec, s[56:57]
	v_add_f32_e32 v134, v134, v70
	v_mul_f32_e32 v134, 0xbfb8aa3b, v134
	v_exp_f32_e32 v134, v134
	v_add_f32_e32 v132, v132, v68
	v_mul_f32_e32 v132, 0xbfb8aa3b, v132
	v_exp_f32_e32 v132, v132
	v_add_f32_e32 v133, v133, v69
	v_add_f32_e32 v135, v135, v71
	v_add_f32_e32 v134, 1.0, v134
	v_mul_f32_e32 v133, 0xbfb8aa3b, v133
	v_rcp_f32_e32 v134, v134
	v_mul_f32_e32 v135, 0xbfb8aa3b, v135
	v_exp_f32_e32 v133, v133
	v_sqrt_f32_e32 v211, v211
	v_exp_f32_e32 v135, v135
	v_add_f32_e32 v132, 1.0, v132
	v_rcp_f32_e32 v132, v132
	v_lshlrev_b32_e32 v213, 16, v201
	v_add_f32_e32 v128, v128, v80
; __device__ __forceinline__ float bf_lo(unsigned w) { return __uint_as_float(w << 16); }
; __device__ __forceinline__ float bf_hi(unsigned w) { return __uint_as_float(w & 0xffff0000u); }
; __device__ __forceinline__ float fast_sigmoid(float x) { return __builtin_amdgcn_rcpf(1.0f + __builtin_amdgcn_exp2f(-x * LOG2E)); }
;     __device__ __forceinline__ void operator()(const f32x4 (&acc)[2][2][4][2], const Unit& u, int wr, int wc, int fr, int fq) const {
;     ...
;                 for (int m = 0; m < 4; ++m) { const int row = row0 + ai * HALF + m * 16; const size_t off = (size_t)row * DM + ch0 + n * 16;
;                     const u32x2 xw = xall[ai * 4 + m];
;                     const float xv[4] = {bf_lo(xw.x), bf_hi(xw.x), bf_lo(xw.y), bf_hi(xw.y)};
;                     f32x4 av; float bv[4];
; #pragma unroll
;                     for (int j = 0; j < 4; ++j) { const float r = fast_sigmoid(acc[ai][0][m][n][j] + ba[j]), ig = fast_sigmoid(acc[ai][1][m][n][j] + bx[j]);
;                         const float la = sp[j] * r; const float la2 = __uint_as_float(pk_bf16(la * LOG2E, 0.f) << 16);
;                         const float a = __builtin_amdgcn_exp2f(la2); const float x2 = 2.0f * la2 * 0.6931471805599453f; av[j] = la2;
;                         const float om = (x2 > -0.03f) ? -(x2 * (1.0f + x2 * (0.5f + x2 * (1.0f / 6.0f + x2 * (1.0f / 24.0f))))) : (1.0f - a * a);
;                         bv[j] = __builtin_amdgcn_sqrtf(om) * (ig * xv[j]); }
;                     { u32x2 wa; wa.x = pk_bf16(av[0], av[1]); wa.y = pk_bf16(av[2], av[3]); *(u32x2*)(aout + off) = wa; }
;                     u32x2 w; w.x = pk_bf16(bv[0], bv[1]); w.y = pk_bf16(bv[2], bv[3]); *(u32x2*)(bout + off) = w; }
	v_mul_f32_e32 v134, v134, v213
	v_sqrt_f32_e32 v209, v209
	v_add_f32_e32 v133, 1.0, v133
	v_mul_f32_e32 v128, 0xbfb8aa3b, v128
	v_mul_f32_e32 v211, v134, v211
	v_add_f32_e32 v134, 1.0, v135
	v_lshlrev_b32_e32 v135, 16, v200
	v_rcp_f32_e32 v133, v133
	v_exp_f32_e32 v128, v128
	v_mul_f32_e32 v132, v132, v135
	v_sqrt_f32_e32 v135, v210
	v_mul_f32_e32 v209, v132, v209
	v_and_b32_e32 v132, 0xffff0000, v200
	v_rcp_f32_e32 v134, v134
	v_mul_f32_e32 v132, v133, v132
	v_add_f32_e32 v128, 1.0, v128
	v_mul_f32_e32 v200, v132, v135
	v_sqrt_f32_e32 v135, v212
	v_rcp_f32_e32 v128, v128
	v_and_b32_e32 v201, 0xffff0000, v201
	v_lshlrev_b64 v[132:133], 11, v[164:165]
	v_mul_f32_e32 v134, v134, v201
	v_mul_f32_e32 v201, v134, v135
	v_lshl_add_u64 v[134:135], v[132:133], 0, v[152:153]
	v_mul_f32_e32 v128, v76, v128
	v_lshlrev_b64 v[134:135], 1, v[134:135]
	v_mul_f32_e32 v128, 0x3fb8aa3b, v128
	v_cvt_pk_bf16_f32 v136, v136, v137
	v_cvt_pk_bf16_f32 v137, v138, v139
	v_lshl_add_u64 v[138:139], s[16:17], 0, v[134:135]
	v_cvt_pk_bf16_f32 v128, v128, 0
	global_store_dwordx2 v[138:139], v[136:137], off
	v_cvt_pk_bf16_f32 v136, v209, v200
	v_cvt_pk_bf16_f32 v137, v211, v201
	v_lshl_add_u64 v[134:135], s[18:19], 0, v[134:135]
	v_lshlrev_b32_e32 v128, 16, v128
	global_store_dwordx2 v[134:135], v[136:137], off
	v_add_f32_e32 v134, v128, v128
	v_mul_f32_e32 v135, 0x3f317218, v134
	v_cmp_nlt_f32_e32 vcc, s74, v135
	s_and_saveexec_b64 s[56:57], vcc
	s_xor_b64 s[56:57], exec, s[56:57]
	v_exp_f32_e32 v134, v128
	s_nop 0
	v_fma_f32 v134, -v134, v134, 1.0
	s_andn2_saveexec_b64 s[56:57], s[56:57]
	v_fmamk_f32 v134, v135, 0x3d2aaaab, v208
	v_fma_f32 v134, v135, v134, 0.5
	v_fma_f32 v134, v135, v134, 1.0
	v_mul_f32_e64 v134, v135, -v134
	s_or_b64 exec, exec, s[56:57]
	v_add_f32_e32 v129, v129, v81
	v_mul_f32_e32 v129, 0xbfb8aa3b, v129
	v_exp_f32_e32 v129, v129
	s_nop 0
	v_add_f32_e32 v129, 1.0, v129
	v_rcp_f32_e32 v129, v129
	s_nop 0
	v_mul_f32_e32 v129, v77, v129
	v_mul_f32_e32 v129, 0x3fb8aa3b, v129
	v_cvt_pk_bf16_f32 v129, v129, 0
	v_lshlrev_b32_e32 v129, 16, v129
	v_add_f32_e32 v135, v129, v129
	v_mul_f32_e32 v136, 0x3f317218, v135
	v_cmp_nlt_f32_e32 vcc, s74, v136
	s_and_saveexec_b64 s[56:57], vcc
	s_xor_b64 s[56:57], exec, s[56:57]
	v_exp_f32_e32 v135, v129
	s_nop 0
	v_fma_f32 v135, -v135, v135, 1.0
	s_andn2_saveexec_b64 s[56:57], s[56:57]
	v_fmamk_f32 v135, v136, 0x3d2aaaab, v208
	v_fma_f32 v135, v136, v135, 0.5
	v_fma_f32 v135, v136, v135, 1.0
	v_mul_f32_e64 v135, v136, -v135
	s_or_b64 exec, exec, s[56:57]
	v_add_f32_e32 v130, v130, v82
	v_mul_f32_e32 v130, 0xbfb8aa3b, v130
	v_exp_f32_e32 v130, v130
	s_nop 0
	v_add_f32_e32 v130, 1.0, v130
	v_rcp_f32_e32 v130, v130
	s_nop 0
	v_mul_f32_e32 v130, v78, v130
	v_mul_f32_e32 v130, 0x3fb8aa3b, v130
	v_cvt_pk_bf16_f32 v130, v130, 0
	v_lshlrev_b32_e32 v130, 16, v130
	v_add_f32_e32 v136, v130, v130
	v_mul_f32_e32 v137, 0x3f317218, v136
	v_cmp_nlt_f32_e32 vcc, s74, v137
	s_and_saveexec_b64 s[56:57], vcc
	s_xor_b64 s[56:57], exec, s[56:57]
	v_exp_f32_e32 v136, v130
	s_nop 0
	v_fma_f32 v136, -v136, v136, 1.0
	s_andn2_saveexec_b64 s[56:57], s[56:57]
	v_fmamk_f32 v136, v137, 0x3d2aaaab, v208
	v_fma_f32 v136, v137, v136, 0.5
	v_fma_f32 v136, v137, v136, 1.0
	v_mul_f32_e64 v136, v137, -v136
	s_or_b64 exec, exec, s[56:57]
	v_add_f32_e32 v131, v131, v83
	v_mul_f32_e32 v131, 0xbfb8aa3b, v131
	v_exp_f32_e32 v131, v131
	s_nop 0
	v_add_f32_e32 v131, 1.0, v131
	v_rcp_f32_e32 v131, v131
	s_nop 0
	v_mul_f32_e32 v131, v79, v131
	v_mul_f32_e32 v131, 0x3fb8aa3b, v131
	v_cvt_pk_bf16_f32 v131, v131, 0
	v_lshlrev_b32_e32 v131, 16, v131
	v_add_f32_e32 v137, v131, v131
	v_mul_f32_e32 v138, 0x3f317218, v137
	v_cmp_nlt_f32_e32 vcc, s74, v138
	s_and_saveexec_b64 s[56:57], vcc
	s_xor_b64 s[56:57], exec, s[56:57]
	v_exp_f32_e32 v137, v131
	s_nop 0
	v_fma_f32 v137, -v137, v137, 1.0
	s_andn2_saveexec_b64 s[56:57], s[56:57]
	v_fmamk_f32 v137, v138, 0x3d2aaaab, v208
	v_fma_f32 v137, v138, v137, 0.5
	v_fma_f32 v137, v138, v137, 1.0
	v_mul_f32_e64 v137, v138, -v137
	s_or_b64 exec, exec, s[56:57]
	v_add_f32_e32 v126, v126, v70
	v_mul_f32_e32 v126, 0xbfb8aa3b, v126
	v_exp_f32_e32 v126, v126
	v_add_f32_e32 v124, v124, v68
	v_mul_f32_e32 v124, 0xbfb8aa3b, v124
	v_exp_f32_e32 v124, v124
	v_add_f32_e32 v125, v125, v69
	v_add_f32_e32 v127, v127, v71
	v_add_f32_e32 v126, 1.0, v126
	v_mul_f32_e32 v125, 0xbfb8aa3b, v125
	v_rcp_f32_e32 v126, v126
	v_mul_f32_e32 v127, 0xbfb8aa3b, v127
	v_exp_f32_e32 v125, v125
	v_sqrt_f32_e32 v136, v136
	v_exp_f32_e32 v127, v127
	v_add_f32_e32 v124, 1.0, v124
	v_rcp_f32_e32 v124, v124
	v_lshlrev_b32_e32 v138, 16, v199
	v_add_f32_e32 v120, v120, v80
	v_mul_f32_e32 v126, v126, v138
	v_sqrt_f32_e32 v134, v134
	v_add_f32_e32 v125, 1.0, v125
	v_mul_f32_e32 v120, 0xbfb8aa3b, v120
	v_mul_f32_e32 v136, v126, v136
	v_add_f32_e32 v126, 1.0, v127
	v_lshlrev_b32_e32 v127, 16, v198
	v_rcp_f32_e32 v125, v125
	v_exp_f32_e32 v120, v120
	v_mul_f32_e32 v124, v124, v127
	v_sqrt_f32_e32 v127, v135
	v_mul_f32_e32 v134, v124, v134
	v_and_b32_e32 v124, 0xffff0000, v198
	v_rcp_f32_e32 v126, v126
	v_mul_f32_e32 v124, v125, v124
	v_add_f32_e32 v120, 1.0, v120
	v_mul_f32_e32 v135, v124, v127
	v_sqrt_f32_e32 v127, v137
	v_rcp_f32_e32 v120, v120
	v_and_b32_e32 v137, 0xffff0000, v199
	v_lshlrev_b64 v[124:125], 11, v[196:197]
	v_mul_f32_e32 v126, v126, v137
	v_mul_f32_e32 v137, v126, v127
	v_lshl_add_u64 v[126:127], v[124:125], 0, v[152:153]
	v_mul_f32_e32 v120, v76, v120
	v_lshlrev_b64 v[126:127], 1, v[126:127]
	v_mul_f32_e32 v120, 0x3fb8aa3b, v120
	v_cvt_pk_bf16_f32 v128, v128, v129
	v_cvt_pk_bf16_f32 v129, v130, v131
	v_lshl_add_u64 v[130:131], s[16:17], 0, v[126:127]
; __device__ __forceinline__ float bf_lo(unsigned w) { return __uint_as_float(w << 16); }
; __device__ __forceinline__ float bf_hi(unsigned w) { return __uint_as_float(w & 0xffff0000u); }
; __device__ __forceinline__ float fast_sigmoid(float x) { return __builtin_amdgcn_rcpf(1.0f + __builtin_amdgcn_exp2f(-x * LOG2E)); }
;     __device__ __forceinline__ void operator()(const f32x4 (&acc)[2][2][4][2], const Unit& u, int wr, int wc, int fr, int fq) const {
;     ...
;                 for (int m = 0; m < 4; ++m) { const int row = row0 + ai * HALF + m * 16; const size_t off = (size_t)row * DM + ch0 + n * 16;
;                     const u32x2 xw = xall[ai * 4 + m];
;                     const float xv[4] = {bf_lo(xw.x), bf_hi(xw.x), bf_lo(xw.y), bf_hi(xw.y)};
;                     f32x4 av; float bv[4];
; #pragma unroll
;                     for (int j = 0; j < 4; ++j) { const float r = fast_sigmoid(acc[ai][0][m][n][j] + ba[j]), ig = fast_sigmoid(acc[ai][1][m][n][j] + bx[j]);
;                         const float la = sp[j] * r; const float la2 = __uint_as_float(pk_bf16(la * LOG2E, 0.f) << 16);
;                         const float a = __builtin_amdgcn_exp2f(la2); const float x2 = 2.0f * la2 * 0.6931471805599453f; av[j] = la2;
;                         const float om = (x2 > -0.03f) ? -(x2 * (1.0f + x2 * (0.5f + x2 * (1.0f / 6.0f + x2 * (1.0f / 24.0f))))) : (1.0f - a * a);
;                         bv[j] = __builtin_amdgcn_sqrtf(om) * (ig * xv[j]); }
;                     { u32x2 wa; wa.x = pk_bf16(av[0], av[1]); wa.y = pk_bf16(av[2], av[3]); *(u32x2*)(aout + off) = wa; }
;                     u32x2 w; w.x = pk_bf16(bv[0], bv[1]); w.y = pk_bf16(bv[2], bv[3]); *(u32x2*)(bout + off) = w; }
	v_cvt_pk_bf16_f32 v120, v120, 0
	global_store_dwordx2 v[130:131], v[128:129], off
	v_cvt_pk_bf16_f32 v128, v134, v135
	v_cvt_pk_bf16_f32 v129, v136, v137
	v_lshl_add_u64 v[126:127], s[18:19], 0, v[126:127]
	v_lshlrev_b32_e32 v120, 16, v120
	global_store_dwordx2 v[126:127], v[128:129], off
	v_add_f32_e32 v126, v120, v120
	v_mul_f32_e32 v127, 0x3f317218, v126
	v_cmp_nlt_f32_e32 vcc, s74, v127
	s_and_saveexec_b64 s[56:57], vcc
	s_xor_b64 s[56:57], exec, s[56:57]
	v_exp_f32_e32 v126, v120
	s_nop 0
	v_fma_f32 v126, -v126, v126, 1.0
	s_andn2_saveexec_b64 s[56:57], s[56:57]
	v_fmamk_f32 v126, v127, 0x3d2aaaab, v208
	v_fma_f32 v126, v127, v126, 0.5
	v_fma_f32 v126, v127, v126, 1.0
	v_mul_f32_e64 v126, v127, -v126
	s_or_b64 exec, exec, s[56:57]
	v_add_f32_e32 v121, v121, v81
	v_mul_f32_e32 v121, 0xbfb8aa3b, v121
	v_exp_f32_e32 v121, v121
	s_nop 0
	v_add_f32_e32 v121, 1.0, v121
	v_rcp_f32_e32 v121, v121
	s_nop 0
	v_mul_f32_e32 v121, v77, v121
	v_mul_f32_e32 v121, 0x3fb8aa3b, v121
	v_cvt_pk_bf16_f32 v121, v121, 0
	v_lshlrev_b32_e32 v121, 16, v121
	v_add_f32_e32 v127, v121, v121
	v_mul_f32_e32 v128, 0x3f317218, v127
	v_cmp_nlt_f32_e32 vcc, s74, v128
	s_and_saveexec_b64 s[56:57], vcc
	s_xor_b64 s[56:57], exec, s[56:57]
	v_exp_f32_e32 v127, v121
	s_nop 0
	v_fma_f32 v127, -v127, v127, 1.0
	s_andn2_saveexec_b64 s[56:57], s[56:57]
	v_fmamk_f32 v127, v128, 0x3d2aaaab, v208
	v_fma_f32 v127, v128, v127, 0.5
	v_fma_f32 v127, v128, v127, 1.0
	v_mul_f32_e64 v127, v128, -v127
	s_or_b64 exec, exec, s[56:57]
	v_add_f32_e32 v122, v122, v82
	v_mul_f32_e32 v122, 0xbfb8aa3b, v122
	v_exp_f32_e32 v122, v122
	s_nop 0
	v_add_f32_e32 v122, 1.0, v122
	v_rcp_f32_e32 v122, v122
	s_nop 0
	v_mul_f32_e32 v122, v78, v122
	v_mul_f32_e32 v122, 0x3fb8aa3b, v122
	v_cvt_pk_bf16_f32 v122, v122, 0
	v_lshlrev_b32_e32 v122, 16, v122
	v_add_f32_e32 v128, v122, v122
	v_mul_f32_e32 v129, 0x3f317218, v128
	v_cmp_nlt_f32_e32 vcc, s74, v129
	s_and_saveexec_b64 s[56:57], vcc
	s_xor_b64 s[56:57], exec, s[56:57]
	v_exp_f32_e32 v128, v122
	s_nop 0
	v_fma_f32 v128, -v128, v128, 1.0
	s_andn2_saveexec_b64 s[56:57], s[56:57]
	v_fmamk_f32 v128, v129, 0x3d2aaaab, v208
	v_fma_f32 v128, v129, v128, 0.5
	v_fma_f32 v128, v129, v128, 1.0
	v_mul_f32_e64 v128, v129, -v128
	s_or_b64 exec, exec, s[56:57]
	v_add_f32_e32 v123, v123, v83
	v_mul_f32_e32 v123, 0xbfb8aa3b, v123
	v_exp_f32_e32 v123, v123
	s_nop 0
	v_add_f32_e32 v123, 1.0, v123
	v_rcp_f32_e32 v123, v123
	s_nop 0
	v_mul_f32_e32 v123, v79, v123
	v_mul_f32_e32 v123, 0x3fb8aa3b, v123
	v_cvt_pk_bf16_f32 v123, v123, 0
	v_lshlrev_b32_e32 v123, 16, v123
	v_add_f32_e32 v129, v123, v123
	v_mul_f32_e32 v130, 0x3f317218, v129
	v_cmp_nlt_f32_e32 vcc, s74, v130
	s_and_saveexec_b64 s[56:57], vcc
	s_xor_b64 s[56:57], exec, s[56:57]
	v_exp_f32_e32 v129, v123
	s_nop 0
	v_fma_f32 v129, -v129, v129, 1.0
	s_andn2_saveexec_b64 s[56:57], s[56:57]
	v_fmamk_f32 v129, v130, 0x3d2aaaab, v208
	v_fma_f32 v129, v130, v129, 0.5
	v_fma_f32 v129, v130, v129, 1.0
	v_mul_f32_e64 v129, v130, -v129
	s_or_b64 exec, exec, s[56:57]
	v_add_f32_e32 v118, v118, v70
	v_mul_f32_e32 v118, 0xbfb8aa3b, v118
	v_exp_f32_e32 v118, v118
	v_add_f32_e32 v116, v116, v68
	v_mul_f32_e32 v116, 0xbfb8aa3b, v116
	v_exp_f32_e32 v116, v116
	v_add_f32_e32 v117, v117, v69
	v_add_f32_e32 v119, v119, v71
	v_add_f32_e32 v118, 1.0, v118
	v_mul_f32_e32 v117, 0xbfb8aa3b, v117
	v_rcp_f32_e32 v118, v118
	v_mul_f32_e32 v119, 0xbfb8aa3b, v119
	v_exp_f32_e32 v117, v117
	v_sqrt_f32_e32 v128, v128
	v_exp_f32_e32 v119, v119
	v_add_f32_e32 v116, 1.0, v116
	v_rcp_f32_e32 v116, v116
	v_lshlrev_b32_e32 v130, 16, v195
	v_add_f32_e32 v112, v112, v80
	v_mul_f32_e32 v118, v118, v130
	v_sqrt_f32_e32 v126, v126
	v_add_f32_e32 v117, 1.0, v117
	v_mul_f32_e32 v112, 0xbfb8aa3b, v112
	v_mul_f32_e32 v128, v118, v128
	v_add_f32_e32 v118, 1.0, v119
	v_lshlrev_b32_e32 v119, 16, v194
	v_rcp_f32_e32 v117, v117
	v_exp_f32_e32 v112, v112
	v_mul_f32_e32 v116, v116, v119
	v_sqrt_f32_e32 v119, v127
	v_mul_f32_e32 v126, v116, v126
	v_and_b32_e32 v116, 0xffff0000, v194
	v_rcp_f32_e32 v118, v118
	v_mul_f32_e32 v116, v117, v116
	v_add_f32_e32 v112, 1.0, v112
	v_mul_f32_e32 v127, v116, v119
	v_sqrt_f32_e32 v119, v129
	v_rcp_f32_e32 v112, v112
	v_and_b32_e32 v129, 0xffff0000, v195
	v_lshlrev_b64 v[116:117], 11, v[192:193]
	v_mul_f32_e32 v118, v118, v129
	v_mul_f32_e32 v129, v118, v119
	v_lshl_add_u64 v[118:119], v[116:117], 0, v[152:153]
	v_mul_f32_e32 v112, v76, v112
	v_lshlrev_b64 v[118:119], 1, v[118:119]
	v_mul_f32_e32 v112, 0x3fb8aa3b, v112
	v_cvt_pk_bf16_f32 v120, v120, v121
	v_cvt_pk_bf16_f32 v121, v122, v123
	v_lshl_add_u64 v[122:123], s[16:17], 0, v[118:119]
	v_cvt_pk_bf16_f32 v112, v112, 0
	global_store_dwordx2 v[122:123], v[120:121], off
	v_cvt_pk_bf16_f32 v120, v126, v127
	v_cvt_pk_bf16_f32 v121, v128, v129
	v_lshl_add_u64 v[118:119], s[18:19], 0, v[118:119]
	v_lshlrev_b32_e32 v112, 16, v112
	global_store_dwordx2 v[118:119], v[120:121], off
	v_add_f32_e32 v118, v112, v112
	v_mul_f32_e32 v119, 0x3f317218, v118
	v_cmp_nlt_f32_e32 vcc, s74, v119
	s_and_saveexec_b64 s[56:57], vcc
	s_xor_b64 s[56:57], exec, s[56:57]
	v_exp_f32_e32 v118, v112
	s_nop 0
	v_fma_f32 v118, -v118, v118, 1.0
	s_andn2_saveexec_b64 s[56:57], s[56:57]
	v_fmamk_f32 v118, v119, 0x3d2aaaab, v208
	v_fma_f32 v118, v119, v118, 0.5
	v_fma_f32 v118, v119, v118, 1.0
	v_mul_f32_e64 v118, v119, -v118
	s_or_b64 exec, exec, s[56:57]
	v_add_f32_e32 v113, v113, v81
	v_mul_f32_e32 v113, 0xbfb8aa3b, v113
	v_exp_f32_e32 v113, v113
	s_nop 0
	v_add_f32_e32 v113, 1.0, v113
	v_rcp_f32_e32 v113, v113
	s_nop 0
	v_mul_f32_e32 v113, v77, v113
	v_mul_f32_e32 v113, 0x3fb8aa3b, v113
	v_cvt_pk_bf16_f32 v113, v113, 0
; __device__ __forceinline__ float bf_lo(unsigned w) { return __uint_as_float(w << 16); }
; __device__ __forceinline__ float bf_hi(unsigned w) { return __uint_as_float(w & 0xffff0000u); }
; __device__ __forceinline__ float fast_sigmoid(float x) { return __builtin_amdgcn_rcpf(1.0f + __builtin_amdgcn_exp2f(-x * LOG2E)); }
;     __device__ __forceinline__ void operator()(const f32x4 (&acc)[2][2][4][2], const Unit& u, int wr, int wc, int fr, int fq) const {
;     ...
;                 for (int m = 0; m < 4; ++m) { const int row = row0 + ai * HALF + m * 16; const size_t off = (size_t)row * DM + ch0 + n * 16;
;                     const u32x2 xw = xall[ai * 4 + m];
;                     const float xv[4] = {bf_lo(xw.x), bf_hi(xw.x), bf_lo(xw.y), bf_hi(xw.y)};
;                     f32x4 av; float bv[4];
; #pragma unroll
;                     for (int j = 0; j < 4; ++j) { const float r = fast_sigmoid(acc[ai][0][m][n][j] + ba[j]), ig = fast_sigmoid(acc[ai][1][m][n][j] + bx[j]);
;                         const float la = sp[j] * r; const float la2 = __uint_as_float(pk_bf16(la * LOG2E, 0.f) << 16);
;                         const float a = __builtin_amdgcn_exp2f(la2); const float x2 = 2.0f * la2 * 0.6931471805599453f; av[j] = la2;
;                         const float om = (x2 > -0.03f) ? -(x2 * (1.0f + x2 * (0.5f + x2 * (1.0f / 6.0f + x2 * (1.0f / 24.0f))))) : (1.0f - a * a);
;                         bv[j] = __builtin_amdgcn_sqrtf(om) * (ig * xv[j]); }
;                     { u32x2 wa; wa.x = pk_bf16(av[0], av[1]); wa.y = pk_bf16(av[2], av[3]); *(u32x2*)(aout + off) = wa; }
;                     u32x2 w; w.x = pk_bf16(bv[0], bv[1]); w.y = pk_bf16(bv[2], bv[3]); *(u32x2*)(bout + off) = w; }
	v_lshlrev_b32_e32 v113, 16, v113
	v_add_f32_e32 v119, v113, v113
	v_mul_f32_e32 v120, 0x3f317218, v119
	v_cmp_nlt_f32_e32 vcc, s74, v120
	s_and_saveexec_b64 s[56:57], vcc
	s_xor_b64 s[56:57], exec, s[56:57]
	v_exp_f32_e32 v119, v113
	s_nop 0
	v_fma_f32 v119, -v119, v119, 1.0
	s_andn2_saveexec_b64 s[56:57], s[56:57]
	v_fmamk_f32 v119, v120, 0x3d2aaaab, v208
	v_fma_f32 v119, v120, v119, 0.5
	v_fma_f32 v119, v120, v119, 1.0
	v_mul_f32_e64 v119, v120, -v119
	s_or_b64 exec, exec, s[56:57]
	v_add_f32_e32 v114, v114, v82
	v_mul_f32_e32 v114, 0xbfb8aa3b, v114
	v_exp_f32_e32 v114, v114
	s_nop 0
	v_add_f32_e32 v114, 1.0, v114
	v_rcp_f32_e32 v114, v114
	s_nop 0
	v_mul_f32_e32 v114, v78, v114
	v_mul_f32_e32 v114, 0x3fb8aa3b, v114
	v_cvt_pk_bf16_f32 v114, v114, 0
	v_lshlrev_b32_e32 v114, 16, v114
	v_add_f32_e32 v120, v114, v114
	v_mul_f32_e32 v121, 0x3f317218, v120
	v_cmp_nlt_f32_e32 vcc, s74, v121
	s_and_saveexec_b64 s[56:57], vcc
	s_xor_b64 s[56:57], exec, s[56:57]
	v_exp_f32_e32 v120, v114
	s_nop 0
	v_fma_f32 v120, -v120, v120, 1.0
	s_andn2_saveexec_b64 s[56:57], s[56:57]
	v_fmamk_f32 v120, v121, 0x3d2aaaab, v208
	v_fma_f32 v120, v121, v120, 0.5
	v_fma_f32 v120, v121, v120, 1.0
	v_mul_f32_e64 v120, v121, -v120
	s_or_b64 exec, exec, s[56:57]
	v_add_f32_e32 v115, v115, v83
	v_mul_f32_e32 v115, 0xbfb8aa3b, v115
	v_exp_f32_e32 v115, v115
	s_nop 0
	v_add_f32_e32 v115, 1.0, v115
	v_rcp_f32_e32 v115, v115
	s_nop 0
	v_mul_f32_e32 v115, v79, v115
	v_mul_f32_e32 v115, 0x3fb8aa3b, v115
	v_cvt_pk_bf16_f32 v115, v115, 0
	v_lshlrev_b32_e32 v115, 16, v115
	v_add_f32_e32 v121, v115, v115
	v_mul_f32_e32 v122, 0x3f317218, v121
	v_cmp_nlt_f32_e32 vcc, s74, v122
	s_and_saveexec_b64 s[56:57], vcc
	s_xor_b64 s[56:57], exec, s[56:57]
	v_exp_f32_e32 v121, v115
	s_nop 0
	v_fma_f32 v121, -v121, v121, 1.0
	s_andn2_saveexec_b64 s[56:57], s[56:57]
	v_fmamk_f32 v121, v122, 0x3d2aaaab, v208
	v_fma_f32 v121, v122, v121, 0.5
	v_fma_f32 v121, v122, v121, 1.0
	v_mul_f32_e64 v121, v122, -v121
	s_or_b64 exec, exec, s[56:57]
	v_add_f32_e32 v110, v110, v70
	v_mul_f32_e32 v110, 0xbfb8aa3b, v110
	v_exp_f32_e32 v110, v110
	v_add_f32_e32 v108, v108, v68
	v_mul_f32_e32 v108, 0xbfb8aa3b, v108
	v_exp_f32_e32 v108, v108
	v_add_f32_e32 v109, v109, v69
	v_add_f32_e32 v111, v111, v71
	v_add_f32_e32 v110, 1.0, v110
	v_mul_f32_e32 v109, 0xbfb8aa3b, v109
	v_rcp_f32_e32 v110, v110
	v_mul_f32_e32 v111, 0xbfb8aa3b, v111
	v_exp_f32_e32 v109, v109
	v_sqrt_f32_e32 v120, v120
	v_exp_f32_e32 v111, v111
	v_add_f32_e32 v108, 1.0, v108
	v_rcp_f32_e32 v108, v108
	v_lshlrev_b32_e32 v122, 16, v191
	v_add_f32_e32 v104, v104, v80
	v_mul_f32_e32 v110, v110, v122
	v_sqrt_f32_e32 v118, v118
	v_add_f32_e32 v109, 1.0, v109
	v_mul_f32_e32 v104, 0xbfb8aa3b, v104
	v_mul_f32_e32 v120, v110, v120
	v_add_f32_e32 v110, 1.0, v111
	v_lshlrev_b32_e32 v111, 16, v190
	v_rcp_f32_e32 v109, v109
	v_exp_f32_e32 v104, v104
	v_mul_f32_e32 v108, v108, v111
	v_sqrt_f32_e32 v111, v119
	v_mul_f32_e32 v118, v108, v118
	v_and_b32_e32 v108, 0xffff0000, v190
	v_rcp_f32_e32 v110, v110
	v_mul_f32_e32 v108, v109, v108
	v_add_f32_e32 v104, 1.0, v104
	v_mul_f32_e32 v119, v108, v111
	v_sqrt_f32_e32 v111, v121
	v_rcp_f32_e32 v104, v104
	v_and_b32_e32 v121, 0xffff0000, v191
	v_lshlrev_b64 v[108:109], 11, v[188:189]
	v_mul_f32_e32 v110, v110, v121
	v_mul_f32_e32 v121, v110, v111
	v_lshl_add_u64 v[110:111], v[108:109], 0, v[152:153]
	v_mul_f32_e32 v104, v76, v104
	v_lshlrev_b64 v[110:111], 1, v[110:111]
	v_mul_f32_e32 v104, 0x3fb8aa3b, v104
	v_cvt_pk_bf16_f32 v112, v112, v113
	v_cvt_pk_bf16_f32 v113, v114, v115
	v_lshl_add_u64 v[114:115], s[16:17], 0, v[110:111]
	v_cvt_pk_bf16_f32 v104, v104, 0
	global_store_dwordx2 v[114:115], v[112:113], off
	v_cvt_pk_bf16_f32 v112, v118, v119
	v_cvt_pk_bf16_f32 v113, v120, v121
	v_lshl_add_u64 v[110:111], s[18:19], 0, v[110:111]
	v_lshlrev_b32_e32 v104, 16, v104
	global_store_dwordx2 v[110:111], v[112:113], off
	v_add_f32_e32 v110, v104, v104
	v_mul_f32_e32 v111, 0x3f317218, v110
	v_cmp_nlt_f32_e32 vcc, s74, v111
	s_and_saveexec_b64 s[56:57], vcc
	s_xor_b64 s[56:57], exec, s[56:57]
	v_exp_f32_e32 v110, v104
	s_nop 0
	v_fma_f32 v110, -v110, v110, 1.0
	s_andn2_saveexec_b64 s[56:57], s[56:57]
	v_fmamk_f32 v110, v111, 0x3d2aaaab, v208
	v_fma_f32 v110, v111, v110, 0.5
	v_fma_f32 v110, v111, v110, 1.0
	v_mul_f32_e64 v110, v111, -v110
	s_or_b64 exec, exec, s[56:57]
	v_add_f32_e32 v105, v105, v81
	v_mul_f32_e32 v105, 0xbfb8aa3b, v105
	v_exp_f32_e32 v105, v105
	s_nop 0
	v_add_f32_e32 v105, 1.0, v105
	v_rcp_f32_e32 v105, v105
	s_nop 0
	v_mul_f32_e32 v105, v77, v105
	v_mul_f32_e32 v105, 0x3fb8aa3b, v105
	v_cvt_pk_bf16_f32 v105, v105, 0
	v_lshlrev_b32_e32 v105, 16, v105
	v_add_f32_e32 v111, v105, v105
	v_mul_f32_e32 v112, 0x3f317218, v111
	v_cmp_nlt_f32_e32 vcc, s74, v112
	s_and_saveexec_b64 s[56:57], vcc
	s_xor_b64 s[56:57], exec, s[56:57]
	v_exp_f32_e32 v111, v105
	s_nop 0
	v_fma_f32 v111, -v111, v111, 1.0
	s_andn2_saveexec_b64 s[56:57], s[56:57]
	v_fmamk_f32 v111, v112, 0x3d2aaaab, v208
	v_fma_f32 v111, v112, v111, 0.5
	v_fma_f32 v111, v112, v111, 1.0
	v_mul_f32_e64 v111, v112, -v111
	s_or_b64 exec, exec, s[56:57]
	v_add_f32_e32 v106, v106, v82
	v_mul_f32_e32 v106, 0xbfb8aa3b, v106
	v_exp_f32_e32 v106, v106
	s_nop 0
	v_add_f32_e32 v106, 1.0, v106
	v_rcp_f32_e32 v106, v106
	s_nop 0
	v_mul_f32_e32 v106, v78, v106
	v_mul_f32_e32 v106, 0x3fb8aa3b, v106
	v_cvt_pk_bf16_f32 v106, v106, 0
	v_lshlrev_b32_e32 v106, 16, v106
	v_add_f32_e32 v112, v106, v106
	v_mul_f32_e32 v113, 0x3f317218, v112
	v_cmp_nlt_f32_e32 vcc, s74, v113
	s_and_saveexec_b64 s[56:57], vcc
	s_xor_b64 s[56:57], exec, s[56:57]
	v_exp_f32_e32 v112, v106
	s_nop 0
; __device__ __forceinline__ float bf_lo(unsigned w) { return __uint_as_float(w << 16); }
; __device__ __forceinline__ float bf_hi(unsigned w) { return __uint_as_float(w & 0xffff0000u); }
; __device__ __forceinline__ float fast_sigmoid(float x) { return __builtin_amdgcn_rcpf(1.0f + __builtin_amdgcn_exp2f(-x * LOG2E)); }
;     __device__ __forceinline__ void operator()(const f32x4 (&acc)[2][2][4][2], const Unit& u, int wr, int wc, int fr, int fq) const {
;     ...
;                 for (int m = 0; m < 4; ++m) { const int row = row0 + ai * HALF + m * 16; const size_t off = (size_t)row * DM + ch0 + n * 16;
;                     const u32x2 xw = xall[ai * 4 + m];
;                     const float xv[4] = {bf_lo(xw.x), bf_hi(xw.x), bf_lo(xw.y), bf_hi(xw.y)};
;                     f32x4 av; float bv[4];
; #pragma unroll
;                     for (int j = 0; j < 4; ++j) { const float r = fast_sigmoid(acc[ai][0][m][n][j] + ba[j]), ig = fast_sigmoid(acc[ai][1][m][n][j] + bx[j]);
;                         const float la = sp[j] * r; const float la2 = __uint_as_float(pk_bf16(la * LOG2E, 0.f) << 16);
;                         const float a = __builtin_amdgcn_exp2f(la2); const float x2 = 2.0f * la2 * 0.6931471805599453f; av[j] = la2;
;                         const float om = (x2 > -0.03f) ? -(x2 * (1.0f + x2 * (0.5f + x2 * (1.0f / 6.0f + x2 * (1.0f / 24.0f))))) : (1.0f - a * a);
;                         bv[j] = __builtin_amdgcn_sqrtf(om) * (ig * xv[j]); }
;                     { u32x2 wa; wa.x = pk_bf16(av[0], av[1]); wa.y = pk_bf16(av[2], av[3]); *(u32x2*)(aout + off) = wa; }
;                     u32x2 w; w.x = pk_bf16(bv[0], bv[1]); w.y = pk_bf16(bv[2], bv[3]); *(u32x2*)(bout + off) = w; }
	v_fma_f32 v112, -v112, v112, 1.0
	s_andn2_saveexec_b64 s[56:57], s[56:57]
	v_fmamk_f32 v112, v113, 0x3d2aaaab, v208
	v_fma_f32 v112, v113, v112, 0.5
	v_fma_f32 v112, v113, v112, 1.0
	v_mul_f32_e64 v112, v113, -v112
	s_or_b64 exec, exec, s[56:57]
	v_add_f32_e32 v107, v107, v83
	v_mul_f32_e32 v107, 0xbfb8aa3b, v107
	v_exp_f32_e32 v107, v107
	s_nop 0
	v_add_f32_e32 v107, 1.0, v107
	v_rcp_f32_e32 v107, v107
	s_nop 0
	v_mul_f32_e32 v107, v79, v107
	v_mul_f32_e32 v107, 0x3fb8aa3b, v107
	v_cvt_pk_bf16_f32 v107, v107, 0
	v_lshlrev_b32_e32 v107, 16, v107
	v_add_f32_e32 v113, v107, v107
	v_mul_f32_e32 v114, 0x3f317218, v113
	v_cmp_nlt_f32_e32 vcc, s74, v114
	s_and_saveexec_b64 s[56:57], vcc
	s_xor_b64 s[56:57], exec, s[56:57]
	v_exp_f32_e32 v113, v107
	s_nop 0
	v_fma_f32 v113, -v113, v113, 1.0
	s_andn2_saveexec_b64 s[56:57], s[56:57]
	v_fmamk_f32 v113, v114, 0x3d2aaaab, v208
	v_fma_f32 v113, v114, v113, 0.5
	v_fma_f32 v113, v114, v113, 1.0
	v_mul_f32_e64 v113, v114, -v113
	s_or_b64 exec, exec, s[56:57]
	v_add_f32_e32 v102, v102, v70
	v_mul_f32_e32 v102, 0xbfb8aa3b, v102
	v_exp_f32_e32 v102, v102
	v_add_f32_e32 v100, v100, v68
	v_mul_f32_e32 v100, 0xbfb8aa3b, v100
	v_exp_f32_e32 v100, v100
	v_add_f32_e32 v101, v101, v69
	v_add_f32_e32 v103, v103, v71
	v_add_f32_e32 v102, 1.0, v102
	v_mul_f32_e32 v101, 0xbfb8aa3b, v101
	v_rcp_f32_e32 v102, v102
	v_mul_f32_e32 v103, 0xbfb8aa3b, v103
	v_exp_f32_e32 v101, v101
	v_sqrt_f32_e32 v112, v112
	v_exp_f32_e32 v103, v103
	v_add_f32_e32 v100, 1.0, v100
	v_rcp_f32_e32 v100, v100
	v_lshlrev_b32_e32 v114, 16, v187
	v_add_f32_e32 v96, v96, v80
	v_mul_f32_e32 v102, v102, v114
	v_sqrt_f32_e32 v110, v110
	v_add_f32_e32 v101, 1.0, v101
	v_mul_f32_e32 v96, 0xbfb8aa3b, v96
	v_mul_f32_e32 v112, v102, v112
	v_add_f32_e32 v102, 1.0, v103
	v_lshlrev_b32_e32 v103, 16, v186
	v_rcp_f32_e32 v101, v101
	v_exp_f32_e32 v96, v96
	v_mul_f32_e32 v100, v100, v103
	v_sqrt_f32_e32 v103, v111
	v_mul_f32_e32 v110, v100, v110
	v_and_b32_e32 v100, 0xffff0000, v186
	v_rcp_f32_e32 v102, v102
	v_mul_f32_e32 v100, v101, v100
	v_add_f32_e32 v96, 1.0, v96
	v_mul_f32_e32 v111, v100, v103
	v_sqrt_f32_e32 v103, v113
	v_rcp_f32_e32 v96, v96
	v_and_b32_e32 v113, 0xffff0000, v187
	v_lshlrev_b64 v[100:101], 11, v[184:185]
	v_mul_f32_e32 v102, v102, v113
	v_mul_f32_e32 v113, v102, v103
	v_lshl_add_u64 v[102:103], v[100:101], 0, v[152:153]
	v_mul_f32_e32 v96, v76, v96
	v_lshlrev_b64 v[102:103], 1, v[102:103]
	v_mul_f32_e32 v96, 0x3fb8aa3b, v96
	v_cvt_pk_bf16_f32 v104, v104, v105
	v_cvt_pk_bf16_f32 v105, v106, v107
	v_lshl_add_u64 v[106:107], s[16:17], 0, v[102:103]
	v_cvt_pk_bf16_f32 v96, v96, 0
	global_store_dwordx2 v[106:107], v[104:105], off
	v_cvt_pk_bf16_f32 v104, v110, v111
	v_cvt_pk_bf16_f32 v105, v112, v113
	v_lshl_add_u64 v[102:103], s[18:19], 0, v[102:103]
	v_lshlrev_b32_e32 v96, 16, v96
	global_store_dwordx2 v[102:103], v[104:105], off
	v_add_f32_e32 v102, v96, v96
	v_mul_f32_e32 v103, 0x3f317218, v102
	v_cmp_nlt_f32_e32 vcc, s74, v103
	s_and_saveexec_b64 s[56:57], vcc
	s_xor_b64 s[56:57], exec, s[56:57]
	v_exp_f32_e32 v102, v96
	s_nop 0
	v_fma_f32 v102, -v102, v102, 1.0
	s_andn2_saveexec_b64 s[56:57], s[56:57]
	v_fmamk_f32 v102, v103, 0x3d2aaaab, v208
	v_fma_f32 v102, v103, v102, 0.5
	v_fma_f32 v102, v103, v102, 1.0
	v_mul_f32_e64 v102, v103, -v102
	s_or_b64 exec, exec, s[56:57]
	v_add_f32_e32 v97, v97, v81
	v_mul_f32_e32 v97, 0xbfb8aa3b, v97
	v_exp_f32_e32 v97, v97
	s_nop 0
	v_add_f32_e32 v97, 1.0, v97
	v_rcp_f32_e32 v97, v97
	s_nop 0
	v_mul_f32_e32 v97, v77, v97
	v_mul_f32_e32 v97, 0x3fb8aa3b, v97
	v_cvt_pk_bf16_f32 v97, v97, 0
	v_lshlrev_b32_e32 v97, 16, v97
	v_add_f32_e32 v103, v97, v97
	v_mul_f32_e32 v104, 0x3f317218, v103
	v_cmp_nlt_f32_e32 vcc, s74, v104
	s_and_saveexec_b64 s[56:57], vcc
	s_xor_b64 s[56:57], exec, s[56:57]
	v_exp_f32_e32 v103, v97
	s_nop 0
	v_fma_f32 v103, -v103, v103, 1.0
	s_andn2_saveexec_b64 s[56:57], s[56:57]
	v_fmamk_f32 v103, v104, 0x3d2aaaab, v208
	v_fma_f32 v103, v104, v103, 0.5
	v_fma_f32 v103, v104, v103, 1.0
	v_mul_f32_e64 v103, v104, -v103
	s_or_b64 exec, exec, s[56:57]
	v_add_f32_e32 v98, v98, v82
	v_mul_f32_e32 v98, 0xbfb8aa3b, v98
	v_exp_f32_e32 v98, v98
	s_nop 0
	v_add_f32_e32 v98, 1.0, v98
	v_rcp_f32_e32 v98, v98
	s_nop 0
	v_mul_f32_e32 v98, v78, v98
	v_mul_f32_e32 v98, 0x3fb8aa3b, v98
	v_cvt_pk_bf16_f32 v98, v98, 0
	v_lshlrev_b32_e32 v98, 16, v98
	v_add_f32_e32 v104, v98, v98
	v_mul_f32_e32 v104, 0x3f317218, v104
	v_cmp_nlt_f32_e32 vcc, s74, v104
	s_and_saveexec_b64 s[56:57], vcc
	s_xor_b64 s[56:57], exec, s[56:57]
	v_exp_f32_e32 v104, v98
	s_nop 0
	v_fma_f32 v105, -v104, v104, 1.0
	s_andn2_saveexec_b64 s[56:57], s[56:57]
	v_fmamk_f32 v105, v104, 0x3d2aaaab, v208
	v_fma_f32 v105, v104, v105, 0.5
	v_fma_f32 v105, v104, v105, 1.0
	v_mul_f32_e64 v105, v104, -v105
	s_or_b64 exec, exec, s[56:57]
	v_add_f32_e32 v99, v99, v83
	v_mul_f32_e32 v99, 0xbfb8aa3b, v99
	v_exp_f32_e32 v99, v99
	s_nop 0
	v_add_f32_e32 v99, 1.0, v99
	v_rcp_f32_e32 v99, v99
	s_nop 0
	v_mul_f32_e32 v99, v79, v99
	v_mul_f32_e32 v99, 0x3fb8aa3b, v99
	v_cvt_pk_bf16_f32 v99, v99, 0
	v_lshlrev_b32_e32 v99, 16, v99
	v_add_f32_e32 v104, v99, v99
	v_mul_f32_e32 v106, 0x3f317218, v104
	v_cmp_nlt_f32_e32 vcc, s74, v106
	s_and_saveexec_b64 s[56:57], vcc
	s_xor_b64 s[56:57], exec, s[56:57]
	v_exp_f32_e32 v104, v99
	s_nop 0
	v_fma_f32 v104, -v104, v104, 1.0
	s_andn2_saveexec_b64 s[56:57], s[56:57]
	v_fmamk_f32 v104, v106, 0x3d2aaaab, v208
	v_fma_f32 v104, v106, v104, 0.5
	v_fma_f32 v104, v106, v104, 1.0
	v_mul_f32_e64 v104, v106, -v104
	s_or_b64 exec, exec, s[56:57]
	v_add_f32_e32 v94, v94, v70
	v_mul_f32_e32 v94, 0xbfb8aa3b, v94
	v_exp_f32_e32 v94, v94
; __device__ __forceinline__ float bf_lo(unsigned w) { return __uint_as_float(w << 16); }
; __device__ __forceinline__ float bf_hi(unsigned w) { return __uint_as_float(w & 0xffff0000u); }
; __device__ __forceinline__ float fast_sigmoid(float x) { return __builtin_amdgcn_rcpf(1.0f + __builtin_amdgcn_exp2f(-x * LOG2E)); }
;     __device__ __forceinline__ void operator()(const f32x4 (&acc)[2][2][4][2], const Unit& u, int wr, int wc, int fr, int fq) const {
;     ...
;                 for (int m = 0; m < 4; ++m) { const int row = row0 + ai * HALF + m * 16; const size_t off = (size_t)row * DM + ch0 + n * 16;
;                     const u32x2 xw = xall[ai * 4 + m];
;                     const float xv[4] = {bf_lo(xw.x), bf_hi(xw.x), bf_lo(xw.y), bf_hi(xw.y)};
;                     f32x4 av; float bv[4];
; #pragma unroll
;                     for (int j = 0; j < 4; ++j) { const float r = fast_sigmoid(acc[ai][0][m][n][j] + ba[j]), ig = fast_sigmoid(acc[ai][1][m][n][j] + bx[j]);
;                         const float la = sp[j] * r; const float la2 = __uint_as_float(pk_bf16(la * LOG2E, 0.f) << 16);
;                         const float a = __builtin_amdgcn_exp2f(la2); const float x2 = 2.0f * la2 * 0.6931471805599453f; av[j] = la2;
;                         const float om = (x2 > -0.03f) ? -(x2 * (1.0f + x2 * (0.5f + x2 * (1.0f / 6.0f + x2 * (1.0f / 24.0f))))) : (1.0f - a * a);
;                         bv[j] = __builtin_amdgcn_sqrtf(om) * (ig * xv[j]); }
;                     { u32x2 wa; wa.x = pk_bf16(av[0], av[1]); wa.y = pk_bf16(av[2], av[3]); *(u32x2*)(aout + off) = wa; }
;                     u32x2 w; w.x = pk_bf16(bv[0], bv[1]); w.y = pk_bf16(bv[2], bv[3]); *(u32x2*)(bout + off) = w; }
	v_add_f32_e32 v92, v92, v68
	v_mul_f32_e32 v92, 0xbfb8aa3b, v92
	v_exp_f32_e32 v92, v92
	v_add_f32_e32 v93, v93, v69
	v_add_f32_e32 v95, v95, v71
	v_add_f32_e32 v94, 1.0, v94
	v_mul_f32_e32 v93, 0xbfb8aa3b, v93
	v_rcp_f32_e32 v94, v94
	v_mul_f32_e32 v95, 0xbfb8aa3b, v95
	v_exp_f32_e32 v93, v93
	v_sqrt_f32_e32 v105, v105
	v_exp_f32_e32 v95, v95
	v_add_f32_e32 v92, 1.0, v92
	v_rcp_f32_e32 v92, v92
	v_lshlrev_b32_e32 v106, 16, v183
	v_add_f32_e32 v88, v88, v80
	v_mul_f32_e32 v94, v94, v106
	v_sqrt_f32_e32 v102, v102
	v_add_f32_e32 v93, 1.0, v93
	v_mul_f32_e32 v88, 0xbfb8aa3b, v88
	v_mul_f32_e32 v105, v94, v105
	v_add_f32_e32 v94, 1.0, v95
	v_lshlrev_b32_e32 v95, 16, v182
	v_rcp_f32_e32 v93, v93
	v_exp_f32_e32 v88, v88
	v_mul_f32_e32 v92, v92, v95
	v_sqrt_f32_e32 v95, v103
	v_mul_f32_e32 v102, v92, v102
	v_and_b32_e32 v92, 0xffff0000, v182
	v_rcp_f32_e32 v94, v94
	v_mul_f32_e32 v92, v93, v92
	v_add_f32_e32 v88, 1.0, v88
	v_mul_f32_e32 v103, v92, v95
	v_sqrt_f32_e32 v95, v104
	v_rcp_f32_e32 v88, v88
	v_lshlrev_b64 v[92:93], 11, v[164:165]
	v_and_b32_e32 v104, 0xffff0000, v183
	v_lshl_add_u64 v[92:93], v[92:93], 0, s[40:41]
	v_mul_f32_e32 v94, v94, v104
	v_mul_f32_e32 v104, v94, v95
	v_lshl_add_u64 v[94:95], v[92:93], 0, v[152:153]
	v_mul_f32_e32 v88, v76, v88
	v_lshlrev_b64 v[94:95], 1, v[94:95]
	v_mul_f32_e32 v88, 0x3fb8aa3b, v88
	v_cvt_pk_bf16_f32 v96, v96, v97
	v_cvt_pk_bf16_f32 v97, v98, v99
	v_lshl_add_u64 v[98:99], s[16:17], 0, v[94:95]
	v_cvt_pk_bf16_f32 v88, v88, 0
	global_store_dwordx2 v[98:99], v[96:97], off
	v_cvt_pk_bf16_f32 v96, v102, v103
	v_cvt_pk_bf16_f32 v97, v105, v104
	v_lshl_add_u64 v[94:95], s[18:19], 0, v[94:95]
	v_lshlrev_b32_e32 v88, 16, v88
	global_store_dwordx2 v[94:95], v[96:97], off
	v_add_f32_e32 v94, v88, v88
	v_mul_f32_e32 v95, 0x3f317218, v94
	v_cmp_nlt_f32_e32 vcc, s74, v95
	s_and_saveexec_b64 s[56:57], vcc
	s_xor_b64 s[56:57], exec, s[56:57]
	v_exp_f32_e32 v94, v88
	s_nop 0
	v_fma_f32 v94, -v94, v94, 1.0
	s_andn2_saveexec_b64 s[56:57], s[56:57]
	v_fmamk_f32 v94, v95, 0x3d2aaaab, v208
	v_fma_f32 v94, v95, v94, 0.5
	v_fma_f32 v94, v95, v94, 1.0
	v_mul_f32_e64 v94, v95, -v94
	s_or_b64 exec, exec, s[56:57]
	v_add_f32_e32 v89, v89, v81
	v_mul_f32_e32 v89, 0xbfb8aa3b, v89
	v_exp_f32_e32 v89, v89
	s_nop 0
	v_add_f32_e32 v89, 1.0, v89
	v_rcp_f32_e32 v89, v89
	s_nop 0
	v_mul_f32_e32 v89, v77, v89
	v_mul_f32_e32 v89, 0x3fb8aa3b, v89
	v_cvt_pk_bf16_f32 v89, v89, 0
	v_lshlrev_b32_e32 v89, 16, v89
	v_add_f32_e32 v95, v89, v89
	v_mul_f32_e32 v96, 0x3f317218, v95
	v_cmp_nlt_f32_e32 vcc, s74, v96
	s_and_saveexec_b64 s[56:57], vcc
	s_xor_b64 s[56:57], exec, s[56:57]
	v_exp_f32_e32 v95, v89
	s_nop 0
	v_fma_f32 v95, -v95, v95, 1.0
	s_andn2_saveexec_b64 s[56:57], s[56:57]
	v_fmamk_f32 v95, v96, 0x3d2aaaab, v208
	v_fma_f32 v95, v96, v95, 0.5
	v_fma_f32 v95, v96, v95, 1.0
	v_mul_f32_e64 v95, v96, -v95
	s_or_b64 exec, exec, s[56:57]
	v_add_f32_e32 v90, v90, v82
	v_mul_f32_e32 v90, 0xbfb8aa3b, v90
	v_exp_f32_e32 v90, v90
	s_nop 0
	v_add_f32_e32 v90, 1.0, v90
	v_rcp_f32_e32 v90, v90
	s_nop 0
	v_mul_f32_e32 v90, v78, v90
	v_mul_f32_e32 v90, 0x3fb8aa3b, v90
	v_cvt_pk_bf16_f32 v90, v90, 0
	v_lshlrev_b32_e32 v90, 16, v90
	v_add_f32_e32 v96, v90, v90
	v_mul_f32_e32 v96, 0x3f317218, v96
	v_cmp_nlt_f32_e32 vcc, s74, v96
	s_and_saveexec_b64 s[56:57], vcc
	s_xor_b64 s[56:57], exec, s[56:57]
	v_exp_f32_e32 v96, v90
	s_nop 0
	v_fma_f32 v97, -v96, v96, 1.0
	s_andn2_saveexec_b64 s[56:57], s[56:57]
	v_fmamk_f32 v97, v96, 0x3d2aaaab, v208
	v_fma_f32 v97, v96, v97, 0.5
	v_fma_f32 v97, v96, v97, 1.0
	v_mul_f32_e64 v97, v96, -v97
	s_or_b64 exec, exec, s[56:57]
	v_add_f32_e32 v91, v91, v83
	v_mul_f32_e32 v91, 0xbfb8aa3b, v91
	v_exp_f32_e32 v91, v91
	s_nop 0
	v_add_f32_e32 v91, 1.0, v91
	v_rcp_f32_e32 v91, v91
	s_nop 0
	v_mul_f32_e32 v91, v79, v91
	v_mul_f32_e32 v91, 0x3fb8aa3b, v91
	v_cvt_pk_bf16_f32 v91, v91, 0
	v_lshlrev_b32_e32 v91, 16, v91
	v_add_f32_e32 v96, v91, v91
	v_mul_f32_e32 v98, 0x3f317218, v96
	v_cmp_nlt_f32_e32 vcc, s74, v98
	s_and_saveexec_b64 s[56:57], vcc
	s_xor_b64 s[56:57], exec, s[56:57]
	v_exp_f32_e32 v96, v91
	s_nop 0
	v_fma_f32 v96, -v96, v96, 1.0
	s_andn2_saveexec_b64 s[56:57], s[56:57]
	v_fmamk_f32 v96, v98, 0x3d2aaaab, v208
	v_fma_f32 v96, v98, v96, 0.5
	v_fma_f32 v96, v98, v96, 1.0
	v_mul_f32_e64 v96, v98, -v96
	s_or_b64 exec, exec, s[56:57]
	v_add_f32_e32 v86, v86, v70
	v_mul_f32_e32 v86, 0xbfb8aa3b, v86
	v_exp_f32_e32 v86, v86
	v_add_f32_e32 v84, v84, v68
	v_mul_f32_e32 v84, 0xbfb8aa3b, v84
	v_exp_f32_e32 v84, v84
	v_add_f32_e32 v85, v85, v69
	v_add_f32_e32 v87, v87, v71
	v_add_f32_e32 v86, 1.0, v86
	v_mul_f32_e32 v85, 0xbfb8aa3b, v85
	v_rcp_f32_e32 v86, v86
	v_mul_f32_e32 v87, 0xbfb8aa3b, v87
	v_exp_f32_e32 v85, v85
	v_add_f32_e32 v72, v72, v80
	v_sqrt_f32_e32 v97, v97
	v_exp_f32_e32 v87, v87
	v_add_f32_e32 v84, 1.0, v84
	v_mul_f32_e32 v72, 0xbfb8aa3b, v72
	v_rcp_f32_e32 v84, v84
	v_exp_f32_e32 v72, v72
	v_lshlrev_b32_e32 v98, 16, v181
	v_mul_f32_e32 v86, v86, v98
	v_sqrt_f32_e32 v94, v94
	v_add_f32_e32 v85, 1.0, v85
	v_mul_f32_e32 v97, v86, v97
	v_add_f32_e32 v86, 1.0, v87
	v_lshlrev_b32_e32 v87, 16, v180
	v_rcp_f32_e32 v85, v85
	v_mul_f32_e32 v84, v84, v87
	v_sqrt_f32_e32 v87, v95
	v_add_f32_e32 v72, 1.0, v72
	v_rcp_f32_e32 v72, v72
	v_mul_f32_e32 v94, v84, v94
	v_and_b32_e32 v84, 0xffff0000, v180
	v_rcp_f32_e32 v86, v86
	v_mul_f32_e32 v84, v85, v84
	v_mul_f32_e32 v95, v84, v87
	v_sqrt_f32_e32 v87, v96
	v_mul_f32_e32 v72, v76, v72
	v_lshlrev_b64 v[84:85], 11, v[164:165]
	v_and_b32_e32 v96, 0xffff0000, v181
	v_mul_f32_e32 v72, 0x3fb8aa3b, v72
	v_lshl_add_u64 v[84:85], v[84:85], 0, s[42:43]
	v_mul_f32_e32 v86, v86, v96
; __device__ __forceinline__ float bf_lo(unsigned w) { return __uint_as_float(w << 16); }
; __device__ __forceinline__ float bf_hi(unsigned w) { return __uint_as_float(w & 0xffff0000u); }
; __device__ __forceinline__ float fast_sigmoid(float x) { return __builtin_amdgcn_rcpf(1.0f + __builtin_amdgcn_exp2f(-x * LOG2E)); }
;     __device__ __forceinline__ void operator()(const f32x4 (&acc)[2][2][4][2], const Unit& u, int wr, int wc, int fr, int fq) const {
;     ...
; #pragma unroll
;         for (int n = 0; n < 2; ++n) {
;             const f32x4 ba = *(const f32x4*)(b_ga + ch0 + n * 16), bx = *(const f32x4*)(b_gx + ch0 + n * 16), sp = *(const f32x4*)(lam + ch0 + n * 16);
;             u32x2 xall[8];
; #pragma unroll
;             for (int it = 0; it < 8; ++it) xall[it] = *(const u32x2*)(xc + (size_t)(row0 + (it >> 2) * HALF + (it & 3) * 16) * DM + ch0 + n * 16);
;             asm volatile("" ::: "memory");
; #pragma unroll
;             for (int ai = 0; ai < 2; ++ai)
; #pragma unroll
;                 for (int m = 0; m < 4; ++m) { const int row = row0 + ai * HALF + m * 16; const size_t off = (size_t)row * DM + ch0 + n * 16;
;                     const u32x2 xw = xall[ai * 4 + m];
;                     const float xv[4] = {bf_lo(xw.x), bf_hi(xw.x), bf_lo(xw.y), bf_hi(xw.y)};
;                     f32x4 av; float bv[4];
; #pragma unroll
;                     for (int j = 0; j < 4; ++j) { const float r = fast_sigmoid(acc[ai][0][m][n][j] + ba[j]), ig = fast_sigmoid(acc[ai][1][m][n][j] + bx[j]);
;                         const float la = sp[j] * r; const float la2 = __uint_as_float(pk_bf16(la * LOG2E, 0.f) << 16);
;                         const float a = __builtin_amdgcn_exp2f(la2); const float x2 = 2.0f * la2 * 0.6931471805599453f; av[j] = la2;
;                         const float om = (x2 > -0.03f) ? -(x2 * (1.0f + x2 * (0.5f + x2 * (1.0f / 6.0f + x2 * (1.0f / 24.0f))))) : (1.0f - a * a);
;                         bv[j] = __builtin_amdgcn_sqrtf(om) * (ig * xv[j]); }
;                     { u32x2 wa; wa.x = pk_bf16(av[0], av[1]); wa.y = pk_bf16(av[2], av[3]); *(u32x2*)(aout + off) = wa; }
;                     u32x2 w; w.x = pk_bf16(bv[0], bv[1]); w.y = pk_bf16(bv[2], bv[3]); *(u32x2*)(bout + off) = w; }
	v_cvt_pk_bf16_f32 v72, v72, 0
	v_mul_f32_e32 v96, v86, v87
	v_lshl_add_u64 v[86:87], v[84:85], 0, v[152:153]
	v_lshlrev_b32_e32 v72, 16, v72
	v_lshlrev_b64 v[86:87], 1, v[86:87]
	v_add_f32_e32 v76, v72, v72
	v_cvt_pk_bf16_f32 v88, v88, v89
	v_cvt_pk_bf16_f32 v89, v90, v91
	v_lshl_add_u64 v[90:91], s[16:17], 0, v[86:87]
	v_mul_f32_e32 v80, 0x3f317218, v76
	global_store_dwordx2 v[90:91], v[88:89], off
	v_cvt_pk_bf16_f32 v88, v94, v95
	v_cvt_pk_bf16_f32 v89, v97, v96
	v_lshl_add_u64 v[86:87], s[18:19], 0, v[86:87]
	v_cmp_nlt_f32_e32 vcc, s74, v80
	global_store_dwordx2 v[86:87], v[88:89], off
	s_and_saveexec_b64 s[56:57], vcc
	s_xor_b64 s[56:57], exec, s[56:57]
	v_exp_f32_e32 v76, v72
	s_nop 0
	v_fma_f32 v76, -v76, v76, 1.0
	s_andn2_saveexec_b64 s[56:57], s[56:57]
	v_fmamk_f32 v76, v80, 0x3d2aaaab, v208
	v_fma_f32 v76, v80, v76, 0.5
	v_fma_f32 v76, v80, v76, 1.0
	v_mul_f32_e64 v76, v80, -v76
	s_or_b64 exec, exec, s[56:57]
	v_add_f32_e32 v73, v73, v81
	v_mul_f32_e32 v73, 0xbfb8aa3b, v73
	v_exp_f32_e32 v73, v73
	s_nop 0
	v_add_f32_e32 v73, 1.0, v73
	v_rcp_f32_e32 v73, v73
	s_nop 0
	v_mul_f32_e32 v73, v77, v73
	v_mul_f32_e32 v73, 0x3fb8aa3b, v73
	v_cvt_pk_bf16_f32 v73, v73, 0
	v_lshlrev_b32_e32 v73, 16, v73
	v_add_f32_e32 v77, v73, v73
	v_mul_f32_e32 v80, 0x3f317218, v77
	v_cmp_nlt_f32_e32 vcc, s74, v80
	s_and_saveexec_b64 s[56:57], vcc
	s_xor_b64 s[56:57], exec, s[56:57]
	v_exp_f32_e32 v77, v73
	s_nop 0
	v_fma_f32 v77, -v77, v77, 1.0
	s_andn2_saveexec_b64 s[56:57], s[56:57]
	v_fmamk_f32 v77, v80, 0x3d2aaaab, v208
	v_fma_f32 v77, v80, v77, 0.5
	v_fma_f32 v77, v80, v77, 1.0
	v_mul_f32_e64 v77, v80, -v77
	s_or_b64 exec, exec, s[56:57]
	v_add_f32_e32 v74, v74, v82
	v_mul_f32_e32 v74, 0xbfb8aa3b, v74
	v_exp_f32_e32 v74, v74
	s_nop 0
	v_add_f32_e32 v74, 1.0, v74
	v_rcp_f32_e32 v74, v74
	s_nop 0
	v_mul_f32_e32 v74, v78, v74
	v_mul_f32_e32 v74, 0x3fb8aa3b, v74
	v_cvt_pk_bf16_f32 v74, v74, 0
	v_lshlrev_b32_e32 v74, 16, v74
	v_add_f32_e32 v78, v74, v74
	v_mul_f32_e32 v78, 0x3f317218, v78
	v_cmp_nlt_f32_e32 vcc, s74, v78
	s_and_saveexec_b64 s[56:57], vcc
	s_xor_b64 s[56:57], exec, s[56:57]
	v_exp_f32_e32 v78, v74
	s_nop 0
	v_fma_f32 v80, -v78, v78, 1.0
	s_andn2_saveexec_b64 s[56:57], s[56:57]
	v_fmamk_f32 v80, v78, 0x3d2aaaab, v208
	v_fma_f32 v80, v78, v80, 0.5
	v_fma_f32 v80, v78, v80, 1.0
	v_mul_f32_e64 v80, v78, -v80
	s_or_b64 exec, exec, s[56:57]
	v_add_f32_e32 v75, v75, v83
	v_mul_f32_e32 v75, 0xbfb8aa3b, v75
	v_exp_f32_e32 v75, v75
	s_nop 0
	v_add_f32_e32 v75, 1.0, v75
	v_rcp_f32_e32 v75, v75
	s_nop 0
	v_mul_f32_e32 v75, v79, v75
	v_mul_f32_e32 v75, 0x3fb8aa3b, v75
	v_cvt_pk_bf16_f32 v75, v75, 0
	v_lshlrev_b32_e32 v75, 16, v75
	v_add_f32_e32 v78, v75, v75
	v_mul_f32_e32 v79, 0x3f317218, v78
	v_cmp_nlt_f32_e32 vcc, s74, v79
	s_and_saveexec_b64 s[56:57], vcc
	s_xor_b64 s[56:57], exec, s[56:57]
	v_exp_f32_e32 v78, v75
	s_nop 0
	v_fma_f32 v78, -v78, v78, 1.0
	s_andn2_saveexec_b64 s[56:57], s[56:57]
	v_fmamk_f32 v78, v79, 0x3d2aaaab, v208
	v_fma_f32 v78, v79, v78, 0.5
	v_fma_f32 v78, v79, v78, 1.0
	v_mul_f32_e64 v78, v79, -v78
	s_or_b64 exec, exec, s[56:57]
	v_add_f32_e32 v66, v66, v70
	v_mul_f32_e32 v66, 0xbfb8aa3b, v66
	v_exp_f32_e32 v66, v66
	v_add_f32_e32 v64, v64, v68
	v_mul_f32_e32 v64, 0xbfb8aa3b, v64
	v_exp_f32_e32 v64, v64
	v_add_f32_e32 v65, v65, v69
	v_add_f32_e32 v67, v67, v71
	v_add_f32_e32 v66, 1.0, v66
	v_mul_f32_e32 v65, 0xbfb8aa3b, v65
	v_rcp_f32_e32 v66, v66
	v_mul_f32_e32 v67, 0xbfb8aa3b, v67
	v_exp_f32_e32 v65, v65
	v_sqrt_f32_e32 v79, v80
	v_exp_f32_e32 v67, v67
	v_add_f32_e32 v64, 1.0, v64
	v_rcp_f32_e32 v64, v64
	v_lshlrev_b32_e32 v70, 16, v179
	v_mul_f32_e32 v66, v66, v70
	v_sqrt_f32_e32 v68, v76
	v_add_f32_e32 v65, 1.0, v65
	v_mul_f32_e32 v70, v66, v79
	v_add_f32_e32 v66, 1.0, v67
	v_lshlrev_b32_e32 v67, 16, v178
	v_rcp_f32_e32 v65, v65
	v_mul_f32_e32 v64, v64, v67
	v_sqrt_f32_e32 v67, v77
	v_mul_f32_e32 v71, v64, v68
	v_and_b32_e32 v64, 0xffff0000, v178
	v_rcp_f32_e32 v66, v66
	v_mul_f32_e32 v64, v65, v64
	v_mul_f32_e32 v79, v64, v67
	v_sqrt_f32_e32 v67, v78
	v_lshlrev_b64 v[64:65], 11, v[164:165]
	v_lshl_add_u64 v[76:77], v[64:65], 0, s[44:45]
	v_and_b32_e32 v64, 0xffff0000, v179
	v_mul_f32_e32 v64, v66, v64
	v_mul_f32_e32 v78, v64, v67
	v_lshl_add_u64 v[64:65], v[76:77], 0, v[152:153]
	v_lshlrev_b64 v[64:65], 1, v[64:65]
	v_cvt_pk_bf16_f32 v66, v72, v73
	v_cvt_pk_bf16_f32 v67, v74, v75
	v_lshl_add_u64 v[68:69], s[16:17], 0, v[64:65]
	global_store_dwordx2 v[68:69], v[66:67], off
	v_cvt_pk_bf16_f32 v66, v71, v79
	v_cvt_pk_bf16_f32 v67, v70, v78
	v_lshl_add_u64 v[64:65], s[18:19], 0, v[64:65]
	global_store_dwordx2 v[64:65], v[66:67], off
	global_load_dwordx4 v[72:75], v[154:155], off offset:64
	s_nop 0
	global_load_dwordx4 v[64:67], v[156:157], off offset:64
	global_load_dwordx4 v[68:71], v[158:159], off offset:64
	global_load_dwordx2 v[96:97], v[160:161], off offset:32
	global_load_dwordx2 v[94:95], v[162:163], off offset:32
	global_load_dwordx2 v[90:91], v[166:167], off offset:32
	global_load_dwordx2 v[88:89], v[168:169], off offset:32
	global_load_dwordx2 v[86:87], v[170:171], off offset:32
	global_load_dwordx2 v[82:83], v[172:173], off offset:32
	global_load_dwordx2 v[80:81], v[174:175], off offset:32
	global_load_dwordx2 v[78:79], v[176:177], off offset:32
	s_waitcnt vmcnt(0)
; __device__ __forceinline__ float bf_lo(unsigned w) { return __uint_as_float(w << 16); }
; __device__ __forceinline__ float bf_hi(unsigned w) { return __uint_as_float(w & 0xffff0000u); }
; __device__ __forceinline__ float fast_sigmoid(float x) { return __builtin_amdgcn_rcpf(1.0f + __builtin_amdgcn_exp2f(-x * LOG2E)); }
;     __device__ __forceinline__ void operator()(const f32x4 (&acc)[2][2][4][2], const Unit& u, int wr, int wc, int fr, int fq) const {
;     ...
;                 for (int m = 0; m < 4; ++m) { const int row = row0 + ai * HALF + m * 16; const size_t off = (size_t)row * DM + ch0 + n * 16;
;                     const u32x2 xw = xall[ai * 4 + m];
;                     const float xv[4] = {bf_lo(xw.x), bf_hi(xw.x), bf_lo(xw.y), bf_hi(xw.y)};
;                     f32x4 av; float bv[4];
; #pragma unroll
;                     for (int j = 0; j < 4; ++j) { const float r = fast_sigmoid(acc[ai][0][m][n][j] + ba[j]), ig = fast_sigmoid(acc[ai][1][m][n][j] + bx[j]);
;                         const float la = sp[j] * r; const float la2 = __uint_as_float(pk_bf16(la * LOG2E, 0.f) << 16);
;                         const float a = __builtin_amdgcn_exp2f(la2); const float x2 = 2.0f * la2 * 0.6931471805599453f; av[j] = la2;
;                         const float om = (x2 > -0.03f) ? -(x2 * (1.0f + x2 * (0.5f + x2 * (1.0f / 6.0f + x2 * (1.0f / 24.0f))))) : (1.0f - a * a);
;                         bv[j] = __builtin_amdgcn_sqrtf(om) * (ig * xv[j]); }
;                     { u32x2 wa; wa.x = pk_bf16(av[0], av[1]); wa.y = pk_bf16(av[2], av[3]); *(u32x2*)(aout + off) = wa; }
;                     u32x2 w; w.x = pk_bf16(bv[0], bv[1]); w.y = pk_bf16(bv[2], bv[3]); *(u32x2*)(bout + off) = w; }
	v_add_f32_e32 v60, v60, v72
	v_mul_f32_e32 v60, 0xbfb8aa3b, v60
	v_exp_f32_e32 v60, v60
	s_nop 0
	v_add_f32_e32 v60, 1.0, v60
	v_rcp_f32_e32 v60, v60
	s_nop 0
	v_mul_f32_e32 v60, v68, v60
	v_mul_f32_e32 v60, 0x3fb8aa3b, v60
	v_cvt_pk_bf16_f32 v60, v60, 0
	v_lshlrev_b32_e32 v60, 16, v60
	v_add_f32_e32 v98, v60, v60
	v_mul_f32_e32 v99, 0x3f317218, v98
	v_cmp_nlt_f32_e32 vcc, s74, v99
	s_and_saveexec_b64 s[56:57], vcc
	s_xor_b64 s[56:57], exec, s[56:57]
	v_exp_f32_e32 v98, v60
	s_nop 0
	v_fma_f32 v98, -v98, v98, 1.0
	s_andn2_saveexec_b64 s[56:57], s[56:57]
	v_fmamk_f32 v98, v99, 0x3d2aaaab, v208
	v_fma_f32 v98, v99, v98, 0.5
	v_fma_f32 v98, v99, v98, 1.0
	v_mul_f32_e64 v98, v99, -v98
	s_or_b64 exec, exec, s[56:57]
	v_add_f32_e32 v61, v61, v73
	v_mul_f32_e32 v61, 0xbfb8aa3b, v61
	v_exp_f32_e32 v61, v61
	s_nop 0
	v_add_f32_e32 v61, 1.0, v61
	v_rcp_f32_e32 v61, v61
	s_nop 0
	v_mul_f32_e32 v61, v69, v61
	v_mul_f32_e32 v61, 0x3fb8aa3b, v61
	v_cvt_pk_bf16_f32 v61, v61, 0
	v_lshlrev_b32_e32 v61, 16, v61
	v_add_f32_e32 v99, v61, v61
	v_mul_f32_e32 v102, 0x3f317218, v99
	v_cmp_nlt_f32_e32 vcc, s74, v102
	s_and_saveexec_b64 s[56:57], vcc
	s_xor_b64 s[56:57], exec, s[56:57]
	v_exp_f32_e32 v99, v61
	s_nop 0
	v_fma_f32 v99, -v99, v99, 1.0
	s_andn2_saveexec_b64 s[56:57], s[56:57]
	v_fmamk_f32 v99, v102, 0x3d2aaaab, v208
	v_fma_f32 v99, v102, v99, 0.5
	v_fma_f32 v99, v102, v99, 1.0
	v_mul_f32_e64 v99, v102, -v99
	s_or_b64 exec, exec, s[56:57]
	v_add_f32_e32 v62, v62, v74
	v_mul_f32_e32 v62, 0xbfb8aa3b, v62
	v_exp_f32_e32 v62, v62
	s_nop 0
	v_add_f32_e32 v62, 1.0, v62
	v_rcp_f32_e32 v62, v62
	s_nop 0
	v_mul_f32_e32 v62, v70, v62
	v_mul_f32_e32 v62, 0x3fb8aa3b, v62
	v_cvt_pk_bf16_f32 v62, v62, 0
	v_lshlrev_b32_e32 v62, 16, v62
	v_add_f32_e32 v102, v62, v62
	v_mul_f32_e32 v103, 0x3f317218, v102
	v_cmp_nlt_f32_e32 vcc, s74, v103
	s_and_saveexec_b64 s[56:57], vcc
	s_xor_b64 s[56:57], exec, s[56:57]
	v_exp_f32_e32 v102, v62
	s_nop 0
	v_fma_f32 v102, -v102, v102, 1.0
	s_andn2_saveexec_b64 s[56:57], s[56:57]
	v_fmamk_f32 v102, v103, 0x3d2aaaab, v208
	v_fma_f32 v102, v103, v102, 0.5
	v_fma_f32 v102, v103, v102, 1.0
	v_mul_f32_e64 v102, v103, -v102
	s_or_b64 exec, exec, s[56:57]
	v_add_f32_e32 v63, v63, v75
	v_mul_f32_e32 v63, 0xbfb8aa3b, v63
	v_exp_f32_e32 v63, v63
	s_nop 0
	v_add_f32_e32 v63, 1.0, v63
	v_rcp_f32_e32 v63, v63
	s_nop 0
	v_mul_f32_e32 v63, v71, v63
	v_mul_f32_e32 v63, 0x3fb8aa3b, v63
	v_cvt_pk_bf16_f32 v63, v63, 0
	v_lshlrev_b32_e32 v63, 16, v63
	v_add_f32_e32 v103, v63, v63
	v_mul_f32_e32 v104, 0x3f317218, v103
	v_cmp_nlt_f32_e32 vcc, s74, v104
	s_and_saveexec_b64 s[56:57], vcc
	s_xor_b64 s[56:57], exec, s[56:57]
	v_exp_f32_e32 v103, v63
	s_nop 0
	v_fma_f32 v103, -v103, v103, 1.0
	s_andn2_saveexec_b64 s[56:57], s[56:57]
	v_fmamk_f32 v103, v104, 0x3d2aaaab, v208
	v_fma_f32 v103, v104, v103, 0.5
	v_fma_f32 v103, v104, v103, 1.0
	v_mul_f32_e64 v103, v104, -v103
	s_or_b64 exec, exec, s[56:57]
	v_add_f32_e32 v58, v58, v66
	v_mul_f32_e32 v58, 0xbfb8aa3b, v58
	v_exp_f32_e32 v58, v58
	v_add_f32_e32 v56, v56, v64
	v_mul_f32_e32 v56, 0xbfb8aa3b, v56
	v_exp_f32_e32 v56, v56
	v_add_f32_e32 v57, v57, v65
	v_add_f32_e32 v59, v59, v67
	v_add_f32_e32 v58, 1.0, v58
	v_mul_f32_e32 v57, 0xbfb8aa3b, v57
	v_rcp_f32_e32 v58, v58
	v_mul_f32_e32 v59, 0xbfb8aa3b, v59
	v_exp_f32_e32 v57, v57
	v_sqrt_f32_e32 v102, v102
	v_exp_f32_e32 v59, v59
	v_add_f32_e32 v56, 1.0, v56
	v_rcp_f32_e32 v56, v56
	v_lshlrev_b32_e32 v104, 16, v97
	v_add_f32_e32 v52, v52, v72
	v_mul_f32_e32 v58, v58, v104
	v_sqrt_f32_e32 v98, v98
	v_add_f32_e32 v57, 1.0, v57
	v_mul_f32_e32 v52, 0xbfb8aa3b, v52
	v_mul_f32_e32 v102, v58, v102
	v_add_f32_e32 v58, 1.0, v59
	v_lshlrev_b32_e32 v59, 16, v96
	v_rcp_f32_e32 v57, v57
	v_exp_f32_e32 v52, v52
	v_mul_f32_e32 v56, v56, v59
	v_sqrt_f32_e32 v59, v99
	v_mul_f32_e32 v98, v56, v98
	v_and_b32_e32 v56, 0xffff0000, v96
	v_rcp_f32_e32 v58, v58
	v_mul_f32_e32 v56, v57, v56
	v_add_f32_e32 v52, 1.0, v52
	v_mul_f32_e32 v96, v56, v59
	v_sqrt_f32_e32 v56, v103
	v_rcp_f32_e32 v52, v52
	v_and_b32_e32 v57, 0xffff0000, v97
	v_or_b32_e32 v152, 16, v152
	v_mul_f32_e32 v57, v58, v57
	v_mul_f32_e32 v97, v57, v56
	v_lshl_add_u64 v[56:57], v[132:133], 0, v[152:153]
	v_mul_f32_e32 v52, v68, v52
	v_lshlrev_b64 v[56:57], 1, v[56:57]
	v_mul_f32_e32 v52, 0x3fb8aa3b, v52
	v_cvt_pk_bf16_f32 v58, v60, v61
	v_cvt_pk_bf16_f32 v59, v62, v63
	v_lshl_add_u64 v[60:61], s[16:17], 0, v[56:57]
	v_cvt_pk_bf16_f32 v52, v52, 0
	global_store_dwordx2 v[60:61], v[58:59], off
	v_cvt_pk_bf16_f32 v58, v98, v96
	v_cvt_pk_bf16_f32 v59, v102, v97
	v_lshl_add_u64 v[56:57], s[18:19], 0, v[56:57]
	v_lshlrev_b32_e32 v52, 16, v52
	global_store_dwordx2 v[56:57], v[58:59], off
	v_add_f32_e32 v56, v52, v52
	v_mul_f32_e32 v57, 0x3f317218, v56
	v_cmp_nlt_f32_e32 vcc, s74, v57
	s_and_saveexec_b64 s[56:57], vcc
	s_xor_b64 s[56:57], exec, s[56:57]
	v_exp_f32_e32 v56, v52
	s_nop 0
	v_fma_f32 v56, -v56, v56, 1.0
	s_andn2_saveexec_b64 s[56:57], s[56:57]
	v_fmamk_f32 v56, v57, 0x3d2aaaab, v208
	v_fma_f32 v56, v57, v56, 0.5
	v_fma_f32 v56, v57, v56, 1.0
	v_mul_f32_e64 v56, v57, -v56
	s_or_b64 exec, exec, s[56:57]
	v_add_f32_e32 v53, v53, v73
	v_mul_f32_e32 v53, 0xbfb8aa3b, v53
	v_exp_f32_e32 v53, v53
	s_nop 0
	v_add_f32_e32 v53, 1.0, v53
	v_rcp_f32_e32 v53, v53
	s_nop 0
	v_mul_f32_e32 v53, v69, v53
	v_mul_f32_e32 v53, 0x3fb8aa3b, v53
	v_cvt_pk_bf16_f32 v53, v53, 0
	v_lshlrev_b32_e32 v53, 16, v53
	v_add_f32_e32 v57, v53, v53
	v_mul_f32_e32 v58, 0x3f317218, v57
	v_cmp_nlt_f32_e32 vcc, s74, v58
	s_and_saveexec_b64 s[56:57], vcc
	s_xor_b64 s[56:57], exec, s[56:57]
	v_exp_f32_e32 v57, v53
	s_nop 0
	v_fma_f32 v57, -v57, v57, 1.0
; __device__ __forceinline__ float bf_lo(unsigned w) { return __uint_as_float(w << 16); }
; __device__ __forceinline__ float bf_hi(unsigned w) { return __uint_as_float(w & 0xffff0000u); }
; __device__ __forceinline__ float fast_sigmoid(float x) { return __builtin_amdgcn_rcpf(1.0f + __builtin_amdgcn_exp2f(-x * LOG2E)); }
;     __device__ __forceinline__ void operator()(const f32x4 (&acc)[2][2][4][2], const Unit& u, int wr, int wc, int fr, int fq) const {
;     ...
;                 for (int m = 0; m < 4; ++m) { const int row = row0 + ai * HALF + m * 16; const size_t off = (size_t)row * DM + ch0 + n * 16;
;                     const u32x2 xw = xall[ai * 4 + m];
;                     const float xv[4] = {bf_lo(xw.x), bf_hi(xw.x), bf_lo(xw.y), bf_hi(xw.y)};
;                     f32x4 av; float bv[4];
; #pragma unroll
;                     for (int j = 0; j < 4; ++j) { const float r = fast_sigmoid(acc[ai][0][m][n][j] + ba[j]), ig = fast_sigmoid(acc[ai][1][m][n][j] + bx[j]);
;                         const float la = sp[j] * r; const float la2 = __uint_as_float(pk_bf16(la * LOG2E, 0.f) << 16);
;                         const float a = __builtin_amdgcn_exp2f(la2); const float x2 = 2.0f * la2 * 0.6931471805599453f; av[j] = la2;
;                         const float om = (x2 > -0.03f) ? -(x2 * (1.0f + x2 * (0.5f + x2 * (1.0f / 6.0f + x2 * (1.0f / 24.0f))))) : (1.0f - a * a);
;                         bv[j] = __builtin_amdgcn_sqrtf(om) * (ig * xv[j]); }
;                     { u32x2 wa; wa.x = pk_bf16(av[0], av[1]); wa.y = pk_bf16(av[2], av[3]); *(u32x2*)(aout + off) = wa; }
;                     u32x2 w; w.x = pk_bf16(bv[0], bv[1]); w.y = pk_bf16(bv[2], bv[3]); *(u32x2*)(bout + off) = w; }
	s_andn2_saveexec_b64 s[56:57], s[56:57]
	v_fmamk_f32 v57, v58, 0x3d2aaaab, v208
	v_fma_f32 v57, v58, v57, 0.5
	v_fma_f32 v57, v58, v57, 1.0
	v_mul_f32_e64 v57, v58, -v57
	s_or_b64 exec, exec, s[56:57]
	v_add_f32_e32 v54, v54, v74
	v_mul_f32_e32 v54, 0xbfb8aa3b, v54
	v_exp_f32_e32 v54, v54
	s_nop 0
	v_add_f32_e32 v54, 1.0, v54
	v_rcp_f32_e32 v54, v54
	s_nop 0
	v_mul_f32_e32 v54, v70, v54
	v_mul_f32_e32 v54, 0x3fb8aa3b, v54
	v_cvt_pk_bf16_f32 v54, v54, 0
	v_lshlrev_b32_e32 v54, 16, v54
	v_add_f32_e32 v58, v54, v54
	v_mul_f32_e32 v59, 0x3f317218, v58
	v_cmp_nlt_f32_e32 vcc, s74, v59
	s_and_saveexec_b64 s[56:57], vcc
	s_xor_b64 s[56:57], exec, s[56:57]
	v_exp_f32_e32 v58, v54
	s_nop 0
	v_fma_f32 v58, -v58, v58, 1.0
	s_andn2_saveexec_b64 s[56:57], s[56:57]
	v_fmamk_f32 v58, v59, 0x3d2aaaab, v208
	v_fma_f32 v58, v59, v58, 0.5
	v_fma_f32 v58, v59, v58, 1.0
	v_mul_f32_e64 v58, v59, -v58
	s_or_b64 exec, exec, s[56:57]
	v_add_f32_e32 v55, v55, v75
	v_mul_f32_e32 v55, 0xbfb8aa3b, v55
	v_exp_f32_e32 v55, v55
	s_nop 0
	v_add_f32_e32 v55, 1.0, v55
	v_rcp_f32_e32 v55, v55
	s_nop 0
	v_mul_f32_e32 v55, v71, v55
	v_mul_f32_e32 v55, 0x3fb8aa3b, v55
	v_cvt_pk_bf16_f32 v55, v55, 0
	v_lshlrev_b32_e32 v55, 16, v55
	v_add_f32_e32 v59, v55, v55
	v_mul_f32_e32 v60, 0x3f317218, v59
	v_cmp_nlt_f32_e32 vcc, s74, v60
	s_and_saveexec_b64 s[56:57], vcc
	s_xor_b64 s[56:57], exec, s[56:57]
	v_exp_f32_e32 v59, v55
	s_nop 0
	v_fma_f32 v59, -v59, v59, 1.0
	s_andn2_saveexec_b64 s[56:57], s[56:57]
	v_fmamk_f32 v59, v60, 0x3d2aaaab, v208
	v_fma_f32 v59, v60, v59, 0.5
	v_fma_f32 v59, v60, v59, 1.0
	v_mul_f32_e64 v59, v60, -v59
	s_or_b64 exec, exec, s[56:57]
	v_add_f32_e32 v50, v50, v66
	v_mul_f32_e32 v50, 0xbfb8aa3b, v50
	v_exp_f32_e32 v50, v50
	v_add_f32_e32 v48, v48, v64
	v_mul_f32_e32 v48, 0xbfb8aa3b, v48
	v_exp_f32_e32 v48, v48
	v_add_f32_e32 v49, v49, v65
	v_add_f32_e32 v51, v51, v67
	v_add_f32_e32 v50, 1.0, v50
	v_mul_f32_e32 v49, 0xbfb8aa3b, v49
	v_rcp_f32_e32 v50, v50
	v_mul_f32_e32 v51, 0xbfb8aa3b, v51
	v_exp_f32_e32 v49, v49
	v_sqrt_f32_e32 v58, v58
	v_exp_f32_e32 v51, v51
	v_add_f32_e32 v48, 1.0, v48
	v_rcp_f32_e32 v48, v48
	v_add_f32_e32 v44, v44, v72
	v_lshlrev_b32_e32 v60, 16, v95
	v_sqrt_f32_e32 v56, v56
	v_mul_f32_e32 v44, 0xbfb8aa3b, v44
	v_mul_f32_e32 v50, v50, v60
	v_add_f32_e32 v49, 1.0, v49
	v_exp_f32_e32 v44, v44
	v_mul_f32_e32 v58, v50, v58
	v_add_f32_e32 v50, 1.0, v51
	v_lshlrev_b32_e32 v51, 16, v94
	v_rcp_f32_e32 v49, v49
	v_mul_f32_e32 v48, v48, v51
	v_mul_f32_e32 v56, v48, v56
	v_sqrt_f32_e32 v48, v57
	v_rcp_f32_e32 v50, v50
	v_and_b32_e32 v51, 0xffff0000, v94
	v_add_f32_e32 v44, 1.0, v44
	v_mul_f32_e32 v49, v49, v51
	v_sqrt_f32_e32 v51, v59
	v_rcp_f32_e32 v44, v44
	v_mul_f32_e32 v57, v49, v48
	v_and_b32_e32 v48, 0xffff0000, v95
	v_mul_f32_e32 v48, v50, v48
	v_mul_f32_e32 v59, v48, v51
	v_lshl_add_u64 v[48:49], v[124:125], 0, v[152:153]
	v_mul_f32_e32 v44, v68, v44
	v_lshlrev_b64 v[48:49], 1, v[48:49]
	v_mul_f32_e32 v44, 0x3fb8aa3b, v44
	v_cvt_pk_bf16_f32 v50, v52, v53
	v_cvt_pk_bf16_f32 v51, v54, v55
	v_lshl_add_u64 v[52:53], s[16:17], 0, v[48:49]
	v_cvt_pk_bf16_f32 v44, v44, 0
	global_store_dwordx2 v[52:53], v[50:51], off
	v_cvt_pk_bf16_f32 v50, v56, v57
	v_cvt_pk_bf16_f32 v51, v58, v59
	v_lshl_add_u64 v[48:49], s[18:19], 0, v[48:49]
	v_lshlrev_b32_e32 v44, 16, v44
	global_store_dwordx2 v[48:49], v[50:51], off
	v_add_f32_e32 v48, v44, v44
	v_mul_f32_e32 v49, 0x3f317218, v48
	v_cmp_nlt_f32_e32 vcc, s74, v49
	s_and_saveexec_b64 s[56:57], vcc
	s_xor_b64 s[56:57], exec, s[56:57]
	v_exp_f32_e32 v48, v44
	s_nop 0
	v_fma_f32 v48, -v48, v48, 1.0
	s_andn2_saveexec_b64 s[56:57], s[56:57]
	v_fmamk_f32 v48, v49, 0x3d2aaaab, v208
	v_fma_f32 v48, v49, v48, 0.5
	v_fma_f32 v48, v49, v48, 1.0
	v_mul_f32_e64 v48, v49, -v48
	s_or_b64 exec, exec, s[56:57]
	v_add_f32_e32 v45, v45, v73
	v_mul_f32_e32 v45, 0xbfb8aa3b, v45
	v_exp_f32_e32 v45, v45
	s_nop 0
	v_add_f32_e32 v45, 1.0, v45
	v_rcp_f32_e32 v45, v45
	s_nop 0
	v_mul_f32_e32 v45, v69, v45
	v_mul_f32_e32 v45, 0x3fb8aa3b, v45
	v_cvt_pk_bf16_f32 v45, v45, 0
	v_lshlrev_b32_e32 v45, 16, v45
	v_add_f32_e32 v49, v45, v45
	v_mul_f32_e32 v50, 0x3f317218, v49
	v_cmp_nlt_f32_e32 vcc, s74, v50
	s_and_saveexec_b64 s[56:57], vcc
	s_xor_b64 s[56:57], exec, s[56:57]
	v_exp_f32_e32 v49, v45
	s_nop 0
	v_fma_f32 v49, -v49, v49, 1.0
	s_andn2_saveexec_b64 s[56:57], s[56:57]
	v_fmamk_f32 v49, v50, 0x3d2aaaab, v208
	v_fma_f32 v49, v50, v49, 0.5
	v_fma_f32 v49, v50, v49, 1.0
	v_mul_f32_e64 v49, v50, -v49
	s_or_b64 exec, exec, s[56:57]
	v_add_f32_e32 v46, v46, v74
	v_mul_f32_e32 v46, 0xbfb8aa3b, v46
	v_exp_f32_e32 v46, v46
	s_nop 0
	v_add_f32_e32 v46, 1.0, v46
	v_rcp_f32_e32 v46, v46
	s_nop 0
	v_mul_f32_e32 v46, v70, v46
	v_mul_f32_e32 v46, 0x3fb8aa3b, v46
	v_cvt_pk_bf16_f32 v46, v46, 0
	v_lshlrev_b32_e32 v46, 16, v46
	v_add_f32_e32 v50, v46, v46
	v_mul_f32_e32 v51, 0x3f317218, v50
	v_cmp_nlt_f32_e32 vcc, s74, v51
	s_and_saveexec_b64 s[56:57], vcc
	s_xor_b64 s[56:57], exec, s[56:57]
	v_exp_f32_e32 v50, v46
	s_nop 0
	v_fma_f32 v50, -v50, v50, 1.0
	s_andn2_saveexec_b64 s[56:57], s[56:57]
	v_fmamk_f32 v50, v51, 0x3d2aaaab, v208
	v_fma_f32 v50, v51, v50, 0.5
	v_fma_f32 v50, v51, v50, 1.0
	v_mul_f32_e64 v50, v51, -v50
	s_or_b64 exec, exec, s[56:57]
	v_add_f32_e32 v47, v47, v75
	v_mul_f32_e32 v47, 0xbfb8aa3b, v47
	v_exp_f32_e32 v47, v47
	s_nop 0
	v_add_f32_e32 v47, 1.0, v47
	v_rcp_f32_e32 v47, v47
	s_nop 0
	v_mul_f32_e32 v47, v71, v47
	v_mul_f32_e32 v47, 0x3fb8aa3b, v47
	v_cvt_pk_bf16_f32 v47, v47, 0
	v_lshlrev_b32_e32 v47, 16, v47
	v_add_f32_e32 v51, v47, v47
	v_mul_f32_e32 v52, 0x3f317218, v51
	v_cmp_nlt_f32_e32 vcc, s74, v52
; __device__ __forceinline__ float bf_lo(unsigned w) { return __uint_as_float(w << 16); }
; __device__ __forceinline__ float bf_hi(unsigned w) { return __uint_as_float(w & 0xffff0000u); }
; __device__ __forceinline__ float fast_sigmoid(float x) { return __builtin_amdgcn_rcpf(1.0f + __builtin_amdgcn_exp2f(-x * LOG2E)); }
;     __device__ __forceinline__ void operator()(const f32x4 (&acc)[2][2][4][2], const Unit& u, int wr, int wc, int fr, int fq) const {
;     ...
;                 for (int m = 0; m < 4; ++m) { const int row = row0 + ai * HALF + m * 16; const size_t off = (size_t)row * DM + ch0 + n * 16;
;                     const u32x2 xw = xall[ai * 4 + m];
;                     const float xv[4] = {bf_lo(xw.x), bf_hi(xw.x), bf_lo(xw.y), bf_hi(xw.y)};
;                     f32x4 av; float bv[4];
; #pragma unroll
;                     for (int j = 0; j < 4; ++j) { const float r = fast_sigmoid(acc[ai][0][m][n][j] + ba[j]), ig = fast_sigmoid(acc[ai][1][m][n][j] + bx[j]);
;                         const float la = sp[j] * r; const float la2 = __uint_as_float(pk_bf16(la * LOG2E, 0.f) << 16);
;                         const float a = __builtin_amdgcn_exp2f(la2); const float x2 = 2.0f * la2 * 0.6931471805599453f; av[j] = la2;
;                         const float om = (x2 > -0.03f) ? -(x2 * (1.0f + x2 * (0.5f + x2 * (1.0f / 6.0f + x2 * (1.0f / 24.0f))))) : (1.0f - a * a);
;                         bv[j] = __builtin_amdgcn_sqrtf(om) * (ig * xv[j]); }
;                     { u32x2 wa; wa.x = pk_bf16(av[0], av[1]); wa.y = pk_bf16(av[2], av[3]); *(u32x2*)(aout + off) = wa; }
;                     u32x2 w; w.x = pk_bf16(bv[0], bv[1]); w.y = pk_bf16(bv[2], bv[3]); *(u32x2*)(bout + off) = w; }
	s_and_saveexec_b64 s[56:57], vcc
	s_xor_b64 s[56:57], exec, s[56:57]
	v_exp_f32_e32 v51, v47
	s_nop 0
	v_fma_f32 v51, -v51, v51, 1.0
	s_andn2_saveexec_b64 s[56:57], s[56:57]
	v_fmamk_f32 v51, v52, 0x3d2aaaab, v208
	v_fma_f32 v51, v52, v51, 0.5
	v_fma_f32 v51, v52, v51, 1.0
	v_mul_f32_e64 v51, v52, -v51
	s_or_b64 exec, exec, s[56:57]
	v_add_f32_e32 v42, v42, v66
	v_mul_f32_e32 v42, 0xbfb8aa3b, v42
	v_exp_f32_e32 v42, v42
	v_add_f32_e32 v40, v40, v64
	v_mul_f32_e32 v40, 0xbfb8aa3b, v40
	v_exp_f32_e32 v40, v40
	v_add_f32_e32 v41, v41, v65
	v_add_f32_e32 v43, v43, v67
	v_add_f32_e32 v42, 1.0, v42
	v_mul_f32_e32 v41, 0xbfb8aa3b, v41
	v_rcp_f32_e32 v42, v42
	v_mul_f32_e32 v43, 0xbfb8aa3b, v43
	v_exp_f32_e32 v41, v41
	v_sqrt_f32_e32 v50, v50
	v_exp_f32_e32 v43, v43
	v_add_f32_e32 v40, 1.0, v40
	v_rcp_f32_e32 v40, v40
	v_add_f32_e32 v36, v36, v72
	v_lshlrev_b32_e32 v52, 16, v91
	v_sqrt_f32_e32 v48, v48
	v_mul_f32_e32 v36, 0xbfb8aa3b, v36
	v_mul_f32_e32 v42, v42, v52
	v_add_f32_e32 v41, 1.0, v41
	v_exp_f32_e32 v36, v36
	v_mul_f32_e32 v50, v42, v50
	v_add_f32_e32 v42, 1.0, v43
	v_lshlrev_b32_e32 v43, 16, v90
	v_rcp_f32_e32 v41, v41
	v_mul_f32_e32 v40, v40, v43
	v_mul_f32_e32 v48, v40, v48
	v_sqrt_f32_e32 v40, v49
	v_rcp_f32_e32 v42, v42
	v_and_b32_e32 v43, 0xffff0000, v90
	v_add_f32_e32 v36, 1.0, v36
	v_mul_f32_e32 v41, v41, v43
	v_sqrt_f32_e32 v43, v51
	v_rcp_f32_e32 v36, v36
	v_mul_f32_e32 v49, v41, v40
	v_and_b32_e32 v40, 0xffff0000, v91
	v_mul_f32_e32 v40, v42, v40
	v_mul_f32_e32 v51, v40, v43
	v_lshl_add_u64 v[40:41], v[116:117], 0, v[152:153]
	v_mul_f32_e32 v36, v68, v36
	v_lshlrev_b64 v[40:41], 1, v[40:41]
	v_mul_f32_e32 v36, 0x3fb8aa3b, v36
	v_cvt_pk_bf16_f32 v42, v44, v45
	v_cvt_pk_bf16_f32 v43, v46, v47
	v_lshl_add_u64 v[44:45], s[16:17], 0, v[40:41]
	v_cvt_pk_bf16_f32 v36, v36, 0
	global_store_dwordx2 v[44:45], v[42:43], off
	v_cvt_pk_bf16_f32 v42, v48, v49
	v_cvt_pk_bf16_f32 v43, v50, v51
	v_lshl_add_u64 v[40:41], s[18:19], 0, v[40:41]
	v_lshlrev_b32_e32 v36, 16, v36
	global_store_dwordx2 v[40:41], v[42:43], off
	v_add_f32_e32 v40, v36, v36
	v_mul_f32_e32 v41, 0x3f317218, v40
	v_cmp_nlt_f32_e32 vcc, s74, v41
	s_and_saveexec_b64 s[56:57], vcc
	s_xor_b64 s[56:57], exec, s[56:57]
	v_exp_f32_e32 v40, v36
	s_nop 0
	v_fma_f32 v40, -v40, v40, 1.0
	s_andn2_saveexec_b64 s[56:57], s[56:57]
	v_fmamk_f32 v40, v41, 0x3d2aaaab, v208
	v_fma_f32 v40, v41, v40, 0.5
	v_fma_f32 v40, v41, v40, 1.0
	v_mul_f32_e64 v40, v41, -v40
	s_or_b64 exec, exec, s[56:57]
	v_add_f32_e32 v37, v37, v73
	v_mul_f32_e32 v37, 0xbfb8aa3b, v37
	v_exp_f32_e32 v37, v37
	s_nop 0
	v_add_f32_e32 v37, 1.0, v37
	v_rcp_f32_e32 v37, v37
	s_nop 0
	v_mul_f32_e32 v37, v69, v37
	v_mul_f32_e32 v37, 0x3fb8aa3b, v37
	v_cvt_pk_bf16_f32 v37, v37, 0
	v_lshlrev_b32_e32 v37, 16, v37
	v_add_f32_e32 v41, v37, v37
	v_mul_f32_e32 v42, 0x3f317218, v41
	v_cmp_nlt_f32_e32 vcc, s74, v42
	s_and_saveexec_b64 s[56:57], vcc
	s_xor_b64 s[56:57], exec, s[56:57]
	v_exp_f32_e32 v41, v37
	s_nop 0
	v_fma_f32 v41, -v41, v41, 1.0
	s_andn2_saveexec_b64 s[56:57], s[56:57]
	v_fmamk_f32 v41, v42, 0x3d2aaaab, v208
	v_fma_f32 v41, v42, v41, 0.5
	v_fma_f32 v41, v42, v41, 1.0
	v_mul_f32_e64 v41, v42, -v41
	s_or_b64 exec, exec, s[56:57]
	v_add_f32_e32 v38, v38, v74
	v_mul_f32_e32 v38, 0xbfb8aa3b, v38
	v_exp_f32_e32 v38, v38
	s_nop 0
	v_add_f32_e32 v38, 1.0, v38
	v_rcp_f32_e32 v38, v38
	s_nop 0
	v_mul_f32_e32 v38, v70, v38
	v_mul_f32_e32 v38, 0x3fb8aa3b, v38
	v_cvt_pk_bf16_f32 v38, v38, 0
	v_lshlrev_b32_e32 v38, 16, v38
	v_add_f32_e32 v42, v38, v38
	v_mul_f32_e32 v43, 0x3f317218, v42
	v_cmp_nlt_f32_e32 vcc, s74, v43
	s_and_saveexec_b64 s[56:57], vcc
	s_xor_b64 s[56:57], exec, s[56:57]
	v_exp_f32_e32 v42, v38
	s_nop 0
	v_fma_f32 v42, -v42, v42, 1.0
	s_andn2_saveexec_b64 s[56:57], s[56:57]
	v_fmamk_f32 v42, v43, 0x3d2aaaab, v208
	v_fma_f32 v42, v43, v42, 0.5
	v_fma_f32 v42, v43, v42, 1.0
	v_mul_f32_e64 v42, v43, -v42
	s_or_b64 exec, exec, s[56:57]
	v_add_f32_e32 v39, v39, v75
	v_mul_f32_e32 v39, 0xbfb8aa3b, v39
	v_exp_f32_e32 v39, v39
	s_nop 0
	v_add_f32_e32 v39, 1.0, v39
	v_rcp_f32_e32 v39, v39
	s_nop 0
	v_mul_f32_e32 v39, v71, v39
	v_mul_f32_e32 v39, 0x3fb8aa3b, v39
	v_cvt_pk_bf16_f32 v39, v39, 0
	v_lshlrev_b32_e32 v39, 16, v39
	v_add_f32_e32 v43, v39, v39
	v_mul_f32_e32 v44, 0x3f317218, v43
	v_cmp_nlt_f32_e32 vcc, s74, v44
	s_and_saveexec_b64 s[56:57], vcc
	s_xor_b64 s[56:57], exec, s[56:57]
	v_exp_f32_e32 v43, v39
	s_nop 0
	v_fma_f32 v43, -v43, v43, 1.0
	s_andn2_saveexec_b64 s[56:57], s[56:57]
	v_fmamk_f32 v43, v44, 0x3d2aaaab, v208
	v_fma_f32 v43, v44, v43, 0.5
	v_fma_f32 v43, v44, v43, 1.0
	v_mul_f32_e64 v43, v44, -v43
	s_or_b64 exec, exec, s[56:57]
	v_add_f32_e32 v34, v34, v66
	v_mul_f32_e32 v34, 0xbfb8aa3b, v34
	v_exp_f32_e32 v34, v34
	v_add_f32_e32 v32, v32, v64
	v_mul_f32_e32 v32, 0xbfb8aa3b, v32
	v_exp_f32_e32 v32, v32
	v_add_f32_e32 v33, v33, v65
	v_add_f32_e32 v35, v35, v67
	v_add_f32_e32 v34, 1.0, v34
	v_mul_f32_e32 v33, 0xbfb8aa3b, v33
	v_rcp_f32_e32 v34, v34
	v_mul_f32_e32 v35, 0xbfb8aa3b, v35
	v_exp_f32_e32 v33, v33
	v_sqrt_f32_e32 v42, v42
	v_exp_f32_e32 v35, v35
	v_add_f32_e32 v32, 1.0, v32
	v_rcp_f32_e32 v32, v32
	v_add_f32_e32 v28, v28, v72
	v_lshlrev_b32_e32 v44, 16, v89
	v_sqrt_f32_e32 v40, v40
	v_mul_f32_e32 v28, 0xbfb8aa3b, v28
	v_mul_f32_e32 v34, v34, v44
	v_add_f32_e32 v33, 1.0, v33
	v_exp_f32_e32 v28, v28
	v_mul_f32_e32 v42, v34, v42
	v_add_f32_e32 v34, 1.0, v35
	v_lshlrev_b32_e32 v35, 16, v88
	v_rcp_f32_e32 v33, v33
	v_mul_f32_e32 v32, v32, v35
	v_mul_f32_e32 v40, v32, v40
	v_sqrt_f32_e32 v32, v41
	v_rcp_f32_e32 v34, v34
	v_and_b32_e32 v35, 0xffff0000, v88
	v_add_f32_e32 v28, 1.0, v28
; __device__ __forceinline__ float bf_lo(unsigned w) { return __uint_as_float(w << 16); }
; __device__ __forceinline__ float bf_hi(unsigned w) { return __uint_as_float(w & 0xffff0000u); }
; __device__ __forceinline__ float fast_sigmoid(float x) { return __builtin_amdgcn_rcpf(1.0f + __builtin_amdgcn_exp2f(-x * LOG2E)); }
;     __device__ __forceinline__ void operator()(const f32x4 (&acc)[2][2][4][2], const Unit& u, int wr, int wc, int fr, int fq) const {
;     ...
;                 for (int m = 0; m < 4; ++m) { const int row = row0 + ai * HALF + m * 16; const size_t off = (size_t)row * DM + ch0 + n * 16;
;                     const u32x2 xw = xall[ai * 4 + m];
;                     const float xv[4] = {bf_lo(xw.x), bf_hi(xw.x), bf_lo(xw.y), bf_hi(xw.y)};
;                     f32x4 av; float bv[4];
; #pragma unroll
;                     for (int j = 0; j < 4; ++j) { const float r = fast_sigmoid(acc[ai][0][m][n][j] + ba[j]), ig = fast_sigmoid(acc[ai][1][m][n][j] + bx[j]);
;                         const float la = sp[j] * r; const float la2 = __uint_as_float(pk_bf16(la * LOG2E, 0.f) << 16);
;                         const float a = __builtin_amdgcn_exp2f(la2); const float x2 = 2.0f * la2 * 0.6931471805599453f; av[j] = la2;
;                         const float om = (x2 > -0.03f) ? -(x2 * (1.0f + x2 * (0.5f + x2 * (1.0f / 6.0f + x2 * (1.0f / 24.0f))))) : (1.0f - a * a);
;                         bv[j] = __builtin_amdgcn_sqrtf(om) * (ig * xv[j]); }
;                     { u32x2 wa; wa.x = pk_bf16(av[0], av[1]); wa.y = pk_bf16(av[2], av[3]); *(u32x2*)(aout + off) = wa; }
;                     u32x2 w; w.x = pk_bf16(bv[0], bv[1]); w.y = pk_bf16(bv[2], bv[3]); *(u32x2*)(bout + off) = w; }
	v_mul_f32_e32 v33, v33, v35
	v_sqrt_f32_e32 v35, v43
	v_rcp_f32_e32 v28, v28
	v_mul_f32_e32 v41, v33, v32
	v_and_b32_e32 v32, 0xffff0000, v89
	v_mul_f32_e32 v32, v34, v32
	v_mul_f32_e32 v43, v32, v35
	v_lshl_add_u64 v[32:33], v[108:109], 0, v[152:153]
	v_mul_f32_e32 v28, v68, v28
	v_lshlrev_b64 v[32:33], 1, v[32:33]
	v_mul_f32_e32 v28, 0x3fb8aa3b, v28
	v_cvt_pk_bf16_f32 v34, v36, v37
	v_cvt_pk_bf16_f32 v35, v38, v39
	v_lshl_add_u64 v[36:37], s[16:17], 0, v[32:33]
	v_cvt_pk_bf16_f32 v28, v28, 0
	global_store_dwordx2 v[36:37], v[34:35], off
	v_cvt_pk_bf16_f32 v34, v40, v41
	v_cvt_pk_bf16_f32 v35, v42, v43
	v_lshl_add_u64 v[32:33], s[18:19], 0, v[32:33]
	v_lshlrev_b32_e32 v28, 16, v28
	global_store_dwordx2 v[32:33], v[34:35], off
	v_add_f32_e32 v32, v28, v28
	v_mul_f32_e32 v33, 0x3f317218, v32
	v_cmp_nlt_f32_e32 vcc, s74, v33
	s_and_saveexec_b64 s[56:57], vcc
	s_xor_b64 s[56:57], exec, s[56:57]
	v_exp_f32_e32 v32, v28
	s_nop 0
	v_fma_f32 v32, -v32, v32, 1.0
	s_andn2_saveexec_b64 s[56:57], s[56:57]
	v_fmamk_f32 v32, v33, 0x3d2aaaab, v208
	v_fma_f32 v32, v33, v32, 0.5
	v_fma_f32 v32, v33, v32, 1.0
	v_mul_f32_e64 v32, v33, -v32
	s_or_b64 exec, exec, s[56:57]
	v_add_f32_e32 v29, v29, v73
	v_mul_f32_e32 v29, 0xbfb8aa3b, v29
	v_exp_f32_e32 v29, v29
	s_nop 0
	v_add_f32_e32 v29, 1.0, v29
	v_rcp_f32_e32 v29, v29
	s_nop 0
	v_mul_f32_e32 v29, v69, v29
	v_mul_f32_e32 v29, 0x3fb8aa3b, v29
	v_cvt_pk_bf16_f32 v29, v29, 0
	v_lshlrev_b32_e32 v29, 16, v29
	v_add_f32_e32 v33, v29, v29
	v_mul_f32_e32 v34, 0x3f317218, v33
	v_cmp_nlt_f32_e32 vcc, s74, v34
	s_and_saveexec_b64 s[56:57], vcc
	s_xor_b64 s[56:57], exec, s[56:57]
	v_exp_f32_e32 v33, v29
	s_nop 0
	v_fma_f32 v33, -v33, v33, 1.0
	s_andn2_saveexec_b64 s[56:57], s[56:57]
	v_fmamk_f32 v33, v34, 0x3d2aaaab, v208
	v_fma_f32 v33, v34, v33, 0.5
	v_fma_f32 v33, v34, v33, 1.0
	v_mul_f32_e64 v33, v34, -v33
	s_or_b64 exec, exec, s[56:57]
	v_add_f32_e32 v30, v30, v74
	v_mul_f32_e32 v30, 0xbfb8aa3b, v30
	v_exp_f32_e32 v30, v30
	s_nop 0
	v_add_f32_e32 v30, 1.0, v30
	v_rcp_f32_e32 v30, v30
	s_nop 0
	v_mul_f32_e32 v30, v70, v30
	v_mul_f32_e32 v30, 0x3fb8aa3b, v30
	v_cvt_pk_bf16_f32 v30, v30, 0
	v_lshlrev_b32_e32 v30, 16, v30
	v_add_f32_e32 v34, v30, v30
	v_mul_f32_e32 v35, 0x3f317218, v34
	v_cmp_nlt_f32_e32 vcc, s74, v35
	s_and_saveexec_b64 s[56:57], vcc
	s_xor_b64 s[56:57], exec, s[56:57]
	v_exp_f32_e32 v34, v30
	s_nop 0
	v_fma_f32 v34, -v34, v34, 1.0
	s_andn2_saveexec_b64 s[56:57], s[56:57]
	v_fmamk_f32 v34, v35, 0x3d2aaaab, v208
	v_fma_f32 v34, v35, v34, 0.5
	v_fma_f32 v34, v35, v34, 1.0
	v_mul_f32_e64 v34, v35, -v34
	s_or_b64 exec, exec, s[56:57]
	v_add_f32_e32 v31, v31, v75
	v_mul_f32_e32 v31, 0xbfb8aa3b, v31
	v_exp_f32_e32 v31, v31
	s_nop 0
	v_add_f32_e32 v31, 1.0, v31
	v_rcp_f32_e32 v31, v31
	s_nop 0
	v_mul_f32_e32 v31, v71, v31
	v_mul_f32_e32 v31, 0x3fb8aa3b, v31
	v_cvt_pk_bf16_f32 v31, v31, 0
	v_lshlrev_b32_e32 v31, 16, v31
	v_add_f32_e32 v35, v31, v31
	v_mul_f32_e32 v36, 0x3f317218, v35
	v_cmp_nlt_f32_e32 vcc, s74, v36
	s_and_saveexec_b64 s[56:57], vcc
	s_xor_b64 s[56:57], exec, s[56:57]
	v_exp_f32_e32 v35, v31
	s_nop 0
	v_fma_f32 v35, -v35, v35, 1.0
	s_andn2_saveexec_b64 s[56:57], s[56:57]
	v_fmamk_f32 v35, v36, 0x3d2aaaab, v208
	v_fma_f32 v35, v36, v35, 0.5
	v_fma_f32 v35, v36, v35, 1.0
	v_mul_f32_e64 v35, v36, -v35
	s_or_b64 exec, exec, s[56:57]
	v_add_f32_e32 v26, v26, v66
	v_mul_f32_e32 v26, 0xbfb8aa3b, v26
	v_exp_f32_e32 v26, v26
	v_add_f32_e32 v24, v24, v64
	v_mul_f32_e32 v24, 0xbfb8aa3b, v24
	v_exp_f32_e32 v24, v24
	v_add_f32_e32 v25, v25, v65
	v_add_f32_e32 v27, v27, v67
	v_add_f32_e32 v26, 1.0, v26
	v_mul_f32_e32 v25, 0xbfb8aa3b, v25
	v_rcp_f32_e32 v26, v26
	v_mul_f32_e32 v27, 0xbfb8aa3b, v27
	v_exp_f32_e32 v25, v25
	v_sqrt_f32_e32 v34, v34
	v_exp_f32_e32 v27, v27
	v_add_f32_e32 v24, 1.0, v24
	v_rcp_f32_e32 v24, v24
	v_add_f32_e32 v20, v20, v72
	v_lshlrev_b32_e32 v36, 16, v87
	v_sqrt_f32_e32 v32, v32
	v_mul_f32_e32 v20, 0xbfb8aa3b, v20
	v_mul_f32_e32 v26, v26, v36
	v_add_f32_e32 v25, 1.0, v25
	v_exp_f32_e32 v20, v20
	v_mul_f32_e32 v34, v26, v34
	v_add_f32_e32 v26, 1.0, v27
	v_lshlrev_b32_e32 v27, 16, v86
	v_rcp_f32_e32 v25, v25
	v_mul_f32_e32 v24, v24, v27
	v_mul_f32_e32 v32, v24, v32
	v_sqrt_f32_e32 v24, v33
	v_rcp_f32_e32 v26, v26
	v_and_b32_e32 v27, 0xffff0000, v86
	v_add_f32_e32 v20, 1.0, v20
	v_mul_f32_e32 v25, v25, v27
	v_sqrt_f32_e32 v27, v35
	v_rcp_f32_e32 v20, v20
	v_mul_f32_e32 v33, v25, v24
	v_and_b32_e32 v24, 0xffff0000, v87
	v_mul_f32_e32 v24, v26, v24
	v_mul_f32_e32 v35, v24, v27
	v_lshl_add_u64 v[24:25], v[100:101], 0, v[152:153]
	v_mul_f32_e32 v20, v68, v20
	v_lshlrev_b64 v[24:25], 1, v[24:25]
	v_mul_f32_e32 v20, 0x3fb8aa3b, v20
	v_cvt_pk_bf16_f32 v26, v28, v29
	v_cvt_pk_bf16_f32 v27, v30, v31
	v_lshl_add_u64 v[28:29], s[16:17], 0, v[24:25]
	v_cvt_pk_bf16_f32 v20, v20, 0
	global_store_dwordx2 v[28:29], v[26:27], off
	v_cvt_pk_bf16_f32 v26, v32, v33
	v_cvt_pk_bf16_f32 v27, v34, v35
	v_lshl_add_u64 v[24:25], s[18:19], 0, v[24:25]
	v_lshlrev_b32_e32 v20, 16, v20
	global_store_dwordx2 v[24:25], v[26:27], off
	v_add_f32_e32 v24, v20, v20
	v_mul_f32_e32 v25, 0x3f317218, v24
	v_cmp_nlt_f32_e32 vcc, s74, v25
	s_and_saveexec_b64 s[56:57], vcc
	s_xor_b64 s[56:57], exec, s[56:57]
	v_exp_f32_e32 v24, v20
	s_nop 0
	v_fma_f32 v24, -v24, v24, 1.0
	s_andn2_saveexec_b64 s[56:57], s[56:57]
	v_fmamk_f32 v24, v25, 0x3d2aaaab, v208
	v_fma_f32 v24, v25, v24, 0.5
	v_fma_f32 v24, v25, v24, 1.0
	v_mul_f32_e64 v24, v25, -v24
	s_or_b64 exec, exec, s[56:57]
	v_add_f32_e32 v21, v21, v73
	v_mul_f32_e32 v21, 0xbfb8aa3b, v21
	v_exp_f32_e32 v21, v21
	s_nop 0
	v_add_f32_e32 v21, 1.0, v21
	v_rcp_f32_e32 v21, v21
; __device__ __forceinline__ float bf_lo(unsigned w) { return __uint_as_float(w << 16); }
; __device__ __forceinline__ float bf_hi(unsigned w) { return __uint_as_float(w & 0xffff0000u); }
; __device__ __forceinline__ float fast_sigmoid(float x) { return __builtin_amdgcn_rcpf(1.0f + __builtin_amdgcn_exp2f(-x * LOG2E)); }
;     __device__ __forceinline__ void operator()(const f32x4 (&acc)[2][2][4][2], const Unit& u, int wr, int wc, int fr, int fq) const {
;     ...
;                 for (int m = 0; m < 4; ++m) { const int row = row0 + ai * HALF + m * 16; const size_t off = (size_t)row * DM + ch0 + n * 16;
;                     const u32x2 xw = xall[ai * 4 + m];
;                     const float xv[4] = {bf_lo(xw.x), bf_hi(xw.x), bf_lo(xw.y), bf_hi(xw.y)};
;                     f32x4 av; float bv[4];
; #pragma unroll
;                     for (int j = 0; j < 4; ++j) { const float r = fast_sigmoid(acc[ai][0][m][n][j] + ba[j]), ig = fast_sigmoid(acc[ai][1][m][n][j] + bx[j]);
;                         const float la = sp[j] * r; const float la2 = __uint_as_float(pk_bf16(la * LOG2E, 0.f) << 16);
;                         const float a = __builtin_amdgcn_exp2f(la2); const float x2 = 2.0f * la2 * 0.6931471805599453f; av[j] = la2;
;                         const float om = (x2 > -0.03f) ? -(x2 * (1.0f + x2 * (0.5f + x2 * (1.0f / 6.0f + x2 * (1.0f / 24.0f))))) : (1.0f - a * a);
;                         bv[j] = __builtin_amdgcn_sqrtf(om) * (ig * xv[j]); }
;                     { u32x2 wa; wa.x = pk_bf16(av[0], av[1]); wa.y = pk_bf16(av[2], av[3]); *(u32x2*)(aout + off) = wa; }
;                     u32x2 w; w.x = pk_bf16(bv[0], bv[1]); w.y = pk_bf16(bv[2], bv[3]); *(u32x2*)(bout + off) = w; }
	s_nop 0
	v_mul_f32_e32 v21, v69, v21
	v_mul_f32_e32 v21, 0x3fb8aa3b, v21
	v_cvt_pk_bf16_f32 v21, v21, 0
	v_lshlrev_b32_e32 v21, 16, v21
	v_add_f32_e32 v25, v21, v21
	v_mul_f32_e32 v26, 0x3f317218, v25
	v_cmp_nlt_f32_e32 vcc, s74, v26
	s_and_saveexec_b64 s[56:57], vcc
	s_xor_b64 s[56:57], exec, s[56:57]
	v_exp_f32_e32 v25, v21
	s_nop 0
	v_fma_f32 v25, -v25, v25, 1.0
	s_andn2_saveexec_b64 s[56:57], s[56:57]
	v_fmamk_f32 v25, v26, 0x3d2aaaab, v208
	v_fma_f32 v25, v26, v25, 0.5
	v_fma_f32 v25, v26, v25, 1.0
	v_mul_f32_e64 v25, v26, -v25
	s_or_b64 exec, exec, s[56:57]
	v_add_f32_e32 v22, v22, v74
	v_mul_f32_e32 v22, 0xbfb8aa3b, v22
	v_exp_f32_e32 v22, v22
	s_nop 0
	v_add_f32_e32 v22, 1.0, v22
	v_rcp_f32_e32 v22, v22
	s_nop 0
	v_mul_f32_e32 v22, v70, v22
	v_mul_f32_e32 v22, 0x3fb8aa3b, v22
	v_cvt_pk_bf16_f32 v22, v22, 0
	v_lshlrev_b32_e32 v22, 16, v22
	v_add_f32_e32 v26, v22, v22
	v_mul_f32_e32 v27, 0x3f317218, v26
	v_cmp_nlt_f32_e32 vcc, s74, v27
	s_and_saveexec_b64 s[56:57], vcc
	s_xor_b64 s[56:57], exec, s[56:57]
	v_exp_f32_e32 v26, v22
	s_nop 0
	v_fma_f32 v26, -v26, v26, 1.0
	s_andn2_saveexec_b64 s[56:57], s[56:57]
	v_fmamk_f32 v26, v27, 0x3d2aaaab, v208
	v_fma_f32 v26, v27, v26, 0.5
	v_fma_f32 v26, v27, v26, 1.0
	v_mul_f32_e64 v26, v27, -v26
	s_or_b64 exec, exec, s[56:57]
	v_add_f32_e32 v23, v23, v75
	v_mul_f32_e32 v23, 0xbfb8aa3b, v23
	v_exp_f32_e32 v23, v23
	s_nop 0
	v_add_f32_e32 v23, 1.0, v23
	v_rcp_f32_e32 v23, v23
	s_nop 0
	v_mul_f32_e32 v23, v71, v23
	v_mul_f32_e32 v23, 0x3fb8aa3b, v23
	v_cvt_pk_bf16_f32 v23, v23, 0
	v_lshlrev_b32_e32 v23, 16, v23
	v_add_f32_e32 v27, v23, v23
	v_mul_f32_e32 v28, 0x3f317218, v27
	v_cmp_nlt_f32_e32 vcc, s74, v28
	s_and_saveexec_b64 s[56:57], vcc
	s_xor_b64 s[56:57], exec, s[56:57]
	v_exp_f32_e32 v27, v23
	s_nop 0
	v_fma_f32 v27, -v27, v27, 1.0
	s_andn2_saveexec_b64 s[56:57], s[56:57]
	v_fmamk_f32 v27, v28, 0x3d2aaaab, v208
	v_fma_f32 v27, v28, v27, 0.5
	v_fma_f32 v27, v28, v27, 1.0
	v_mul_f32_e64 v27, v28, -v27
	s_or_b64 exec, exec, s[56:57]
	v_add_f32_e32 v18, v18, v66
	v_mul_f32_e32 v18, 0xbfb8aa3b, v18
	v_exp_f32_e32 v18, v18
	v_add_f32_e32 v16, v16, v64
	v_mul_f32_e32 v16, 0xbfb8aa3b, v16
	v_exp_f32_e32 v16, v16
	v_add_f32_e32 v17, v17, v65
	v_add_f32_e32 v19, v19, v67
	v_add_f32_e32 v18, 1.0, v18
	v_mul_f32_e32 v17, 0xbfb8aa3b, v17
	v_rcp_f32_e32 v18, v18
	v_mul_f32_e32 v19, 0xbfb8aa3b, v19
	v_exp_f32_e32 v17, v17
	v_sqrt_f32_e32 v26, v26
	v_exp_f32_e32 v19, v19
	v_add_f32_e32 v16, 1.0, v16
	v_rcp_f32_e32 v16, v16
	v_add_f32_e32 v12, v12, v72
	v_lshlrev_b32_e32 v28, 16, v83
	v_sqrt_f32_e32 v24, v24
	v_mul_f32_e32 v12, 0xbfb8aa3b, v12
	v_mul_f32_e32 v18, v18, v28
	v_add_f32_e32 v17, 1.0, v17
	v_exp_f32_e32 v12, v12
	v_mul_f32_e32 v26, v18, v26
	v_add_f32_e32 v18, 1.0, v19
	v_lshlrev_b32_e32 v19, 16, v82
	v_rcp_f32_e32 v17, v17
	v_mul_f32_e32 v16, v16, v19
	v_mul_f32_e32 v24, v16, v24
	v_sqrt_f32_e32 v16, v25
	v_rcp_f32_e32 v18, v18
	v_and_b32_e32 v19, 0xffff0000, v82
	v_add_f32_e32 v12, 1.0, v12
	v_mul_f32_e32 v17, v17, v19
	v_sqrt_f32_e32 v19, v27
	v_rcp_f32_e32 v12, v12
	v_mul_f32_e32 v25, v17, v16
	v_and_b32_e32 v16, 0xffff0000, v83
	v_mul_f32_e32 v16, v18, v16
	v_mul_f32_e32 v27, v16, v19
	v_lshl_add_u64 v[16:17], v[92:93], 0, v[152:153]
	v_mul_f32_e32 v12, v68, v12
	v_lshlrev_b64 v[16:17], 1, v[16:17]
	v_mul_f32_e32 v12, 0x3fb8aa3b, v12
	v_cvt_pk_bf16_f32 v18, v20, v21
	v_cvt_pk_bf16_f32 v19, v22, v23
	v_lshl_add_u64 v[20:21], s[16:17], 0, v[16:17]
	v_cvt_pk_bf16_f32 v12, v12, 0
	global_store_dwordx2 v[20:21], v[18:19], off
	v_cvt_pk_bf16_f32 v18, v24, v25
	v_cvt_pk_bf16_f32 v19, v26, v27
	v_lshl_add_u64 v[16:17], s[18:19], 0, v[16:17]
	v_lshlrev_b32_e32 v12, 16, v12
	global_store_dwordx2 v[16:17], v[18:19], off
	v_add_f32_e32 v16, v12, v12
	v_mul_f32_e32 v17, 0x3f317218, v16
	v_cmp_nlt_f32_e32 vcc, s74, v17
	s_and_saveexec_b64 s[56:57], vcc
	s_xor_b64 s[56:57], exec, s[56:57]
	v_exp_f32_e32 v16, v12
	s_nop 0
	v_fma_f32 v16, -v16, v16, 1.0
	s_andn2_saveexec_b64 s[56:57], s[56:57]
	v_fmamk_f32 v16, v17, 0x3d2aaaab, v208
	v_fma_f32 v16, v17, v16, 0.5
	v_fma_f32 v16, v17, v16, 1.0
	v_mul_f32_e64 v16, v17, -v16
	s_or_b64 exec, exec, s[56:57]
	v_add_f32_e32 v13, v13, v73
	v_mul_f32_e32 v13, 0xbfb8aa3b, v13
	v_exp_f32_e32 v13, v13
	s_nop 0
	v_add_f32_e32 v13, 1.0, v13
	v_rcp_f32_e32 v13, v13
	s_nop 0
	v_mul_f32_e32 v13, v69, v13
	v_mul_f32_e32 v13, 0x3fb8aa3b, v13
	v_cvt_pk_bf16_f32 v13, v13, 0
	v_lshlrev_b32_e32 v13, 16, v13
	v_add_f32_e32 v17, v13, v13
	v_mul_f32_e32 v18, 0x3f317218, v17
	v_cmp_nlt_f32_e32 vcc, s74, v18
	s_and_saveexec_b64 s[56:57], vcc
	s_xor_b64 s[56:57], exec, s[56:57]
	v_exp_f32_e32 v17, v13
	s_nop 0
	v_fma_f32 v17, -v17, v17, 1.0
	s_andn2_saveexec_b64 s[56:57], s[56:57]
	v_fmamk_f32 v17, v18, 0x3d2aaaab, v208
	v_fma_f32 v17, v18, v17, 0.5
	v_fma_f32 v17, v18, v17, 1.0
	v_mul_f32_e64 v17, v18, -v17
	s_or_b64 exec, exec, s[56:57]
	v_add_f32_e32 v14, v14, v74
	v_mul_f32_e32 v14, 0xbfb8aa3b, v14
	v_exp_f32_e32 v14, v14
	s_nop 0
	v_add_f32_e32 v14, 1.0, v14
	v_rcp_f32_e32 v14, v14
	s_nop 0
	v_mul_f32_e32 v14, v70, v14
	v_mul_f32_e32 v14, 0x3fb8aa3b, v14
	v_cvt_pk_bf16_f32 v14, v14, 0
	v_lshlrev_b32_e32 v14, 16, v14
	v_add_f32_e32 v18, v14, v14
	v_mul_f32_e32 v19, 0x3f317218, v18
; __device__ __forceinline__ float bf_lo(unsigned w) { return __uint_as_float(w << 16); }
; __device__ __forceinline__ float bf_hi(unsigned w) { return __uint_as_float(w & 0xffff0000u); }
; __device__ __forceinline__ float fast_sigmoid(float x) { return __builtin_amdgcn_rcpf(1.0f + __builtin_amdgcn_exp2f(-x * LOG2E)); }
; template <class Epi>
; __device__ __forceinline__ void gemm_phase(LAS unsigned char* lds, const Gemm g, const StaticOrder& S, const Epi& E, int wv) {
;     ...
;         if (!has_next) break;
; #pragma unroll
;         for (int a = 0; a < 2; ++a)
; #pragma unroll
;             for (int b = 0; b < 2; ++b)
; #pragma unroll
;                 for (int m = 0; m < 4; ++m)
; #pragma unroll
;                     for (int n = 0; n < 2; ++n) acc[a][b][m][n] = (f32x4){0.f, 0.f, 0.f, 0.f};
;         cur = nxt; cA = nA; cB = nB; ++ui;
;     __device__ __forceinline__ void operator()(const f32x4 (&acc)[2][2][4][2], const Unit& u, int wr, int wc, int fr, int fq) const {
;     ...
;                 for (int m = 0; m < 4; ++m) { const int row = row0 + ai * HALF + m * 16; const size_t off = (size_t)row * DM + ch0 + n * 16;
;                     const u32x2 xw = xall[ai * 4 + m];
;                     const float xv[4] = {bf_lo(xw.x), bf_hi(xw.x), bf_lo(xw.y), bf_hi(xw.y)};
;                     f32x4 av; float bv[4];
; #pragma unroll
;                     for (int j = 0; j < 4; ++j) { const float r = fast_sigmoid(acc[ai][0][m][n][j] + ba[j]), ig = fast_sigmoid(acc[ai][1][m][n][j] + bx[j]);
;                         const float la = sp[j] * r; const float la2 = __uint_as_float(pk_bf16(la * LOG2E, 0.f) << 16);
;                         const float a = __builtin_amdgcn_exp2f(la2); const float x2 = 2.0f * la2 * 0.6931471805599453f; av[j] = la2;
;                         const float om = (x2 > -0.03f) ? -(x2 * (1.0f + x2 * (0.5f + x2 * (1.0f / 6.0f + x2 * (1.0f / 24.0f))))) : (1.0f - a * a);
;                         bv[j] = __builtin_amdgcn_sqrtf(om) * (ig * xv[j]); }
;                     { u32x2 wa; wa.x = pk_bf16(av[0], av[1]); wa.y = pk_bf16(av[2], av[3]); *(u32x2*)(aout + off) = wa; }
;                     u32x2 w; w.x = pk_bf16(bv[0], bv[1]); w.y = pk_bf16(bv[2], bv[3]); *(u32x2*)(bout + off) = w; }
	v_cmp_nlt_f32_e32 vcc, s74, v19
	s_and_saveexec_b64 s[56:57], vcc
	s_xor_b64 s[56:57], exec, s[56:57]
	v_exp_f32_e32 v18, v14
	s_nop 0
	v_fma_f32 v18, -v18, v18, 1.0
	s_andn2_saveexec_b64 s[56:57], s[56:57]
	v_fmamk_f32 v18, v19, 0x3d2aaaab, v208
	v_fma_f32 v18, v19, v18, 0.5
	v_fma_f32 v18, v19, v18, 1.0
	v_mul_f32_e64 v18, v19, -v18
	s_or_b64 exec, exec, s[56:57]
	v_add_f32_e32 v15, v15, v75
	v_mul_f32_e32 v15, 0xbfb8aa3b, v15
	v_exp_f32_e32 v15, v15
	s_nop 0
	v_add_f32_e32 v15, 1.0, v15
	v_rcp_f32_e32 v15, v15
	s_nop 0
	v_mul_f32_e32 v15, v71, v15
	v_mul_f32_e32 v15, 0x3fb8aa3b, v15
	v_cvt_pk_bf16_f32 v15, v15, 0
	v_lshlrev_b32_e32 v15, 16, v15
	v_add_f32_e32 v19, v15, v15
	v_mul_f32_e32 v20, 0x3f317218, v19
	v_cmp_nlt_f32_e32 vcc, s74, v20
	s_and_saveexec_b64 s[56:57], vcc
	s_xor_b64 s[56:57], exec, s[56:57]
	v_exp_f32_e32 v19, v15
	s_nop 0
	v_fma_f32 v19, -v19, v19, 1.0
	s_andn2_saveexec_b64 s[56:57], s[56:57]
	v_fmamk_f32 v19, v20, 0x3d2aaaab, v208
	v_fma_f32 v19, v20, v19, 0.5
	v_fma_f32 v19, v20, v19, 1.0
	v_mul_f32_e64 v19, v20, -v19
	s_or_b64 exec, exec, s[56:57]
	v_add_f32_e32 v10, v10, v66
	v_mul_f32_e32 v10, 0xbfb8aa3b, v10
	v_exp_f32_e32 v10, v10
	v_add_f32_e32 v8, v8, v64
	v_mul_f32_e32 v8, 0xbfb8aa3b, v8
	v_exp_f32_e32 v8, v8
	v_add_f32_e32 v9, v9, v65
	v_add_f32_e32 v11, v11, v67
	v_add_f32_e32 v10, 1.0, v10
	v_mul_f32_e32 v9, 0xbfb8aa3b, v9
	v_rcp_f32_e32 v10, v10
	v_mul_f32_e32 v11, 0xbfb8aa3b, v11
	v_exp_f32_e32 v9, v9
	v_sqrt_f32_e32 v18, v18
	v_exp_f32_e32 v11, v11
	v_add_f32_e32 v8, 1.0, v8
	v_rcp_f32_e32 v8, v8
	v_add_f32_e32 v4, v4, v72
	v_lshlrev_b32_e32 v20, 16, v81
	v_sqrt_f32_e32 v16, v16
	v_mul_f32_e32 v4, 0xbfb8aa3b, v4
	v_mul_f32_e32 v10, v10, v20
	v_add_f32_e32 v9, 1.0, v9
	v_exp_f32_e32 v4, v4
	v_mul_f32_e32 v18, v10, v18
	v_add_f32_e32 v10, 1.0, v11
	v_lshlrev_b32_e32 v11, 16, v80
	v_rcp_f32_e32 v9, v9
	v_mul_f32_e32 v8, v8, v11
	v_mul_f32_e32 v16, v8, v16
	v_sqrt_f32_e32 v8, v17
	v_rcp_f32_e32 v10, v10
	v_and_b32_e32 v11, 0xffff0000, v80
	v_add_f32_e32 v4, 1.0, v4
	v_mul_f32_e32 v9, v9, v11
	v_sqrt_f32_e32 v11, v19
	v_rcp_f32_e32 v4, v4
	v_mul_f32_e32 v17, v9, v8
	v_and_b32_e32 v8, 0xffff0000, v81
	v_mul_f32_e32 v8, v10, v8
	v_mul_f32_e32 v19, v8, v11
	v_lshl_add_u64 v[8:9], v[84:85], 0, v[152:153]
	v_mul_f32_e32 v4, v68, v4
	v_lshlrev_b64 v[8:9], 1, v[8:9]
	v_mul_f32_e32 v4, 0x3fb8aa3b, v4
	v_cvt_pk_bf16_f32 v10, v12, v13
	v_cvt_pk_bf16_f32 v11, v14, v15
	v_lshl_add_u64 v[12:13], s[16:17], 0, v[8:9]
	v_cvt_pk_bf16_f32 v4, v4, 0
	global_store_dwordx2 v[12:13], v[10:11], off
	v_cvt_pk_bf16_f32 v10, v16, v17
	v_cvt_pk_bf16_f32 v11, v18, v19
	v_lshl_add_u64 v[8:9], s[18:19], 0, v[8:9]
	v_lshlrev_b32_e32 v4, 16, v4
	global_store_dwordx2 v[8:9], v[10:11], off
	v_add_f32_e32 v8, v4, v4
	v_mul_f32_e32 v9, 0x3f317218, v8
	v_cmp_nlt_f32_e32 vcc, s74, v9
	s_and_saveexec_b64 s[56:57], vcc
	s_xor_b64 s[56:57], exec, s[56:57]
	v_exp_f32_e32 v8, v4
	s_nop 0
	v_fma_f32 v8, -v8, v8, 1.0
	s_andn2_saveexec_b64 s[56:57], s[56:57]
	v_fmamk_f32 v8, v9, 0x3d2aaaab, v208
	v_fma_f32 v8, v9, v8, 0.5
	v_fma_f32 v8, v9, v8, 1.0
	v_mul_f32_e64 v8, v9, -v8
	s_or_b64 exec, exec, s[56:57]
	v_add_f32_e32 v5, v5, v73
	v_mul_f32_e32 v5, 0xbfb8aa3b, v5
	v_exp_f32_e32 v5, v5
	s_nop 0
	v_add_f32_e32 v5, 1.0, v5
	v_rcp_f32_e32 v5, v5
	s_nop 0
	v_mul_f32_e32 v5, v69, v5
	v_mul_f32_e32 v5, 0x3fb8aa3b, v5
	v_cvt_pk_bf16_f32 v5, v5, 0
	v_lshlrev_b32_e32 v5, 16, v5
	v_add_f32_e32 v9, v5, v5
	v_mul_f32_e32 v10, 0x3f317218, v9
	v_cmp_nlt_f32_e32 vcc, s74, v10
	s_and_saveexec_b64 s[56:57], vcc
	s_xor_b64 s[56:57], exec, s[56:57]
	v_exp_f32_e32 v9, v5
	s_nop 0
	v_fma_f32 v9, -v9, v9, 1.0
	s_andn2_saveexec_b64 s[56:57], s[56:57]
	v_fmamk_f32 v9, v10, 0x3d2aaaab, v208
	v_fma_f32 v9, v10, v9, 0.5
	v_fma_f32 v9, v10, v9, 1.0
	v_mul_f32_e64 v9, v10, -v9
	s_or_b64 exec, exec, s[56:57]
	v_add_f32_e32 v6, v6, v74
	v_mul_f32_e32 v6, 0xbfb8aa3b, v6
	v_exp_f32_e32 v6, v6
	s_nop 0
	v_add_f32_e32 v6, 1.0, v6
	v_rcp_f32_e32 v6, v6
	s_nop 0
	v_mul_f32_e32 v6, v70, v6
	v_mul_f32_e32 v6, 0x3fb8aa3b, v6
	v_cvt_pk_bf16_f32 v6, v6, 0
	v_lshlrev_b32_e32 v6, 16, v6
	v_add_f32_e32 v10, v6, v6
	v_mul_f32_e32 v11, 0x3f317218, v10
	v_cmp_nlt_f32_e32 vcc, s74, v11
	s_and_saveexec_b64 s[56:57], vcc
	s_xor_b64 s[56:57], exec, s[56:57]
	v_exp_f32_e32 v10, v6
	s_nop 0
	v_fma_f32 v10, -v10, v10, 1.0
	s_andn2_saveexec_b64 s[56:57], s[56:57]
	v_fmamk_f32 v10, v11, 0x3d2aaaab, v208
	v_fma_f32 v10, v11, v10, 0.5
	v_fma_f32 v10, v11, v10, 1.0
	v_mul_f32_e64 v10, v11, -v10
	s_or_b64 exec, exec, s[56:57]
	v_add_f32_e32 v7, v7, v75
	v_mul_f32_e32 v7, 0xbfb8aa3b, v7
	v_exp_f32_e32 v7, v7
	s_nop 0
	v_add_f32_e32 v7, 1.0, v7
	v_rcp_f32_e32 v7, v7
	s_nop 0
	v_mul_f32_e32 v7, v71, v7
	v_mul_f32_e32 v7, 0x3fb8aa3b, v7
	v_cvt_pk_bf16_f32 v7, v7, 0
	v_lshlrev_b32_e32 v7, 16, v7
	v_add_f32_e32 v11, v7, v7
	v_mul_f32_e32 v12, 0x3f317218, v11
	v_cmp_nlt_f32_e32 vcc, s74, v12
	s_and_saveexec_b64 s[56:57], vcc
	s_xor_b64 s[56:57], exec, s[56:57]
	v_exp_f32_e32 v11, v7
	s_nop 0
	v_fma_f32 v11, -v11, v11, 1.0
	s_andn2_saveexec_b64 s[56:57], s[56:57]
	s_cbranch_execz .LBB0_1119
	v_fmamk_f32 v11, v12, 0x3d2aaaab, v208
	v_fma_f32 v11, v12, v11, 0.5
	v_fma_f32 v11, v12, v11, 1.0
	v_mul_f32_e64 v11, v12, -v11
	s_branch .LBB0_1119

; #define PG8_STAGE(bufoff, gbase, voff) do { _Pragma("unroll") for (int _i = 0; _i < 2; ++_i) \
;         __builtin_amdgcn_global_load_lds((const unsigned*)((const char*)(gbase) + (voff)[_i]), (LAS unsigned*)(lds + (bufoff) + ldsw + _i * 8192), 16, 0, 0); } while (0)
; #define PG8_LDA(dst, b, h) do { _Pragma("unroll") for (int m = 0; m < 4; ++m) _Pragma("unroll") for (int k = 0; k < 2; ++k) dst[m][k] = *(const LAS bf16x8*)(lds + PG8_SA(b, h) + aoff + m * 2048 + k * 1024); } while (0)
; #define PG8_LDB(dst, b, h) do { _Pragma("unroll") for (int n = 0; n < 2; ++n) _Pragma("unroll") for (int k = 0; k < 2; ++k) dst[n][k] = *(const LAS bf16x8*)(lds + PG8_SB(b, h) + boff + n * 2048 + k * 1024); } while (0)
; #define PG8_MMA(ai, bj, At, Bt) do { __builtin_amdgcn_s_setprio(1); _Pragma("unroll") for (int m = 0; m < 4; ++m) _Pragma("unroll") for (int n = 0; n < 2; ++n) _Pragma("unroll") for (int k = 0; k < 2; ++k) \
;         acc[ai][bj][m][n] = __builtin_amdgcn_mfma_f32_16x16x32_bf16(Bt[n][k], At[m][k], acc[ai][bj][m][n], 0, 0, 0); __builtin_amdgcn_s_setprio(0); } while (0)
; #define PG8_WAIT_V(n) asm volatile("s_waitcnt vmcnt(" #n ")" ::: "memory")
; #define PG8_WAIT_L(n) asm volatile("s_waitcnt lgkmcnt(" #n ")" ::: "memory")
; #define PG8_BAR __builtin_amdgcn_s_barrier()
; template <class Epi>
; __device__ __forceinline__ void gemm_phase(LAS unsigned char* lds, const Gemm g, const StaticOrder& S, const Epi& E, int wv) {
;     ...
;             const bool last = (t == nt - 2);
;             const char* a1 = cA + (ptrdiff_t)(t + 1) * kstep;
;             const char* a2 = last ? nA : cA + (ptrdiff_t)(t + 2) * kstep; const char* b2 = last ? nB : cB + (ptrdiff_t)(t + 2) * kstep;
;             const char* a3 = a2 + kstep; const char* b3 = b2 + kstep;
;             PG8_LDB(B0, 0, 0); PG8_SCHED; PG8_LDA(At, 0, 0); PG8_STAGE(PG8_SA(1, 1), a1 + hstepA, voffA);
;             PG8_WAIT_L(8); PG8_BAR; PG8_WAIT_L(0); PG8_MMA(0, 0, At, B0); PG8_BAR; PG8_SCHED;
;             PG8_LDB(B1, 0, 1); PG8_STAGE(PG8_SB(0, 0), b2, voffB);
;             PG8_BAR; PG8_WAIT_L(0); PG8_MMA(0, 1, At, B1); PG8_BAR;
;             PG8_LDA(At, 0, 1); PG8_STAGE(PG8_SA(0, 0), a2, voffA);
;             PG8_BAR; PG8_WAIT_L(0); PG8_MMA(1, 0, At, B0); PG8_BAR; PG8_SCHED;
;             PG8_STAGE(PG8_SB(0, 1), b2 + hstepB, voffB);
;             PG8_WAIT_V(6); PG8_BAR; PG8_MMA(1, 1, At, B1); PG8_BAR;
.Lrot_in_1581:
	s_add_u32 s48, s46, 0xfff80080
	s_addc_u32 s49, s47, -1
	s_cmp_eq_u32 s63, 28
	s_cselect_b32 s51, s37, s49
	s_cselect_b32 s50, s43, s48
	s_cselect_b32 s49, s35, s62
	s_cselect_b32 s48, s60, s61
	s_add_i32 m0, s33, 0xc000
	ds_read_b128 v[160:163], v180
	ds_read_b128 v[164:167], v180 offset:1024
	ds_read_b128 v[168:171], v180 offset:2048
	ds_read_b128 v[172:175], v180 offset:3072
	ds_read_b128 v[182:185], v180 offset:4096
	ds_read_b128 v[186:189], v180 offset:5120
	ds_read_b128 v[190:193], v180 offset:6144
	ds_read_b128 v[194:197], v180 offset:7168
	global_load_lds_dwordx4 v154, s[46:47]
	s_add_i32 m0, s33, 0xe000
	s_nop 0
	global_load_lds_dwordx4 v152, s[46:47]
	s_waitcnt lgkmcnt(8)
	s_barrier
	s_waitcnt lgkmcnt(0)
	v_mfma_f32_16x16x32_bf16 v[124:127], v[128:131], v[160:163], v[124:127]
	v_mfma_f32_16x16x32_bf16 v[120:123], v[136:139], v[160:163], v[120:123]
	v_mfma_f32_16x16x32_bf16 v[108:111], v[128:131], v[168:171], v[108:111]
	v_mfma_f32_16x16x32_bf16 v[104:107], v[136:139], v[168:171], v[104:107]
	v_mfma_f32_16x16x32_bf16 v[92:95], v[128:131], v[182:185], v[92:95]
	v_mfma_f32_16x16x32_bf16 v[88:91], v[136:139], v[182:185], v[88:91]
	v_mfma_f32_16x16x32_bf16 v[76:79], v[128:131], v[190:193], v[76:79]
	v_mfma_f32_16x16x32_bf16 v[72:75], v[136:139], v[190:193], v[72:75]
	v_mfma_f32_16x16x32_bf16 v[124:127], v[132:135], v[164:167], v[124:127]
	v_mfma_f32_16x16x32_bf16 v[120:123], v[140:143], v[164:167], v[120:123]
	v_mfma_f32_16x16x32_bf16 v[108:111], v[132:135], v[172:175], v[108:111]
	v_mfma_f32_16x16x32_bf16 v[104:107], v[140:143], v[172:175], v[104:107]
	v_mfma_f32_16x16x32_bf16 v[92:95], v[132:135], v[186:189], v[92:95]
	v_mfma_f32_16x16x32_bf16 v[88:91], v[140:143], v[186:189], v[88:91]
	v_mfma_f32_16x16x32_bf16 v[76:79], v[132:135], v[194:197], v[76:79]
	v_mfma_f32_16x16x32_bf16 v[72:75], v[140:143], v[194:197], v[72:75]
	s_barrier
	s_add_i32 s64, s57, s25
	s_add_u32 s98, s48, s16
	s_addc_u32 s99, s49, s17
	s_mov_b32 m0, s64
	ds_read_b128 v[198:201], v181
	ds_read_b128 v[202:205], v181 offset:1024
	ds_read_b128 v[206:209], v181 offset:2048
	ds_read_b128 v[210:213], v181 offset:3072
	global_load_lds_dwordx4 v146, s[48:49]
	s_add_i32 m0, s64, 0x2000
	s_nop 0
	global_load_lds_dwordx4 v150, s[48:49]
	s_barrier
	s_waitcnt lgkmcnt(0)
	v_mfma_f32_16x16x32_bf16 v[116:119], v[198:201], v[160:163], v[116:119]
	v_mfma_f32_16x16x32_bf16 v[112:115], v[206:209], v[160:163], v[112:115]
	v_mfma_f32_16x16x32_bf16 v[100:103], v[198:201], v[168:171], v[100:103]
	v_mfma_f32_16x16x32_bf16 v[96:99], v[206:209], v[168:171], v[96:99]
	v_mfma_f32_16x16x32_bf16 v[84:87], v[198:201], v[182:185], v[84:87]
	v_mfma_f32_16x16x32_bf16 v[80:83], v[206:209], v[182:185], v[80:83]
	v_mfma_f32_16x16x32_bf16 v[68:71], v[198:201], v[190:193], v[68:71]
	v_mfma_f32_16x16x32_bf16 v[64:67], v[206:209], v[190:193], v[64:67]
	v_mfma_f32_16x16x32_bf16 v[116:119], v[202:205], v[164:167], v[116:119]
	v_mfma_f32_16x16x32_bf16 v[112:115], v[210:213], v[164:167], v[112:115]
	v_mfma_f32_16x16x32_bf16 v[100:103], v[202:205], v[172:175], v[100:103]
	v_mfma_f32_16x16x32_bf16 v[96:99], v[210:213], v[172:175], v[96:99]
	v_mfma_f32_16x16x32_bf16 v[84:87], v[202:205], v[186:189], v[84:87]
	v_mfma_f32_16x16x32_bf16 v[80:83], v[210:213], v[186:189], v[80:83]
	v_mfma_f32_16x16x32_bf16 v[68:71], v[202:205], v[194:197], v[68:71]
	v_mfma_f32_16x16x32_bf16 v[64:67], v[210:213], v[194:197], v[64:67]
	s_mov_b32 m0, s33
	s_add_u32 s100, s50, s16
	s_addc_u32 s101, s51, s17
	s_barrier
	ds_read_b128 v[160:163], v180 offset:16384
	ds_read_b128 v[164:167], v180 offset:17408
	ds_read_b128 v[168:171], v180 offset:18432
	ds_read_b128 v[172:175], v180 offset:19456
	ds_read_b128 v[182:185], v180 offset:20480
	ds_read_b128 v[186:189], v180 offset:21504
	ds_read_b128 v[190:193], v180 offset:22528
	ds_read_b128 v[194:197], v180 offset:23552
	global_load_lds_dwordx4 v144, s[50:51]
	s_mov_b32 m0, s45
	s_nop 0
	global_load_lds_dwordx4 v148, s[50:51]
	s_waitcnt vmcnt(10)
	s_barrier
	s_waitcnt lgkmcnt(0)
	v_mfma_f32_16x16x32_bf16 v[60:63], v[128:131], v[160:163], v[60:63]
	v_mfma_f32_16x16x32_bf16 v[56:59], v[136:139], v[160:163], v[56:59]
	v_mfma_f32_16x16x32_bf16 v[44:47], v[128:131], v[168:171], v[44:47]
	v_mfma_f32_16x16x32_bf16 v[40:43], v[136:139], v[168:171], v[40:43]
	v_mfma_f32_16x16x32_bf16 v[28:31], v[128:131], v[182:185], v[28:31]
	v_mfma_f32_16x16x32_bf16 v[24:27], v[136:139], v[182:185], v[24:27]
	v_mfma_f32_16x16x32_bf16 v[12:15], v[128:131], v[190:193], v[12:15]
	v_mfma_f32_16x16x32_bf16 v[8:11], v[136:139], v[190:193], v[8:11]
	v_mfma_f32_16x16x32_bf16 v[60:63], v[132:135], v[164:167], v[60:63]
	v_mfma_f32_16x16x32_bf16 v[56:59], v[140:143], v[164:167], v[56:59]
	v_mfma_f32_16x16x32_bf16 v[44:47], v[132:135], v[172:175], v[44:47]
	v_mfma_f32_16x16x32_bf16 v[40:43], v[140:143], v[172:175], v[40:43]
	v_mfma_f32_16x16x32_bf16 v[28:31], v[132:135], v[186:189], v[28:31]
	v_mfma_f32_16x16x32_bf16 v[24:27], v[140:143], v[186:189], v[24:27]
	v_mfma_f32_16x16x32_bf16 v[12:15], v[132:135], v[194:197], v[12:15]
	v_mfma_f32_16x16x32_bf16 v[8:11], v[140:143], v[194:197], v[8:11]
	s_barrier
	s_add_u32 s64, s48, 0x80000
	s_addc_u32 s65, s49, 0
	s_add_i32 s66, s58, s25
	s_mov_b32 m0, s66
	s_nop 0
	global_load_lds_dwordx4 v146, s[64:65]
	s_add_i32 m0, s66, 0x2000
	s_nop 0
	global_load_lds_dwordx4 v150, s[64:65]
	s_add_i32 s64, 0, 0x18000
	v_add_u32_e32 v140, s64, v177
	ds_read_b128 v[128:131], v140
	ds_read_b128 v[132:135], v140 offset:1024
	ds_read_b128 v[136:139], v140 offset:2048
	ds_read_b128 v[140:143], v140 offset:3072
	s_waitcnt vmcnt(6)
	s_barrier
; #define PG8_STAGE(bufoff, gbase, voff) do { _Pragma("unroll") for (int _i = 0; _i < 2; ++_i) \
;         __builtin_amdgcn_global_load_lds((const unsigned*)((const char*)(gbase) + (voff)[_i]), (LAS unsigned*)(lds + (bufoff) + ldsw + _i * 8192), 16, 0, 0); } while (0)
; #define PG8_LDA(dst, b, h) do { _Pragma("unroll") for (int m = 0; m < 4; ++m) _Pragma("unroll") for (int k = 0; k < 2; ++k) dst[m][k] = *(const LAS bf16x8*)(lds + PG8_SA(b, h) + aoff + m * 2048 + k * 1024); } while (0)
; #define PG8_LDB(dst, b, h) do { _Pragma("unroll") for (int n = 0; n < 2; ++n) _Pragma("unroll") for (int k = 0; k < 2; ++k) dst[n][k] = *(const LAS bf16x8*)(lds + PG8_SB(b, h) + boff + n * 2048 + k * 1024); } while (0)
; #define PG8_MMA(ai, bj, At, Bt) do { __builtin_amdgcn_s_setprio(1); _Pragma("unroll") for (int m = 0; m < 4; ++m) _Pragma("unroll") for (int n = 0; n < 2; ++n) _Pragma("unroll") for (int k = 0; k < 2; ++k) \
;         acc[ai][bj][m][n] = __builtin_amdgcn_mfma_f32_16x16x32_bf16(Bt[n][k], At[m][k], acc[ai][bj][m][n], 0, 0, 0); __builtin_amdgcn_s_setprio(0); } while (0)
; #define PG8_WAIT_V(n) asm volatile("s_waitcnt vmcnt(" #n ")" ::: "memory")
; #define PG8_WAIT_L(n) asm volatile("s_waitcnt lgkmcnt(" #n ")" ::: "memory")
; #define PG8_BAR __builtin_amdgcn_s_barrier()
; #define PG8_SCHED __builtin_amdgcn_sched_barrier(0)
; template <class Epi>
; __device__ __forceinline__ void gemm_phase(LAS unsigned char* lds, const Gemm g, const StaticOrder& S, const Epi& E, int wv) {
;     ...
;             PG8_WAIT_V(6); PG8_BAR; PG8_MMA(1, 1, At, B1); PG8_BAR;
;             PG8_LDB(B0, 1, 0); PG8_SCHED; PG8_LDA(At, 1, 0); PG8_STAGE(PG8_SA(0, 1), a2 + hstepA, voffA);
;             PG8_WAIT_L(8); PG8_BAR; PG8_WAIT_L(0); PG8_MMA(0, 0, At, B0); PG8_BAR; PG8_SCHED;
;             PG8_LDB(B1, 1, 1); PG8_STAGE(PG8_SB(1, 0), b3, voffB);
;             PG8_BAR; PG8_WAIT_L(0); PG8_MMA(0, 1, At, B1); PG8_BAR;
;             PG8_LDA(At, 1, 1); PG8_STAGE(PG8_SA(1, 0), a3, voffA);
;             PG8_BAR; PG8_WAIT_L(0); PG8_MMA(1, 0, At, B0); PG8_BAR; PG8_SCHED;
;             PG8_STAGE(PG8_SB(1, 1), b3 + hstepB, voffB);
;             PG8_WAIT_V(6); PG8_BAR; PG8_MMA(1, 1, At, B1); PG8_BAR;
	v_mfma_f32_16x16x32_bf16 v[52:55], v[198:201], v[160:163], v[52:55]
	v_mfma_f32_16x16x32_bf16 v[48:51], v[206:209], v[160:163], v[48:51]
	v_mfma_f32_16x16x32_bf16 v[36:39], v[198:201], v[168:171], v[36:39]
	v_mfma_f32_16x16x32_bf16 v[32:35], v[206:209], v[168:171], v[32:35]
	v_mfma_f32_16x16x32_bf16 v[20:23], v[198:201], v[182:185], v[20:23]
	v_mfma_f32_16x16x32_bf16 v[16:19], v[206:209], v[182:185], v[16:19]
	v_mfma_f32_16x16x32_bf16 v[4:7], v[198:201], v[190:193], v[4:7]
	v_mfma_f32_16x16x32_bf16 v[0:3], v[206:209], v[190:193], v[0:3]
	v_mfma_f32_16x16x32_bf16 v[52:55], v[202:205], v[164:167], v[52:55]
	v_mfma_f32_16x16x32_bf16 v[48:51], v[210:213], v[164:167], v[48:51]
	v_mfma_f32_16x16x32_bf16 v[36:39], v[202:205], v[172:175], v[36:39]
	v_mfma_f32_16x16x32_bf16 v[32:35], v[210:213], v[172:175], v[32:35]
	v_mfma_f32_16x16x32_bf16 v[20:23], v[202:205], v[186:189], v[20:23]
	v_mfma_f32_16x16x32_bf16 v[16:19], v[210:213], v[186:189], v[16:19]
	v_mfma_f32_16x16x32_bf16 v[4:7], v[202:205], v[194:197], v[4:7]
	v_mfma_f32_16x16x32_bf16 v[0:3], v[210:213], v[194:197], v[0:3]
	s_waitcnt lgkmcnt(0)
	s_barrier
	s_add_u32 s50, s50, 0x80000
	s_addc_u32 s51, s51, 0
	s_mov_b32 m0, s52
	ds_read_b128 v[160:163], v180 offset:32768
	ds_read_b128 v[164:167], v180 offset:33792
	ds_read_b128 v[168:171], v180 offset:34816
	ds_read_b128 v[172:175], v180 offset:35840
	ds_read_b128 v[182:185], v180 offset:36864
	ds_read_b128 v[186:189], v180 offset:37888
	ds_read_b128 v[190:193], v180 offset:38912
	ds_read_b128 v[194:197], v180 offset:39936
	global_load_lds_dwordx4 v144, s[50:51]
	s_mov_b32 m0, s53
	s_nop 0
	global_load_lds_dwordx4 v148, s[50:51]
	s_waitcnt lgkmcnt(8)
	s_barrier
	s_waitcnt lgkmcnt(0)
	v_mfma_f32_16x16x32_bf16 v[124:127], v[128:131], v[160:163], v[124:127]
	v_mfma_f32_16x16x32_bf16 v[120:123], v[136:139], v[160:163], v[120:123]
	v_mfma_f32_16x16x32_bf16 v[108:111], v[128:131], v[168:171], v[108:111]
	v_mfma_f32_16x16x32_bf16 v[104:107], v[136:139], v[168:171], v[104:107]
	v_mfma_f32_16x16x32_bf16 v[92:95], v[128:131], v[182:185], v[92:95]
	v_mfma_f32_16x16x32_bf16 v[88:91], v[136:139], v[182:185], v[88:91]
	v_mfma_f32_16x16x32_bf16 v[76:79], v[128:131], v[190:193], v[76:79]
	v_mfma_f32_16x16x32_bf16 v[72:75], v[136:139], v[190:193], v[72:75]
	v_mfma_f32_16x16x32_bf16 v[124:127], v[132:135], v[164:167], v[124:127]
	v_mfma_f32_16x16x32_bf16 v[120:123], v[140:143], v[164:167], v[120:123]
	v_mfma_f32_16x16x32_bf16 v[108:111], v[132:135], v[172:175], v[108:111]
	v_mfma_f32_16x16x32_bf16 v[104:107], v[140:143], v[172:175], v[104:107]
	v_mfma_f32_16x16x32_bf16 v[92:95], v[132:135], v[186:189], v[92:95]
	v_mfma_f32_16x16x32_bf16 v[88:91], v[140:143], v[186:189], v[88:91]
	v_mfma_f32_16x16x32_bf16 v[76:79], v[132:135], v[194:197], v[76:79]
	v_mfma_f32_16x16x32_bf16 v[72:75], v[140:143], v[194:197], v[72:75]
	s_barrier
	s_add_i32 s50, 0, 0x1c000
	s_add_i32 s51, s64, s25
	v_add_u32_e32 v210, s50, v177
	s_mov_b32 m0, s51
	ds_read_b128 v[198:201], v210
	ds_read_b128 v[202:205], v210 offset:1024
	ds_read_b128 v[206:209], v210 offset:2048
	ds_read_b128 v[210:213], v210 offset:3072
	global_load_lds_dwordx4 v146, s[98:99]
	s_add_i32 m0, s51, 0x2000
	s_nop 0
	global_load_lds_dwordx4 v150, s[98:99]
	s_barrier
	s_waitcnt lgkmcnt(0)
	v_mfma_f32_16x16x32_bf16 v[116:119], v[198:201], v[160:163], v[116:119]
	v_mfma_f32_16x16x32_bf16 v[112:115], v[206:209], v[160:163], v[112:115]
	v_mfma_f32_16x16x32_bf16 v[100:103], v[198:201], v[168:171], v[100:103]
	v_mfma_f32_16x16x32_bf16 v[96:99], v[206:209], v[168:171], v[96:99]
	v_mfma_f32_16x16x32_bf16 v[84:87], v[198:201], v[182:185], v[84:87]
	v_mfma_f32_16x16x32_bf16 v[80:83], v[206:209], v[182:185], v[80:83]
	v_mfma_f32_16x16x32_bf16 v[68:71], v[198:201], v[190:193], v[68:71]
	v_mfma_f32_16x16x32_bf16 v[64:67], v[206:209], v[190:193], v[64:67]
	v_mfma_f32_16x16x32_bf16 v[116:119], v[202:205], v[164:167], v[116:119]
	v_mfma_f32_16x16x32_bf16 v[112:115], v[210:213], v[164:167], v[112:115]
	v_mfma_f32_16x16x32_bf16 v[100:103], v[202:205], v[172:175], v[100:103]
	v_mfma_f32_16x16x32_bf16 v[96:99], v[210:213], v[172:175], v[96:99]
	v_mfma_f32_16x16x32_bf16 v[84:87], v[202:205], v[186:189], v[84:87]
	v_mfma_f32_16x16x32_bf16 v[80:83], v[210:213], v[186:189], v[80:83]
	v_mfma_f32_16x16x32_bf16 v[68:71], v[202:205], v[194:197], v[68:71]
	v_mfma_f32_16x16x32_bf16 v[64:67], v[210:213], v[194:197], v[64:67]
	s_mov_b32 m0, s55
	s_barrier
	ds_read_b128 v[160:163], v180 offset:49152
	ds_read_b128 v[164:167], v180 offset:50176
	ds_read_b128 v[168:171], v180 offset:51200
	ds_read_b128 v[172:175], v180 offset:52224
	ds_read_b128 v[182:185], v180 offset:53248
	ds_read_b128 v[186:189], v180 offset:54272
	ds_read_b128 v[190:193], v180 offset:55296
	ds_read_b128 v[194:197], v180 offset:56320
	global_load_lds_dwordx4 v144, s[100:101]
	s_mov_b32 m0, s56
	s_nop 0
	global_load_lds_dwordx4 v148, s[100:101]
	s_waitcnt vmcnt(10)
	s_barrier
	s_waitcnt lgkmcnt(0)
	v_mfma_f32_16x16x32_bf16 v[60:63], v[128:131], v[160:163], v[60:63]
	v_mfma_f32_16x16x32_bf16 v[56:59], v[136:139], v[160:163], v[56:59]
	v_mfma_f32_16x16x32_bf16 v[44:47], v[128:131], v[168:171], v[44:47]
	v_mfma_f32_16x16x32_bf16 v[40:43], v[136:139], v[168:171], v[40:43]
	v_mfma_f32_16x16x32_bf16 v[28:31], v[128:131], v[182:185], v[28:31]
	v_mfma_f32_16x16x32_bf16 v[24:27], v[136:139], v[182:185], v[24:27]
	v_mfma_f32_16x16x32_bf16 v[12:15], v[128:131], v[190:193], v[12:15]
	v_mfma_f32_16x16x32_bf16 v[8:11], v[136:139], v[190:193], v[8:11]
	v_mfma_f32_16x16x32_bf16 v[60:63], v[132:135], v[164:167], v[60:63]
	v_mfma_f32_16x16x32_bf16 v[56:59], v[140:143], v[164:167], v[56:59]
	v_mfma_f32_16x16x32_bf16 v[44:47], v[132:135], v[172:175], v[44:47]
	v_mfma_f32_16x16x32_bf16 v[40:43], v[140:143], v[172:175], v[40:43]
	v_mfma_f32_16x16x32_bf16 v[28:31], v[132:135], v[186:189], v[28:31]
	v_mfma_f32_16x16x32_bf16 v[24:27], v[140:143], v[186:189], v[24:27]
	v_mfma_f32_16x16x32_bf16 v[12:15], v[132:135], v[194:197], v[12:15]
	v_mfma_f32_16x16x32_bf16 v[8:11], v[140:143], v[194:197], v[8:11]
	s_barrier
	s_add_u32 s48, s48, 0x80080
	s_addc_u32 s49, s49, 0
	s_add_i32 s50, s50, s25
	s_mov_b32 m0, s50
	s_nop 0
	global_load_lds_dwordx4 v146, s[48:49]
	s_add_i32 m0, s50, 0x2000
	s_nop 0
	global_load_lds_dwordx4 v150, s[48:49]
	ds_read_b128 v[128:131], v179
	ds_read_b128 v[132:135], v179 offset:1024
	ds_read_b128 v[136:139], v179 offset:2048
	ds_read_b128 v[140:143], v179 offset:3072
	s_waitcnt vmcnt(6)
	s_branch .LBB0_1581

; #define PG8_STAGE(bufoff, gbase, voff) do { _Pragma("unroll") for (int _i = 0; _i < 2; ++_i) \
;         __builtin_amdgcn_global_load_lds((const unsigned*)((const char*)(gbase) + (voff)[_i]), (LAS unsigned*)(lds + (bufoff) + ldsw + _i * 8192), 16, 0, 0); } while (0)
; #define PG8_LDA(dst, b, h) do { _Pragma("unroll") for (int m = 0; m < 4; ++m) _Pragma("unroll") for (int k = 0; k < 2; ++k) dst[m][k] = *(const LAS bf16x8*)(lds + PG8_SA(b, h) + aoff + m * 2048 + k * 1024); } while (0)
; #define PG8_LDB(dst, b, h) do { _Pragma("unroll") for (int n = 0; n < 2; ++n) _Pragma("unroll") for (int k = 0; k < 2; ++k) dst[n][k] = *(const LAS bf16x8*)(lds + PG8_SB(b, h) + boff + n * 2048 + k * 1024); } while (0)
; #define PG8_MMA(ai, bj, At, Bt) do { __builtin_amdgcn_s_setprio(1); _Pragma("unroll") for (int m = 0; m < 4; ++m) _Pragma("unroll") for (int n = 0; n < 2; ++n) _Pragma("unroll") for (int k = 0; k < 2; ++k) \
;         acc[ai][bj][m][n] = __builtin_amdgcn_mfma_f32_16x16x32_bf16(Bt[n][k], At[m][k], acc[ai][bj][m][n], 0, 0, 0); __builtin_amdgcn_s_setprio(0); } while (0)
; #define PG8_WAIT_V(n) asm volatile("s_waitcnt vmcnt(" #n ")" ::: "memory")
; #define PG8_WAIT_L(n) asm volatile("s_waitcnt lgkmcnt(" #n ")" ::: "memory")
; template <class Epi>
; __device__ __forceinline__ void gemm_phase(LAS unsigned char* lds, const Gemm g, const StaticOrder& S, const Epi& E, int wv) {
;     ...
;         for (int t = 0; t < nt; t += 2) {
;             const bool last = (t == nt - 2);
;             const char* a1 = cA + (ptrdiff_t)(t + 1) * kstep;
;             const char* a2 = last ? nA : cA + (ptrdiff_t)(t + 2) * kstep; const char* b2 = last ? nB : cB + (ptrdiff_t)(t + 2) * kstep;
;             const char* a3 = a2 + kstep; const char* b3 = b2 + kstep;
;             PG8_LDB(B0, 0, 0); PG8_SCHED; PG8_LDA(At, 0, 0); PG8_STAGE(PG8_SA(1, 1), a1 + hstepA, voffA);
;             PG8_WAIT_L(8); PG8_BAR; PG8_WAIT_L(0); PG8_MMA(0, 0, At, B0); PG8_BAR; PG8_SCHED;
;             PG8_LDB(B1, 0, 1); PG8_STAGE(PG8_SB(0, 0), b2, voffB);
;             PG8_BAR; PG8_WAIT_L(0); PG8_MMA(0, 1, At, B1); PG8_BAR;
;             PG8_LDA(At, 0, 1); PG8_STAGE(PG8_SA(0, 0), a2, voffA);
;             PG8_BAR; PG8_WAIT_L(0); PG8_MMA(1, 0, At, B0); PG8_BAR; PG8_SCHED;
;             PG8_STAGE(PG8_SB(0, 1), b2 + hstepB, voffB);
;             PG8_WAIT_V(6); PG8_BAR; PG8_MMA(1, 1, At, B1); PG8_BAR;
.Lrot_in_1668:
	s_add_u32 s46, s44, 0xfff80080
	s_addc_u32 s47, s45, -1
	s_cmp_eq_u32 s66, 28
	s_cselect_b32 s49, s37, s47
	s_cselect_b32 s48, s62, s46
	s_cselect_b32 s47, s35, s65
	s_cselect_b32 s46, s63, s64
	s_add_i32 m0, s33, 0xc000
	ds_read_b128 v[170:173], v154
	ds_read_b128 v[174:177], v154 offset:1024
	ds_read_b128 v[178:181], v154 offset:2048
	ds_read_b128 v[182:185], v154 offset:3072
	ds_read_b128 v[186:189], v154 offset:4096
	ds_read_b128 v[190:193], v154 offset:5120
	ds_read_b128 v[194:197], v154 offset:6144
	ds_read_b128 v[198:201], v154 offset:7168
	global_load_lds_dwordx4 v138, s[44:45]
	s_add_i32 m0, s33, 0xe000
	s_nop 0
	global_load_lds_dwordx4 v136, s[44:45]
	s_waitcnt lgkmcnt(8)
	s_barrier
	s_waitcnt lgkmcnt(0)
	v_mfma_f32_16x16x32_bf16 v[124:127], v[144:147], v[170:173], v[124:127]
	v_mfma_f32_16x16x32_bf16 v[120:123], v[162:165], v[170:173], v[120:123]
	v_mfma_f32_16x16x32_bf16 v[116:119], v[144:147], v[178:181], v[116:119]
	v_mfma_f32_16x16x32_bf16 v[112:115], v[162:165], v[178:181], v[112:115]
	v_mfma_f32_16x16x32_bf16 v[92:95], v[144:147], v[186:189], v[92:95]
	v_mfma_f32_16x16x32_bf16 v[88:91], v[162:165], v[186:189], v[88:91]
	v_mfma_f32_16x16x32_bf16 v[76:79], v[144:147], v[194:197], v[76:79]
	v_mfma_f32_16x16x32_bf16 v[72:75], v[162:165], v[194:197], v[72:75]
	v_mfma_f32_16x16x32_bf16 v[124:127], v[158:161], v[174:177], v[124:127]
	v_mfma_f32_16x16x32_bf16 v[120:123], v[166:169], v[174:177], v[120:123]
	v_mfma_f32_16x16x32_bf16 v[116:119], v[158:161], v[182:185], v[116:119]
	v_mfma_f32_16x16x32_bf16 v[112:115], v[166:169], v[182:185], v[112:115]
	v_mfma_f32_16x16x32_bf16 v[92:95], v[158:161], v[190:193], v[92:95]
	v_mfma_f32_16x16x32_bf16 v[88:91], v[166:169], v[190:193], v[88:91]
	v_mfma_f32_16x16x32_bf16 v[76:79], v[158:161], v[198:201], v[76:79]
	v_mfma_f32_16x16x32_bf16 v[72:75], v[166:169], v[198:201], v[72:75]
	s_barrier
	s_add_i32 s67, s55, s25
	s_add_u32 s98, s46, s12
	s_addc_u32 s99, s47, s13
	s_mov_b32 m0, s67
	ds_read_b128 v[202:205], v155
	ds_read_b128 v[206:209], v155 offset:1024
	ds_read_b128 v[210:213], v155 offset:2048
	ds_read_b128 v[214:217], v155 offset:3072
	global_load_lds_dwordx4 v130, s[46:47]
	s_add_i32 m0, s67, 0x2000
	s_nop 0
	global_load_lds_dwordx4 v134, s[46:47]
	s_barrier
	s_waitcnt lgkmcnt(0)
	v_mfma_f32_16x16x32_bf16 v[108:111], v[202:205], v[170:173], v[108:111]
	v_mfma_f32_16x16x32_bf16 v[104:107], v[210:213], v[170:173], v[104:107]
	v_mfma_f32_16x16x32_bf16 v[100:103], v[202:205], v[178:181], v[100:103]
	v_mfma_f32_16x16x32_bf16 v[96:99], v[210:213], v[178:181], v[96:99]
	v_mfma_f32_16x16x32_bf16 v[84:87], v[202:205], v[186:189], v[84:87]
	v_mfma_f32_16x16x32_bf16 v[80:83], v[210:213], v[186:189], v[80:83]
	v_mfma_f32_16x16x32_bf16 v[68:71], v[202:205], v[194:197], v[68:71]
	v_mfma_f32_16x16x32_bf16 v[64:67], v[210:213], v[194:197], v[64:67]
	v_mfma_f32_16x16x32_bf16 v[108:111], v[206:209], v[174:177], v[108:111]
	v_mfma_f32_16x16x32_bf16 v[104:107], v[214:217], v[174:177], v[104:107]
	v_mfma_f32_16x16x32_bf16 v[100:103], v[206:209], v[182:185], v[100:103]
	v_mfma_f32_16x16x32_bf16 v[96:99], v[214:217], v[182:185], v[96:99]
	v_mfma_f32_16x16x32_bf16 v[84:87], v[206:209], v[190:193], v[84:87]
	v_mfma_f32_16x16x32_bf16 v[80:83], v[214:217], v[190:193], v[80:83]
	v_mfma_f32_16x16x32_bf16 v[68:71], v[206:209], v[198:201], v[68:71]
	v_mfma_f32_16x16x32_bf16 v[64:67], v[214:217], v[198:201], v[64:67]
	s_mov_b32 m0, s33
	s_add_u32 s100, s48, s12
	s_addc_u32 s101, s49, s13
	s_barrier
	ds_read_b128 v[170:173], v154 offset:16384
	ds_read_b128 v[174:177], v154 offset:17408
	ds_read_b128 v[178:181], v154 offset:18432
	ds_read_b128 v[182:185], v154 offset:19456
	ds_read_b128 v[186:189], v154 offset:20480
	ds_read_b128 v[190:193], v154 offset:21504
	ds_read_b128 v[194:197], v154 offset:22528
	ds_read_b128 v[198:201], v154 offset:23552
	global_load_lds_dwordx4 v128, s[48:49]
	s_mov_b32 m0, s43
	s_nop 0
	global_load_lds_dwordx4 v132, s[48:49]
	s_waitcnt vmcnt(10)
	s_barrier
	s_waitcnt lgkmcnt(0)
	v_mfma_f32_16x16x32_bf16 v[60:63], v[144:147], v[170:173], v[60:63]
	v_mfma_f32_16x16x32_bf16 v[56:59], v[162:165], v[170:173], v[56:59]
	v_mfma_f32_16x16x32_bf16 v[44:47], v[144:147], v[178:181], v[44:47]
	v_mfma_f32_16x16x32_bf16 v[40:43], v[162:165], v[178:181], v[40:43]
	v_mfma_f32_16x16x32_bf16 v[28:31], v[144:147], v[186:189], v[28:31]
	v_mfma_f32_16x16x32_bf16 v[24:27], v[162:165], v[186:189], v[24:27]
	v_mfma_f32_16x16x32_bf16 v[12:15], v[144:147], v[194:197], v[12:15]
	v_mfma_f32_16x16x32_bf16 v[8:11], v[162:165], v[194:197], v[8:11]
	v_mfma_f32_16x16x32_bf16 v[60:63], v[158:161], v[174:177], v[60:63]
	v_mfma_f32_16x16x32_bf16 v[56:59], v[166:169], v[174:177], v[56:59]
	v_mfma_f32_16x16x32_bf16 v[44:47], v[158:161], v[182:185], v[44:47]
	v_mfma_f32_16x16x32_bf16 v[40:43], v[166:169], v[182:185], v[40:43]
	v_mfma_f32_16x16x32_bf16 v[28:31], v[158:161], v[190:193], v[28:31]
	v_mfma_f32_16x16x32_bf16 v[24:27], v[166:169], v[190:193], v[24:27]
	v_mfma_f32_16x16x32_bf16 v[12:15], v[158:161], v[198:201], v[12:15]
	v_mfma_f32_16x16x32_bf16 v[8:11], v[166:169], v[198:201], v[8:11]
	s_barrier
	s_add_u32 s68, s46, 0x80000
	s_addc_u32 s69, s47, 0
	s_add_i32 s67, s56, s25
	s_mov_b32 m0, s67
	s_nop 0
	global_load_lds_dwordx4 v130, s[68:69]
	s_add_i32 m0, s67, 0x2000
	s_nop 0
	global_load_lds_dwordx4 v134, s[68:69]
	s_add_i32 s67, 0, 0x18000
	v_add_u32_e32 v157, s67, v151
	ds_read_b128 v[144:147], v157
	ds_read_b128 v[158:161], v157 offset:1024
	ds_read_b128 v[162:165], v157 offset:2048
	ds_read_b128 v[166:169], v157 offset:3072
	s_waitcnt vmcnt(6)
	s_barrier
; #define PG8_STAGE(bufoff, gbase, voff) do { _Pragma("unroll") for (int _i = 0; _i < 2; ++_i) \
;         __builtin_amdgcn_global_load_lds((const unsigned*)((const char*)(gbase) + (voff)[_i]), (LAS unsigned*)(lds + (bufoff) + ldsw + _i * 8192), 16, 0, 0); } while (0)
; #define PG8_LDA(dst, b, h) do { _Pragma("unroll") for (int m = 0; m < 4; ++m) _Pragma("unroll") for (int k = 0; k < 2; ++k) dst[m][k] = *(const LAS bf16x8*)(lds + PG8_SA(b, h) + aoff + m * 2048 + k * 1024); } while (0)
; #define PG8_LDB(dst, b, h) do { _Pragma("unroll") for (int n = 0; n < 2; ++n) _Pragma("unroll") for (int k = 0; k < 2; ++k) dst[n][k] = *(const LAS bf16x8*)(lds + PG8_SB(b, h) + boff + n * 2048 + k * 1024); } while (0)
; #define PG8_MMA(ai, bj, At, Bt) do { __builtin_amdgcn_s_setprio(1); _Pragma("unroll") for (int m = 0; m < 4; ++m) _Pragma("unroll") for (int n = 0; n < 2; ++n) _Pragma("unroll") for (int k = 0; k < 2; ++k) \
;         acc[ai][bj][m][n] = __builtin_amdgcn_mfma_f32_16x16x32_bf16(Bt[n][k], At[m][k], acc[ai][bj][m][n], 0, 0, 0); __builtin_amdgcn_s_setprio(0); } while (0)
; #define PG8_WAIT_V(n) asm volatile("s_waitcnt vmcnt(" #n ")" ::: "memory")
; #define PG8_WAIT_L(n) asm volatile("s_waitcnt lgkmcnt(" #n ")" ::: "memory")
; #define PG8_BAR __builtin_amdgcn_s_barrier()
; #define PG8_SCHED __builtin_amdgcn_sched_barrier(0)
; template <class Epi>
; __device__ __forceinline__ void gemm_phase(LAS unsigned char* lds, const Gemm g, const StaticOrder& S, const Epi& E, int wv) {
;     ...
;             PG8_WAIT_V(6); PG8_BAR; PG8_MMA(1, 1, At, B1); PG8_BAR;
;             PG8_LDB(B0, 1, 0); PG8_SCHED; PG8_LDA(At, 1, 0); PG8_STAGE(PG8_SA(0, 1), a2 + hstepA, voffA);
;             PG8_WAIT_L(8); PG8_BAR; PG8_WAIT_L(0); PG8_MMA(0, 0, At, B0); PG8_BAR; PG8_SCHED;
;             PG8_LDB(B1, 1, 1); PG8_STAGE(PG8_SB(1, 0), b3, voffB);
;             PG8_BAR; PG8_WAIT_L(0); PG8_MMA(0, 1, At, B1); PG8_BAR;
;             PG8_LDA(At, 1, 1); PG8_STAGE(PG8_SA(1, 0), a3, voffA);
;             PG8_BAR; PG8_WAIT_L(0); PG8_MMA(1, 0, At, B0); PG8_BAR; PG8_SCHED;
;             PG8_STAGE(PG8_SB(1, 1), b3 + hstepB, voffB);
;             PG8_WAIT_V(6); PG8_BAR; PG8_MMA(1, 1, At, B1); PG8_BAR;
	v_mfma_f32_16x16x32_bf16 v[52:55], v[202:205], v[170:173], v[52:55]
	v_mfma_f32_16x16x32_bf16 v[48:51], v[210:213], v[170:173], v[48:51]
	v_mfma_f32_16x16x32_bf16 v[36:39], v[202:205], v[178:181], v[36:39]
	v_mfma_f32_16x16x32_bf16 v[32:35], v[210:213], v[178:181], v[32:35]
	v_mfma_f32_16x16x32_bf16 v[20:23], v[202:205], v[186:189], v[20:23]
	v_mfma_f32_16x16x32_bf16 v[16:19], v[210:213], v[186:189], v[16:19]
	v_mfma_f32_16x16x32_bf16 v[4:7], v[202:205], v[194:197], v[4:7]
	v_mfma_f32_16x16x32_bf16 v[0:3], v[210:213], v[194:197], v[0:3]
	v_mfma_f32_16x16x32_bf16 v[52:55], v[206:209], v[174:177], v[52:55]
	v_mfma_f32_16x16x32_bf16 v[48:51], v[214:217], v[174:177], v[48:51]
	v_mfma_f32_16x16x32_bf16 v[36:39], v[206:209], v[182:185], v[36:39]
	v_mfma_f32_16x16x32_bf16 v[32:35], v[214:217], v[182:185], v[32:35]
	v_mfma_f32_16x16x32_bf16 v[20:23], v[206:209], v[190:193], v[20:23]
	v_mfma_f32_16x16x32_bf16 v[16:19], v[214:217], v[190:193], v[16:19]
	v_mfma_f32_16x16x32_bf16 v[4:7], v[206:209], v[198:201], v[4:7]
	v_mfma_f32_16x16x32_bf16 v[0:3], v[214:217], v[198:201], v[0:3]
	s_waitcnt lgkmcnt(0)
	s_barrier
	s_add_u32 s48, s48, 0x80000
	s_addc_u32 s49, s49, 0
	s_mov_b32 m0, s50
	ds_read_b128 v[170:173], v154 offset:32768
	ds_read_b128 v[174:177], v154 offset:33792
	ds_read_b128 v[178:181], v154 offset:34816
	ds_read_b128 v[182:185], v154 offset:35840
	ds_read_b128 v[186:189], v154 offset:36864
	ds_read_b128 v[190:193], v154 offset:37888
	ds_read_b128 v[194:197], v154 offset:38912
	ds_read_b128 v[198:201], v154 offset:39936
	global_load_lds_dwordx4 v128, s[48:49]
	s_mov_b32 m0, s51
	s_nop 0
	global_load_lds_dwordx4 v132, s[48:49]
	s_waitcnt lgkmcnt(8)
	s_barrier
	s_waitcnt lgkmcnt(0)
	v_mfma_f32_16x16x32_bf16 v[124:127], v[144:147], v[170:173], v[124:127]
	v_mfma_f32_16x16x32_bf16 v[120:123], v[162:165], v[170:173], v[120:123]
	v_mfma_f32_16x16x32_bf16 v[116:119], v[144:147], v[178:181], v[116:119]
	v_mfma_f32_16x16x32_bf16 v[112:115], v[162:165], v[178:181], v[112:115]
	v_mfma_f32_16x16x32_bf16 v[92:95], v[144:147], v[186:189], v[92:95]
	v_mfma_f32_16x16x32_bf16 v[88:91], v[162:165], v[186:189], v[88:91]
	v_mfma_f32_16x16x32_bf16 v[76:79], v[144:147], v[194:197], v[76:79]
	v_mfma_f32_16x16x32_bf16 v[72:75], v[162:165], v[194:197], v[72:75]
	v_mfma_f32_16x16x32_bf16 v[124:127], v[158:161], v[174:177], v[124:127]
	v_mfma_f32_16x16x32_bf16 v[120:123], v[166:169], v[174:177], v[120:123]
	v_mfma_f32_16x16x32_bf16 v[116:119], v[158:161], v[182:185], v[116:119]
	v_mfma_f32_16x16x32_bf16 v[112:115], v[166:169], v[182:185], v[112:115]
	v_mfma_f32_16x16x32_bf16 v[92:95], v[158:161], v[190:193], v[92:95]
	v_mfma_f32_16x16x32_bf16 v[88:91], v[166:169], v[190:193], v[88:91]
	v_mfma_f32_16x16x32_bf16 v[76:79], v[158:161], v[198:201], v[76:79]
	v_mfma_f32_16x16x32_bf16 v[72:75], v[166:169], v[198:201], v[72:75]
	s_barrier
	s_add_i32 s48, 0, 0x1c000
	s_add_i32 s49, s67, s25
	v_add_u32_e32 v157, s48, v151
	s_mov_b32 m0, s49
	ds_read_b128 v[202:205], v157
	ds_read_b128 v[206:209], v157 offset:1024
	ds_read_b128 v[210:213], v157 offset:2048
	ds_read_b128 v[214:217], v157 offset:3072
	global_load_lds_dwordx4 v130, s[98:99]
	s_add_i32 m0, s49, 0x2000
	s_nop 0
	global_load_lds_dwordx4 v134, s[98:99]
	s_barrier
	s_waitcnt lgkmcnt(0)
	v_mfma_f32_16x16x32_bf16 v[108:111], v[202:205], v[170:173], v[108:111]
	v_mfma_f32_16x16x32_bf16 v[104:107], v[210:213], v[170:173], v[104:107]
	v_mfma_f32_16x16x32_bf16 v[100:103], v[202:205], v[178:181], v[100:103]
	v_mfma_f32_16x16x32_bf16 v[96:99], v[210:213], v[178:181], v[96:99]
	v_mfma_f32_16x16x32_bf16 v[84:87], v[202:205], v[186:189], v[84:87]
	v_mfma_f32_16x16x32_bf16 v[80:83], v[210:213], v[186:189], v[80:83]
	v_mfma_f32_16x16x32_bf16 v[68:71], v[202:205], v[194:197], v[68:71]
	v_mfma_f32_16x16x32_bf16 v[64:67], v[210:213], v[194:197], v[64:67]
	v_mfma_f32_16x16x32_bf16 v[108:111], v[206:209], v[174:177], v[108:111]
	v_mfma_f32_16x16x32_bf16 v[104:107], v[214:217], v[174:177], v[104:107]
	v_mfma_f32_16x16x32_bf16 v[100:103], v[206:209], v[182:185], v[100:103]
	v_mfma_f32_16x16x32_bf16 v[96:99], v[214:217], v[182:185], v[96:99]
	v_mfma_f32_16x16x32_bf16 v[84:87], v[206:209], v[190:193], v[84:87]
	v_mfma_f32_16x16x32_bf16 v[80:83], v[214:217], v[190:193], v[80:83]
	v_mfma_f32_16x16x32_bf16 v[68:71], v[206:209], v[198:201], v[68:71]
	v_mfma_f32_16x16x32_bf16 v[64:67], v[214:217], v[198:201], v[64:67]
	s_mov_b32 m0, s53
	s_barrier
	ds_read_b128 v[170:173], v154 offset:49152
	ds_read_b128 v[174:177], v154 offset:50176
	ds_read_b128 v[178:181], v154 offset:51200
	ds_read_b128 v[182:185], v154 offset:52224
	ds_read_b128 v[186:189], v154 offset:53248
	ds_read_b128 v[190:193], v154 offset:54272
	ds_read_b128 v[194:197], v154 offset:55296
	ds_read_b128 v[198:201], v154 offset:56320
	global_load_lds_dwordx4 v128, s[100:101]
	s_mov_b32 m0, s54
	s_nop 0
	global_load_lds_dwordx4 v132, s[100:101]
	s_waitcnt vmcnt(10)
	s_barrier
	s_waitcnt lgkmcnt(0)
	v_mfma_f32_16x16x32_bf16 v[60:63], v[144:147], v[170:173], v[60:63]
	v_mfma_f32_16x16x32_bf16 v[56:59], v[162:165], v[170:173], v[56:59]
	v_mfma_f32_16x16x32_bf16 v[44:47], v[144:147], v[178:181], v[44:47]
	v_mfma_f32_16x16x32_bf16 v[40:43], v[162:165], v[178:181], v[40:43]
	v_mfma_f32_16x16x32_bf16 v[28:31], v[144:147], v[186:189], v[28:31]
	v_mfma_f32_16x16x32_bf16 v[24:27], v[162:165], v[186:189], v[24:27]
	v_mfma_f32_16x16x32_bf16 v[12:15], v[144:147], v[194:197], v[12:15]
	v_mfma_f32_16x16x32_bf16 v[8:11], v[162:165], v[194:197], v[8:11]
	v_mfma_f32_16x16x32_bf16 v[60:63], v[158:161], v[174:177], v[60:63]
	v_mfma_f32_16x16x32_bf16 v[56:59], v[166:169], v[174:177], v[56:59]
	v_mfma_f32_16x16x32_bf16 v[44:47], v[158:161], v[182:185], v[44:47]
	v_mfma_f32_16x16x32_bf16 v[40:43], v[166:169], v[182:185], v[40:43]
	v_mfma_f32_16x16x32_bf16 v[28:31], v[158:161], v[190:193], v[28:31]
	v_mfma_f32_16x16x32_bf16 v[24:27], v[166:169], v[190:193], v[24:27]
	v_mfma_f32_16x16x32_bf16 v[12:15], v[158:161], v[198:201], v[12:15]
	v_mfma_f32_16x16x32_bf16 v[8:11], v[166:169], v[198:201], v[8:11]
	s_barrier
	s_add_u32 s46, s46, 0x80080
	s_addc_u32 s47, s47, 0
	s_add_i32 s48, s48, s25
	s_mov_b32 m0, s48
	s_nop 0
	global_load_lds_dwordx4 v130, s[46:47]
	s_add_i32 m0, s48, 0x2000
	s_nop 0
	global_load_lds_dwordx4 v134, s[46:47]
	ds_read_b128 v[144:147], v153
	ds_read_b128 v[158:161], v153 offset:1024
	ds_read_b128 v[162:165], v153 offset:2048
	ds_read_b128 v[166:169], v153 offset:3072
	s_waitcnt vmcnt(6)
	s_branch .LBB0_1668

; #define PG8_STAGE(bufoff, gbase, voff) do { _Pragma("unroll") for (int _i = 0; _i < 2; ++_i) \
;         __builtin_amdgcn_global_load_lds((const unsigned*)((const char*)(gbase) + (voff)[_i]), (LAS unsigned*)(lds + (bufoff) + ldsw + _i * 8192), 16, 0, 0); } while (0)
; #define PG8_LDA(dst, b, h) do { _Pragma("unroll") for (int m = 0; m < 4; ++m) _Pragma("unroll") for (int k = 0; k < 2; ++k) dst[m][k] = *(const LAS bf16x8*)(lds + PG8_SA(b, h) + aoff + m * 2048 + k * 1024); } while (0)
; #define PG8_LDB(dst, b, h) do { _Pragma("unroll") for (int n = 0; n < 2; ++n) _Pragma("unroll") for (int k = 0; k < 2; ++k) dst[n][k] = *(const LAS bf16x8*)(lds + PG8_SB(b, h) + boff + n * 2048 + k * 1024); } while (0)
; #define PG8_MMA(ai, bj, At, Bt) do { __builtin_amdgcn_s_setprio(1); _Pragma("unroll") for (int m = 0; m < 4; ++m) _Pragma("unroll") for (int n = 0; n < 2; ++n) _Pragma("unroll") for (int k = 0; k < 2; ++k) \
;         acc[ai][bj][m][n] = __builtin_amdgcn_mfma_f32_16x16x32_bf16(Bt[n][k], At[m][k], acc[ai][bj][m][n], 0, 0, 0); __builtin_amdgcn_s_setprio(0); } while (0)
; #define PG8_WAIT_V(n) asm volatile("s_waitcnt vmcnt(" #n ")" ::: "memory")
; #define PG8_WAIT_L(n) asm volatile("s_waitcnt lgkmcnt(" #n ")" ::: "memory")
; template <class Epi>
; __device__ __forceinline__ void gemm_phase(LAS unsigned char* lds, const Gemm g, const StaticOrder& S, const Epi& E, int wv) {
;     ...
;         for (int t = 0; t < nt; t += 2) {
;             const bool last = (t == nt - 2);
;             const char* a1 = cA + (ptrdiff_t)(t + 1) * kstep;
;             const char* a2 = last ? nA : cA + (ptrdiff_t)(t + 2) * kstep; const char* b2 = last ? nB : cB + (ptrdiff_t)(t + 2) * kstep;
;             const char* a3 = a2 + kstep; const char* b3 = b2 + kstep;
;             PG8_LDB(B0, 0, 0); PG8_SCHED; PG8_LDA(At, 0, 0); PG8_STAGE(PG8_SA(1, 1), a1 + hstepA, voffA);
;             PG8_WAIT_L(8); PG8_BAR; PG8_WAIT_L(0); PG8_MMA(0, 0, At, B0); PG8_BAR; PG8_SCHED;
;             PG8_LDB(B1, 0, 1); PG8_STAGE(PG8_SB(0, 0), b2, voffB);
;             PG8_BAR; PG8_WAIT_L(0); PG8_MMA(0, 1, At, B1); PG8_BAR;
;             PG8_LDA(At, 0, 1); PG8_STAGE(PG8_SA(0, 0), a2, voffA);
;             PG8_BAR; PG8_WAIT_L(0); PG8_MMA(1, 0, At, B0); PG8_BAR; PG8_SCHED;
;             PG8_STAGE(PG8_SB(0, 1), b2 + hstepB, voffB);
;             PG8_WAIT_V(6); PG8_BAR; PG8_MMA(1, 1, At, B1); PG8_BAR;
.LBB0_1743:
	s_or_b32 s10, s43, 1
	s_lshl_b64 s[68:69], s[10:11], 7
	s_sub_u32 s10, 0, s68
	s_subb_u32 s55, 0, s69
	s_add_u32 s68, s35, s10
	s_addc_u32 s69, s37, s55
	s_add_i32 m0, s24, 0xc000
	ds_read_b128 v[156:159], v175
	ds_read_b128 v[160:163], v175 offset:1024
	ds_read_b128 v[164:167], v175 offset:2048
	ds_read_b128 v[168:171], v175 offset:3072
	ds_read_b128 v[176:179], v175 offset:4096
	ds_read_b128 v[180:183], v175 offset:5120
	ds_read_b128 v[184:187], v175 offset:6144
	ds_read_b128 v[188:191], v175 offset:7168
	global_load_lds_dwordx4 v144, s[68:69]
	s_add_i32 m0, s24, 0xe000
	s_nop 0
	global_load_lds_dwordx4 v148, s[68:69]
	s_waitcnt lgkmcnt(8)
	s_barrier
	s_waitcnt lgkmcnt(0)
	v_mfma_f32_16x16x32_bf16 v[124:127], v[128:131], v[156:159], v[124:127]
	v_mfma_f32_16x16x32_bf16 v[120:123], v[136:139], v[156:159], v[120:123]
	v_mfma_f32_16x16x32_bf16 v[108:111], v[128:131], v[164:167], v[108:111]
	v_mfma_f32_16x16x32_bf16 v[104:107], v[136:139], v[164:167], v[104:107]
	v_mfma_f32_16x16x32_bf16 v[92:95], v[128:131], v[176:179], v[92:95]
	v_mfma_f32_16x16x32_bf16 v[88:91], v[136:139], v[176:179], v[88:91]
	v_mfma_f32_16x16x32_bf16 v[76:79], v[128:131], v[184:187], v[76:79]
	v_mfma_f32_16x16x32_bf16 v[72:75], v[136:139], v[184:187], v[72:75]
	v_mfma_f32_16x16x32_bf16 v[124:127], v[132:135], v[160:163], v[124:127]
	v_mfma_f32_16x16x32_bf16 v[120:123], v[140:143], v[160:163], v[120:123]
	v_mfma_f32_16x16x32_bf16 v[108:111], v[132:135], v[168:171], v[108:111]
	v_mfma_f32_16x16x32_bf16 v[104:107], v[140:143], v[168:171], v[104:107]
	v_mfma_f32_16x16x32_bf16 v[92:95], v[132:135], v[180:183], v[92:95]
	v_mfma_f32_16x16x32_bf16 v[88:91], v[140:143], v[180:183], v[88:91]
	v_mfma_f32_16x16x32_bf16 v[76:79], v[132:135], v[188:191], v[76:79]
	v_mfma_f32_16x16x32_bf16 v[72:75], v[140:143], v[188:191], v[72:75]
	s_barrier
	s_add_i32 s10, s64, s23
	v_add_u32_e32 v204, s65, v173
	s_add_u32 s98, s56, s18
	s_addc_u32 s99, s57, s19
	s_mov_b32 m0, s10
	ds_read_b128 v[192:195], v204
	ds_read_b128 v[196:199], v204 offset:1024
	ds_read_b128 v[200:203], v204 offset:2048
	ds_read_b128 v[204:207], v204 offset:3072
	global_load_lds_dwordx4 v146, s[56:57]
	s_add_i32 m0, s10, 0x2000
	s_nop 0
	global_load_lds_dwordx4 v150, s[56:57]
	s_barrier
	s_waitcnt lgkmcnt(0)
	v_mfma_f32_16x16x32_bf16 v[116:119], v[192:195], v[156:159], v[116:119]
	v_mfma_f32_16x16x32_bf16 v[112:115], v[200:203], v[156:159], v[112:115]
	v_mfma_f32_16x16x32_bf16 v[100:103], v[192:195], v[164:167], v[100:103]
	v_mfma_f32_16x16x32_bf16 v[96:99], v[200:203], v[164:167], v[96:99]
	v_mfma_f32_16x16x32_bf16 v[84:87], v[192:195], v[176:179], v[84:87]
	v_mfma_f32_16x16x32_bf16 v[80:83], v[200:203], v[176:179], v[80:83]
	v_mfma_f32_16x16x32_bf16 v[68:71], v[192:195], v[184:187], v[68:71]
	v_mfma_f32_16x16x32_bf16 v[64:67], v[200:203], v[184:187], v[64:67]
	v_mfma_f32_16x16x32_bf16 v[116:119], v[196:199], v[160:163], v[116:119]
	v_mfma_f32_16x16x32_bf16 v[112:115], v[204:207], v[160:163], v[112:115]
	v_mfma_f32_16x16x32_bf16 v[100:103], v[196:199], v[168:171], v[100:103]
	v_mfma_f32_16x16x32_bf16 v[96:99], v[204:207], v[168:171], v[96:99]
	v_mfma_f32_16x16x32_bf16 v[84:87], v[196:199], v[180:183], v[84:87]
	v_mfma_f32_16x16x32_bf16 v[80:83], v[204:207], v[180:183], v[80:83]
	v_mfma_f32_16x16x32_bf16 v[68:71], v[196:199], v[188:191], v[68:71]
	v_mfma_f32_16x16x32_bf16 v[64:67], v[204:207], v[188:191], v[64:67]
	s_mov_b32 m0, s24
	s_add_u32 s100, s58, s18
	s_addc_u32 s101, s59, s19
	s_barrier
	ds_read_b128 v[156:159], v175 offset:16384
	ds_read_b128 v[160:163], v175 offset:17408
	ds_read_b128 v[164:167], v175 offset:18432
	ds_read_b128 v[168:171], v175 offset:19456
	ds_read_b128 v[176:179], v175 offset:20480
	ds_read_b128 v[180:183], v175 offset:21504
	ds_read_b128 v[184:187], v175 offset:22528
	ds_read_b128 v[188:191], v175 offset:23552
	global_load_lds_dwordx4 v144, s[58:59]
	s_mov_b32 m0, s25
	s_nop 0
	global_load_lds_dwordx4 v148, s[58:59]
	s_waitcnt vmcnt(10)
	s_barrier
	s_waitcnt lgkmcnt(0)
	v_mfma_f32_16x16x32_bf16 v[60:63], v[128:131], v[156:159], v[60:63]
	v_mfma_f32_16x16x32_bf16 v[56:59], v[136:139], v[156:159], v[56:59]
	v_mfma_f32_16x16x32_bf16 v[44:47], v[128:131], v[164:167], v[44:47]
	v_mfma_f32_16x16x32_bf16 v[40:43], v[136:139], v[164:167], v[40:43]
	v_mfma_f32_16x16x32_bf16 v[28:31], v[128:131], v[176:179], v[28:31]
	v_mfma_f32_16x16x32_bf16 v[24:27], v[136:139], v[176:179], v[24:27]
	v_mfma_f32_16x16x32_bf16 v[12:15], v[128:131], v[184:187], v[12:15]
	v_mfma_f32_16x16x32_bf16 v[8:11], v[136:139], v[184:187], v[8:11]
	v_mfma_f32_16x16x32_bf16 v[60:63], v[132:135], v[160:163], v[60:63]
	v_mfma_f32_16x16x32_bf16 v[56:59], v[140:143], v[160:163], v[56:59]
	v_mfma_f32_16x16x32_bf16 v[44:47], v[132:135], v[168:171], v[44:47]
	v_mfma_f32_16x16x32_bf16 v[40:43], v[140:143], v[168:171], v[40:43]
	v_mfma_f32_16x16x32_bf16 v[28:31], v[132:135], v[180:183], v[28:31]
	v_mfma_f32_16x16x32_bf16 v[24:27], v[140:143], v[180:183], v[24:27]
	v_mfma_f32_16x16x32_bf16 v[12:15], v[132:135], v[188:191], v[12:15]
	v_mfma_f32_16x16x32_bf16 v[8:11], v[140:143], v[188:191], v[8:11]
	s_barrier
	s_add_u32 s68, s56, 0x200000
	s_addc_u32 s69, s57, 0
	s_add_i32 s10, s65, s23
	s_mov_b32 m0, s10
	s_nop 0
	global_load_lds_dwordx4 v146, s[68:69]
	s_add_i32 m0, s10, 0x2000
	s_nop 0
	global_load_lds_dwordx4 v150, s[68:69]
	s_add_i32 s10, 0, 0x18000
	v_add_u32_e32 v140, s10, v173
	ds_read_b128 v[128:131], v140
	ds_read_b128 v[132:135], v140 offset:1024
	ds_read_b128 v[136:139], v140 offset:2048
	ds_read_b128 v[140:143], v140 offset:3072
	s_waitcnt vmcnt(6)
	s_barrier
; #define PG8_STAGE(bufoff, gbase, voff) do { _Pragma("unroll") for (int _i = 0; _i < 2; ++_i) \
;         __builtin_amdgcn_global_load_lds((const unsigned*)((const char*)(gbase) + (voff)[_i]), (LAS unsigned*)(lds + (bufoff) + ldsw + _i * 8192), 16, 0, 0); } while (0)
; #define PG8_LDA(dst, b, h) do { _Pragma("unroll") for (int m = 0; m < 4; ++m) _Pragma("unroll") for (int k = 0; k < 2; ++k) dst[m][k] = *(const LAS bf16x8*)(lds + PG8_SA(b, h) + aoff + m * 2048 + k * 1024); } while (0)
; #define PG8_LDB(dst, b, h) do { _Pragma("unroll") for (int n = 0; n < 2; ++n) _Pragma("unroll") for (int k = 0; k < 2; ++k) dst[n][k] = *(const LAS bf16x8*)(lds + PG8_SB(b, h) + boff + n * 2048 + k * 1024); } while (0)
; #define PG8_MMA(ai, bj, At, Bt) do { __builtin_amdgcn_s_setprio(1); _Pragma("unroll") for (int m = 0; m < 4; ++m) _Pragma("unroll") for (int n = 0; n < 2; ++n) _Pragma("unroll") for (int k = 0; k < 2; ++k) \
;         acc[ai][bj][m][n] = __builtin_amdgcn_mfma_f32_16x16x32_bf16(Bt[n][k], At[m][k], acc[ai][bj][m][n], 0, 0, 0); __builtin_amdgcn_s_setprio(0); } while (0)
; #define PG8_WAIT_V(n) asm volatile("s_waitcnt vmcnt(" #n ")" ::: "memory")
; #define PG8_WAIT_L(n) asm volatile("s_waitcnt lgkmcnt(" #n ")" ::: "memory")
; #define PG8_BAR __builtin_amdgcn_s_barrier()
; #define PG8_SCHED __builtin_amdgcn_sched_barrier(0)
; template <class Epi>
; __device__ __forceinline__ void gemm_phase(LAS unsigned char* lds, const Gemm g, const StaticOrder& S, const Epi& E, int wv) {
;     ...
;             PG8_WAIT_V(6); PG8_BAR; PG8_MMA(1, 1, At, B1); PG8_BAR;
;             PG8_LDB(B0, 1, 0); PG8_SCHED; PG8_LDA(At, 1, 0); PG8_STAGE(PG8_SA(0, 1), a2 + hstepA, voffA);
;             PG8_WAIT_L(8); PG8_BAR; PG8_WAIT_L(0); PG8_MMA(0, 0, At, B0); PG8_BAR; PG8_SCHED;
;             PG8_LDB(B1, 1, 1); PG8_STAGE(PG8_SB(1, 0), b3, voffB);
;             PG8_BAR; PG8_WAIT_L(0); PG8_MMA(0, 1, At, B1); PG8_BAR;
;             PG8_LDA(At, 1, 1); PG8_STAGE(PG8_SA(1, 0), a3, voffA);
;             PG8_BAR; PG8_WAIT_L(0); PG8_MMA(1, 0, At, B0); PG8_BAR; PG8_SCHED;
	v_mfma_f32_16x16x32_bf16 v[52:55], v[192:195], v[156:159], v[52:55]
	v_mfma_f32_16x16x32_bf16 v[48:51], v[200:203], v[156:159], v[48:51]
	v_mfma_f32_16x16x32_bf16 v[36:39], v[192:195], v[164:167], v[36:39]
	v_mfma_f32_16x16x32_bf16 v[32:35], v[200:203], v[164:167], v[32:35]
	v_mfma_f32_16x16x32_bf16 v[20:23], v[192:195], v[176:179], v[20:23]
	v_mfma_f32_16x16x32_bf16 v[16:19], v[200:203], v[176:179], v[16:19]
	v_mfma_f32_16x16x32_bf16 v[4:7], v[192:195], v[184:187], v[4:7]
	v_mfma_f32_16x16x32_bf16 v[0:3], v[200:203], v[184:187], v[0:3]
	v_mfma_f32_16x16x32_bf16 v[52:55], v[196:199], v[160:163], v[52:55]
	v_mfma_f32_16x16x32_bf16 v[48:51], v[204:207], v[160:163], v[48:51]
	v_mfma_f32_16x16x32_bf16 v[36:39], v[196:199], v[168:171], v[36:39]
	v_mfma_f32_16x16x32_bf16 v[32:35], v[204:207], v[168:171], v[32:35]
	v_mfma_f32_16x16x32_bf16 v[20:23], v[196:199], v[180:183], v[20:23]
	v_mfma_f32_16x16x32_bf16 v[16:19], v[204:207], v[180:183], v[16:19]
	v_mfma_f32_16x16x32_bf16 v[4:7], v[196:199], v[188:191], v[4:7]
	v_mfma_f32_16x16x32_bf16 v[0:3], v[204:207], v[188:191], v[0:3]
	s_waitcnt lgkmcnt(0)
	s_barrier
	s_add_u32 s58, s58, 0x200000
	s_addc_u32 s59, s59, 0
	s_mov_b32 m0, s33
	ds_read_b128 v[156:159], v175 offset:32768
	ds_read_b128 v[160:163], v175 offset:33792
	ds_read_b128 v[164:167], v175 offset:34816
	ds_read_b128 v[168:171], v175 offset:35840
	ds_read_b128 v[176:179], v175 offset:36864
	ds_read_b128 v[180:183], v175 offset:37888
	ds_read_b128 v[184:187], v175 offset:38912
	ds_read_b128 v[188:191], v175 offset:39936
	global_load_lds_dwordx4 v144, s[58:59]
	s_mov_b32 m0, s45
	s_nop 0
	global_load_lds_dwordx4 v148, s[58:59]
	s_waitcnt lgkmcnt(8)
	s_barrier
	s_waitcnt lgkmcnt(0)
	v_mfma_f32_16x16x32_bf16 v[124:127], v[128:131], v[156:159], v[124:127]
	v_mfma_f32_16x16x32_bf16 v[120:123], v[136:139], v[156:159], v[120:123]
	v_mfma_f32_16x16x32_bf16 v[108:111], v[128:131], v[164:167], v[108:111]
	v_mfma_f32_16x16x32_bf16 v[104:107], v[136:139], v[164:167], v[104:107]
	v_mfma_f32_16x16x32_bf16 v[92:95], v[128:131], v[176:179], v[92:95]
	v_mfma_f32_16x16x32_bf16 v[88:91], v[136:139], v[176:179], v[88:91]
	v_mfma_f32_16x16x32_bf16 v[76:79], v[128:131], v[184:187], v[76:79]
	v_mfma_f32_16x16x32_bf16 v[72:75], v[136:139], v[184:187], v[72:75]
	v_mfma_f32_16x16x32_bf16 v[124:127], v[132:135], v[160:163], v[124:127]
	v_mfma_f32_16x16x32_bf16 v[120:123], v[140:143], v[160:163], v[120:123]
	v_mfma_f32_16x16x32_bf16 v[108:111], v[132:135], v[168:171], v[108:111]
	v_mfma_f32_16x16x32_bf16 v[104:107], v[140:143], v[168:171], v[104:107]
	v_mfma_f32_16x16x32_bf16 v[92:95], v[132:135], v[180:183], v[92:95]
	v_mfma_f32_16x16x32_bf16 v[88:91], v[140:143], v[180:183], v[88:91]
	v_mfma_f32_16x16x32_bf16 v[76:79], v[132:135], v[188:191], v[76:79]
	v_mfma_f32_16x16x32_bf16 v[72:75], v[140:143], v[188:191], v[72:75]
	s_barrier
	s_add_i32 s55, 0, 0x1c000
	s_add_i32 s10, s10, s23
	v_add_u32_e32 v204, s55, v173
	s_mov_b32 m0, s10
	ds_read_b128 v[192:195], v204
	ds_read_b128 v[196:199], v204 offset:1024
	ds_read_b128 v[200:203], v204 offset:2048
	ds_read_b128 v[204:207], v204 offset:3072
	global_load_lds_dwordx4 v146, s[98:99]
	s_add_i32 m0, s10, 0x2000
	s_nop 0
	global_load_lds_dwordx4 v150, s[98:99]
	s_barrier
	s_waitcnt lgkmcnt(0)
	v_mfma_f32_16x16x32_bf16 v[116:119], v[192:195], v[156:159], v[116:119]
	v_mfma_f32_16x16x32_bf16 v[112:115], v[200:203], v[156:159], v[112:115]
	v_mfma_f32_16x16x32_bf16 v[100:103], v[192:195], v[164:167], v[100:103]
	v_mfma_f32_16x16x32_bf16 v[96:99], v[200:203], v[164:167], v[96:99]
	v_mfma_f32_16x16x32_bf16 v[84:87], v[192:195], v[176:179], v[84:87]
	v_mfma_f32_16x16x32_bf16 v[80:83], v[200:203], v[176:179], v[80:83]
	v_mfma_f32_16x16x32_bf16 v[68:71], v[192:195], v[184:187], v[68:71]
	v_mfma_f32_16x16x32_bf16 v[64:67], v[200:203], v[184:187], v[64:67]
	v_mfma_f32_16x16x32_bf16 v[116:119], v[196:199], v[160:163], v[116:119]
	v_mfma_f32_16x16x32_bf16 v[112:115], v[204:207], v[160:163], v[112:115]
	v_mfma_f32_16x16x32_bf16 v[100:103], v[196:199], v[168:171], v[100:103]
	v_mfma_f32_16x16x32_bf16 v[96:99], v[204:207], v[168:171], v[96:99]
	v_mfma_f32_16x16x32_bf16 v[84:87], v[196:199], v[180:183], v[84:87]
	v_mfma_f32_16x16x32_bf16 v[80:83], v[204:207], v[180:183], v[80:83]
	v_mfma_f32_16x16x32_bf16 v[68:71], v[196:199], v[188:191], v[68:71]
	v_mfma_f32_16x16x32_bf16 v[64:67], v[204:207], v[188:191], v[64:67]
	s_mov_b32 m0, s60
	s_barrier
; #define PG8_STAGE(bufoff, gbase, voff) do { _Pragma("unroll") for (int _i = 0; _i < 2; ++_i) \
;         __builtin_amdgcn_global_load_lds((const unsigned*)((const char*)(gbase) + (voff)[_i]), (LAS unsigned*)(lds + (bufoff) + ldsw + _i * 8192), 16, 0, 0); } while (0)
; #define PG8_LDA(dst, b, h) do { _Pragma("unroll") for (int m = 0; m < 4; ++m) _Pragma("unroll") for (int k = 0; k < 2; ++k) dst[m][k] = *(const LAS bf16x8*)(lds + PG8_SA(b, h) + aoff + m * 2048 + k * 1024); } while (0)
; #define PG8_MMA(ai, bj, At, Bt) do { __builtin_amdgcn_s_setprio(1); _Pragma("unroll") for (int m = 0; m < 4; ++m) _Pragma("unroll") for (int n = 0; n < 2; ++n) _Pragma("unroll") for (int k = 0; k < 2; ++k) \
;         acc[ai][bj][m][n] = __builtin_amdgcn_mfma_f32_16x16x32_bf16(Bt[n][k], At[m][k], acc[ai][bj][m][n], 0, 0, 0); __builtin_amdgcn_s_setprio(0); } while (0)
; #define PG8_WAIT_V(n) asm volatile("s_waitcnt vmcnt(" #n ")" ::: "memory")
; #define PG8_WAIT_L(n) asm volatile("s_waitcnt lgkmcnt(" #n ")" ::: "memory")
; #define PG8_BAR __builtin_amdgcn_s_barrier()
; #define PG8_SCHED __builtin_amdgcn_sched_barrier(0)
; template <class Epi>
; __device__ __forceinline__ void gemm_phase(LAS unsigned char* lds, const Gemm g, const StaticOrder& S, const Epi& E, int wv) {
;     ...
;             PG8_LDA(At, 1, 1); PG8_STAGE(PG8_SA(1, 0), a3, voffA);
;             PG8_BAR; PG8_WAIT_L(0); PG8_MMA(1, 0, At, B0); PG8_BAR; PG8_SCHED;
;             PG8_STAGE(PG8_SB(1, 1), b3 + hstepB, voffB);
;             PG8_WAIT_V(6); PG8_BAR; PG8_MMA(1, 1, At, B1); PG8_BAR;
;         }
	ds_read_b128 v[156:159], v175 offset:49152
	ds_read_b128 v[160:163], v175 offset:50176
	ds_read_b128 v[164:167], v175 offset:51200
	ds_read_b128 v[168:171], v175 offset:52224
	ds_read_b128 v[176:179], v175 offset:53248
	ds_read_b128 v[180:183], v175 offset:54272
	ds_read_b128 v[184:187], v175 offset:55296
	ds_read_b128 v[188:191], v175 offset:56320
	global_load_lds_dwordx4 v144, s[100:101]
	s_mov_b32 m0, s61
	s_nop 0
	global_load_lds_dwordx4 v148, s[100:101]
	s_waitcnt vmcnt(10)
	s_barrier
	s_waitcnt lgkmcnt(0)
	v_mfma_f32_16x16x32_bf16 v[60:63], v[128:131], v[156:159], v[60:63]
	v_mfma_f32_16x16x32_bf16 v[56:59], v[136:139], v[156:159], v[56:59]
	v_mfma_f32_16x16x32_bf16 v[44:47], v[128:131], v[164:167], v[44:47]
	v_mfma_f32_16x16x32_bf16 v[40:43], v[136:139], v[164:167], v[40:43]
	v_mfma_f32_16x16x32_bf16 v[28:31], v[128:131], v[176:179], v[28:31]
	v_mfma_f32_16x16x32_bf16 v[24:27], v[136:139], v[176:179], v[24:27]
	v_mfma_f32_16x16x32_bf16 v[12:15], v[128:131], v[184:187], v[12:15]
	v_mfma_f32_16x16x32_bf16 v[8:11], v[136:139], v[184:187], v[8:11]
	v_mfma_f32_16x16x32_bf16 v[60:63], v[132:135], v[160:163], v[60:63]
	v_mfma_f32_16x16x32_bf16 v[56:59], v[140:143], v[160:163], v[56:59]
	v_mfma_f32_16x16x32_bf16 v[44:47], v[132:135], v[168:171], v[44:47]
	v_mfma_f32_16x16x32_bf16 v[40:43], v[140:143], v[168:171], v[40:43]
	v_mfma_f32_16x16x32_bf16 v[28:31], v[132:135], v[180:183], v[28:31]
	v_mfma_f32_16x16x32_bf16 v[24:27], v[140:143], v[180:183], v[24:27]
	v_mfma_f32_16x16x32_bf16 v[12:15], v[132:135], v[188:191], v[12:15]
	v_mfma_f32_16x16x32_bf16 v[8:11], v[140:143], v[188:191], v[8:11]
	s_barrier
	s_add_u32 s56, s56, 0x1fff80
	s_addc_u32 s57, s57, 0
	s_add_i32 s10, s55, s23
	s_mov_b32 m0, s10
	s_nop 0
	global_load_lds_dwordx4 v146, s[56:57]
	s_add_i32 m0, s10, 0x2000
	s_nop 0
	global_load_lds_dwordx4 v150, s[56:57]
	v_add_u32_e32 v140, s64, v173
	ds_read_b128 v[128:131], v140
	ds_read_b128 v[132:135], v140 offset:1024
	ds_read_b128 v[136:139], v140 offset:2048
	ds_read_b128 v[140:143], v140 offset:3072
	s_waitcnt vmcnt(6)
	s_barrier
	v_mfma_f32_16x16x32_bf16 v[52:55], v[192:195], v[156:159], v[52:55]
	v_mfma_f32_16x16x32_bf16 v[48:51], v[200:203], v[156:159], v[48:51]
	v_mfma_f32_16x16x32_bf16 v[36:39], v[192:195], v[164:167], v[36:39]
	v_mfma_f32_16x16x32_bf16 v[32:35], v[200:203], v[164:167], v[32:35]
	v_mfma_f32_16x16x32_bf16 v[20:23], v[192:195], v[176:179], v[20:23]
	v_mfma_f32_16x16x32_bf16 v[16:19], v[200:203], v[176:179], v[16:19]
	v_mfma_f32_16x16x32_bf16 v[4:7], v[192:195], v[184:187], v[4:7]
	v_mfma_f32_16x16x32_bf16 v[0:3], v[200:203], v[184:187], v[0:3]
	v_mfma_f32_16x16x32_bf16 v[52:55], v[196:199], v[160:163], v[52:55]
	v_mfma_f32_16x16x32_bf16 v[48:51], v[204:207], v[160:163], v[48:51]
	v_mfma_f32_16x16x32_bf16 v[36:39], v[196:199], v[168:171], v[36:39]
	v_mfma_f32_16x16x32_bf16 v[32:35], v[204:207], v[168:171], v[32:35]
	v_mfma_f32_16x16x32_bf16 v[20:23], v[196:199], v[180:183], v[20:23]
	v_mfma_f32_16x16x32_bf16 v[16:19], v[204:207], v[180:183], v[16:19]
	v_mfma_f32_16x16x32_bf16 v[4:7], v[196:199], v[188:191], v[4:7]
	v_mfma_f32_16x16x32_bf16 v[0:3], v[204:207], v[188:191], v[0:3]
	s_waitcnt lgkmcnt(0)
	s_cmpk_gt_u32 s43, 0x7d
	s_mov_b32 s43, s54
	s_barrier
	s_cbranch_scc1 .LBB0_1748

; #define PG8_STAGE(bufoff, gbase, voff) do { _Pragma("unroll") for (int _i = 0; _i < 2; ++_i) \
;         __builtin_amdgcn_global_load_lds((const unsigned*)((const char*)(gbase) + (voff)[_i]), (LAS unsigned*)(lds + (bufoff) + ldsw + _i * 8192), 16, 0, 0); } while (0)
; #define PG8_LDA(dst, b, h) do { _Pragma("unroll") for (int m = 0; m < 4; ++m) _Pragma("unroll") for (int k = 0; k < 2; ++k) dst[m][k] = *(const LAS bf16x8*)(lds + PG8_SA(b, h) + aoff + m * 2048 + k * 1024); } while (0)
; #define PG8_LDB(dst, b, h) do { _Pragma("unroll") for (int n = 0; n < 2; ++n) _Pragma("unroll") for (int k = 0; k < 2; ++k) dst[n][k] = *(const LAS bf16x8*)(lds + PG8_SB(b, h) + boff + n * 2048 + k * 1024); } while (0)
; #define PG8_MMA(ai, bj, At, Bt) do { __builtin_amdgcn_s_setprio(1); _Pragma("unroll") for (int m = 0; m < 4; ++m) _Pragma("unroll") for (int n = 0; n < 2; ++n) _Pragma("unroll") for (int k = 0; k < 2; ++k) \
;         acc[ai][bj][m][n] = __builtin_amdgcn_mfma_f32_16x16x32_bf16(Bt[n][k], At[m][k], acc[ai][bj][m][n], 0, 0, 0); __builtin_amdgcn_s_setprio(0); } while (0)
; template <class Epi>
; __device__ __forceinline__ void gemm_phase(LAS unsigned char* lds, const Gemm g, const StaticOrder& S, const Epi& E, int wv) {
;     ...
;         const bool has_next = S.next(ui + 1, nxt);
;         const char* nA = has_next ? (const char*)g.A + (size_t)nxt.pm * tstepA + ((g.adiag & 1) ? (size_t)(nxt.pn >> 1) * K * 2 : 0) + kbeg : cA;
;         const char* nB = has_next ? (const char*)g.Bt + (size_t)nxt.pn * tstepB + kbeg : cB;
;         for (int t = 0; t < nt; t += 2) {
;             const bool last = (t == nt - 2);
;             const char* a1 = cA + (ptrdiff_t)(t + 1) * kstep;
;             const char* a2 = last ? nA : cA + (ptrdiff_t)(t + 2) * kstep; const char* b2 = last ? nB : cB + (ptrdiff_t)(t + 2) * kstep;
;             const char* a3 = a2 + kstep; const char* b3 = b2 + kstep;
;             PG8_LDB(B0, 0, 0); PG8_SCHED; PG8_LDA(At, 0, 0); PG8_STAGE(PG8_SA(1, 1), a1 + hstepA, voffA);
;             PG8_WAIT_L(8); PG8_BAR; PG8_WAIT_L(0); PG8_MMA(0, 0, At, B0); PG8_BAR; PG8_SCHED;
;             PG8_LDB(B1, 0, 1); PG8_STAGE(PG8_SB(0, 0), b2, voffB);
;             PG8_BAR; PG8_WAIT_L(0); PG8_MMA(0, 1, At, B1); PG8_BAR;
;             PG8_LDA(At, 0, 1); PG8_STAGE(PG8_SA(0, 0), a2, voffA);
;             PG8_BAR; PG8_WAIT_L(0); PG8_MMA(1, 0, At, B0); PG8_BAR; PG8_SCHED;
.LBB0_1776:
	s_ashr_i32 s43, s42, 31
	s_lshl_b64 s[44:45], s[42:43], 17
	s_add_u32 s44, s5, s44
	v_cmp_lt_i64_e32 vcc, s[36:37], v[8:9]
	s_addc_u32 s45, s22, s45
	ds_read_b128 v[18:21], v15
	ds_read_b128 v[22:25], v15 offset:1024
	ds_read_b128 v[26:29], v15 offset:2048
	ds_read_b128 v[30:33], v15 offset:3072
	s_and_b64 s[46:47], vcc, exec
	s_cselect_b32 s55, s45, s49
	s_cselect_b32 s54, s44, s48
	s_ashr_i32 s41, s40, 31
	s_lshl_b64 s[46:47], s[40:41], 17
	s_add_u32 s46, s23, s46
	s_addc_u32 s47, s24, s47
	s_and_b64 s[52:53], vcc, exec
	s_cselect_b32 s53, s47, s51
	s_cselect_b32 s52, s46, s50
	s_add_u32 s70, s48, 0x10080
	s_addc_u32 s71, s49, 0
	s_mov_b32 m0, s61
	v_lshl_add_u64 v[66:67], s[70:71], 0, v[0:1]
	ds_read_b128 v[34:37], v16
	ds_read_b128 v[38:41], v16 offset:1024
	ds_read_b128 v[42:45], v16 offset:2048
	ds_read_b128 v[46:49], v16 offset:3072
	ds_read_b128 v[50:53], v16 offset:4096
	ds_read_b128 v[54:57], v16 offset:5120
	ds_read_b128 v[58:61], v16 offset:6144
	ds_read_b128 v[62:65], v16 offset:7168
	global_load_lds_dwordx4 v[66:67], off
	v_lshl_add_u64 v[66:67], s[70:71], 0, v[4:5]
	s_mov_b32 m0, s62
	s_nop 0
	global_load_lds_dwordx4 v[66:67], off
	s_waitcnt lgkmcnt(8)
	s_barrier
	s_waitcnt lgkmcnt(0)
	v_mfma_f32_16x16x32_bf16 v[66:69], v[18:21], v[34:37], 0
	v_mfma_f32_16x16x32_bf16 v[70:73], v[26:29], v[34:37], 0
	v_mfma_f32_16x16x32_bf16 v[74:77], v[18:21], v[42:45], 0
	v_mfma_f32_16x16x32_bf16 v[78:81], v[26:29], v[42:45], 0
	v_mfma_f32_16x16x32_bf16 v[82:85], v[18:21], v[50:53], 0
	v_mfma_f32_16x16x32_bf16 v[86:89], v[26:29], v[50:53], 0
	v_mfma_f32_16x16x32_bf16 v[90:93], v[18:21], v[58:61], 0
	v_mfma_f32_16x16x32_bf16 v[94:97], v[26:29], v[58:61], 0
	v_mfma_f32_16x16x32_bf16 v[66:69], v[22:25], v[38:41], v[66:69]
	v_mfma_f32_16x16x32_bf16 v[70:73], v[30:33], v[38:41], v[70:73]
	v_mfma_f32_16x16x32_bf16 v[74:77], v[22:25], v[46:49], v[74:77]
	v_mfma_f32_16x16x32_bf16 v[78:81], v[30:33], v[46:49], v[78:81]
	v_mfma_f32_16x16x32_bf16 v[82:85], v[22:25], v[54:57], v[82:85]
	v_mfma_f32_16x16x32_bf16 v[86:89], v[30:33], v[54:57], v[86:89]
	v_mfma_f32_16x16x32_bf16 v[90:93], v[22:25], v[62:65], v[90:93]
	v_mfma_f32_16x16x32_bf16 v[94:97], v[30:33], v[62:65], v[94:97]
	s_barrier
	v_lshl_add_u64 v[210:211], s[50:51], 0, v[2:3]
	s_add_i32 s69, s60, s25
	v_lshl_add_u64 v[114:115], v[210:211], 0, s[12:13]
	s_mov_b32 m0, s69
	v_lshl_add_u64 v[212:213], s[50:51], 0, v[6:7]
	s_add_i32 s41, s69, 0x2000
	ds_read_b128 v[98:101], v17
	ds_read_b128 v[102:105], v17 offset:1024
	ds_read_b128 v[106:109], v17 offset:2048
	ds_read_b128 v[110:113], v17 offset:3072
	global_load_lds_dwordx4 v[114:115], off
	v_lshl_add_u64 v[114:115], v[212:213], 0, s[12:13]
	s_mov_b32 m0, s41
	s_nop 0
	global_load_lds_dwordx4 v[114:115], off
	s_barrier
	s_waitcnt lgkmcnt(0)
	v_mfma_f32_16x16x32_bf16 v[114:117], v[98:101], v[34:37], 0
	v_mfma_f32_16x16x32_bf16 v[34:37], v[106:109], v[34:37], 0
	v_mfma_f32_16x16x32_bf16 v[114:117], v[102:105], v[38:41], v[114:117]
	v_mfma_f32_16x16x32_bf16 v[34:37], v[110:113], v[38:41], v[34:37]
	v_mfma_f32_16x16x32_bf16 v[38:41], v[98:101], v[42:45], 0
	v_mfma_f32_16x16x32_bf16 v[42:45], v[106:109], v[42:45], 0
	v_mfma_f32_16x16x32_bf16 v[38:41], v[102:105], v[46:49], v[38:41]
	v_mfma_f32_16x16x32_bf16 v[42:45], v[110:113], v[46:49], v[42:45]
	v_mfma_f32_16x16x32_bf16 v[46:49], v[98:101], v[50:53], 0
	v_mfma_f32_16x16x32_bf16 v[50:53], v[106:109], v[50:53], 0
	v_mfma_f32_16x16x32_bf16 v[46:49], v[102:105], v[54:57], v[46:49]
	v_mfma_f32_16x16x32_bf16 v[50:53], v[110:113], v[54:57], v[50:53]
	v_mfma_f32_16x16x32_bf16 v[54:57], v[98:101], v[58:61], 0
	v_mfma_f32_16x16x32_bf16 v[58:61], v[106:109], v[58:61], 0
	v_mfma_f32_16x16x32_bf16 v[54:57], v[102:105], v[62:65], v[54:57]
	v_mfma_f32_16x16x32_bf16 v[58:61], v[110:113], v[62:65], v[58:61]
	v_lshl_add_u64 v[214:215], s[48:49], 0, v[0:1]
	s_mov_b32 m0, s33
	v_lshl_add_u64 v[146:147], v[214:215], 0, s[12:13]
	v_lshl_add_u64 v[216:217], s[48:49], 0, v[4:5]
	s_barrier
	ds_read_b128 v[62:65], v16 offset:16384
	ds_read_b128 v[118:121], v16 offset:17408
	ds_read_b128 v[122:125], v16 offset:18432
	ds_read_b128 v[126:129], v16 offset:19456
	ds_read_b128 v[130:133], v16 offset:20480
	ds_read_b128 v[134:137], v16 offset:21504
	ds_read_b128 v[138:141], v16 offset:22528
	ds_read_b128 v[142:145], v16 offset:23552
	global_load_lds_dwordx4 v[146:147], off
	v_lshl_add_u64 v[146:147], v[216:217], 0, s[12:13]
	s_mov_b32 m0, s39
	s_nop 0
	global_load_lds_dwordx4 v[146:147], off
	s_barrier
	s_waitcnt lgkmcnt(0)
	v_mfma_f32_16x16x32_bf16 v[146:149], v[18:21], v[62:65], 0
	v_mfma_f32_16x16x32_bf16 v[154:157], v[18:21], v[122:125], 0
	v_mfma_f32_16x16x32_bf16 v[162:165], v[18:21], v[130:133], 0
	v_mfma_f32_16x16x32_bf16 v[18:21], v[18:21], v[138:141], 0
	v_mfma_f32_16x16x32_bf16 v[146:149], v[22:25], v[118:121], v[146:149]
	v_mfma_f32_16x16x32_bf16 v[150:153], v[26:29], v[62:65], 0
	v_mfma_f32_16x16x32_bf16 v[154:157], v[22:25], v[126:129], v[154:157]
	v_mfma_f32_16x16x32_bf16 v[158:161], v[26:29], v[122:125], 0
	v_mfma_f32_16x16x32_bf16 v[162:165], v[22:25], v[134:137], v[162:165]
	v_mfma_f32_16x16x32_bf16 v[166:169], v[26:29], v[130:133], 0
	v_mfma_f32_16x16x32_bf16 v[18:21], v[22:25], v[142:145], v[18:21]
	v_mfma_f32_16x16x32_bf16 v[22:25], v[26:29], v[138:141], 0
	v_mfma_f32_16x16x32_bf16 v[150:153], v[30:33], v[118:121], v[150:153]
	v_mfma_f32_16x16x32_bf16 v[158:161], v[30:33], v[126:129], v[158:161]
	v_mfma_f32_16x16x32_bf16 v[166:169], v[30:33], v[134:137], v[166:169]
	v_mfma_f32_16x16x32_bf16 v[22:25], v[30:33], v[142:145], v[22:25]
	s_barrier
; #define PG8_STAGE(bufoff, gbase, voff) do { _Pragma("unroll") for (int _i = 0; _i < 2; ++_i) \
;         __builtin_amdgcn_global_load_lds((const unsigned*)((const char*)(gbase) + (voff)[_i]), (LAS unsigned*)(lds + (bufoff) + ldsw + _i * 8192), 16, 0, 0); } while (0)
; #define PG8_LDA(dst, b, h) do { _Pragma("unroll") for (int m = 0; m < 4; ++m) _Pragma("unroll") for (int k = 0; k < 2; ++k) dst[m][k] = *(const LAS bf16x8*)(lds + PG8_SA(b, h) + aoff + m * 2048 + k * 1024); } while (0)
; #define PG8_LDB(dst, b, h) do { _Pragma("unroll") for (int n = 0; n < 2; ++n) _Pragma("unroll") for (int k = 0; k < 2; ++k) dst[n][k] = *(const LAS bf16x8*)(lds + PG8_SB(b, h) + boff + n * 2048 + k * 1024); } while (0)
; #define PG8_MMA(ai, bj, At, Bt) do { __builtin_amdgcn_s_setprio(1); _Pragma("unroll") for (int m = 0; m < 4; ++m) _Pragma("unroll") for (int n = 0; n < 2; ++n) _Pragma("unroll") for (int k = 0; k < 2; ++k) \
;         acc[ai][bj][m][n] = __builtin_amdgcn_mfma_f32_16x16x32_bf16(Bt[n][k], At[m][k], acc[ai][bj][m][n], 0, 0, 0); __builtin_amdgcn_s_setprio(0); } while (0)
; #define PG8_WAIT_V(n) asm volatile("s_waitcnt vmcnt(" #n ")" ::: "memory")
; #define PG8_WAIT_L(n) asm volatile("s_waitcnt lgkmcnt(" #n ")" ::: "memory")
; #define PG8_BAR __builtin_amdgcn_s_barrier()
; #define PG8_SCHED __builtin_amdgcn_sched_barrier(0)
; template <class Epi>
; __device__ __forceinline__ void gemm_phase(LAS unsigned char* lds, const Gemm g, const StaticOrder& S, const Epi& E, int wv) {
;     ...
;             PG8_STAGE(PG8_SB(0, 1), b2 + hstepB, voffB);
;             PG8_WAIT_V(6); PG8_BAR; PG8_MMA(1, 1, At, B1); PG8_BAR;
;             PG8_LDB(B0, 1, 0); PG8_SCHED; PG8_LDA(At, 1, 0); PG8_STAGE(PG8_SA(0, 1), a2 + hstepA, voffA);
;             PG8_WAIT_L(8); PG8_BAR; PG8_WAIT_L(0); PG8_MMA(0, 0, At, B0); PG8_BAR; PG8_SCHED;
;             PG8_LDB(B1, 1, 1); PG8_STAGE(PG8_SB(1, 0), b3, voffB);
;             PG8_BAR; PG8_WAIT_L(0); PG8_MMA(0, 1, At, B1); PG8_BAR;
	s_add_u32 s72, s50, 0x10100
	s_addc_u32 s73, s51, 0
	s_add_i32 s70, s63, s25
	v_lshl_add_u64 v[26:27], s[72:73], 0, v[2:3]
	s_mov_b32 m0, s70
	s_add_i32 s43, s70, 0x2000
	global_load_lds_dwordx4 v[26:27], off
	v_lshl_add_u64 v[26:27], s[72:73], 0, v[6:7]
	s_mov_b32 m0, s43
	s_nop 0
	global_load_lds_dwordx4 v[26:27], off
	s_waitcnt vmcnt(6)
	s_barrier
	v_mfma_f32_16x16x32_bf16 v[26:29], v[98:101], v[62:65], 0
	v_mfma_f32_16x16x32_bf16 v[30:33], v[106:109], v[62:65], 0
	v_mfma_f32_16x16x32_bf16 v[26:29], v[102:105], v[118:121], v[26:29]
	v_mfma_f32_16x16x32_bf16 v[30:33], v[110:113], v[118:121], v[30:33]
	v_mfma_f32_16x16x32_bf16 v[62:65], v[98:101], v[122:125], 0
	v_mfma_f32_16x16x32_bf16 v[118:121], v[106:109], v[122:125], 0
	v_mfma_f32_16x16x32_bf16 v[122:125], v[98:101], v[130:133], 0
	v_mfma_f32_16x16x32_bf16 v[98:101], v[98:101], v[138:141], 0
	v_mfma_f32_16x16x32_bf16 v[62:65], v[102:105], v[126:129], v[62:65]
	v_mfma_f32_16x16x32_bf16 v[118:121], v[110:113], v[126:129], v[118:121]
	v_mfma_f32_16x16x32_bf16 v[122:125], v[102:105], v[134:137], v[122:125]
	v_mfma_f32_16x16x32_bf16 v[126:129], v[106:109], v[130:133], 0
	v_mfma_f32_16x16x32_bf16 v[98:101], v[102:105], v[142:145], v[98:101]
	v_mfma_f32_16x16x32_bf16 v[102:105], v[106:109], v[138:141], 0
	v_mfma_f32_16x16x32_bf16 v[126:129], v[110:113], v[134:137], v[126:129]
	v_mfma_f32_16x16x32_bf16 v[102:105], v[110:113], v[142:145], v[102:105]
	s_add_i32 s71, 0, 0x18000
	v_add_u32_e32 v218, s71, v13
	s_barrier
	ds_read_b128 v[106:109], v218
	ds_read_b128 v[110:113], v218 offset:1024
	ds_read_b128 v[130:133], v218 offset:2048
	ds_read_b128 v[134:137], v218 offset:3072
	s_add_u32 s72, s48, 0x10100
	s_addc_u32 s73, s49, 0
	s_mov_b32 m0, s56
	v_lshl_add_u64 v[194:195], s[72:73], 0, v[0:1]
	ds_read_b128 v[138:141], v16 offset:32768
	ds_read_b128 v[142:145], v16 offset:33792
	ds_read_b128 v[170:173], v16 offset:34816
	ds_read_b128 v[174:177], v16 offset:35840
	ds_read_b128 v[178:181], v16 offset:36864
	ds_read_b128 v[182:185], v16 offset:37888
	ds_read_b128 v[186:189], v16 offset:38912
	ds_read_b128 v[190:193], v16 offset:39936
	global_load_lds_dwordx4 v[194:195], off
	v_lshl_add_u64 v[194:195], s[72:73], 0, v[4:5]
	s_mov_b32 m0, s57
	s_nop 0
	global_load_lds_dwordx4 v[194:195], off
	s_waitcnt lgkmcnt(8)
	s_barrier
	s_waitcnt lgkmcnt(0)
	v_mfma_f32_16x16x32_bf16 v[66:69], v[106:109], v[138:141], v[66:69]
	v_mfma_f32_16x16x32_bf16 v[70:73], v[130:133], v[138:141], v[70:73]
	v_mfma_f32_16x16x32_bf16 v[74:77], v[106:109], v[170:173], v[74:77]
	v_mfma_f32_16x16x32_bf16 v[78:81], v[130:133], v[170:173], v[78:81]
	v_mfma_f32_16x16x32_bf16 v[82:85], v[106:109], v[178:181], v[82:85]
	v_mfma_f32_16x16x32_bf16 v[86:89], v[130:133], v[178:181], v[86:89]
	v_mfma_f32_16x16x32_bf16 v[90:93], v[106:109], v[186:189], v[90:93]
	v_mfma_f32_16x16x32_bf16 v[94:97], v[130:133], v[186:189], v[94:97]
	v_mfma_f32_16x16x32_bf16 v[66:69], v[110:113], v[142:145], v[66:69]
	v_mfma_f32_16x16x32_bf16 v[70:73], v[134:137], v[142:145], v[70:73]
	v_mfma_f32_16x16x32_bf16 v[74:77], v[110:113], v[174:177], v[74:77]
	v_mfma_f32_16x16x32_bf16 v[78:81], v[134:137], v[174:177], v[78:81]
	v_mfma_f32_16x16x32_bf16 v[82:85], v[110:113], v[182:185], v[82:85]
	v_mfma_f32_16x16x32_bf16 v[86:89], v[134:137], v[182:185], v[86:89]
	v_mfma_f32_16x16x32_bf16 v[90:93], v[110:113], v[190:193], v[90:93]
	v_mfma_f32_16x16x32_bf16 v[94:97], v[134:137], v[190:193], v[94:97]
	s_barrier
	s_add_i32 s73, 0, 0x1c000
	s_add_i32 s72, s71, s25
	v_add_u32_e32 v219, s73, v13
	v_lshl_add_u64 v[210:211], v[210:211], 0, s[14:15]
	s_mov_b32 m0, s72
	s_add_i32 s71, s72, 0x2000
	ds_read_b128 v[194:197], v219
	ds_read_b128 v[198:201], v219 offset:1024
	ds_read_b128 v[202:205], v219 offset:2048
	ds_read_b128 v[206:209], v219 offset:3072
	global_load_lds_dwordx4 v[210:211], off
	v_lshl_add_u64 v[210:211], v[212:213], 0, s[14:15]
	s_mov_b32 m0, s71
	s_nop 0
	global_load_lds_dwordx4 v[210:211], off
	s_barrier
	s_waitcnt lgkmcnt(0)
	v_mfma_f32_16x16x32_bf16 v[114:117], v[194:197], v[138:141], v[114:117]
	v_mfma_f32_16x16x32_bf16 v[34:37], v[202:205], v[138:141], v[34:37]
	v_mfma_f32_16x16x32_bf16 v[38:41], v[194:197], v[170:173], v[38:41]
	v_mfma_f32_16x16x32_bf16 v[42:45], v[202:205], v[170:173], v[42:45]
	v_mfma_f32_16x16x32_bf16 v[46:49], v[194:197], v[178:181], v[46:49]
	v_mfma_f32_16x16x32_bf16 v[50:53], v[202:205], v[178:181], v[50:53]
	v_mfma_f32_16x16x32_bf16 v[54:57], v[194:197], v[186:189], v[54:57]
	v_mfma_f32_16x16x32_bf16 v[58:61], v[202:205], v[186:189], v[58:61]
	v_mfma_f32_16x16x32_bf16 v[114:117], v[198:201], v[142:145], v[114:117]
	v_mfma_f32_16x16x32_bf16 v[34:37], v[206:209], v[142:145], v[34:37]
	v_mfma_f32_16x16x32_bf16 v[38:41], v[198:201], v[174:177], v[38:41]
	v_mfma_f32_16x16x32_bf16 v[42:45], v[206:209], v[174:177], v[42:45]
	v_mfma_f32_16x16x32_bf16 v[46:49], v[198:201], v[182:185], v[46:49]
	v_mfma_f32_16x16x32_bf16 v[50:53], v[206:209], v[182:185], v[50:53]
	v_mfma_f32_16x16x32_bf16 v[54:57], v[198:201], v[190:193], v[54:57]
	v_mfma_f32_16x16x32_bf16 v[58:61], v[206:209], v[190:193], v[58:61]
	s_mov_b32 m0, s58
	v_lshl_add_u64 v[210:211], v[214:215], 0, s[14:15]
	s_barrier
	ds_read_b128 v[138:141], v16 offset:49152
	ds_read_b128 v[142:145], v16 offset:50176
	ds_read_b128 v[170:173], v16 offset:51200
	ds_read_b128 v[174:177], v16 offset:52224
	ds_read_b128 v[178:181], v16 offset:53248
	ds_read_b128 v[182:185], v16 offset:54272
	ds_read_b128 v[186:189], v16 offset:55296
	ds_read_b128 v[190:193], v16 offset:56320
	global_load_lds_dwordx4 v[210:211], off
	v_lshl_add_u64 v[210:211], v[216:217], 0, s[14:15]
	s_mov_b32 m0, s59
	s_nop 0
	global_load_lds_dwordx4 v[210:211], off
	s_barrier
; #define PG8_STAGE(bufoff, gbase, voff) do { _Pragma("unroll") for (int _i = 0; _i < 2; ++_i) \
;         __builtin_amdgcn_global_load_lds((const unsigned*)((const char*)(gbase) + (voff)[_i]), (LAS unsigned*)(lds + (bufoff) + ldsw + _i * 8192), 16, 0, 0); } while (0)
; #define PG8_LDA(dst, b, h) do { _Pragma("unroll") for (int m = 0; m < 4; ++m) _Pragma("unroll") for (int k = 0; k < 2; ++k) dst[m][k] = *(const LAS bf16x8*)(lds + PG8_SA(b, h) + aoff + m * 2048 + k * 1024); } while (0)
; #define PG8_LDB(dst, b, h) do { _Pragma("unroll") for (int n = 0; n < 2; ++n) _Pragma("unroll") for (int k = 0; k < 2; ++k) dst[n][k] = *(const LAS bf16x8*)(lds + PG8_SB(b, h) + boff + n * 2048 + k * 1024); } while (0)
; #define PG8_WAIT_V(n) asm volatile("s_waitcnt vmcnt(" #n ")" ::: "memory")
; #define PG8_WAIT_L(n) asm volatile("s_waitcnt lgkmcnt(" #n ")" ::: "memory")
; #define PG8_BAR __builtin_amdgcn_s_barrier()
; #define PG8_SCHED __builtin_amdgcn_sched_barrier(0)
; template <class Epi>
; __device__ __forceinline__ void gemm_phase(LAS unsigned char* lds, const Gemm g, const StaticOrder& S, const Epi& E, int wv) {
;     ...
;             PG8_LDB(B0, 0, 0); PG8_SCHED; PG8_LDA(At, 0, 0); PG8_STAGE(PG8_SA(1, 1), a1 + hstepA, voffA);
;             PG8_WAIT_L(8); PG8_BAR; PG8_WAIT_L(0); PG8_MMA(0, 0, At, B0); PG8_BAR; PG8_SCHED;
;             PG8_LDB(B1, 0, 1); PG8_STAGE(PG8_SB(0, 0), b2, voffB);
;             PG8_BAR; PG8_WAIT_L(0); PG8_MMA(0, 1, At, B1); PG8_BAR;
;             PG8_LDA(At, 0, 1); PG8_STAGE(PG8_SA(0, 0), a2, voffA);
;             PG8_BAR; PG8_WAIT_L(0); PG8_MMA(1, 0, At, B0); PG8_BAR; PG8_SCHED;
;             PG8_STAGE(PG8_SB(0, 1), b2 + hstepB, voffB);
;             PG8_WAIT_V(6); PG8_BAR; PG8_MMA(1, 1, At, B1); PG8_BAR;
;             PG8_LDB(B0, 1, 0); PG8_SCHED; PG8_LDA(At, 1, 0); PG8_STAGE(PG8_SA(0, 1), a2 + hstepA, voffA);
;             PG8_WAIT_L(8); PG8_BAR; PG8_WAIT_L(0); PG8_MMA(0, 0, At, B0); PG8_BAR; PG8_SCHED;
;             PG8_LDB(B1, 1, 1); PG8_STAGE(PG8_SB(1, 0), b3, voffB);
;             PG8_BAR; PG8_WAIT_L(0); PG8_MMA(0, 1, At, B1); PG8_BAR;
;             PG8_LDA(At, 1, 1); PG8_STAGE(PG8_SA(1, 0), a3, voffA);
;             PG8_BAR; PG8_WAIT_L(0); PG8_MMA(1, 0, At, B0); PG8_BAR; PG8_SCHED;
;             PG8_STAGE(PG8_SB(1, 1), b3 + hstepB, voffB);
;             PG8_WAIT_V(6); PG8_BAR; PG8_MMA(1, 1, At, B1); PG8_BAR;
	s_waitcnt lgkmcnt(0)
	v_mfma_f32_16x16x32_bf16 v[146:149], v[106:109], v[138:141], v[146:149]
	v_mfma_f32_16x16x32_bf16 v[150:153], v[130:133], v[138:141], v[150:153]
	v_mfma_f32_16x16x32_bf16 v[154:157], v[106:109], v[170:173], v[154:157]
	v_mfma_f32_16x16x32_bf16 v[158:161], v[130:133], v[170:173], v[158:161]
	v_mfma_f32_16x16x32_bf16 v[162:165], v[106:109], v[178:181], v[162:165]
	v_mfma_f32_16x16x32_bf16 v[166:169], v[130:133], v[178:181], v[166:169]
	v_mfma_f32_16x16x32_bf16 v[18:21], v[106:109], v[186:189], v[18:21]
	v_mfma_f32_16x16x32_bf16 v[22:25], v[130:133], v[186:189], v[22:25]
	v_mfma_f32_16x16x32_bf16 v[146:149], v[110:113], v[142:145], v[146:149]
	v_mfma_f32_16x16x32_bf16 v[150:153], v[134:137], v[142:145], v[150:153]
	v_mfma_f32_16x16x32_bf16 v[154:157], v[110:113], v[174:177], v[154:157]
	v_mfma_f32_16x16x32_bf16 v[158:161], v[134:137], v[174:177], v[158:161]
	v_mfma_f32_16x16x32_bf16 v[162:165], v[110:113], v[182:185], v[162:165]
	v_mfma_f32_16x16x32_bf16 v[166:169], v[134:137], v[182:185], v[166:169]
	v_mfma_f32_16x16x32_bf16 v[18:21], v[110:113], v[190:193], v[18:21]
	v_mfma_f32_16x16x32_bf16 v[22:25], v[134:137], v[190:193], v[22:25]
	s_barrier
	s_add_u32 s74, s50, 0x10180
	s_addc_u32 s75, s51, 0
	s_add_i32 s51, s73, s25
	v_lshl_add_u64 v[106:107], s[74:75], 0, v[2:3]
	s_mov_b32 m0, s51
	s_add_i32 s50, s51, 0x2000
	global_load_lds_dwordx4 v[106:107], off
	v_lshl_add_u64 v[106:107], s[74:75], 0, v[6:7]
	s_mov_b32 m0, s50
	s_nop 0
	global_load_lds_dwordx4 v[106:107], off
	s_waitcnt vmcnt(6)
	s_barrier
	v_mfma_f32_16x16x32_bf16 v[26:29], v[194:197], v[138:141], v[26:29]
	v_mfma_f32_16x16x32_bf16 v[30:33], v[202:205], v[138:141], v[30:33]
	v_mfma_f32_16x16x32_bf16 v[62:65], v[194:197], v[170:173], v[62:65]
	v_mfma_f32_16x16x32_bf16 v[106:109], v[202:205], v[170:173], v[118:121]
	v_mfma_f32_16x16x32_bf16 v[110:113], v[194:197], v[178:181], v[122:125]
	v_mfma_f32_16x16x32_bf16 v[118:121], v[202:205], v[178:181], v[126:129]
	v_mfma_f32_16x16x32_bf16 v[98:101], v[194:197], v[186:189], v[98:101]
	v_mfma_f32_16x16x32_bf16 v[102:105], v[202:205], v[186:189], v[102:105]
	v_mfma_f32_16x16x32_bf16 v[26:29], v[198:201], v[142:145], v[26:29]
	v_mfma_f32_16x16x32_bf16 v[30:33], v[206:209], v[142:145], v[30:33]
	v_mfma_f32_16x16x32_bf16 v[62:65], v[198:201], v[174:177], v[62:65]
	v_mfma_f32_16x16x32_bf16 v[106:109], v[206:209], v[174:177], v[106:109]
	v_mfma_f32_16x16x32_bf16 v[110:113], v[198:201], v[182:185], v[110:113]
	v_mfma_f32_16x16x32_bf16 v[118:121], v[206:209], v[182:185], v[118:121]
	v_mfma_f32_16x16x32_bf16 v[98:101], v[198:201], v[190:193], v[98:101]
	v_mfma_f32_16x16x32_bf16 v[102:105], v[206:209], v[190:193], v[102:105]
	s_barrier
	ds_read_b128 v[122:125], v15
	ds_read_b128 v[126:129], v15 offset:1024
	ds_read_b128 v[130:133], v15 offset:2048
	ds_read_b128 v[134:137], v15 offset:3072
	s_add_u32 s48, s48, 0x10180
	s_addc_u32 s49, s49, 0
	s_mov_b32 m0, s61
	v_lshl_add_u64 v[194:195], s[48:49], 0, v[0:1]
	ds_read_b128 v[138:141], v16
	ds_read_b128 v[142:145], v16 offset:1024
	ds_read_b128 v[170:173], v16 offset:2048
	ds_read_b128 v[174:177], v16 offset:3072
	ds_read_b128 v[178:181], v16 offset:4096
	ds_read_b128 v[182:185], v16 offset:5120
	ds_read_b128 v[186:189], v16 offset:6144
	ds_read_b128 v[190:193], v16 offset:7168
	global_load_lds_dwordx4 v[194:195], off
	v_lshl_add_u64 v[194:195], s[48:49], 0, v[4:5]
	s_mov_b32 m0, s62
	s_nop 0
	global_load_lds_dwordx4 v[194:195], off
	s_waitcnt lgkmcnt(8)
	s_barrier
	s_waitcnt lgkmcnt(0)
	v_mfma_f32_16x16x32_bf16 v[66:69], v[122:125], v[138:141], v[66:69]
	v_mfma_f32_16x16x32_bf16 v[70:73], v[130:133], v[138:141], v[70:73]
	v_mfma_f32_16x16x32_bf16 v[74:77], v[122:125], v[170:173], v[74:77]
	v_mfma_f32_16x16x32_bf16 v[78:81], v[130:133], v[170:173], v[78:81]
	v_mfma_f32_16x16x32_bf16 v[82:85], v[122:125], v[178:181], v[82:85]
	v_mfma_f32_16x16x32_bf16 v[86:89], v[130:133], v[178:181], v[86:89]
	v_mfma_f32_16x16x32_bf16 v[90:93], v[122:125], v[186:189], v[90:93]
	v_mfma_f32_16x16x32_bf16 v[94:97], v[130:133], v[186:189], v[94:97]
	v_mfma_f32_16x16x32_bf16 v[66:69], v[126:129], v[142:145], v[66:69]
	v_mfma_f32_16x16x32_bf16 v[70:73], v[134:137], v[142:145], v[70:73]
	v_mfma_f32_16x16x32_bf16 v[74:77], v[126:129], v[174:177], v[74:77]
	v_mfma_f32_16x16x32_bf16 v[78:81], v[134:137], v[174:177], v[78:81]
	v_mfma_f32_16x16x32_bf16 v[82:85], v[126:129], v[182:185], v[82:85]
	v_mfma_f32_16x16x32_bf16 v[86:89], v[134:137], v[182:185], v[86:89]
	v_mfma_f32_16x16x32_bf16 v[90:93], v[126:129], v[190:193], v[90:93]
	v_mfma_f32_16x16x32_bf16 v[94:97], v[134:137], v[190:193], v[94:97]
	s_barrier
	s_mov_b32 m0, s69
	v_lshl_add_u64 v[210:211], s[52:53], 0, v[2:3]
	ds_read_b128 v[194:197], v17
	ds_read_b128 v[198:201], v17 offset:1024
	ds_read_b128 v[202:205], v17 offset:2048
	ds_read_b128 v[206:209], v17 offset:3072
	global_load_lds_dwordx4 v[210:211], off
	v_lshl_add_u64 v[212:213], s[52:53], 0, v[6:7]
	s_mov_b32 m0, s41
	s_nop 0
	global_load_lds_dwordx4 v[212:213], off
	s_barrier
	s_waitcnt lgkmcnt(0)
	v_mfma_f32_16x16x32_bf16 v[114:117], v[194:197], v[138:141], v[114:117]
	v_mfma_f32_16x16x32_bf16 v[34:37], v[202:205], v[138:141], v[34:37]
	v_mfma_f32_16x16x32_bf16 v[38:41], v[194:197], v[170:173], v[38:41]
	v_mfma_f32_16x16x32_bf16 v[42:45], v[202:205], v[170:173], v[42:45]
	v_mfma_f32_16x16x32_bf16 v[46:49], v[194:197], v[178:181], v[46:49]
	v_mfma_f32_16x16x32_bf16 v[50:53], v[202:205], v[178:181], v[50:53]
	v_mfma_f32_16x16x32_bf16 v[54:57], v[194:197], v[186:189], v[54:57]
	v_mfma_f32_16x16x32_bf16 v[58:61], v[202:205], v[186:189], v[58:61]
	v_mfma_f32_16x16x32_bf16 v[114:117], v[198:201], v[142:145], v[114:117]
	v_mfma_f32_16x16x32_bf16 v[34:37], v[206:209], v[142:145], v[34:37]
	v_mfma_f32_16x16x32_bf16 v[38:41], v[198:201], v[174:177], v[38:41]
	v_mfma_f32_16x16x32_bf16 v[42:45], v[206:209], v[174:177], v[42:45]
	v_mfma_f32_16x16x32_bf16 v[46:49], v[198:201], v[182:185], v[46:49]
	v_mfma_f32_16x16x32_bf16 v[50:53], v[206:209], v[182:185], v[50:53]
	v_mfma_f32_16x16x32_bf16 v[54:57], v[198:201], v[190:193], v[54:57]
	v_mfma_f32_16x16x32_bf16 v[58:61], v[206:209], v[190:193], v[58:61]
	s_mov_b32 m0, s33
	v_lshl_add_u64 v[214:215], s[54:55], 0, v[0:1]
	s_barrier
; #define PG8_STAGE(bufoff, gbase, voff) do { _Pragma("unroll") for (int _i = 0; _i < 2; ++_i) \
;         __builtin_amdgcn_global_load_lds((const unsigned*)((const char*)(gbase) + (voff)[_i]), (LAS unsigned*)(lds + (bufoff) + ldsw + _i * 8192), 16, 0, 0); } while (0)
; #define PG8_LDA(dst, b, h) do { _Pragma("unroll") for (int m = 0; m < 4; ++m) _Pragma("unroll") for (int k = 0; k < 2; ++k) dst[m][k] = *(const LAS bf16x8*)(lds + PG8_SA(b, h) + aoff + m * 2048 + k * 1024); } while (0)
; #define PG8_LDB(dst, b, h) do { _Pragma("unroll") for (int n = 0; n < 2; ++n) _Pragma("unroll") for (int k = 0; k < 2; ++k) dst[n][k] = *(const LAS bf16x8*)(lds + PG8_SB(b, h) + boff + n * 2048 + k * 1024); } while (0)
; #define PG8_WAIT_V(n) asm volatile("s_waitcnt vmcnt(" #n ")" ::: "memory")
; #define PG8_WAIT_L(n) asm volatile("s_waitcnt lgkmcnt(" #n ")" ::: "memory")
; #define PG8_BAR __builtin_amdgcn_s_barrier()
; #define PG8_SCHED __builtin_amdgcn_sched_barrier(0)
; template <class Epi>
; __device__ __forceinline__ void gemm_phase(LAS unsigned char* lds, const Gemm g, const StaticOrder& S, const Epi& E, int wv) {
;     ...
;             PG8_LDB(B0, 0, 0); PG8_SCHED; PG8_LDA(At, 0, 0); PG8_STAGE(PG8_SA(1, 1), a1 + hstepA, voffA);
;             PG8_WAIT_L(8); PG8_BAR; PG8_WAIT_L(0); PG8_MMA(0, 0, At, B0); PG8_BAR; PG8_SCHED;
;             PG8_LDB(B1, 0, 1); PG8_STAGE(PG8_SB(0, 0), b2, voffB);
;             PG8_BAR; PG8_WAIT_L(0); PG8_MMA(0, 1, At, B1); PG8_BAR;
;             PG8_LDA(At, 0, 1); PG8_STAGE(PG8_SA(0, 0), a2, voffA);
;             PG8_BAR; PG8_WAIT_L(0); PG8_MMA(1, 0, At, B0); PG8_BAR; PG8_SCHED;
;             PG8_STAGE(PG8_SB(0, 1), b2 + hstepB, voffB);
;             PG8_WAIT_V(6); PG8_BAR; PG8_MMA(1, 1, At, B1); PG8_BAR;
;             PG8_LDB(B0, 1, 0); PG8_SCHED; PG8_LDA(At, 1, 0); PG8_STAGE(PG8_SA(0, 1), a2 + hstepA, voffA);
;             PG8_WAIT_L(8); PG8_BAR; PG8_WAIT_L(0); PG8_MMA(0, 0, At, B0); PG8_BAR; PG8_SCHED;
;             PG8_LDB(B1, 1, 1); PG8_STAGE(PG8_SB(1, 0), b3, voffB);
;             PG8_BAR; PG8_WAIT_L(0); PG8_MMA(0, 1, At, B1); PG8_BAR;
;             PG8_LDA(At, 1, 1); PG8_STAGE(PG8_SA(1, 0), a3, voffA);
;             PG8_BAR; PG8_WAIT_L(0); PG8_MMA(1, 0, At, B0); PG8_BAR; PG8_SCHED;
;             PG8_STAGE(PG8_SB(1, 1), b3 + hstepB, voffB);
;             PG8_WAIT_V(6); PG8_BAR; PG8_MMA(1, 1, At, B1); PG8_BAR;
	ds_read_b128 v[138:141], v16 offset:16384
	ds_read_b128 v[142:145], v16 offset:17408
	ds_read_b128 v[170:173], v16 offset:18432
	ds_read_b128 v[174:177], v16 offset:19456
	ds_read_b128 v[178:181], v16 offset:20480
	ds_read_b128 v[182:185], v16 offset:21504
	ds_read_b128 v[186:189], v16 offset:22528
	ds_read_b128 v[190:193], v16 offset:23552
	global_load_lds_dwordx4 v[214:215], off
	v_lshl_add_u64 v[216:217], s[54:55], 0, v[4:5]
	s_mov_b32 m0, s39
	s_nop 0
	global_load_lds_dwordx4 v[216:217], off
	s_barrier
	s_waitcnt lgkmcnt(0)
	v_mfma_f32_16x16x32_bf16 v[146:149], v[122:125], v[138:141], v[146:149]
	v_mfma_f32_16x16x32_bf16 v[150:153], v[130:133], v[138:141], v[150:153]
	v_mfma_f32_16x16x32_bf16 v[154:157], v[122:125], v[170:173], v[154:157]
	v_mfma_f32_16x16x32_bf16 v[158:161], v[130:133], v[170:173], v[158:161]
	v_mfma_f32_16x16x32_bf16 v[162:165], v[122:125], v[178:181], v[162:165]
	v_mfma_f32_16x16x32_bf16 v[166:169], v[130:133], v[178:181], v[166:169]
	v_mfma_f32_16x16x32_bf16 v[18:21], v[122:125], v[186:189], v[18:21]
	v_mfma_f32_16x16x32_bf16 v[22:25], v[130:133], v[186:189], v[22:25]
	v_mfma_f32_16x16x32_bf16 v[146:149], v[126:129], v[142:145], v[146:149]
	v_mfma_f32_16x16x32_bf16 v[150:153], v[134:137], v[142:145], v[150:153]
	v_mfma_f32_16x16x32_bf16 v[154:157], v[126:129], v[174:177], v[154:157]
	v_mfma_f32_16x16x32_bf16 v[158:161], v[134:137], v[174:177], v[158:161]
	v_mfma_f32_16x16x32_bf16 v[162:165], v[126:129], v[182:185], v[162:165]
	v_mfma_f32_16x16x32_bf16 v[166:169], v[134:137], v[182:185], v[166:169]
	v_mfma_f32_16x16x32_bf16 v[18:21], v[126:129], v[190:193], v[18:21]
	v_mfma_f32_16x16x32_bf16 v[22:25], v[134:137], v[190:193], v[22:25]
	s_barrier
	s_add_u32 s48, s52, 0x10000
	s_addc_u32 s49, s53, 0
	s_mov_b32 m0, s70
	v_lshl_add_u64 v[122:123], s[48:49], 0, v[2:3]
	global_load_lds_dwordx4 v[122:123], off
	v_lshl_add_u64 v[122:123], s[48:49], 0, v[6:7]
	s_mov_b32 m0, s43
	s_nop 0
	global_load_lds_dwordx4 v[122:123], off
	s_waitcnt vmcnt(6)
	s_barrier
	v_mfma_f32_16x16x32_bf16 v[26:29], v[194:197], v[138:141], v[26:29]
	v_mfma_f32_16x16x32_bf16 v[30:33], v[202:205], v[138:141], v[30:33]
	v_mfma_f32_16x16x32_bf16 v[62:65], v[194:197], v[170:173], v[62:65]
	v_mfma_f32_16x16x32_bf16 v[106:109], v[202:205], v[170:173], v[106:109]
	v_mfma_f32_16x16x32_bf16 v[110:113], v[194:197], v[178:181], v[110:113]
	v_mfma_f32_16x16x32_bf16 v[118:121], v[202:205], v[178:181], v[118:121]
	v_mfma_f32_16x16x32_bf16 v[98:101], v[194:197], v[186:189], v[98:101]
	v_mfma_f32_16x16x32_bf16 v[102:105], v[202:205], v[186:189], v[102:105]
	v_mfma_f32_16x16x32_bf16 v[26:29], v[198:201], v[142:145], v[26:29]
	v_mfma_f32_16x16x32_bf16 v[30:33], v[206:209], v[142:145], v[30:33]
	v_mfma_f32_16x16x32_bf16 v[62:65], v[198:201], v[174:177], v[62:65]
	v_mfma_f32_16x16x32_bf16 v[106:109], v[206:209], v[174:177], v[106:109]
	v_mfma_f32_16x16x32_bf16 v[110:113], v[198:201], v[182:185], v[110:113]
	v_mfma_f32_16x16x32_bf16 v[118:121], v[206:209], v[182:185], v[118:121]
	v_mfma_f32_16x16x32_bf16 v[98:101], v[198:201], v[190:193], v[98:101]
	v_mfma_f32_16x16x32_bf16 v[102:105], v[206:209], v[190:193], v[102:105]
	s_barrier
	ds_read_b128 v[122:125], v218
	ds_read_b128 v[126:129], v218 offset:1024
	ds_read_b128 v[130:133], v218 offset:2048
	ds_read_b128 v[134:137], v218 offset:3072
	s_add_u32 s48, s54, 0x10000
	s_addc_u32 s49, s55, 0
	s_mov_b32 m0, s56
	v_lshl_add_u64 v[194:195], s[48:49], 0, v[0:1]
	ds_read_b128 v[138:141], v16 offset:32768
	ds_read_b128 v[142:145], v16 offset:33792
	ds_read_b128 v[170:173], v16 offset:34816
	ds_read_b128 v[174:177], v16 offset:35840
	ds_read_b128 v[178:181], v16 offset:36864
	ds_read_b128 v[182:185], v16 offset:37888
	ds_read_b128 v[186:189], v16 offset:38912
	ds_read_b128 v[190:193], v16 offset:39936
	global_load_lds_dwordx4 v[194:195], off
	v_lshl_add_u64 v[194:195], s[48:49], 0, v[4:5]
	s_mov_b32 m0, s57
	s_nop 0
	global_load_lds_dwordx4 v[194:195], off
	s_waitcnt lgkmcnt(8)
	s_barrier
	s_waitcnt lgkmcnt(0)
	v_mfma_f32_16x16x32_bf16 v[66:69], v[122:125], v[138:141], v[66:69]
	v_mfma_f32_16x16x32_bf16 v[70:73], v[130:133], v[138:141], v[70:73]
	v_mfma_f32_16x16x32_bf16 v[74:77], v[122:125], v[170:173], v[74:77]
	v_mfma_f32_16x16x32_bf16 v[78:81], v[130:133], v[170:173], v[78:81]
	v_mfma_f32_16x16x32_bf16 v[82:85], v[122:125], v[178:181], v[82:85]
	v_mfma_f32_16x16x32_bf16 v[86:89], v[130:133], v[178:181], v[86:89]
	v_mfma_f32_16x16x32_bf16 v[90:93], v[122:125], v[186:189], v[90:93]
	v_mfma_f32_16x16x32_bf16 v[94:97], v[130:133], v[186:189], v[94:97]
	v_mfma_f32_16x16x32_bf16 v[66:69], v[126:129], v[142:145], v[66:69]
	v_mfma_f32_16x16x32_bf16 v[70:73], v[134:137], v[142:145], v[70:73]
	v_mfma_f32_16x16x32_bf16 v[74:77], v[126:129], v[174:177], v[74:77]
	v_mfma_f32_16x16x32_bf16 v[78:81], v[134:137], v[174:177], v[78:81]
	v_mfma_f32_16x16x32_bf16 v[82:85], v[126:129], v[182:185], v[82:85]
	v_mfma_f32_16x16x32_bf16 v[86:89], v[134:137], v[182:185], v[86:89]
	v_mfma_f32_16x16x32_bf16 v[90:93], v[126:129], v[190:193], v[90:93]
	v_mfma_f32_16x16x32_bf16 v[94:97], v[134:137], v[190:193], v[94:97]
	s_barrier
	s_mov_b32 m0, s72
	v_lshl_add_u64 v[210:211], v[210:211], 0, s[10:11]
	ds_read_b128 v[194:197], v219
	ds_read_b128 v[198:201], v219 offset:1024
	ds_read_b128 v[202:205], v219 offset:2048
	ds_read_b128 v[206:209], v219 offset:3072
	global_load_lds_dwordx4 v[210:211], off
	v_lshl_add_u64 v[210:211], v[212:213], 0, s[10:11]
	s_mov_b32 m0, s71
	s_nop 0
	global_load_lds_dwordx4 v[210:211], off
	s_barrier
; __device__ __forceinline__ float fast_sigmoid(float x) { return __builtin_amdgcn_rcpf(1.0f + __builtin_amdgcn_exp2f(-x * LOG2E)); }
; #define PG8_STAGE(bufoff, gbase, voff) do { _Pragma("unroll") for (int _i = 0; _i < 2; ++_i) \
;         __builtin_amdgcn_global_load_lds((const unsigned*)((const char*)(gbase) + (voff)[_i]), (LAS unsigned*)(lds + (bufoff) + ldsw + _i * 8192), 16, 0, 0); } while (0)
; #define PG8_LDA(dst, b, h) do { _Pragma("unroll") for (int m = 0; m < 4; ++m) _Pragma("unroll") for (int k = 0; k < 2; ++k) dst[m][k] = *(const LAS bf16x8*)(lds + PG8_SA(b, h) + aoff + m * 2048 + k * 1024); } while (0)
; #define PG8_WAIT_V(n) asm volatile("s_waitcnt vmcnt(" #n ")" ::: "memory")
; #define PG8_WAIT_L(n) asm volatile("s_waitcnt lgkmcnt(" #n ")" ::: "memory")
; template <class Epi>
; __device__ __forceinline__ void gemm_phase(LAS unsigned char* lds, const Gemm g, const StaticOrder& S, const Epi& E, int wv) {
;     ...
;             PG8_LDA(At, 1, 1); PG8_STAGE(PG8_SA(1, 0), a3, voffA);
;             PG8_BAR; PG8_WAIT_L(0); PG8_MMA(1, 0, At, B0); PG8_BAR; PG8_SCHED;
;             PG8_STAGE(PG8_SB(1, 1), b3 + hstepB, voffB);
;             PG8_WAIT_V(6); PG8_BAR; PG8_MMA(1, 1, At, B1); PG8_BAR;
;     __device__ __forceinline__ void operator()(const f32x4 (&acc)[2][2][4][2], const Unit& u, int wr, int wc, int fr, int fq) const {
;     ...
;                 bf16_t* rowp = base + (size_t)row * ldc + col0;
; #pragma unroll
;                 for (int bj = 0; bj < 2; ++bj) { f32x4 v0 = acc[ai][bj][m][0], v1 = acc[ai][bj][m][1];
;                     if (SM == 1) { v0 *= rs; v1 *= rs; }
;                     if (SM == 2) { v0 *= cs[bj][0]; v1 *= cs[bj][1]; }
;                     if (ACT == 1) {
; #pragma unroll
;                         for (int j = 0; j < 4; ++j) { const float a = fmaxf(v0[j], 0.f), b = fmaxf(v1[j], 0.f); v0[j] = a * a; v1[j] = b * b; } }
;                     if (ACT == 2) { if (tsel == 0) {
; #pragma unroll
;                         for (int j = 0; j < 4; ++j) { const float a = v0[j], b = v1[j];
;                             v0[j] = a * fast_sigmoid(1.5957691216057308f * (a + 0.044715f * a * a * a)); v1[j] = b * fast_sigmoid(1.5957691216057308f * (b + 0.044715f * b * b * b)); } } }
;                     u32x4 w; w.x = pk_bf16(v0[0], v0[1]); w.y = pk_bf16(v0[2], v0[3]); w.z = pk_bf16(v1[0], v1[1]); w.w = pk_bf16(v1[2], v1[3]);
	s_waitcnt lgkmcnt(0)
	v_mfma_f32_16x16x32_bf16 v[114:117], v[194:197], v[138:141], v[114:117]
	v_mfma_f32_16x16x32_bf16 v[34:37], v[202:205], v[138:141], v[34:37]
	v_mfma_f32_16x16x32_bf16 v[38:41], v[194:197], v[170:173], v[38:41]
	v_mfma_f32_16x16x32_bf16 v[42:45], v[202:205], v[170:173], v[42:45]
	v_mfma_f32_16x16x32_bf16 v[46:49], v[194:197], v[178:181], v[46:49]
	v_mfma_f32_16x16x32_bf16 v[50:53], v[202:205], v[178:181], v[50:53]
	v_mfma_f32_16x16x32_bf16 v[54:57], v[194:197], v[186:189], v[54:57]
	v_mfma_f32_16x16x32_bf16 v[58:61], v[202:205], v[186:189], v[58:61]
	v_mfma_f32_16x16x32_bf16 v[114:117], v[198:201], v[142:145], v[114:117]
	v_mfma_f32_16x16x32_bf16 v[34:37], v[206:209], v[142:145], v[34:37]
	v_mfma_f32_16x16x32_bf16 v[38:41], v[198:201], v[174:177], v[38:41]
	v_mfma_f32_16x16x32_bf16 v[42:45], v[206:209], v[174:177], v[42:45]
	v_mfma_f32_16x16x32_bf16 v[46:49], v[198:201], v[182:185], v[46:49]
	v_mfma_f32_16x16x32_bf16 v[50:53], v[206:209], v[182:185], v[50:53]
	v_mfma_f32_16x16x32_bf16 v[54:57], v[198:201], v[190:193], v[54:57]
	v_mfma_f32_16x16x32_bf16 v[58:61], v[206:209], v[190:193], v[58:61]
	s_mov_b32 m0, s58
	v_lshl_add_u64 v[210:211], v[214:215], 0, s[10:11]
	s_barrier
	ds_read_b128 v[138:141], v16 offset:49152
	ds_read_b128 v[142:145], v16 offset:50176
	ds_read_b128 v[170:173], v16 offset:51200
	ds_read_b128 v[174:177], v16 offset:52224
	ds_read_b128 v[178:181], v16 offset:53248
	ds_read_b128 v[182:185], v16 offset:54272
	ds_read_b128 v[186:189], v16 offset:55296
	ds_read_b128 v[190:193], v16 offset:56320
	global_load_lds_dwordx4 v[210:211], off
	v_lshl_add_u64 v[210:211], v[216:217], 0, s[10:11]
	s_mov_b32 m0, s59
	s_nop 0
	global_load_lds_dwordx4 v[210:211], off
	s_barrier
	s_waitcnt lgkmcnt(0)
	v_mfma_f32_16x16x32_bf16 v[146:149], v[122:125], v[138:141], v[146:149]
	v_mfma_f32_16x16x32_bf16 v[150:153], v[130:133], v[138:141], v[150:153]
	v_mfma_f32_16x16x32_bf16 v[154:157], v[122:125], v[170:173], v[154:157]
	v_mfma_f32_16x16x32_bf16 v[158:161], v[130:133], v[170:173], v[158:161]
	v_mfma_f32_16x16x32_bf16 v[162:165], v[122:125], v[178:181], v[162:165]
	v_mfma_f32_16x16x32_bf16 v[166:169], v[130:133], v[178:181], v[166:169]
	v_mfma_f32_16x16x32_bf16 v[18:21], v[122:125], v[186:189], v[18:21]
	v_mfma_f32_16x16x32_bf16 v[22:25], v[130:133], v[186:189], v[22:25]
	v_mfma_f32_16x16x32_bf16 v[146:149], v[126:129], v[142:145], v[146:149]
	v_mfma_f32_16x16x32_bf16 v[150:153], v[134:137], v[142:145], v[150:153]
	v_mfma_f32_16x16x32_bf16 v[154:157], v[126:129], v[174:177], v[154:157]
	v_mfma_f32_16x16x32_bf16 v[158:161], v[134:137], v[174:177], v[158:161]
	v_mfma_f32_16x16x32_bf16 v[162:165], v[126:129], v[182:185], v[162:165]
	v_mfma_f32_16x16x32_bf16 v[166:169], v[134:137], v[182:185], v[166:169]
	v_mfma_f32_16x16x32_bf16 v[18:21], v[126:129], v[190:193], v[18:21]
	v_mfma_f32_16x16x32_bf16 v[22:25], v[134:137], v[190:193], v[22:25]
	s_barrier
	s_add_u32 s48, s52, 0x10080
	s_addc_u32 s49, s53, 0
	s_mov_b32 m0, s51
	v_lshl_add_u64 v[122:123], s[48:49], 0, v[2:3]
	global_load_lds_dwordx4 v[122:123], off
	v_lshl_add_u64 v[122:123], s[48:49], 0, v[6:7]
	s_mov_b32 m0, s50
	s_nop 0
	global_load_lds_dwordx4 v[122:123], off
	s_waitcnt vmcnt(6)
	s_barrier
	v_mfma_f32_16x16x32_bf16 v[26:29], v[194:197], v[138:141], v[26:29]
	v_mfma_f32_16x16x32_bf16 v[30:33], v[202:205], v[138:141], v[30:33]
	v_mfma_f32_16x16x32_bf16 v[62:65], v[194:197], v[170:173], v[62:65]
	v_mfma_f32_16x16x32_bf16 v[106:109], v[202:205], v[170:173], v[106:109]
	v_mfma_f32_16x16x32_bf16 v[110:113], v[194:197], v[178:181], v[110:113]
	v_mfma_f32_16x16x32_bf16 v[118:121], v[202:205], v[178:181], v[118:121]
	v_mfma_f32_16x16x32_bf16 v[98:101], v[194:197], v[186:189], v[98:101]
	v_mfma_f32_16x16x32_bf16 v[102:105], v[202:205], v[186:189], v[102:105]
	v_mfma_f32_16x16x32_bf16 v[26:29], v[198:201], v[142:145], v[26:29]
	v_mfma_f32_16x16x32_bf16 v[30:33], v[206:209], v[142:145], v[30:33]
	v_mfma_f32_16x16x32_bf16 v[62:65], v[198:201], v[174:177], v[62:65]
	v_mfma_f32_16x16x32_bf16 v[106:109], v[206:209], v[174:177], v[106:109]
	v_mfma_f32_16x16x32_bf16 v[110:113], v[198:201], v[182:185], v[110:113]
	v_mfma_f32_16x16x32_bf16 v[118:121], v[206:209], v[182:185], v[118:121]
	v_mfma_f32_16x16x32_bf16 v[98:101], v[198:201], v[190:193], v[98:101]
	v_mfma_f32_16x16x32_bf16 v[102:105], v[206:209], v[190:193], v[102:105]
	v_lshl_add_u32 v122, s38, 8, v12
	v_lshl_or_b32 v124, s68, 8, v14
	v_ashrrev_i32_e32 v125, 31, v124
	v_ashrrev_i32_e32 v123, 31, v122
	v_lshl_add_u64 v[124:125], v[124:125], 1, s[8:9]
	v_lshlrev_b64 v[126:127], 12, v[122:123]
	v_lshl_add_u64 v[126:127], v[124:125], 0, v[126:127]
	v_cvt_pk_bf16_f32 v66, v66, v67
	v_cvt_pk_bf16_f32 v67, v68, v69
	v_cvt_pk_bf16_f32 v68, v70, v71
	v_cvt_pk_bf16_f32 v69, v72, v73
	s_barrier
; __device__ __forceinline__ float fast_sigmoid(float x) { return __builtin_amdgcn_rcpf(1.0f + __builtin_amdgcn_exp2f(-x * LOG2E)); }
;     __device__ __forceinline__ const CAS char* base() const { const CAS char* ka = (const CAS char*)__builtin_amdgcn_kernarg_segment_ptr(); asm volatile("" : "+s"(ka)); return ka; }
; template <class Epi>
; __device__ __forceinline__ void gemm_phase(LAS unsigned char* lds, const Gemm g, const StaticOrder& S, const Epi& E, int wv) {
;     ...
;         if (!has_next) break;
; #pragma unroll
;         for (int a = 0; a < 2; ++a)
; #pragma unroll
;             for (int b = 0; b < 2; ++b)
; #pragma unroll
;                 for (int m = 0; m < 4; ++m)
; #pragma unroll
;                     for (int n = 0; n < 2; ++n) acc[a][b][m][n] = (f32x4){0.f, 0.f, 0.f, 0.f};
;         cur = nxt; cA = nA; cB = nB; ++ui;
;     __device__ __forceinline__ void operator()(const f32x4 (&acc)[2][2][4][2], const Unit& u, int wr, int wc, int fr, int fq) const {
;     ...
;                 bf16_t* rowp = base + (size_t)row * ldc + col0;
; #pragma unroll
;                 for (int bj = 0; bj < 2; ++bj) { f32x4 v0 = acc[ai][bj][m][0], v1 = acc[ai][bj][m][1];
;                     if (SM == 1) { v0 *= rs; v1 *= rs; }
;                     if (SM == 2) { v0 *= cs[bj][0]; v1 *= cs[bj][1]; }
;                     if (ACT == 1) {
; #pragma unroll
;                         for (int j = 0; j < 4; ++j) { const float a = fmaxf(v0[j], 0.f), b = fmaxf(v1[j], 0.f); v0[j] = a * a; v1[j] = b * b; } }
;                     if (ACT == 2) { if (tsel == 0) {
; #pragma unroll
;                         for (int j = 0; j < 4; ++j) { const float a = v0[j], b = v1[j];
;                             v0[j] = a * fast_sigmoid(1.5957691216057308f * (a + 0.044715f * a * a * a)); v1[j] = b * fast_sigmoid(1.5957691216057308f * (b + 0.044715f * b * b * b)); } } }
;                     u32x4 w; w.x = pk_bf16(v0[0], v0[1]); w.y = pk_bf16(v0[2], v0[3]); w.z = pk_bf16(v1[0], v1[1]); w.w = pk_bf16(v1[2], v1[3]);
;                     *(u32x4*)(rowp + bj * HALF) = w; } }
	global_store_dwordx4 v[126:127], v[66:69], off
	v_cvt_pk_bf16_f32 v26, v26, v27
	v_cvt_pk_bf16_f32 v27, v28, v29
	v_cvt_pk_bf16_f32 v68, v34, v35
	v_or_b32_e32 v34, 16, v122
	v_ashrrev_i32_e32 v35, 31, v34
	v_cvt_pk_bf16_f32 v66, v114, v115
	v_cvt_pk_bf16_f32 v67, v116, v117
	v_cvt_pk_bf16_f32 v69, v36, v37
	v_lshlrev_b64 v[34:35], 12, v[34:35]
	global_store_dwordx4 v[126:127], v[66:69], off offset:256
	v_cvt_pk_bf16_f32 v36, v78, v79
	v_cvt_pk_bf16_f32 v37, v80, v81
	v_lshl_add_u64 v[66:67], v[124:125], 0, v[34:35]
	v_cvt_pk_bf16_f32 v34, v74, v75
	v_cvt_pk_bf16_f32 v35, v76, v77
	global_store_dwordx4 v[66:67], v[34:37], off
	v_cvt_pk_bf16_f32 v28, v30, v31
	v_cvt_pk_bf16_f32 v29, v32, v33
	v_cvt_pk_bf16_f32 v34, v38, v39
	v_cvt_pk_bf16_f32 v35, v40, v41
	v_cvt_pk_bf16_f32 v36, v42, v43
	v_cvt_pk_bf16_f32 v37, v44, v45
	global_store_dwordx4 v[66:67], v[34:37], off offset:256
	v_add_co_u32_e32 v40, vcc, s64, v126
	s_nop 0
	v_or_b32_e32 v34, 32, v122
	v_ashrrev_i32_e32 v35, 31, v34
	v_lshlrev_b64 v[34:35], 12, v[34:35]
	v_lshl_add_u64 v[38:39], v[124:125], 0, v[34:35]
	v_cvt_pk_bf16_f32 v34, v82, v83
	v_cvt_pk_bf16_f32 v35, v84, v85
	v_cvt_pk_bf16_f32 v36, v86, v87
	v_cvt_pk_bf16_f32 v37, v88, v89
	global_store_dwordx4 v[38:39], v[34:37], off
	v_addc_co_u32_e32 v41, vcc, 0, v127, vcc
	s_nop 0
	v_cvt_pk_bf16_f32 v34, v46, v47
	v_cvt_pk_bf16_f32 v35, v48, v49
	v_cvt_pk_bf16_f32 v36, v50, v51
	v_cvt_pk_bf16_f32 v37, v52, v53
	global_store_dwordx4 v[38:39], v[34:37], off offset:256
	v_add_co_u32_e32 v32, vcc, s65, v126
	s_nop 0
	v_or_b32_e32 v34, 48, v122
	v_ashrrev_i32_e32 v35, 31, v34
	v_lshlrev_b64 v[34:35], 12, v[34:35]
	v_lshl_add_u64 v[38:39], v[124:125], 0, v[34:35]
	v_cvt_pk_bf16_f32 v34, v90, v91
	v_cvt_pk_bf16_f32 v35, v92, v93
	v_cvt_pk_bf16_f32 v36, v94, v95
	v_cvt_pk_bf16_f32 v37, v96, v97
	global_store_dwordx4 v[38:39], v[34:37], off
	v_addc_co_u32_e32 v33, vcc, 0, v127, vcc
	s_nop 0
	v_cvt_pk_bf16_f32 v34, v54, v55
	v_cvt_pk_bf16_f32 v35, v56, v57
	v_cvt_pk_bf16_f32 v36, v58, v59
	v_cvt_pk_bf16_f32 v37, v60, v61
	global_store_dwordx4 v[38:39], v[34:37], off offset:256
	v_lshl_add_u64 v[38:39], v[126:127], 0, s[16:17]
	global_store_dwordx4 v[38:39], v[26:29], off offset:256
	v_lshl_add_u64 v[30:31], v[126:127], 0, s[18:19]
	v_cvt_pk_bf16_f32 v18, v18, v19
	v_cvt_pk_bf16_f32 v26, v154, v155
	v_cvt_pk_bf16_f32 v27, v156, v157
	v_cvt_pk_bf16_f32 v28, v158, v159
	v_cvt_pk_bf16_f32 v29, v160, v161
	global_store_dwordx4 v[32:33], v[26:29], off
	v_add_co_u32_e32 v32, vcc, s66, v126
	s_nop 0
	v_cvt_pk_bf16_f32 v26, v62, v63
	v_cvt_pk_bf16_f32 v27, v64, v65
	v_cvt_pk_bf16_f32 v28, v106, v107
	v_cvt_pk_bf16_f32 v29, v108, v109
	v_addc_co_u32_e32 v33, vcc, 0, v127, vcc
	global_store_dwordx4 v[30:31], v[26:29], off offset:256
	v_cvt_pk_bf16_f32 v19, v20, v21
	v_cvt_pk_bf16_f32 v20, v22, v23
	v_cvt_pk_bf16_f32 v26, v162, v163
	v_cvt_pk_bf16_f32 v27, v164, v165
	v_cvt_pk_bf16_f32 v28, v166, v167
	v_cvt_pk_bf16_f32 v29, v168, v169
	v_add_co_u32_e32 v22, vcc, s67, v126
	v_readlane_b32 s38, v255, 9
	v_lshl_add_u64 v[30:31], v[126:127], 0, s[30:31]
	global_store_dwordx4 v[32:33], v[26:29], off
	v_cvt_pk_bf16_f32 v21, v24, v25
	v_addc_co_u32_e32 v23, vcc, 0, v127, vcc
	v_cvt_pk_bf16_f32 v26, v110, v111
	v_cvt_pk_bf16_f32 v27, v112, v113
	v_cvt_pk_bf16_f32 v28, v118, v119
	v_cvt_pk_bf16_f32 v29, v120, v121
	s_add_i32 s38, s38, s28
	v_cvt_pk_bf16_f32 v34, v146, v147
	v_cvt_pk_bf16_f32 v35, v148, v149
	v_cvt_pk_bf16_f32 v36, v150, v151
	v_cvt_pk_bf16_f32 v37, v152, v153
	global_store_dwordx4 v[30:31], v[26:29], off offset:256
	global_store_dwordx4 v[22:23], v[18:21], off
	v_writelane_b32 v255, s38, 9
	v_lshl_add_u64 v[26:27], v[126:127], 0, s[34:35]
	v_cvt_pk_bf16_f32 v18, v98, v99
	v_cvt_pk_bf16_f32 v19, v100, v101
	v_cvt_pk_bf16_f32 v20, v102, v103
	v_cvt_pk_bf16_f32 v21, v104, v105
	s_andn2_b64 vcc, exec, s[6:7]
	s_mov_b32 s68, s40
	s_mov_b32 s38, s42
	s_mov_b64 s[50:51], s[46:47]
	s_mov_b64 s[48:49], s[44:45]
	global_store_dwordx4 v[40:41], v[34:37], off
	global_store_dwordx4 v[26:27], v[18:21], off offset:256
	s_cbranch_vccz .LBB0_1782

; #define PG8_STAGE(bufoff, gbase, voff) do { _Pragma("unroll") for (int _i = 0; _i < 2; ++_i) \
;         __builtin_amdgcn_global_load_lds((const unsigned*)((const char*)(gbase) + (voff)[_i]), (LAS unsigned*)(lds + (bufoff) + ldsw + _i * 8192), 16, 0, 0); } while (0)
; #define PG8_LDA(dst, b, h) do { _Pragma("unroll") for (int m = 0; m < 4; ++m) _Pragma("unroll") for (int k = 0; k < 2; ++k) dst[m][k] = *(const LAS bf16x8*)(lds + PG8_SA(b, h) + aoff + m * 2048 + k * 1024); } while (0)
; #define PG8_LDB(dst, b, h) do { _Pragma("unroll") for (int n = 0; n < 2; ++n) _Pragma("unroll") for (int k = 0; k < 2; ++k) dst[n][k] = *(const LAS bf16x8*)(lds + PG8_SB(b, h) + boff + n * 2048 + k * 1024); } while (0)
; #define PG8_MMA(ai, bj, At, Bt) do { __builtin_amdgcn_s_setprio(1); _Pragma("unroll") for (int m = 0; m < 4; ++m) _Pragma("unroll") for (int n = 0; n < 2; ++n) _Pragma("unroll") for (int k = 0; k < 2; ++k) \
;         acc[ai][bj][m][n] = __builtin_amdgcn_mfma_f32_16x16x32_bf16(Bt[n][k], At[m][k], acc[ai][bj][m][n], 0, 0, 0); __builtin_amdgcn_s_setprio(0); } while (0)
; #define PG8_WAIT_V(n) asm volatile("s_waitcnt vmcnt(" #n ")" ::: "memory")
; #define PG8_WAIT_L(n) asm volatile("s_waitcnt lgkmcnt(" #n ")" ::: "memory")
; template <class Epi>
; __device__ __forceinline__ void gemm_phase(LAS unsigned char* lds, const Gemm g, const StaticOrder& S, const Epi& E, int wv) {
;     ...
;         for (int t = 0; t < nt; t += 2) {
;             const bool last = (t == nt - 2);
;             const char* a1 = cA + (ptrdiff_t)(t + 1) * kstep;
;             const char* a2 = last ? nA : cA + (ptrdiff_t)(t + 2) * kstep; const char* b2 = last ? nB : cB + (ptrdiff_t)(t + 2) * kstep;
;             const char* a3 = a2 + kstep; const char* b3 = b2 + kstep;
;             PG8_LDB(B0, 0, 0); PG8_SCHED; PG8_LDA(At, 0, 0); PG8_STAGE(PG8_SA(1, 1), a1 + hstepA, voffA);
;             PG8_WAIT_L(8); PG8_BAR; PG8_WAIT_L(0); PG8_MMA(0, 0, At, B0); PG8_BAR; PG8_SCHED;
;             PG8_LDB(B1, 0, 1); PG8_STAGE(PG8_SB(0, 0), b2, voffB);
;             PG8_BAR; PG8_WAIT_L(0); PG8_MMA(0, 1, At, B1); PG8_BAR;
;             PG8_LDA(At, 0, 1); PG8_STAGE(PG8_SA(0, 0), a2, voffA);
;             PG8_BAR; PG8_WAIT_L(0); PG8_MMA(1, 0, At, B0); PG8_BAR; PG8_SCHED;
;             PG8_STAGE(PG8_SB(0, 1), b2 + hstepB, voffB);
;             PG8_WAIT_V(6); PG8_BAR; PG8_MMA(1, 1, At, B1); PG8_BAR;
.Lrot_in_1853:
	s_add_u32 s30, s28, 0xfff80080
	s_addc_u32 s31, s29, -1
	s_cmp_eq_u32 s54, 28
	s_cselect_b32 s35, s19, s31
	s_cselect_b32 s34, s50, s30
	s_cselect_b32 s31, s17, s53
	s_cselect_b32 s30, s51, s52
	s_add_i32 m0, s25, 0xc000
	ds_read_b128 v[144:147], v194
	ds_read_b128 v[148:151], v194 offset:1024
	ds_read_b128 v[152:155], v194 offset:2048
	ds_read_b128 v[156:159], v194 offset:3072
	ds_read_b128 v[176:179], v194 offset:4096
	ds_read_b128 v[180:183], v194 offset:5120
	ds_read_b128 v[184:187], v194 offset:6144
	ds_read_b128 v[198:201], v194 offset:7168
	global_load_lds_dwordx4 v170, s[28:29]
	s_add_i32 m0, s25, 0xe000
	s_nop 0
	global_load_lds_dwordx4 v168, s[28:29]
	s_waitcnt lgkmcnt(8)
	s_barrier
	s_waitcnt lgkmcnt(0)
	v_mfma_f32_16x16x32_bf16 v[124:127], v[128:131], v[144:147], v[124:127]
	v_mfma_f32_16x16x32_bf16 v[120:123], v[136:139], v[144:147], v[120:123]
	v_mfma_f32_16x16x32_bf16 v[108:111], v[128:131], v[152:155], v[108:111]
	v_mfma_f32_16x16x32_bf16 v[104:107], v[136:139], v[152:155], v[104:107]
	v_mfma_f32_16x16x32_bf16 v[92:95], v[128:131], v[176:179], v[92:95]
	v_mfma_f32_16x16x32_bf16 v[88:91], v[136:139], v[176:179], v[88:91]
	v_mfma_f32_16x16x32_bf16 v[76:79], v[128:131], v[184:187], v[76:79]
	v_mfma_f32_16x16x32_bf16 v[72:75], v[136:139], v[184:187], v[72:75]
	v_mfma_f32_16x16x32_bf16 v[124:127], v[132:135], v[148:151], v[124:127]
	v_mfma_f32_16x16x32_bf16 v[120:123], v[140:143], v[148:151], v[120:123]
	v_mfma_f32_16x16x32_bf16 v[108:111], v[132:135], v[156:159], v[108:111]
	v_mfma_f32_16x16x32_bf16 v[104:107], v[140:143], v[156:159], v[104:107]
	v_mfma_f32_16x16x32_bf16 v[92:95], v[132:135], v[180:183], v[92:95]
	v_mfma_f32_16x16x32_bf16 v[88:91], v[140:143], v[180:183], v[88:91]
	v_mfma_f32_16x16x32_bf16 v[76:79], v[132:135], v[198:201], v[76:79]
	v_mfma_f32_16x16x32_bf16 v[72:75], v[140:143], v[198:201], v[72:75]
	s_barrier
	s_add_i32 s55, s47, s40
	s_add_u32 s98, s30, s12
	s_addc_u32 s99, s31, s13
	s_mov_b32 m0, s55
	ds_read_b128 v[202:205], v195
	ds_read_b128 v[206:209], v195 offset:1024
	ds_read_b128 v[210:213], v195 offset:2048
	ds_read_b128 v[214:217], v195 offset:3072
	global_load_lds_dwordx4 v162, s[30:31]
	s_add_i32 m0, s55, 0x2000
	s_nop 0
	global_load_lds_dwordx4 v166, s[30:31]
	s_barrier
	s_waitcnt lgkmcnt(0)
	v_mfma_f32_16x16x32_bf16 v[116:119], v[202:205], v[144:147], v[116:119]
	v_mfma_f32_16x16x32_bf16 v[112:115], v[210:213], v[144:147], v[112:115]
	v_mfma_f32_16x16x32_bf16 v[100:103], v[202:205], v[152:155], v[100:103]
	v_mfma_f32_16x16x32_bf16 v[96:99], v[210:213], v[152:155], v[96:99]
	v_mfma_f32_16x16x32_bf16 v[84:87], v[202:205], v[176:179], v[84:87]
	v_mfma_f32_16x16x32_bf16 v[80:83], v[210:213], v[176:179], v[80:83]
	v_mfma_f32_16x16x32_bf16 v[68:71], v[202:205], v[184:187], v[68:71]
	v_mfma_f32_16x16x32_bf16 v[64:67], v[210:213], v[184:187], v[64:67]
	v_mfma_f32_16x16x32_bf16 v[116:119], v[206:209], v[148:151], v[116:119]
	v_mfma_f32_16x16x32_bf16 v[112:115], v[214:217], v[148:151], v[112:115]
	v_mfma_f32_16x16x32_bf16 v[100:103], v[206:209], v[156:159], v[100:103]
	v_mfma_f32_16x16x32_bf16 v[96:99], v[214:217], v[156:159], v[96:99]
	v_mfma_f32_16x16x32_bf16 v[84:87], v[206:209], v[180:183], v[84:87]
	v_mfma_f32_16x16x32_bf16 v[80:83], v[214:217], v[180:183], v[80:83]
	v_mfma_f32_16x16x32_bf16 v[68:71], v[206:209], v[198:201], v[68:71]
	v_mfma_f32_16x16x32_bf16 v[64:67], v[214:217], v[198:201], v[64:67]
	s_mov_b32 m0, s25
	s_add_u32 s100, s34, s12
	s_addc_u32 s101, s35, s13
	s_barrier
	ds_read_b128 v[144:147], v194 offset:16384
	ds_read_b128 v[148:151], v194 offset:17408
	ds_read_b128 v[152:155], v194 offset:18432
	ds_read_b128 v[156:159], v194 offset:19456
	ds_read_b128 v[176:179], v194 offset:20480
	ds_read_b128 v[180:183], v194 offset:21504
	ds_read_b128 v[184:187], v194 offset:22528
	ds_read_b128 v[198:201], v194 offset:23552
	global_load_lds_dwordx4 v160, s[34:35]
	s_mov_b32 m0, s41
	s_nop 0
	global_load_lds_dwordx4 v164, s[34:35]
	s_waitcnt vmcnt(10)
	s_barrier
	s_waitcnt lgkmcnt(0)
	v_mfma_f32_16x16x32_bf16 v[60:63], v[128:131], v[144:147], v[60:63]
	v_mfma_f32_16x16x32_bf16 v[56:59], v[136:139], v[144:147], v[56:59]
	v_mfma_f32_16x16x32_bf16 v[44:47], v[128:131], v[152:155], v[44:47]
	v_mfma_f32_16x16x32_bf16 v[40:43], v[136:139], v[152:155], v[40:43]
	v_mfma_f32_16x16x32_bf16 v[28:31], v[128:131], v[176:179], v[28:31]
	v_mfma_f32_16x16x32_bf16 v[24:27], v[136:139], v[176:179], v[24:27]
	v_mfma_f32_16x16x32_bf16 v[12:15], v[128:131], v[184:187], v[12:15]
	v_mfma_f32_16x16x32_bf16 v[8:11], v[136:139], v[184:187], v[8:11]
	v_mfma_f32_16x16x32_bf16 v[60:63], v[132:135], v[148:151], v[60:63]
	v_mfma_f32_16x16x32_bf16 v[56:59], v[140:143], v[148:151], v[56:59]
	v_mfma_f32_16x16x32_bf16 v[44:47], v[132:135], v[156:159], v[44:47]
	v_mfma_f32_16x16x32_bf16 v[40:43], v[140:143], v[156:159], v[40:43]
	v_mfma_f32_16x16x32_bf16 v[28:31], v[132:135], v[180:183], v[28:31]
	v_mfma_f32_16x16x32_bf16 v[24:27], v[140:143], v[180:183], v[24:27]
	v_mfma_f32_16x16x32_bf16 v[12:15], v[132:135], v[198:201], v[12:15]
	v_mfma_f32_16x16x32_bf16 v[8:11], v[140:143], v[198:201], v[8:11]
	s_barrier
	s_add_u32 s56, s30, 0x80000
	s_addc_u32 s57, s31, 0
	s_add_i32 s55, s48, s40
	s_mov_b32 m0, s55
	s_nop 0
	global_load_lds_dwordx4 v162, s[56:57]
	s_add_i32 m0, s55, 0x2000
	s_nop 0
	global_load_lds_dwordx4 v166, s[56:57]
	s_add_i32 s55, 0, 0x18000
	v_add_u32_e32 v140, s55, v191
	ds_read_b128 v[128:131], v140
	ds_read_b128 v[132:135], v140 offset:1024
	ds_read_b128 v[136:139], v140 offset:2048
	ds_read_b128 v[140:143], v140 offset:3072
	s_waitcnt vmcnt(6)
	s_barrier
; #define PG8_STAGE(bufoff, gbase, voff) do { _Pragma("unroll") for (int _i = 0; _i < 2; ++_i) \
;         __builtin_amdgcn_global_load_lds((const unsigned*)((const char*)(gbase) + (voff)[_i]), (LAS unsigned*)(lds + (bufoff) + ldsw + _i * 8192), 16, 0, 0); } while (0)
; #define PG8_LDA(dst, b, h) do { _Pragma("unroll") for (int m = 0; m < 4; ++m) _Pragma("unroll") for (int k = 0; k < 2; ++k) dst[m][k] = *(const LAS bf16x8*)(lds + PG8_SA(b, h) + aoff + m * 2048 + k * 1024); } while (0)
; #define PG8_LDB(dst, b, h) do { _Pragma("unroll") for (int n = 0; n < 2; ++n) _Pragma("unroll") for (int k = 0; k < 2; ++k) dst[n][k] = *(const LAS bf16x8*)(lds + PG8_SB(b, h) + boff + n * 2048 + k * 1024); } while (0)
; #define PG8_MMA(ai, bj, At, Bt) do { __builtin_amdgcn_s_setprio(1); _Pragma("unroll") for (int m = 0; m < 4; ++m) _Pragma("unroll") for (int n = 0; n < 2; ++n) _Pragma("unroll") for (int k = 0; k < 2; ++k) \
;         acc[ai][bj][m][n] = __builtin_amdgcn_mfma_f32_16x16x32_bf16(Bt[n][k], At[m][k], acc[ai][bj][m][n], 0, 0, 0); __builtin_amdgcn_s_setprio(0); } while (0)
; #define PG8_WAIT_V(n) asm volatile("s_waitcnt vmcnt(" #n ")" ::: "memory")
; #define PG8_WAIT_L(n) asm volatile("s_waitcnt lgkmcnt(" #n ")" ::: "memory")
; #define PG8_BAR __builtin_amdgcn_s_barrier()
; #define PG8_SCHED __builtin_amdgcn_sched_barrier(0)
; template <class Epi>
; __device__ __forceinline__ void gemm_phase(LAS unsigned char* lds, const Gemm g, const StaticOrder& S, const Epi& E, int wv) {
;     ...
;             PG8_WAIT_V(6); PG8_BAR; PG8_MMA(1, 1, At, B1); PG8_BAR;
;             PG8_LDB(B0, 1, 0); PG8_SCHED; PG8_LDA(At, 1, 0); PG8_STAGE(PG8_SA(0, 1), a2 + hstepA, voffA);
;             PG8_WAIT_L(8); PG8_BAR; PG8_WAIT_L(0); PG8_MMA(0, 0, At, B0); PG8_BAR; PG8_SCHED;
;             PG8_LDB(B1, 1, 1); PG8_STAGE(PG8_SB(1, 0), b3, voffB);
;             PG8_BAR; PG8_WAIT_L(0); PG8_MMA(0, 1, At, B1); PG8_BAR;
;             PG8_LDA(At, 1, 1); PG8_STAGE(PG8_SA(1, 0), a3, voffA);
;             PG8_BAR; PG8_WAIT_L(0); PG8_MMA(1, 0, At, B0); PG8_BAR; PG8_SCHED;
;             PG8_STAGE(PG8_SB(1, 1), b3 + hstepB, voffB);
;             PG8_WAIT_V(6); PG8_BAR; PG8_MMA(1, 1, At, B1); PG8_BAR;
	v_mfma_f32_16x16x32_bf16 v[52:55], v[202:205], v[144:147], v[52:55]
	v_mfma_f32_16x16x32_bf16 v[48:51], v[210:213], v[144:147], v[48:51]
	v_mfma_f32_16x16x32_bf16 v[36:39], v[202:205], v[152:155], v[36:39]
	v_mfma_f32_16x16x32_bf16 v[32:35], v[210:213], v[152:155], v[32:35]
	v_mfma_f32_16x16x32_bf16 v[20:23], v[202:205], v[176:179], v[20:23]
	v_mfma_f32_16x16x32_bf16 v[16:19], v[210:213], v[176:179], v[16:19]
	v_mfma_f32_16x16x32_bf16 v[4:7], v[202:205], v[184:187], v[4:7]
	v_mfma_f32_16x16x32_bf16 v[0:3], v[210:213], v[184:187], v[0:3]
	v_mfma_f32_16x16x32_bf16 v[52:55], v[206:209], v[148:151], v[52:55]
	v_mfma_f32_16x16x32_bf16 v[48:51], v[214:217], v[148:151], v[48:51]
	v_mfma_f32_16x16x32_bf16 v[36:39], v[206:209], v[156:159], v[36:39]
	v_mfma_f32_16x16x32_bf16 v[32:35], v[214:217], v[156:159], v[32:35]
	v_mfma_f32_16x16x32_bf16 v[20:23], v[206:209], v[180:183], v[20:23]
	v_mfma_f32_16x16x32_bf16 v[16:19], v[214:217], v[180:183], v[16:19]
	v_mfma_f32_16x16x32_bf16 v[4:7], v[206:209], v[198:201], v[4:7]
	v_mfma_f32_16x16x32_bf16 v[0:3], v[214:217], v[198:201], v[0:3]
	s_waitcnt lgkmcnt(0)
	s_barrier
	s_add_u32 s34, s34, 0x80000
	s_addc_u32 s35, s35, 0
	s_mov_b32 m0, s42
	ds_read_b128 v[144:147], v194 offset:32768
	ds_read_b128 v[148:151], v194 offset:33792
	ds_read_b128 v[152:155], v194 offset:34816
	ds_read_b128 v[156:159], v194 offset:35840
	ds_read_b128 v[176:179], v194 offset:36864
	ds_read_b128 v[180:183], v194 offset:37888
	ds_read_b128 v[184:187], v194 offset:38912
	ds_read_b128 v[198:201], v194 offset:39936
	global_load_lds_dwordx4 v160, s[34:35]
	s_mov_b32 m0, s43
	s_nop 0
	global_load_lds_dwordx4 v164, s[34:35]
	s_waitcnt lgkmcnt(8)
	s_barrier
	s_waitcnt lgkmcnt(0)
	v_mfma_f32_16x16x32_bf16 v[124:127], v[128:131], v[144:147], v[124:127]
	v_mfma_f32_16x16x32_bf16 v[120:123], v[136:139], v[144:147], v[120:123]
	v_mfma_f32_16x16x32_bf16 v[108:111], v[128:131], v[152:155], v[108:111]
	v_mfma_f32_16x16x32_bf16 v[104:107], v[136:139], v[152:155], v[104:107]
	v_mfma_f32_16x16x32_bf16 v[92:95], v[128:131], v[176:179], v[92:95]
	v_mfma_f32_16x16x32_bf16 v[88:91], v[136:139], v[176:179], v[88:91]
	v_mfma_f32_16x16x32_bf16 v[76:79], v[128:131], v[184:187], v[76:79]
	v_mfma_f32_16x16x32_bf16 v[72:75], v[136:139], v[184:187], v[72:75]
	v_mfma_f32_16x16x32_bf16 v[124:127], v[132:135], v[148:151], v[124:127]
	v_mfma_f32_16x16x32_bf16 v[120:123], v[140:143], v[148:151], v[120:123]
	v_mfma_f32_16x16x32_bf16 v[108:111], v[132:135], v[156:159], v[108:111]
	v_mfma_f32_16x16x32_bf16 v[104:107], v[140:143], v[156:159], v[104:107]
	v_mfma_f32_16x16x32_bf16 v[92:95], v[132:135], v[180:183], v[92:95]
	v_mfma_f32_16x16x32_bf16 v[88:91], v[140:143], v[180:183], v[88:91]
	v_mfma_f32_16x16x32_bf16 v[76:79], v[132:135], v[198:201], v[76:79]
	v_mfma_f32_16x16x32_bf16 v[72:75], v[140:143], v[198:201], v[72:75]
	s_barrier
	s_add_i32 s34, 0, 0x1c000
	s_add_i32 s35, s55, s40
	v_add_u32_e32 v197, s34, v191
	s_mov_b32 m0, s35
	ds_read_b128 v[202:205], v197
	ds_read_b128 v[206:209], v197 offset:1024
	ds_read_b128 v[210:213], v197 offset:2048
	ds_read_b128 v[214:217], v197 offset:3072
	global_load_lds_dwordx4 v162, s[98:99]
	s_add_i32 m0, s35, 0x2000
	s_nop 0
	global_load_lds_dwordx4 v166, s[98:99]
	s_barrier
	s_waitcnt lgkmcnt(0)
	v_mfma_f32_16x16x32_bf16 v[116:119], v[202:205], v[144:147], v[116:119]
	v_mfma_f32_16x16x32_bf16 v[112:115], v[210:213], v[144:147], v[112:115]
	v_mfma_f32_16x16x32_bf16 v[100:103], v[202:205], v[152:155], v[100:103]
	v_mfma_f32_16x16x32_bf16 v[96:99], v[210:213], v[152:155], v[96:99]
	v_mfma_f32_16x16x32_bf16 v[84:87], v[202:205], v[176:179], v[84:87]
	v_mfma_f32_16x16x32_bf16 v[80:83], v[210:213], v[176:179], v[80:83]
	v_mfma_f32_16x16x32_bf16 v[68:71], v[202:205], v[184:187], v[68:71]
	v_mfma_f32_16x16x32_bf16 v[64:67], v[210:213], v[184:187], v[64:67]
	v_mfma_f32_16x16x32_bf16 v[116:119], v[206:209], v[148:151], v[116:119]
	v_mfma_f32_16x16x32_bf16 v[112:115], v[214:217], v[148:151], v[112:115]
	v_mfma_f32_16x16x32_bf16 v[100:103], v[206:209], v[156:159], v[100:103]
	v_mfma_f32_16x16x32_bf16 v[96:99], v[214:217], v[156:159], v[96:99]
	v_mfma_f32_16x16x32_bf16 v[84:87], v[206:209], v[180:183], v[84:87]
	v_mfma_f32_16x16x32_bf16 v[80:83], v[214:217], v[180:183], v[80:83]
	v_mfma_f32_16x16x32_bf16 v[68:71], v[206:209], v[198:201], v[68:71]
	v_mfma_f32_16x16x32_bf16 v[64:67], v[214:217], v[198:201], v[64:67]
	s_mov_b32 m0, s45
	s_barrier
	ds_read_b128 v[144:147], v194 offset:49152
	ds_read_b128 v[148:151], v194 offset:50176
	ds_read_b128 v[152:155], v194 offset:51200
	ds_read_b128 v[156:159], v194 offset:52224
	ds_read_b128 v[176:179], v194 offset:53248
	ds_read_b128 v[180:183], v194 offset:54272
	ds_read_b128 v[184:187], v194 offset:55296
	ds_read_b128 v[198:201], v194 offset:56320
	global_load_lds_dwordx4 v160, s[100:101]
	s_mov_b32 m0, s46
	s_nop 0
	global_load_lds_dwordx4 v164, s[100:101]
	s_waitcnt vmcnt(10)
	s_barrier
	s_waitcnt lgkmcnt(0)
	v_mfma_f32_16x16x32_bf16 v[60:63], v[128:131], v[144:147], v[60:63]
	v_mfma_f32_16x16x32_bf16 v[56:59], v[136:139], v[144:147], v[56:59]
	v_mfma_f32_16x16x32_bf16 v[44:47], v[128:131], v[152:155], v[44:47]
	v_mfma_f32_16x16x32_bf16 v[40:43], v[136:139], v[152:155], v[40:43]
	v_mfma_f32_16x16x32_bf16 v[28:31], v[128:131], v[176:179], v[28:31]
	v_mfma_f32_16x16x32_bf16 v[24:27], v[136:139], v[176:179], v[24:27]
	v_mfma_f32_16x16x32_bf16 v[12:15], v[128:131], v[184:187], v[12:15]
	v_mfma_f32_16x16x32_bf16 v[8:11], v[136:139], v[184:187], v[8:11]
	v_mfma_f32_16x16x32_bf16 v[60:63], v[132:135], v[148:151], v[60:63]
	v_mfma_f32_16x16x32_bf16 v[56:59], v[140:143], v[148:151], v[56:59]
	v_mfma_f32_16x16x32_bf16 v[44:47], v[132:135], v[156:159], v[44:47]
	v_mfma_f32_16x16x32_bf16 v[40:43], v[140:143], v[156:159], v[40:43]
	v_mfma_f32_16x16x32_bf16 v[28:31], v[132:135], v[180:183], v[28:31]
	v_mfma_f32_16x16x32_bf16 v[24:27], v[140:143], v[180:183], v[24:27]
	v_mfma_f32_16x16x32_bf16 v[12:15], v[132:135], v[198:201], v[12:15]
	v_mfma_f32_16x16x32_bf16 v[8:11], v[140:143], v[198:201], v[8:11]
	s_barrier
	s_add_u32 s30, s30, 0x80080
	s_addc_u32 s31, s31, 0
	s_add_i32 s34, s34, s40
	s_mov_b32 m0, s34
	s_nop 0
	global_load_lds_dwordx4 v162, s[30:31]
	s_add_i32 m0, s34, 0x2000
	s_nop 0
	global_load_lds_dwordx4 v166, s[30:31]
	ds_read_b128 v[128:131], v193
	ds_read_b128 v[132:135], v193 offset:1024
	ds_read_b128 v[136:139], v193 offset:2048
	ds_read_b128 v[140:143], v193 offset:3072
	s_waitcnt vmcnt(6)
	s_branch .LBB0_1853
